# K-loop: merged vmcnt+lgkmcnt waits before each barrier; pointer/counter bumps moved from behind the last barrier into the first MFMA block's tail
# baseline (speedup 1.0000x reference)
; #define PG8_STAGE(bufoff, gbase, voff, p64) do { _Pragma("unroll") for (int _i = 0; _i < 2; ++_i) { \
;         const char* _gb = (const char*)(gbase) + (size_t)_i * (p64); const unsigned _la = ldsbase + (unsigned)(bufoff) + (unsigned)_i * 8192u; \
;         asm volatile("s_mov_b32 m0, %0\n\ts_nop 0\n\tglobal_load_lds_dwordx4 %1, %2" :: "s"(_la), "v"(voff), "s"(_gb) : "memory"); } } while (0)
; #define PG8_LDA(dst, b, h) do { _Pragma("unroll") for (int m = 0; m < 4; ++m) _Pragma("unroll") for (int k = 0; k < 2; ++k) dst[m][k] = *(const LAS bf16x8*)(lds + PG8_SA(b, h) + aoff + m * 2048 + k * 1024); } while (0)
; #define PG8_LDB(dst, b, h) do { _Pragma("unroll") for (int n = 0; n < 2; ++n) _Pragma("unroll") for (int k = 0; k < 2; ++k) dst[n][k] = *(const LAS bf16x8*)(lds + PG8_SB(b, h) + boff + n * 2048 + k * 1024); } while (0)
; #define PG8_MMA(ai, bj, At, Bt) do { __builtin_amdgcn_s_setprio(1); _Pragma("unroll") for (int m = 0; m < 4; ++m) _Pragma("unroll") for (int n = 0; n < 2; ++n) _Pragma("unroll") for (int k = 0; k < 2; ++k) \
;         acc[ai][bj][m][n] = __builtin_amdgcn_mfma_f32_16x16x32_bf16(Bt[n][k], At[m][k], acc[ai][bj][m][n], 0, 0, 0); __builtin_amdgcn_s_setprio(0); } while (0)
; #define PG8_WAIT_V(n) asm volatile("s_waitcnt vmcnt(" #n ")" ::: "memory")
; #define PG8_BAR __builtin_amdgcn_s_barrier()
; template <class Epi, class Sched>
; __device__ __forceinline__ void gemm_phase(LAS unsigned char* lds, const Sched& S, const Epi& E) {
;     ...
;             const bool last = (t == nt - 2);
;             const char* a1 = cA + (size_t)(t + 1) * kstep;
;             const char* a2 = last ? nA : cA + (size_t)(t + 2) * kstep; const char* b2 = last ? nB : cB + (size_t)(t + 2) * kstep;
;             const char* a3 = a2 + kstep; const char* b3 = b2 + kstep;
;             const unsigned vA2 = voffA, vB2 = voffB, hA2 = hA, hB2 = hB;
;             PG8_LDB(B0, 0, 0); PG8_LDB(B1, 0, 1); PG8_SCHED; PG8_LDA(At, 0, 0); PG8_STAGE(PG8_SA(1, 1), a1 + hA, voffA, hA / 2);
;             PG8_WAIT_V(8); PG8_WAIT_L(0); PG8_BAR; PG8_MMA(0, 0, At, B0); PG8_MMA(0, 1, At, B1); PG8_BAR; PG8_SCHED;
;             PG8_LDA(At, 0, 1); PG8_STAGE(PG8_SB(0, 0), b2, vB2, hB2 / 2); PG8_STAGE(PG8_SB(0, 1), b2 + hB2, vB2, hB2 / 2); PG8_STAGE(PG8_SA(0, 0), a2, vA2, hA2 / 2);
;             PG8_WAIT_V(8); PG8_WAIT_L(0); PG8_BAR; PG8_MMA(1, 0, At, B0); PG8_MMA(1, 1, At, B1); PG8_BAR; PG8_SCHED;
.LBB0_304:
	ds_read_b128 v[144:147], v138
	ds_read_b128 v[148:151], v138 offset:1024
	ds_read_b128 v[152:155], v138 offset:2048
	ds_read_b128 v[156:159], v138 offset:3072
	ds_read_b128 v[160:163], v139
	ds_read_b128 v[164:167], v139 offset:1024
	ds_read_b128 v[168:171], v139 offset:2048
	ds_read_b128 v[172:175], v139 offset:3072
	s_add_u32 s30, s38, 0xfffc0080
	s_addc_u32 s31, s39, -1
	s_cmp_eq_u32 s64, 12
	s_cselect_b32 s40, s24, s30
	s_cselect_b32 s41, s25, s31
	s_cselect_b32 s44, s26, s62
	s_cselect_b32 s45, s27, s63
	s_add_u32 s42, s40, 0x80
	s_addc_u32 s43, s41, 0
	ds_read_b128 v[178:181], v140
	ds_read_b128 v[182:185], v140 offset:1024
	ds_read_b128 v[186:189], v140 offset:2048
	ds_read_b128 v[190:193], v140 offset:3072
	ds_read_b128 v[194:197], v140 offset:4096
	ds_read_b128 v[198:201], v140 offset:5120
	ds_read_b128 v[202:205], v140 offset:6144
	ds_read_b128 v[206:209], v140 offset:7168
	s_mov_b32 m0, s55
	s_nop 0
	global_load_lds_dwordx4 v134, s[38:39]
	s_add_u32 s66, s38, 0x20000
	s_mov_b32 m0, s56
	s_addc_u32 s67, s39, 0
	global_load_lds_dwordx4 v134, s[66:67]
	s_waitcnt vmcnt(8) lgkmcnt(0)
	s_barrier
	s_setprio 1
	v_mfma_f32_16x16x32_bf16 v[124:127], v[144:147], v[178:181], v[124:127]
	v_mfma_f32_16x16x32_bf16 v[120:123], v[152:155], v[178:181], v[120:123]
	v_mfma_f32_16x16x32_bf16 v[108:111], v[144:147], v[186:189], v[108:111]
	v_mfma_f32_16x16x32_bf16 v[104:107], v[152:155], v[186:189], v[104:107]
	v_mfma_f32_16x16x32_bf16 v[92:95], v[144:147], v[194:197], v[92:95]
	v_mfma_f32_16x16x32_bf16 v[88:91], v[152:155], v[194:197], v[88:91]
	v_mfma_f32_16x16x32_bf16 v[76:79], v[144:147], v[202:205], v[76:79]
	v_mfma_f32_16x16x32_bf16 v[72:75], v[152:155], v[202:205], v[72:75]
	v_mfma_f32_16x16x32_bf16 v[124:127], v[148:151], v[182:185], v[124:127]
	v_mfma_f32_16x16x32_bf16 v[120:123], v[156:159], v[182:185], v[120:123]
	v_mfma_f32_16x16x32_bf16 v[108:111], v[148:151], v[190:193], v[108:111]
	v_mfma_f32_16x16x32_bf16 v[104:107], v[156:159], v[190:193], v[104:107]
	v_mfma_f32_16x16x32_bf16 v[92:95], v[148:151], v[198:201], v[92:95]
	v_mfma_f32_16x16x32_bf16 v[88:91], v[156:159], v[198:201], v[88:91]
	v_mfma_f32_16x16x32_bf16 v[76:79], v[148:151], v[206:209], v[76:79]
	v_mfma_f32_16x16x32_bf16 v[72:75], v[156:159], v[206:209], v[72:75]
	s_add_i32 s64, s64, 2
	s_add_u32 s38, s38, 0x100
	s_addc_u32 s39, s39, 0
	s_add_u32 s62, s62, 0x100
	s_addc_u32 s63, s63, 0
	v_mfma_f32_16x16x32_bf16 v[116:119], v[160:163], v[178:181], v[116:119]
	v_mfma_f32_16x16x32_bf16 v[112:115], v[168:171], v[178:181], v[112:115]
	v_mfma_f32_16x16x32_bf16 v[100:103], v[160:163], v[186:189], v[100:103]
	v_mfma_f32_16x16x32_bf16 v[96:99], v[168:171], v[186:189], v[96:99]
	v_mfma_f32_16x16x32_bf16 v[84:87], v[160:163], v[194:197], v[84:87]
	v_mfma_f32_16x16x32_bf16 v[80:83], v[168:171], v[194:197], v[80:83]
	v_mfma_f32_16x16x32_bf16 v[68:71], v[160:163], v[202:205], v[68:71]
	v_mfma_f32_16x16x32_bf16 v[64:67], v[168:171], v[202:205], v[64:67]
	v_mfma_f32_16x16x32_bf16 v[116:119], v[164:167], v[182:185], v[116:119]
	v_mfma_f32_16x16x32_bf16 v[112:115], v[172:175], v[182:185], v[112:115]
	v_mfma_f32_16x16x32_bf16 v[100:103], v[164:167], v[190:193], v[100:103]
	v_mfma_f32_16x16x32_bf16 v[96:99], v[172:175], v[190:193], v[96:99]
	v_mfma_f32_16x16x32_bf16 v[84:87], v[164:167], v[198:201], v[84:87]
	v_mfma_f32_16x16x32_bf16 v[80:83], v[172:175], v[198:201], v[80:83]
	v_mfma_f32_16x16x32_bf16 v[68:71], v[164:167], v[206:209], v[68:71]
	v_mfma_f32_16x16x32_bf16 v[64:67], v[172:175], v[206:209], v[64:67]
	s_setprio 0
	s_barrier
	s_add_u32 s66, s44, 0x20000
	ds_read_b128 v[178:181], v140 offset:16384
	ds_read_b128 v[182:185], v140 offset:17408
	ds_read_b128 v[186:189], v140 offset:18432
	ds_read_b128 v[190:193], v140 offset:19456
	ds_read_b128 v[194:197], v140 offset:20480
	ds_read_b128 v[198:201], v140 offset:21504
	ds_read_b128 v[202:205], v140 offset:22528
	ds_read_b128 v[206:209], v140 offset:23552
	s_mov_b32 m0, s33
	s_nop 0
	global_load_lds_dwordx4 v135, s[44:45]
	s_mov_b32 m0, s34
	s_addc_u32 s67, s45, 0
	global_load_lds_dwordx4 v135, s[66:67]
	s_add_u32 s66, s44, 0x40000
	s_mov_b32 m0, s35
	s_addc_u32 s67, s45, 0
	global_load_lds_dwordx4 v135, s[66:67]
	s_add_u32 s66, s44, 0x60000
	s_mov_b32 m0, s36
	s_addc_u32 s67, s45, 0
	global_load_lds_dwordx4 v135, s[66:67]
	s_mov_b32 m0, s12
	s_nop 0
	global_load_lds_dwordx4 v134, s[40:41]
	s_add_u32 s66, s40, 0x20000
	s_mov_b32 m0, s37
	s_addc_u32 s67, s41, 0
	global_load_lds_dwordx4 v134, s[66:67]
	s_waitcnt vmcnt(8) lgkmcnt(0)
	s_barrier
; #define PG8_STAGE(bufoff, gbase, voff, p64) do { _Pragma("unroll") for (int _i = 0; _i < 2; ++_i) { \
;         const char* _gb = (const char*)(gbase) + (size_t)_i * (p64); const unsigned _la = ldsbase + (unsigned)(bufoff) + (unsigned)_i * 8192u; \
;         asm volatile("s_mov_b32 m0, %0\n\ts_nop 0\n\tglobal_load_lds_dwordx4 %1, %2" :: "s"(_la), "v"(voff), "s"(_gb) : "memory"); } } while (0)
; #define PG8_LDA(dst, b, h) do { _Pragma("unroll") for (int m = 0; m < 4; ++m) _Pragma("unroll") for (int k = 0; k < 2; ++k) dst[m][k] = *(const LAS bf16x8*)(lds + PG8_SA(b, h) + aoff + m * 2048 + k * 1024); } while (0)
; #define PG8_LDB(dst, b, h) do { _Pragma("unroll") for (int n = 0; n < 2; ++n) _Pragma("unroll") for (int k = 0; k < 2; ++k) dst[n][k] = *(const LAS bf16x8*)(lds + PG8_SB(b, h) + boff + n * 2048 + k * 1024); } while (0)
; #define PG8_MMA(ai, bj, At, Bt) do { __builtin_amdgcn_s_setprio(1); _Pragma("unroll") for (int m = 0; m < 4; ++m) _Pragma("unroll") for (int n = 0; n < 2; ++n) _Pragma("unroll") for (int k = 0; k < 2; ++k) \
;         acc[ai][bj][m][n] = __builtin_amdgcn_mfma_f32_16x16x32_bf16(Bt[n][k], At[m][k], acc[ai][bj][m][n], 0, 0, 0); __builtin_amdgcn_s_setprio(0); } while (0)
; #define PG8_WAIT_V(n) asm volatile("s_waitcnt vmcnt(" #n ")" ::: "memory")
; #define PG8_WAIT_L(n) asm volatile("s_waitcnt lgkmcnt(" #n ")" ::: "memory")
; #define PG8_BAR __builtin_amdgcn_s_barrier()
; #define PG8_SCHED __builtin_amdgcn_sched_barrier(0)
; template <class Epi, class Sched>
; __device__ __forceinline__ void gemm_phase(LAS unsigned char* lds, const Sched& S, const Epi& E) {
;     ...
;             PG8_WAIT_V(8); PG8_WAIT_L(0); PG8_BAR; PG8_MMA(1, 0, At, B0); PG8_MMA(1, 1, At, B1); PG8_BAR; PG8_SCHED;
;             PG8_LDB(B0, 1, 0); PG8_LDB(B1, 1, 1); PG8_SCHED; PG8_LDA(At, 1, 0); PG8_STAGE(PG8_SA(0, 1), a2 + hA2, vA2, hA2 / 2);
;             PG8_WAIT_V(8); PG8_WAIT_L(0); PG8_BAR; PG8_MMA(0, 0, At, B0); PG8_MMA(0, 1, At, B1); PG8_BAR; PG8_SCHED;
	s_setprio 1
	v_mfma_f32_16x16x32_bf16 v[60:63], v[144:147], v[178:181], v[60:63]
	v_mfma_f32_16x16x32_bf16 v[56:59], v[152:155], v[178:181], v[56:59]
	v_mfma_f32_16x16x32_bf16 v[44:47], v[144:147], v[186:189], v[44:47]
	v_mfma_f32_16x16x32_bf16 v[40:43], v[152:155], v[186:189], v[40:43]
	v_mfma_f32_16x16x32_bf16 v[28:31], v[144:147], v[194:197], v[28:31]
	v_mfma_f32_16x16x32_bf16 v[24:27], v[152:155], v[194:197], v[24:27]
	v_mfma_f32_16x16x32_bf16 v[12:15], v[144:147], v[202:205], v[12:15]
	v_mfma_f32_16x16x32_bf16 v[8:11], v[152:155], v[202:205], v[8:11]
	v_mfma_f32_16x16x32_bf16 v[60:63], v[148:151], v[182:185], v[60:63]
	v_mfma_f32_16x16x32_bf16 v[56:59], v[156:159], v[182:185], v[56:59]
	v_mfma_f32_16x16x32_bf16 v[44:47], v[148:151], v[190:193], v[44:47]
	v_mfma_f32_16x16x32_bf16 v[40:43], v[156:159], v[190:193], v[40:43]
	v_mfma_f32_16x16x32_bf16 v[28:31], v[148:151], v[198:201], v[28:31]
	v_mfma_f32_16x16x32_bf16 v[24:27], v[156:159], v[198:201], v[24:27]
	v_mfma_f32_16x16x32_bf16 v[12:15], v[148:151], v[206:209], v[12:15]
	v_mfma_f32_16x16x32_bf16 v[8:11], v[156:159], v[206:209], v[8:11]
	v_mfma_f32_16x16x32_bf16 v[52:55], v[160:163], v[178:181], v[52:55]
	v_mfma_f32_16x16x32_bf16 v[48:51], v[168:171], v[178:181], v[48:51]
	v_mfma_f32_16x16x32_bf16 v[36:39], v[160:163], v[186:189], v[36:39]
	v_mfma_f32_16x16x32_bf16 v[32:35], v[168:171], v[186:189], v[32:35]
	v_mfma_f32_16x16x32_bf16 v[20:23], v[160:163], v[194:197], v[20:23]
	v_mfma_f32_16x16x32_bf16 v[16:19], v[168:171], v[194:197], v[16:19]
	v_mfma_f32_16x16x32_bf16 v[4:7], v[160:163], v[202:205], v[4:7]
	v_mfma_f32_16x16x32_bf16 v[0:3], v[168:171], v[202:205], v[0:3]
	v_mfma_f32_16x16x32_bf16 v[52:55], v[164:167], v[182:185], v[52:55]
	v_mfma_f32_16x16x32_bf16 v[48:51], v[172:175], v[182:185], v[48:51]
	v_mfma_f32_16x16x32_bf16 v[36:39], v[164:167], v[190:193], v[36:39]
	v_mfma_f32_16x16x32_bf16 v[32:35], v[172:175], v[190:193], v[32:35]
	v_mfma_f32_16x16x32_bf16 v[20:23], v[164:167], v[198:201], v[20:23]
	v_mfma_f32_16x16x32_bf16 v[16:19], v[172:175], v[198:201], v[16:19]
	v_mfma_f32_16x16x32_bf16 v[4:7], v[164:167], v[206:209], v[4:7]
	v_mfma_f32_16x16x32_bf16 v[0:3], v[172:175], v[206:209], v[0:3]
	s_setprio 0
	s_barrier
	ds_read_b128 v[144:147], v141
	ds_read_b128 v[148:151], v141 offset:1024
	ds_read_b128 v[152:155], v141 offset:2048
	ds_read_b128 v[156:159], v141 offset:3072
	ds_read_b128 v[160:163], v142
	ds_read_b128 v[164:167], v142 offset:1024
	ds_read_b128 v[168:171], v142 offset:2048
	ds_read_b128 v[172:175], v142 offset:3072
	ds_read_b128 v[178:181], v140 offset:32768
	ds_read_b128 v[182:185], v140 offset:33792
	ds_read_b128 v[186:189], v140 offset:34816
	ds_read_b128 v[190:193], v140 offset:35840
	ds_read_b128 v[194:197], v140 offset:36864
	ds_read_b128 v[198:201], v140 offset:37888
	ds_read_b128 v[202:205], v140 offset:38912
	ds_read_b128 v[206:209], v140 offset:39936
	s_add_u32 s66, s40, 0x40000
	s_mov_b32 m0, s46
	s_addc_u32 s67, s41, 0
	global_load_lds_dwordx4 v134, s[66:67]
	s_add_u32 s66, s40, 0x60000
	s_mov_b32 m0, s47
	s_addc_u32 s67, s41, 0
	global_load_lds_dwordx4 v134, s[66:67]
	s_waitcnt vmcnt(8) lgkmcnt(0)
	s_barrier
	s_setprio 1
	v_mfma_f32_16x16x32_bf16 v[124:127], v[144:147], v[178:181], v[124:127]
	v_mfma_f32_16x16x32_bf16 v[120:123], v[152:155], v[178:181], v[120:123]
	v_mfma_f32_16x16x32_bf16 v[108:111], v[144:147], v[186:189], v[108:111]
	v_mfma_f32_16x16x32_bf16 v[104:107], v[152:155], v[186:189], v[104:107]
	v_mfma_f32_16x16x32_bf16 v[92:95], v[144:147], v[194:197], v[92:95]
	v_mfma_f32_16x16x32_bf16 v[88:91], v[152:155], v[194:197], v[88:91]
	v_mfma_f32_16x16x32_bf16 v[76:79], v[144:147], v[202:205], v[76:79]
	v_mfma_f32_16x16x32_bf16 v[72:75], v[152:155], v[202:205], v[72:75]
	v_mfma_f32_16x16x32_bf16 v[124:127], v[148:151], v[182:185], v[124:127]
	v_mfma_f32_16x16x32_bf16 v[120:123], v[156:159], v[182:185], v[120:123]
	v_mfma_f32_16x16x32_bf16 v[108:111], v[148:151], v[190:193], v[108:111]
	v_mfma_f32_16x16x32_bf16 v[104:107], v[156:159], v[190:193], v[104:107]
	v_mfma_f32_16x16x32_bf16 v[92:95], v[148:151], v[198:201], v[92:95]
	v_mfma_f32_16x16x32_bf16 v[88:91], v[156:159], v[198:201], v[88:91]
	v_mfma_f32_16x16x32_bf16 v[76:79], v[148:151], v[206:209], v[76:79]
	v_mfma_f32_16x16x32_bf16 v[72:75], v[156:159], v[206:209], v[72:75]
	v_mfma_f32_16x16x32_bf16 v[116:119], v[160:163], v[178:181], v[116:119]
	v_mfma_f32_16x16x32_bf16 v[112:115], v[168:171], v[178:181], v[112:115]
	v_mfma_f32_16x16x32_bf16 v[100:103], v[160:163], v[186:189], v[100:103]
	v_mfma_f32_16x16x32_bf16 v[96:99], v[168:171], v[186:189], v[96:99]
	v_mfma_f32_16x16x32_bf16 v[84:87], v[160:163], v[194:197], v[84:87]
	v_mfma_f32_16x16x32_bf16 v[80:83], v[168:171], v[194:197], v[80:83]
	v_mfma_f32_16x16x32_bf16 v[68:71], v[160:163], v[202:205], v[68:71]
	v_mfma_f32_16x16x32_bf16 v[64:67], v[168:171], v[202:205], v[64:67]
	v_mfma_f32_16x16x32_bf16 v[116:119], v[164:167], v[182:185], v[116:119]
	v_mfma_f32_16x16x32_bf16 v[112:115], v[172:175], v[182:185], v[112:115]
	v_mfma_f32_16x16x32_bf16 v[100:103], v[164:167], v[190:193], v[100:103]
	v_mfma_f32_16x16x32_bf16 v[96:99], v[172:175], v[190:193], v[96:99]
	v_mfma_f32_16x16x32_bf16 v[84:87], v[164:167], v[198:201], v[84:87]
	v_mfma_f32_16x16x32_bf16 v[80:83], v[172:175], v[198:201], v[80:83]
	v_mfma_f32_16x16x32_bf16 v[68:71], v[164:167], v[206:209], v[68:71]
	v_mfma_f32_16x16x32_bf16 v[64:67], v[172:175], v[206:209], v[64:67]
	s_setprio 0
	s_barrier
; #define PG8_STAGE(bufoff, gbase, voff, p64) do { _Pragma("unroll") for (int _i = 0; _i < 2; ++_i) { \
;         const char* _gb = (const char*)(gbase) + (size_t)_i * (p64); const unsigned _la = ldsbase + (unsigned)(bufoff) + (unsigned)_i * 8192u; \
;         asm volatile("s_mov_b32 m0, %0\n\ts_nop 0\n\tglobal_load_lds_dwordx4 %1, %2" :: "s"(_la), "v"(voff), "s"(_gb) : "memory"); } } while (0)
; #define PG8_LDA(dst, b, h) do { _Pragma("unroll") for (int m = 0; m < 4; ++m) _Pragma("unroll") for (int k = 0; k < 2; ++k) dst[m][k] = *(const LAS bf16x8*)(lds + PG8_SA(b, h) + aoff + m * 2048 + k * 1024); } while (0)
; #define PG8_MMA(ai, bj, At, Bt) do { __builtin_amdgcn_s_setprio(1); _Pragma("unroll") for (int m = 0; m < 4; ++m) _Pragma("unroll") for (int n = 0; n < 2; ++n) _Pragma("unroll") for (int k = 0; k < 2; ++k) \
;         acc[ai][bj][m][n] = __builtin_amdgcn_mfma_f32_16x16x32_bf16(Bt[n][k], At[m][k], acc[ai][bj][m][n], 0, 0, 0); __builtin_amdgcn_s_setprio(0); } while (0)
; #define PG8_WAIT_V(n) asm volatile("s_waitcnt vmcnt(" #n ")" ::: "memory")
; #define PG8_WAIT_L(n) asm volatile("s_waitcnt lgkmcnt(" #n ")" ::: "memory")
; #define PG8_BAR __builtin_amdgcn_s_barrier()
; #define PG8_SCHED __builtin_amdgcn_sched_barrier(0)
; template <class Epi, class Sched>
; __device__ __forceinline__ void gemm_phase(LAS unsigned char* lds, const Sched& S, const Epi& E) {
;     ...
;             PG8_LDA(At, 1, 1); PG8_STAGE(PG8_SB(1, 0), b3, vB2, hB2 / 2); PG8_STAGE(PG8_SB(1, 1), b3 + hB2, vB2, hB2 / 2); PG8_STAGE(PG8_SA(1, 0), a3, vA2, hA2 / 2);
;             PG8_WAIT_V(8); PG8_WAIT_L(0); PG8_BAR; PG8_MMA(1, 0, At, B0); PG8_MMA(1, 1, At, B1); PG8_BAR; PG8_SCHED;
;         }
;         if (wr == 0) PG8_BAR;
	s_add_u32 s66, s44, 0x80
	s_addc_u32 s67, s45, 0
	ds_read_b128 v[178:181], v140 offset:49152
	ds_read_b128 v[182:185], v140 offset:50176
	ds_read_b128 v[186:189], v140 offset:51200
	ds_read_b128 v[190:193], v140 offset:52224
	ds_read_b128 v[194:197], v140 offset:53248
	ds_read_b128 v[198:201], v140 offset:54272
	ds_read_b128 v[202:205], v140 offset:55296
	ds_read_b128 v[206:209], v140 offset:56320
	s_mov_b32 m0, s49
	s_nop 0
	global_load_lds_dwordx4 v135, s[66:67]
	s_add_u32 s66, s44, 0x20080
	s_mov_b32 m0, s50
	s_addc_u32 s67, s45, 0
	global_load_lds_dwordx4 v135, s[66:67]
	s_add_u32 s66, s44, 0x40080
	s_mov_b32 m0, s53
	s_addc_u32 s67, s45, 0
	global_load_lds_dwordx4 v135, s[66:67]
	s_add_u32 s44, s44, 0x60080
	s_mov_b32 m0, s54
	s_addc_u32 s45, s45, 0
	global_load_lds_dwordx4 v135, s[44:45]
	s_mov_b32 m0, s51
	s_nop 0
	global_load_lds_dwordx4 v134, s[42:43]
	s_add_u32 s40, s40, 0x20080
	s_mov_b32 m0, s52
	s_addc_u32 s41, s41, 0
	global_load_lds_dwordx4 v134, s[40:41]
	s_waitcnt vmcnt(8) lgkmcnt(0)
	s_barrier
	s_setprio 1
	v_mfma_f32_16x16x32_bf16 v[60:63], v[144:147], v[178:181], v[60:63]
	v_mfma_f32_16x16x32_bf16 v[56:59], v[152:155], v[178:181], v[56:59]
	v_mfma_f32_16x16x32_bf16 v[44:47], v[144:147], v[186:189], v[44:47]
	v_mfma_f32_16x16x32_bf16 v[40:43], v[152:155], v[186:189], v[40:43]
	v_mfma_f32_16x16x32_bf16 v[28:31], v[144:147], v[194:197], v[28:31]
	v_mfma_f32_16x16x32_bf16 v[24:27], v[152:155], v[194:197], v[24:27]
	v_mfma_f32_16x16x32_bf16 v[12:15], v[144:147], v[202:205], v[12:15]
	v_mfma_f32_16x16x32_bf16 v[8:11], v[152:155], v[202:205], v[8:11]
	v_mfma_f32_16x16x32_bf16 v[60:63], v[148:151], v[182:185], v[60:63]
	v_mfma_f32_16x16x32_bf16 v[56:59], v[156:159], v[182:185], v[56:59]
	v_mfma_f32_16x16x32_bf16 v[44:47], v[148:151], v[190:193], v[44:47]
	v_mfma_f32_16x16x32_bf16 v[40:43], v[156:159], v[190:193], v[40:43]
	v_mfma_f32_16x16x32_bf16 v[28:31], v[148:151], v[198:201], v[28:31]
	v_mfma_f32_16x16x32_bf16 v[24:27], v[156:159], v[198:201], v[24:27]
	v_mfma_f32_16x16x32_bf16 v[12:15], v[148:151], v[206:209], v[12:15]
	v_mfma_f32_16x16x32_bf16 v[8:11], v[156:159], v[206:209], v[8:11]
	v_mfma_f32_16x16x32_bf16 v[52:55], v[160:163], v[178:181], v[52:55]
	v_mfma_f32_16x16x32_bf16 v[48:51], v[168:171], v[178:181], v[48:51]
	v_mfma_f32_16x16x32_bf16 v[36:39], v[160:163], v[186:189], v[36:39]
	v_mfma_f32_16x16x32_bf16 v[32:35], v[168:171], v[186:189], v[32:35]
	v_mfma_f32_16x16x32_bf16 v[20:23], v[160:163], v[194:197], v[20:23]
	v_mfma_f32_16x16x32_bf16 v[16:19], v[168:171], v[194:197], v[16:19]
	v_mfma_f32_16x16x32_bf16 v[4:7], v[160:163], v[202:205], v[4:7]
	v_mfma_f32_16x16x32_bf16 v[0:3], v[168:171], v[202:205], v[0:3]
	v_mfma_f32_16x16x32_bf16 v[52:55], v[164:167], v[182:185], v[52:55]
	v_mfma_f32_16x16x32_bf16 v[48:51], v[172:175], v[182:185], v[48:51]
	v_mfma_f32_16x16x32_bf16 v[36:39], v[164:167], v[190:193], v[36:39]
	v_mfma_f32_16x16x32_bf16 v[32:35], v[172:175], v[190:193], v[32:35]
	v_mfma_f32_16x16x32_bf16 v[20:23], v[164:167], v[198:201], v[20:23]
	v_mfma_f32_16x16x32_bf16 v[16:19], v[172:175], v[198:201], v[16:19]
	v_mfma_f32_16x16x32_bf16 v[4:7], v[164:167], v[206:209], v[4:7]
	v_mfma_f32_16x16x32_bf16 v[0:3], v[172:175], v[206:209], v[0:3]
	s_setprio 0
	s_barrier
	s_cmp_gt_u32 s64, 13
	s_cbranch_scc0 .LBB0_304
	s_and_b64 vcc, exec, s[18:19]
	s_cbranch_vccz .LBB0_307
	s_barrier

; #define PG8_STAGE(bufoff, gbase, voff, p64) do { _Pragma("unroll") for (int _i = 0; _i < 2; ++_i) { \
;         const char* _gb = (const char*)(gbase) + (size_t)_i * (p64); const unsigned _la = ldsbase + (unsigned)(bufoff) + (unsigned)_i * 8192u; \
;         asm volatile("s_mov_b32 m0, %0\n\ts_nop 0\n\tglobal_load_lds_dwordx4 %1, %2" :: "s"(_la), "v"(voff), "s"(_gb) : "memory"); } } while (0)
; #define PG8_LDA(dst, b, h) do { _Pragma("unroll") for (int m = 0; m < 4; ++m) _Pragma("unroll") for (int k = 0; k < 2; ++k) dst[m][k] = *(const LAS bf16x8*)(lds + PG8_SA(b, h) + aoff + m * 2048 + k * 1024); } while (0)
; #define PG8_LDB(dst, b, h) do { _Pragma("unroll") for (int n = 0; n < 2; ++n) _Pragma("unroll") for (int k = 0; k < 2; ++k) dst[n][k] = *(const LAS bf16x8*)(lds + PG8_SB(b, h) + boff + n * 2048 + k * 1024); } while (0)
; #define PG8_MMA(ai, bj, At, Bt) do { __builtin_amdgcn_s_setprio(1); _Pragma("unroll") for (int m = 0; m < 4; ++m) _Pragma("unroll") for (int n = 0; n < 2; ++n) _Pragma("unroll") for (int k = 0; k < 2; ++k) \
;         acc[ai][bj][m][n] = __builtin_amdgcn_mfma_f32_16x16x32_bf16(Bt[n][k], At[m][k], acc[ai][bj][m][n], 0, 0, 0); __builtin_amdgcn_s_setprio(0); } while (0)
; #define PG8_WAIT_V(n) asm volatile("s_waitcnt vmcnt(" #n ")" ::: "memory")
; #define PG8_BAR __builtin_amdgcn_s_barrier()
; template <class Epi, class Sched>
; __device__ __forceinline__ void gemm_phase(LAS unsigned char* lds, const Sched& S, const Epi& E) {
;     ...
;             const bool last = (t == nt - 2);
;             const char* a1 = cA + (size_t)(t + 1) * kstep;
;             const char* a2 = last ? nA : cA + (size_t)(t + 2) * kstep; const char* b2 = last ? nB : cB + (size_t)(t + 2) * kstep;
;             const char* a3 = a2 + kstep; const char* b3 = b2 + kstep;
;             const unsigned vA2 = voffA, vB2 = voffB, hA2 = hA, hB2 = hB;
;             PG8_LDB(B0, 0, 0); PG8_LDB(B1, 0, 1); PG8_SCHED; PG8_LDA(At, 0, 0); PG8_STAGE(PG8_SA(1, 1), a1 + hA, voffA, hA / 2);
;             PG8_WAIT_V(8); PG8_WAIT_L(0); PG8_BAR; PG8_MMA(0, 0, At, B0); PG8_MMA(0, 1, At, B1); PG8_BAR; PG8_SCHED;
;             PG8_LDA(At, 0, 1); PG8_STAGE(PG8_SB(0, 0), b2, vB2, hB2 / 2); PG8_STAGE(PG8_SB(0, 1), b2 + hB2, vB2, hB2 / 2); PG8_STAGE(PG8_SA(0, 0), a2, vA2, hA2 / 2);
;             PG8_WAIT_V(8); PG8_WAIT_L(0); PG8_BAR; PG8_MMA(1, 0, At, B0); PG8_MMA(1, 1, At, B1); PG8_BAR; PG8_SCHED;
.LBB0_398:
	ds_read_b128 v[130:133], v164
	ds_read_b128 v[134:137], v164 offset:1024
	ds_read_b128 v[138:141], v164 offset:2048
	ds_read_b128 v[142:145], v164 offset:3072
	ds_read_b128 v[146:149], v165
	ds_read_b128 v[150:153], v165 offset:1024
	ds_read_b128 v[154:157], v165 offset:2048
	ds_read_b128 v[158:161], v165 offset:3072
	s_add_i32 s73, s38, 2
	s_cmp_eq_u32 s68, s38
	s_cselect_b32 s38, s67, s69
	s_cselect_b32 s39, s66, s70
	s_cselect_b32 s42, s45, s71
	s_cselect_b32 s43, s44, s72
	s_add_u32 s40, s38, 0x80
	s_addc_u32 s41, s39, 0
	ds_read_b128 v[170:173], v166
	ds_read_b128 v[178:181], v166 offset:1024
	ds_read_b128 v[182:185], v166 offset:2048
	ds_read_b128 v[186:189], v166 offset:3072
	ds_read_b128 v[190:193], v166 offset:4096
	ds_read_b128 v[194:197], v166 offset:5120
	ds_read_b128 v[198:201], v166 offset:6144
	ds_read_b128 v[202:205], v166 offset:7168
	s_add_u32 s74, s69, 0xaff80
	s_mov_b32 m0, s59
	s_addc_u32 s75, s70, 0
	global_load_lds_dwordx4 v128, s[74:75]
	s_add_u32 s74, s69, 0x107f80
	s_mov_b32 m0, s60
	s_addc_u32 s75, s70, 0
	global_load_lds_dwordx4 v128, s[74:75]
	s_waitcnt vmcnt(8) lgkmcnt(0)
	s_barrier
	s_setprio 1
	v_mfma_f32_16x16x32_bf16 v[124:127], v[130:133], v[170:173], v[124:127]
	v_mfma_f32_16x16x32_bf16 v[120:123], v[138:141], v[170:173], v[120:123]
	v_mfma_f32_16x16x32_bf16 v[116:119], v[130:133], v[182:185], v[116:119]
	v_mfma_f32_16x16x32_bf16 v[112:115], v[138:141], v[182:185], v[112:115]
	v_mfma_f32_16x16x32_bf16 v[108:111], v[130:133], v[190:193], v[108:111]
	v_mfma_f32_16x16x32_bf16 v[104:107], v[138:141], v[190:193], v[104:107]
	v_mfma_f32_16x16x32_bf16 v[100:103], v[130:133], v[198:201], v[100:103]
	v_mfma_f32_16x16x32_bf16 v[96:99], v[138:141], v[198:201], v[96:99]
	v_mfma_f32_16x16x32_bf16 v[124:127], v[134:137], v[178:181], v[124:127]
	v_mfma_f32_16x16x32_bf16 v[120:123], v[142:145], v[178:181], v[120:123]
	v_mfma_f32_16x16x32_bf16 v[116:119], v[134:137], v[186:189], v[116:119]
	v_mfma_f32_16x16x32_bf16 v[112:115], v[142:145], v[186:189], v[112:115]
	v_mfma_f32_16x16x32_bf16 v[108:111], v[134:137], v[194:197], v[108:111]
	v_mfma_f32_16x16x32_bf16 v[104:107], v[142:145], v[194:197], v[104:107]
	v_mfma_f32_16x16x32_bf16 v[100:103], v[134:137], v[202:205], v[100:103]
	v_mfma_f32_16x16x32_bf16 v[96:99], v[142:145], v[202:205], v[96:99]
	s_add_u32 s69, s69, 0x100
	s_addc_u32 s70, s70, 0
	s_add_u32 s71, s71, 0x100
	s_addc_u32 s72, s72, 0
	v_mfma_f32_16x16x32_bf16 v[60:63], v[146:149], v[170:173], v[60:63]
	v_mfma_f32_16x16x32_bf16 v[56:59], v[154:157], v[170:173], v[56:59]
	v_mfma_f32_16x16x32_bf16 v[52:55], v[146:149], v[182:185], v[52:55]
	v_mfma_f32_16x16x32_bf16 v[48:51], v[154:157], v[182:185], v[48:51]
	v_mfma_f32_16x16x32_bf16 v[44:47], v[146:149], v[190:193], v[44:47]
	v_mfma_f32_16x16x32_bf16 v[40:43], v[154:157], v[190:193], v[40:43]
	v_mfma_f32_16x16x32_bf16 v[36:39], v[146:149], v[198:201], v[36:39]
	v_mfma_f32_16x16x32_bf16 v[32:35], v[154:157], v[198:201], v[32:35]
	v_mfma_f32_16x16x32_bf16 v[60:63], v[150:153], v[178:181], v[60:63]
	v_mfma_f32_16x16x32_bf16 v[56:59], v[158:161], v[178:181], v[56:59]
	v_mfma_f32_16x16x32_bf16 v[52:55], v[150:153], v[186:189], v[52:55]
	v_mfma_f32_16x16x32_bf16 v[48:51], v[158:161], v[186:189], v[48:51]
	v_mfma_f32_16x16x32_bf16 v[44:47], v[150:153], v[194:197], v[44:47]
	v_mfma_f32_16x16x32_bf16 v[40:43], v[158:161], v[194:197], v[40:43]
	v_mfma_f32_16x16x32_bf16 v[36:39], v[150:153], v[202:205], v[36:39]
	v_mfma_f32_16x16x32_bf16 v[32:35], v[158:161], v[202:205], v[32:35]
	s_setprio 0
	s_barrier
	s_add_u32 s74, s42, 0x58000
	ds_read_b128 v[170:173], v166 offset:16384
	ds_read_b128 v[178:181], v166 offset:17408
	ds_read_b128 v[182:185], v166 offset:18432
	ds_read_b128 v[186:189], v166 offset:19456
	ds_read_b128 v[190:193], v166 offset:20480
	ds_read_b128 v[194:197], v166 offset:21504
	ds_read_b128 v[198:201], v166 offset:22528
	ds_read_b128 v[202:205], v166 offset:23552
	s_mov_b32 m0, s15
	s_nop 0
	global_load_lds_dwordx4 v129, s[42:43]
	s_mov_b32 m0, s33
	s_addc_u32 s75, s43, 0
	global_load_lds_dwordx4 v129, s[74:75]
	s_add_u32 s74, s42, 0xb0000
	s_mov_b32 m0, s34
	s_addc_u32 s75, s43, 0
	global_load_lds_dwordx4 v129, s[74:75]
	s_add_u32 s74, s42, 0x108000
	s_mov_b32 m0, s35
	s_addc_u32 s75, s43, 0
	global_load_lds_dwordx4 v129, s[74:75]
	s_mov_b32 m0, s14
	s_nop 0
	global_load_lds_dwordx4 v128, s[38:39]
	s_add_u32 s74, s38, 0x58000
	s_mov_b32 m0, s36
	s_addc_u32 s75, s39, 0
	global_load_lds_dwordx4 v128, s[74:75]
	s_waitcnt vmcnt(8) lgkmcnt(0)
	s_barrier
	s_setprio 1
	v_mfma_f32_16x16x32_bf16 v[92:95], v[130:133], v[170:173], v[92:95]
	v_mfma_f32_16x16x32_bf16 v[88:91], v[138:141], v[170:173], v[88:91]
	v_mfma_f32_16x16x32_bf16 v[84:87], v[130:133], v[182:185], v[84:87]
	v_mfma_f32_16x16x32_bf16 v[80:83], v[138:141], v[182:185], v[80:83]
	v_mfma_f32_16x16x32_bf16 v[76:79], v[130:133], v[190:193], v[76:79]
	v_mfma_f32_16x16x32_bf16 v[72:75], v[138:141], v[190:193], v[72:75]
	v_mfma_f32_16x16x32_bf16 v[68:71], v[130:133], v[198:201], v[68:71]
	v_mfma_f32_16x16x32_bf16 v[64:67], v[138:141], v[198:201], v[64:67]
	v_mfma_f32_16x16x32_bf16 v[92:95], v[134:137], v[178:181], v[92:95]
	v_mfma_f32_16x16x32_bf16 v[88:91], v[142:145], v[178:181], v[88:91]
	v_mfma_f32_16x16x32_bf16 v[84:87], v[134:137], v[186:189], v[84:87]
	v_mfma_f32_16x16x32_bf16 v[80:83], v[142:145], v[186:189], v[80:83]
	v_mfma_f32_16x16x32_bf16 v[76:79], v[134:137], v[194:197], v[76:79]
	v_mfma_f32_16x16x32_bf16 v[72:75], v[142:145], v[194:197], v[72:75]
	v_mfma_f32_16x16x32_bf16 v[68:71], v[134:137], v[202:205], v[68:71]
	v_mfma_f32_16x16x32_bf16 v[64:67], v[142:145], v[202:205], v[64:67]
	v_mfma_f32_16x16x32_bf16 v[28:31], v[146:149], v[170:173], v[28:31]
	v_mfma_f32_16x16x32_bf16 v[24:27], v[154:157], v[170:173], v[24:27]
	v_mfma_f32_16x16x32_bf16 v[20:23], v[146:149], v[182:185], v[20:23]
	v_mfma_f32_16x16x32_bf16 v[16:19], v[154:157], v[182:185], v[16:19]
	v_mfma_f32_16x16x32_bf16 v[12:15], v[146:149], v[190:193], v[12:15]
	v_mfma_f32_16x16x32_bf16 v[8:11], v[154:157], v[190:193], v[8:11]
	v_mfma_f32_16x16x32_bf16 v[4:7], v[146:149], v[198:201], v[4:7]
	v_mfma_f32_16x16x32_bf16 v[0:3], v[154:157], v[198:201], v[0:3]
	v_mfma_f32_16x16x32_bf16 v[28:31], v[150:153], v[178:181], v[28:31]
	v_mfma_f32_16x16x32_bf16 v[24:27], v[158:161], v[178:181], v[24:27]
	v_mfma_f32_16x16x32_bf16 v[20:23], v[150:153], v[186:189], v[20:23]
	v_mfma_f32_16x16x32_bf16 v[16:19], v[158:161], v[186:189], v[16:19]
	v_mfma_f32_16x16x32_bf16 v[12:15], v[150:153], v[194:197], v[12:15]
	v_mfma_f32_16x16x32_bf16 v[8:11], v[158:161], v[194:197], v[8:11]
	v_mfma_f32_16x16x32_bf16 v[4:7], v[150:153], v[202:205], v[4:7]
	v_mfma_f32_16x16x32_bf16 v[0:3], v[158:161], v[202:205], v[0:3]
	s_setprio 0
	s_barrier
; #define PG8_STAGE(bufoff, gbase, voff, p64) do { _Pragma("unroll") for (int _i = 0; _i < 2; ++_i) { \
;         const char* _gb = (const char*)(gbase) + (size_t)_i * (p64); const unsigned _la = ldsbase + (unsigned)(bufoff) + (unsigned)_i * 8192u; \
;         asm volatile("s_mov_b32 m0, %0\n\ts_nop 0\n\tglobal_load_lds_dwordx4 %1, %2" :: "s"(_la), "v"(voff), "s"(_gb) : "memory"); } } while (0)
; #define PG8_LDA(dst, b, h) do { _Pragma("unroll") for (int m = 0; m < 4; ++m) _Pragma("unroll") for (int k = 0; k < 2; ++k) dst[m][k] = *(const LAS bf16x8*)(lds + PG8_SA(b, h) + aoff + m * 2048 + k * 1024); } while (0)
; #define PG8_LDB(dst, b, h) do { _Pragma("unroll") for (int n = 0; n < 2; ++n) _Pragma("unroll") for (int k = 0; k < 2; ++k) dst[n][k] = *(const LAS bf16x8*)(lds + PG8_SB(b, h) + boff + n * 2048 + k * 1024); } while (0)
; #define PG8_MMA(ai, bj, At, Bt) do { __builtin_amdgcn_s_setprio(1); _Pragma("unroll") for (int m = 0; m < 4; ++m) _Pragma("unroll") for (int n = 0; n < 2; ++n) _Pragma("unroll") for (int k = 0; k < 2; ++k) \
;         acc[ai][bj][m][n] = __builtin_amdgcn_mfma_f32_16x16x32_bf16(Bt[n][k], At[m][k], acc[ai][bj][m][n], 0, 0, 0); __builtin_amdgcn_s_setprio(0); } while (0)
; #define PG8_WAIT_V(n) asm volatile("s_waitcnt vmcnt(" #n ")" ::: "memory")
; #define PG8_WAIT_L(n) asm volatile("s_waitcnt lgkmcnt(" #n ")" ::: "memory")
; #define PG8_BAR __builtin_amdgcn_s_barrier()
; #define PG8_SCHED __builtin_amdgcn_sched_barrier(0)
; template <class Epi, class Sched>
; __device__ __forceinline__ void gemm_phase(LAS unsigned char* lds, const Sched& S, const Epi& E) {
;     ...
;             PG8_LDB(B0, 1, 0); PG8_LDB(B1, 1, 1); PG8_SCHED; PG8_LDA(At, 1, 0); PG8_STAGE(PG8_SA(0, 1), a2 + hA2, vA2, hA2 / 2);
;             PG8_WAIT_V(8); PG8_WAIT_L(0); PG8_BAR; PG8_MMA(0, 0, At, B0); PG8_MMA(0, 1, At, B1); PG8_BAR; PG8_SCHED;
;             PG8_LDA(At, 1, 1); PG8_STAGE(PG8_SB(1, 0), b3, vB2, hB2 / 2); PG8_STAGE(PG8_SB(1, 1), b3 + hB2, vB2, hB2 / 2); PG8_STAGE(PG8_SA(1, 0), a3, vA2, hA2 / 2);
;             PG8_WAIT_V(8); PG8_WAIT_L(0); PG8_BAR; PG8_MMA(1, 0, At, B0); PG8_MMA(1, 1, At, B1); PG8_BAR; PG8_SCHED;
;         }
;         if (wr == 0) PG8_BAR;
	ds_read_b128 v[130:133], v167
	ds_read_b128 v[134:137], v167 offset:1024
	ds_read_b128 v[138:141], v167 offset:2048
	ds_read_b128 v[142:145], v167 offset:3072
	ds_read_b128 v[146:149], v168
	ds_read_b128 v[150:153], v168 offset:1024
	ds_read_b128 v[154:157], v168 offset:2048
	ds_read_b128 v[158:161], v168 offset:3072
	ds_read_b128 v[170:173], v166 offset:32768
	ds_read_b128 v[178:181], v166 offset:33792
	ds_read_b128 v[182:185], v166 offset:34816
	ds_read_b128 v[186:189], v166 offset:35840
	ds_read_b128 v[190:193], v166 offset:36864
	ds_read_b128 v[194:197], v166 offset:37888
	ds_read_b128 v[198:201], v166 offset:38912
	ds_read_b128 v[202:205], v166 offset:39936
	s_add_u32 s74, s38, 0xb0000
	s_mov_b32 m0, s37
	s_addc_u32 s75, s39, 0
	global_load_lds_dwordx4 v128, s[74:75]
	s_add_u32 s74, s38, 0x108000
	s_mov_b32 m0, s46
	s_addc_u32 s75, s39, 0
	global_load_lds_dwordx4 v128, s[74:75]
	s_waitcnt vmcnt(8) lgkmcnt(0)
	s_barrier
	s_setprio 1
	v_mfma_f32_16x16x32_bf16 v[124:127], v[130:133], v[170:173], v[124:127]
	v_mfma_f32_16x16x32_bf16 v[120:123], v[138:141], v[170:173], v[120:123]
	v_mfma_f32_16x16x32_bf16 v[116:119], v[130:133], v[182:185], v[116:119]
	v_mfma_f32_16x16x32_bf16 v[112:115], v[138:141], v[182:185], v[112:115]
	v_mfma_f32_16x16x32_bf16 v[108:111], v[130:133], v[190:193], v[108:111]
	v_mfma_f32_16x16x32_bf16 v[104:107], v[138:141], v[190:193], v[104:107]
	v_mfma_f32_16x16x32_bf16 v[100:103], v[130:133], v[198:201], v[100:103]
	v_mfma_f32_16x16x32_bf16 v[96:99], v[138:141], v[198:201], v[96:99]
	v_mfma_f32_16x16x32_bf16 v[124:127], v[134:137], v[178:181], v[124:127]
	v_mfma_f32_16x16x32_bf16 v[120:123], v[142:145], v[178:181], v[120:123]
	v_mfma_f32_16x16x32_bf16 v[116:119], v[134:137], v[186:189], v[116:119]
	v_mfma_f32_16x16x32_bf16 v[112:115], v[142:145], v[186:189], v[112:115]
	v_mfma_f32_16x16x32_bf16 v[108:111], v[134:137], v[194:197], v[108:111]
	v_mfma_f32_16x16x32_bf16 v[104:107], v[142:145], v[194:197], v[104:107]
	v_mfma_f32_16x16x32_bf16 v[100:103], v[134:137], v[202:205], v[100:103]
	v_mfma_f32_16x16x32_bf16 v[96:99], v[142:145], v[202:205], v[96:99]
	v_mfma_f32_16x16x32_bf16 v[60:63], v[146:149], v[170:173], v[60:63]
	v_mfma_f32_16x16x32_bf16 v[56:59], v[154:157], v[170:173], v[56:59]
	v_mfma_f32_16x16x32_bf16 v[52:55], v[146:149], v[182:185], v[52:55]
	v_mfma_f32_16x16x32_bf16 v[48:51], v[154:157], v[182:185], v[48:51]
	v_mfma_f32_16x16x32_bf16 v[44:47], v[146:149], v[190:193], v[44:47]
	v_mfma_f32_16x16x32_bf16 v[40:43], v[154:157], v[190:193], v[40:43]
	v_mfma_f32_16x16x32_bf16 v[36:39], v[146:149], v[198:201], v[36:39]
	v_mfma_f32_16x16x32_bf16 v[32:35], v[154:157], v[198:201], v[32:35]
	v_mfma_f32_16x16x32_bf16 v[60:63], v[150:153], v[178:181], v[60:63]
	v_mfma_f32_16x16x32_bf16 v[56:59], v[158:161], v[178:181], v[56:59]
	v_mfma_f32_16x16x32_bf16 v[52:55], v[150:153], v[186:189], v[52:55]
	v_mfma_f32_16x16x32_bf16 v[48:51], v[158:161], v[186:189], v[48:51]
	v_mfma_f32_16x16x32_bf16 v[44:47], v[150:153], v[194:197], v[44:47]
	v_mfma_f32_16x16x32_bf16 v[40:43], v[158:161], v[194:197], v[40:43]
	v_mfma_f32_16x16x32_bf16 v[36:39], v[150:153], v[202:205], v[36:39]
	v_mfma_f32_16x16x32_bf16 v[32:35], v[158:161], v[202:205], v[32:35]
	s_setprio 0
	s_barrier
	s_add_u32 s74, s42, 0x80
	s_addc_u32 s75, s43, 0
	ds_read_b128 v[170:173], v166 offset:49152
	ds_read_b128 v[178:181], v166 offset:50176
	ds_read_b128 v[182:185], v166 offset:51200
	ds_read_b128 v[186:189], v166 offset:52224
	ds_read_b128 v[190:193], v166 offset:53248
	ds_read_b128 v[194:197], v166 offset:54272
	ds_read_b128 v[198:201], v166 offset:55296
	ds_read_b128 v[202:205], v166 offset:56320
	s_mov_b32 m0, s53
	s_nop 0
	global_load_lds_dwordx4 v129, s[74:75]
	s_add_u32 s74, s42, 0x58080
	s_mov_b32 m0, s54
	s_addc_u32 s75, s43, 0
	global_load_lds_dwordx4 v129, s[74:75]
	s_add_u32 s74, s42, 0xb0080
	s_mov_b32 m0, s57
	s_addc_u32 s75, s43, 0
	global_load_lds_dwordx4 v129, s[74:75]
	s_add_u32 s42, s42, 0x108080
	s_mov_b32 m0, s58
	s_addc_u32 s43, s43, 0
	global_load_lds_dwordx4 v129, s[42:43]
	s_mov_b32 m0, s55
	s_nop 0
	global_load_lds_dwordx4 v128, s[40:41]
	s_add_u32 s38, s38, 0x58080
	s_mov_b32 m0, s56
	s_addc_u32 s39, s39, 0
	global_load_lds_dwordx4 v128, s[38:39]
	s_waitcnt vmcnt(8) lgkmcnt(0)
	s_barrier
	s_setprio 1
	v_mfma_f32_16x16x32_bf16 v[92:95], v[130:133], v[170:173], v[92:95]
	v_mfma_f32_16x16x32_bf16 v[88:91], v[138:141], v[170:173], v[88:91]
	v_mfma_f32_16x16x32_bf16 v[84:87], v[130:133], v[182:185], v[84:87]
	v_mfma_f32_16x16x32_bf16 v[80:83], v[138:141], v[182:185], v[80:83]
	v_mfma_f32_16x16x32_bf16 v[76:79], v[130:133], v[190:193], v[76:79]
	v_mfma_f32_16x16x32_bf16 v[72:75], v[138:141], v[190:193], v[72:75]
	v_mfma_f32_16x16x32_bf16 v[68:71], v[130:133], v[198:201], v[68:71]
	v_mfma_f32_16x16x32_bf16 v[64:67], v[138:141], v[198:201], v[64:67]
	v_mfma_f32_16x16x32_bf16 v[92:95], v[134:137], v[178:181], v[92:95]
	v_mfma_f32_16x16x32_bf16 v[88:91], v[142:145], v[178:181], v[88:91]
	v_mfma_f32_16x16x32_bf16 v[84:87], v[134:137], v[186:189], v[84:87]
	v_mfma_f32_16x16x32_bf16 v[80:83], v[142:145], v[186:189], v[80:83]
	v_mfma_f32_16x16x32_bf16 v[76:79], v[134:137], v[194:197], v[76:79]
	v_mfma_f32_16x16x32_bf16 v[72:75], v[142:145], v[194:197], v[72:75]
	v_mfma_f32_16x16x32_bf16 v[68:71], v[134:137], v[202:205], v[68:71]
	v_mfma_f32_16x16x32_bf16 v[64:67], v[142:145], v[202:205], v[64:67]
	v_mfma_f32_16x16x32_bf16 v[28:31], v[146:149], v[170:173], v[28:31]
	v_mfma_f32_16x16x32_bf16 v[24:27], v[154:157], v[170:173], v[24:27]
	v_mfma_f32_16x16x32_bf16 v[20:23], v[146:149], v[182:185], v[20:23]
	v_mfma_f32_16x16x32_bf16 v[16:19], v[154:157], v[182:185], v[16:19]
	v_mfma_f32_16x16x32_bf16 v[12:15], v[146:149], v[190:193], v[12:15]
	v_mfma_f32_16x16x32_bf16 v[8:11], v[154:157], v[190:193], v[8:11]
	v_mfma_f32_16x16x32_bf16 v[4:7], v[146:149], v[198:201], v[4:7]
	v_mfma_f32_16x16x32_bf16 v[0:3], v[154:157], v[198:201], v[0:3]
	v_mfma_f32_16x16x32_bf16 v[28:31], v[150:153], v[178:181], v[28:31]
	v_mfma_f32_16x16x32_bf16 v[24:27], v[158:161], v[178:181], v[24:27]
	v_mfma_f32_16x16x32_bf16 v[20:23], v[150:153], v[186:189], v[20:23]
	v_mfma_f32_16x16x32_bf16 v[16:19], v[158:161], v[186:189], v[16:19]
	v_mfma_f32_16x16x32_bf16 v[12:15], v[150:153], v[194:197], v[12:15]
	v_mfma_f32_16x16x32_bf16 v[8:11], v[158:161], v[194:197], v[8:11]
	v_mfma_f32_16x16x32_bf16 v[4:7], v[150:153], v[202:205], v[4:7]
	v_mfma_f32_16x16x32_bf16 v[0:3], v[158:161], v[202:205], v[0:3]
	s_setprio 0
	s_barrier
	s_cmp_ge_i32 s73, s21
	s_mov_b32 s38, s73
	s_cbranch_scc0 .LBB0_398
	s_and_b64 vcc, exec, s[18:19]
	s_cbranch_vccz .LBB0_401
	s_barrier

; #define PG8_STAGE(bufoff, gbase, voff, p64) do { _Pragma("unroll") for (int _i = 0; _i < 2; ++_i) { \
;         const char* _gb = (const char*)(gbase) + (size_t)_i * (p64); const unsigned _la = ldsbase + (unsigned)(bufoff) + (unsigned)_i * 8192u; \
;         asm volatile("s_mov_b32 m0, %0\n\ts_nop 0\n\tglobal_load_lds_dwordx4 %1, %2" :: "s"(_la), "v"(voff), "s"(_gb) : "memory"); } } while (0)
; #define PG8_LDA(dst, b, h) do { _Pragma("unroll") for (int m = 0; m < 4; ++m) _Pragma("unroll") for (int k = 0; k < 2; ++k) dst[m][k] = *(const LAS bf16x8*)(lds + PG8_SA(b, h) + aoff + m * 2048 + k * 1024); } while (0)
; #define PG8_LDB(dst, b, h) do { _Pragma("unroll") for (int n = 0; n < 2; ++n) _Pragma("unroll") for (int k = 0; k < 2; ++k) dst[n][k] = *(const LAS bf16x8*)(lds + PG8_SB(b, h) + boff + n * 2048 + k * 1024); } while (0)
; #define PG8_MMA(ai, bj, At, Bt) do { __builtin_amdgcn_s_setprio(1); _Pragma("unroll") for (int m = 0; m < 4; ++m) _Pragma("unroll") for (int n = 0; n < 2; ++n) _Pragma("unroll") for (int k = 0; k < 2; ++k) \
;         acc[ai][bj][m][n] = __builtin_amdgcn_mfma_f32_16x16x32_bf16(Bt[n][k], At[m][k], acc[ai][bj][m][n], 0, 0, 0); __builtin_amdgcn_s_setprio(0); } while (0)
; #define PG8_WAIT_V(n) asm volatile("s_waitcnt vmcnt(" #n ")" ::: "memory")
; #define PG8_BAR __builtin_amdgcn_s_barrier()
; template <class Epi, class Sched>
; __device__ __forceinline__ void gemm_phase(LAS unsigned char* lds, const Sched& S, const Epi& E) {
;     ...
;             const bool last = (t == nt - 2);
;             const char* a1 = cA + (size_t)(t + 1) * kstep;
;             const char* a2 = last ? nA : cA + (size_t)(t + 2) * kstep; const char* b2 = last ? nB : cB + (size_t)(t + 2) * kstep;
;             const char* a3 = a2 + kstep; const char* b3 = b2 + kstep;
;             const unsigned vA2 = voffA, vB2 = voffB, hA2 = hA, hB2 = hB;
;             PG8_LDB(B0, 0, 0); PG8_LDB(B1, 0, 1); PG8_SCHED; PG8_LDA(At, 0, 0); PG8_STAGE(PG8_SA(1, 1), a1 + hA, voffA, hA / 2);
;             PG8_WAIT_V(8); PG8_WAIT_L(0); PG8_BAR; PG8_MMA(0, 0, At, B0); PG8_MMA(0, 1, At, B1); PG8_BAR; PG8_SCHED;
;             PG8_LDA(At, 0, 1); PG8_STAGE(PG8_SB(0, 0), b2, vB2, hB2 / 2); PG8_STAGE(PG8_SB(0, 1), b2 + hB2, vB2, hB2 / 2); PG8_STAGE(PG8_SA(0, 0), a2, vA2, hA2 / 2);
;             PG8_WAIT_V(8); PG8_WAIT_L(0); PG8_BAR; PG8_MMA(1, 0, At, B0); PG8_MMA(1, 1, At, B1); PG8_BAR; PG8_SCHED;
.LBB0_553:
	v_add_u32_e32 v128, 0x10000, v154
	ds_read_b128 v[138:141], v128
	ds_read_b128 v[142:145], v128 offset:1024
	ds_read_b128 v[146:149], v128 offset:2048
	ds_read_b128 v[172:175], v128 offset:3072
	v_add_u32_e32 v128, 0x14000, v154
	ds_read_b128 v[178:181], v128
	ds_read_b128 v[182:185], v128 offset:1024
	ds_read_b128 v[186:189], v128 offset:2048
	ds_read_b128 v[190:193], v128 offset:3072
	s_add_u32 s16, s74, 0xfffc0080
	s_addc_u32 s17, s75, -1
	s_cmp_eq_u32 s81, 12
	s_cselect_b32 s16, s58, s16
	s_cselect_b32 s17, s59, s17
	s_cselect_b32 s76, s62, s57
	s_cselect_b32 s77, s63, s80
	s_add_u32 s22, s16, 0x80
	s_addc_u32 s23, s17, 0
	ds_read_b128 v[194:197], v155
	ds_read_b128 v[198:201], v155 offset:1024
	ds_read_b128 v[202:205], v155 offset:2048
	ds_read_b128 v[206:209], v155 offset:3072
	ds_read_b128 v[210:213], v155 offset:4096
	ds_read_b128 v[214:217], v155 offset:5120
	ds_read_b128 v[218:221], v155 offset:6144
	ds_read_b128 v[222:225], v155 offset:7168
	s_mov_b32 m0, s67
	s_nop 0
	global_load_lds_dwordx4 v150, s[74:75]
	s_add_u32 s82, s74, 0x20000
	s_mov_b32 m0, s69
	s_addc_u32 s83, s75, 0
	global_load_lds_dwordx4 v150, s[82:83]
	s_waitcnt vmcnt(8) lgkmcnt(0)
	s_barrier
	s_setprio 1
	v_mfma_f32_16x16x32_bf16 v[124:127], v[138:141], v[194:197], v[124:127]
	v_mfma_f32_16x16x32_bf16 v[120:123], v[146:149], v[194:197], v[120:123]
	v_mfma_f32_16x16x32_bf16 v[112:115], v[138:141], v[202:205], v[112:115]
	v_mfma_f32_16x16x32_bf16 v[104:107], v[146:149], v[202:205], v[104:107]
	v_mfma_f32_16x16x32_bf16 v[96:99], v[138:141], v[210:213], v[96:99]
	v_mfma_f32_16x16x32_bf16 v[88:91], v[146:149], v[210:213], v[88:91]
	v_mfma_f32_16x16x32_bf16 v[80:83], v[138:141], v[218:221], v[80:83]
	v_mfma_f32_16x16x32_bf16 v[72:75], v[146:149], v[218:221], v[72:75]
	v_mfma_f32_16x16x32_bf16 v[124:127], v[142:145], v[198:201], v[124:127]
	v_mfma_f32_16x16x32_bf16 v[120:123], v[172:175], v[198:201], v[120:123]
	v_mfma_f32_16x16x32_bf16 v[112:115], v[142:145], v[206:209], v[112:115]
	v_mfma_f32_16x16x32_bf16 v[104:107], v[172:175], v[206:209], v[104:107]
	v_mfma_f32_16x16x32_bf16 v[96:99], v[142:145], v[214:217], v[96:99]
	v_mfma_f32_16x16x32_bf16 v[88:91], v[172:175], v[214:217], v[88:91]
	v_mfma_f32_16x16x32_bf16 v[80:83], v[142:145], v[222:225], v[80:83]
	v_mfma_f32_16x16x32_bf16 v[72:75], v[172:175], v[222:225], v[72:75]
	s_add_i32 s81, s81, 2
	s_add_u32 s74, s74, 0x100
	s_addc_u32 s75, s75, 0
	s_add_u32 s57, s57, 0x100
	s_addc_u32 s80, s80, 0
	v_mfma_f32_16x16x32_bf16 v[116:119], v[178:181], v[194:197], v[116:119]
	v_mfma_f32_16x16x32_bf16 v[108:111], v[186:189], v[194:197], v[108:111]
	v_mfma_f32_16x16x32_bf16 v[100:103], v[178:181], v[202:205], v[100:103]
	v_mfma_f32_16x16x32_bf16 v[92:95], v[186:189], v[202:205], v[92:95]
	v_mfma_f32_16x16x32_bf16 v[84:87], v[178:181], v[210:213], v[84:87]
	v_mfma_f32_16x16x32_bf16 v[76:79], v[186:189], v[210:213], v[76:79]
	v_mfma_f32_16x16x32_bf16 v[68:71], v[178:181], v[218:221], v[68:71]
	v_mfma_f32_16x16x32_bf16 v[64:67], v[186:189], v[218:221], v[64:67]
	v_mfma_f32_16x16x32_bf16 v[116:119], v[182:185], v[198:201], v[116:119]
	v_mfma_f32_16x16x32_bf16 v[108:111], v[190:193], v[198:201], v[108:111]
	v_mfma_f32_16x16x32_bf16 v[100:103], v[182:185], v[206:209], v[100:103]
	v_mfma_f32_16x16x32_bf16 v[92:95], v[190:193], v[206:209], v[92:95]
	v_mfma_f32_16x16x32_bf16 v[84:87], v[182:185], v[214:217], v[84:87]
	v_mfma_f32_16x16x32_bf16 v[76:79], v[190:193], v[214:217], v[76:79]
	v_mfma_f32_16x16x32_bf16 v[68:71], v[182:185], v[222:225], v[68:71]
	v_mfma_f32_16x16x32_bf16 v[64:67], v[190:193], v[222:225], v[64:67]
	s_setprio 0
	s_barrier
	s_add_u32 s82, s76, 0x20000
	ds_read_b128 v[194:197], v155 offset:16384
	ds_read_b128 v[198:201], v155 offset:17408
	ds_read_b128 v[202:205], v155 offset:18432
	ds_read_b128 v[206:209], v155 offset:19456
	ds_read_b128 v[210:213], v155 offset:20480
	ds_read_b128 v[214:217], v155 offset:21504
	ds_read_b128 v[218:221], v155 offset:22528
	ds_read_b128 v[222:225], v155 offset:23552
	s_mov_b32 m0, s24
	s_nop 0
	global_load_lds_dwordx4 v151, s[76:77]
	s_mov_b32 m0, s33
	s_addc_u32 s83, s77, 0
	global_load_lds_dwordx4 v151, s[82:83]
	s_add_u32 s82, s76, 0x40000
	s_mov_b32 m0, s34
	s_addc_u32 s83, s77, 0
	global_load_lds_dwordx4 v151, s[82:83]
	s_add_u32 s82, s76, 0x60000
	s_mov_b32 m0, s35
	s_addc_u32 s83, s77, 0
	global_load_lds_dwordx4 v151, s[82:83]
	s_mov_b32 m0, s15
	s_nop 0
	global_load_lds_dwordx4 v150, s[16:17]
	s_add_u32 s82, s16, 0x20000
	s_mov_b32 m0, s36
	s_addc_u32 s83, s17, 0
	global_load_lds_dwordx4 v150, s[82:83]
	s_waitcnt vmcnt(8) lgkmcnt(0)
	s_barrier
; #define PG8_STAGE(bufoff, gbase, voff, p64) do { _Pragma("unroll") for (int _i = 0; _i < 2; ++_i) { \
;         const char* _gb = (const char*)(gbase) + (size_t)_i * (p64); const unsigned _la = ldsbase + (unsigned)(bufoff) + (unsigned)_i * 8192u; \
;         asm volatile("s_mov_b32 m0, %0\n\ts_nop 0\n\tglobal_load_lds_dwordx4 %1, %2" :: "s"(_la), "v"(voff), "s"(_gb) : "memory"); } } while (0)
; #define PG8_LDA(dst, b, h) do { _Pragma("unroll") for (int m = 0; m < 4; ++m) _Pragma("unroll") for (int k = 0; k < 2; ++k) dst[m][k] = *(const LAS bf16x8*)(lds + PG8_SA(b, h) + aoff + m * 2048 + k * 1024); } while (0)
; #define PG8_LDB(dst, b, h) do { _Pragma("unroll") for (int n = 0; n < 2; ++n) _Pragma("unroll") for (int k = 0; k < 2; ++k) dst[n][k] = *(const LAS bf16x8*)(lds + PG8_SB(b, h) + boff + n * 2048 + k * 1024); } while (0)
; #define PG8_MMA(ai, bj, At, Bt) do { __builtin_amdgcn_s_setprio(1); _Pragma("unroll") for (int m = 0; m < 4; ++m) _Pragma("unroll") for (int n = 0; n < 2; ++n) _Pragma("unroll") for (int k = 0; k < 2; ++k) \
;         acc[ai][bj][m][n] = __builtin_amdgcn_mfma_f32_16x16x32_bf16(Bt[n][k], At[m][k], acc[ai][bj][m][n], 0, 0, 0); __builtin_amdgcn_s_setprio(0); } while (0)
; #define PG8_WAIT_V(n) asm volatile("s_waitcnt vmcnt(" #n ")" ::: "memory")
; #define PG8_WAIT_L(n) asm volatile("s_waitcnt lgkmcnt(" #n ")" ::: "memory")
; #define PG8_BAR __builtin_amdgcn_s_barrier()
; #define PG8_SCHED __builtin_amdgcn_sched_barrier(0)
; template <class Epi, class Sched>
; __device__ __forceinline__ void gemm_phase(LAS unsigned char* lds, const Sched& S, const Epi& E) {
;     ...
;             PG8_WAIT_V(8); PG8_WAIT_L(0); PG8_BAR; PG8_MMA(1, 0, At, B0); PG8_MMA(1, 1, At, B1); PG8_BAR; PG8_SCHED;
;             PG8_LDB(B0, 1, 0); PG8_LDB(B1, 1, 1); PG8_SCHED; PG8_LDA(At, 1, 0); PG8_STAGE(PG8_SA(0, 1), a2 + hA2, vA2, hA2 / 2);
;             PG8_WAIT_V(8); PG8_WAIT_L(0); PG8_BAR; PG8_MMA(0, 0, At, B0); PG8_MMA(0, 1, At, B1); PG8_BAR; PG8_SCHED;
	s_setprio 1
	v_mfma_f32_16x16x32_bf16 v[60:63], v[138:141], v[194:197], v[60:63]
	v_mfma_f32_16x16x32_bf16 v[56:59], v[146:149], v[194:197], v[56:59]
	v_mfma_f32_16x16x32_bf16 v[48:51], v[138:141], v[202:205], v[48:51]
	v_mfma_f32_16x16x32_bf16 v[40:43], v[146:149], v[202:205], v[40:43]
	v_mfma_f32_16x16x32_bf16 v[32:35], v[138:141], v[210:213], v[32:35]
	v_mfma_f32_16x16x32_bf16 v[24:27], v[146:149], v[210:213], v[24:27]
	v_mfma_f32_16x16x32_bf16 v[16:19], v[138:141], v[218:221], v[16:19]
	v_mfma_f32_16x16x32_bf16 v[8:11], v[146:149], v[218:221], v[8:11]
	v_mfma_f32_16x16x32_bf16 v[60:63], v[142:145], v[198:201], v[60:63]
	v_mfma_f32_16x16x32_bf16 v[56:59], v[172:175], v[198:201], v[56:59]
	v_mfma_f32_16x16x32_bf16 v[48:51], v[142:145], v[206:209], v[48:51]
	v_mfma_f32_16x16x32_bf16 v[40:43], v[172:175], v[206:209], v[40:43]
	v_mfma_f32_16x16x32_bf16 v[32:35], v[142:145], v[214:217], v[32:35]
	v_mfma_f32_16x16x32_bf16 v[24:27], v[172:175], v[214:217], v[24:27]
	v_mfma_f32_16x16x32_bf16 v[16:19], v[142:145], v[222:225], v[16:19]
	v_mfma_f32_16x16x32_bf16 v[8:11], v[172:175], v[222:225], v[8:11]
	v_mfma_f32_16x16x32_bf16 v[52:55], v[178:181], v[194:197], v[52:55]
	v_mfma_f32_16x16x32_bf16 v[44:47], v[186:189], v[194:197], v[44:47]
	v_mfma_f32_16x16x32_bf16 v[36:39], v[178:181], v[202:205], v[36:39]
	v_mfma_f32_16x16x32_bf16 v[28:31], v[186:189], v[202:205], v[28:31]
	v_mfma_f32_16x16x32_bf16 v[20:23], v[178:181], v[210:213], v[20:23]
	v_mfma_f32_16x16x32_bf16 v[12:15], v[186:189], v[210:213], v[12:15]
	v_mfma_f32_16x16x32_bf16 v[4:7], v[178:181], v[218:221], v[4:7]
	v_mfma_f32_16x16x32_bf16 v[0:3], v[186:189], v[218:221], v[0:3]
	v_mfma_f32_16x16x32_bf16 v[52:55], v[182:185], v[198:201], v[52:55]
	v_mfma_f32_16x16x32_bf16 v[44:47], v[190:193], v[198:201], v[44:47]
	v_mfma_f32_16x16x32_bf16 v[36:39], v[182:185], v[206:209], v[36:39]
	v_mfma_f32_16x16x32_bf16 v[28:31], v[190:193], v[206:209], v[28:31]
	v_mfma_f32_16x16x32_bf16 v[20:23], v[182:185], v[214:217], v[20:23]
	v_mfma_f32_16x16x32_bf16 v[12:15], v[190:193], v[214:217], v[12:15]
	v_mfma_f32_16x16x32_bf16 v[4:7], v[182:185], v[222:225], v[4:7]
	v_mfma_f32_16x16x32_bf16 v[0:3], v[190:193], v[222:225], v[0:3]
	s_setprio 0
	s_barrier
	v_add_u32_e32 v128, 0x18000, v154
	ds_read_b128 v[138:141], v128
	ds_read_b128 v[142:145], v128 offset:1024
	ds_read_b128 v[146:149], v128 offset:2048
	ds_read_b128 v[172:175], v128 offset:3072
	v_add_u32_e32 v128, 0x1c000, v154
	ds_read_b128 v[178:181], v128
	ds_read_b128 v[182:185], v128 offset:1024
	ds_read_b128 v[186:189], v128 offset:2048
	ds_read_b128 v[190:193], v128 offset:3072
	ds_read_b128 v[194:197], v155 offset:32768
	ds_read_b128 v[198:201], v155 offset:33792
	ds_read_b128 v[202:205], v155 offset:34816
	ds_read_b128 v[206:209], v155 offset:35840
	ds_read_b128 v[210:213], v155 offset:36864
	ds_read_b128 v[214:217], v155 offset:37888
	ds_read_b128 v[218:221], v155 offset:38912
	ds_read_b128 v[222:225], v155 offset:39936
	s_add_u32 s82, s16, 0x40000
	s_mov_b32 m0, s37
	s_addc_u32 s83, s17, 0
	global_load_lds_dwordx4 v150, s[82:83]
	s_add_u32 s82, s16, 0x60000
	s_mov_b32 m0, s42
	s_addc_u32 s83, s17, 0
	global_load_lds_dwordx4 v150, s[82:83]
	s_waitcnt vmcnt(8) lgkmcnt(0)
	s_barrier
	s_setprio 1
	v_mfma_f32_16x16x32_bf16 v[124:127], v[138:141], v[194:197], v[124:127]
	v_mfma_f32_16x16x32_bf16 v[120:123], v[146:149], v[194:197], v[120:123]
	v_mfma_f32_16x16x32_bf16 v[112:115], v[138:141], v[202:205], v[112:115]
	v_mfma_f32_16x16x32_bf16 v[104:107], v[146:149], v[202:205], v[104:107]
	v_mfma_f32_16x16x32_bf16 v[96:99], v[138:141], v[210:213], v[96:99]
	v_mfma_f32_16x16x32_bf16 v[88:91], v[146:149], v[210:213], v[88:91]
	v_mfma_f32_16x16x32_bf16 v[80:83], v[138:141], v[218:221], v[80:83]
	v_mfma_f32_16x16x32_bf16 v[72:75], v[146:149], v[218:221], v[72:75]
	v_mfma_f32_16x16x32_bf16 v[124:127], v[142:145], v[198:201], v[124:127]
	v_mfma_f32_16x16x32_bf16 v[120:123], v[172:175], v[198:201], v[120:123]
	v_mfma_f32_16x16x32_bf16 v[112:115], v[142:145], v[206:209], v[112:115]
	v_mfma_f32_16x16x32_bf16 v[104:107], v[172:175], v[206:209], v[104:107]
	v_mfma_f32_16x16x32_bf16 v[96:99], v[142:145], v[214:217], v[96:99]
	v_mfma_f32_16x16x32_bf16 v[88:91], v[172:175], v[214:217], v[88:91]
	v_mfma_f32_16x16x32_bf16 v[80:83], v[142:145], v[222:225], v[80:83]
	v_mfma_f32_16x16x32_bf16 v[72:75], v[172:175], v[222:225], v[72:75]
	v_mfma_f32_16x16x32_bf16 v[116:119], v[178:181], v[194:197], v[116:119]
	v_mfma_f32_16x16x32_bf16 v[108:111], v[186:189], v[194:197], v[108:111]
	v_mfma_f32_16x16x32_bf16 v[100:103], v[178:181], v[202:205], v[100:103]
	v_mfma_f32_16x16x32_bf16 v[92:95], v[186:189], v[202:205], v[92:95]
	v_mfma_f32_16x16x32_bf16 v[84:87], v[178:181], v[210:213], v[84:87]
	v_mfma_f32_16x16x32_bf16 v[76:79], v[186:189], v[210:213], v[76:79]
	v_mfma_f32_16x16x32_bf16 v[68:71], v[178:181], v[218:221], v[68:71]
	v_mfma_f32_16x16x32_bf16 v[64:67], v[186:189], v[218:221], v[64:67]
	v_mfma_f32_16x16x32_bf16 v[116:119], v[182:185], v[198:201], v[116:119]
	v_mfma_f32_16x16x32_bf16 v[108:111], v[190:193], v[198:201], v[108:111]
	v_mfma_f32_16x16x32_bf16 v[100:103], v[182:185], v[206:209], v[100:103]
	v_mfma_f32_16x16x32_bf16 v[92:95], v[190:193], v[206:209], v[92:95]
	v_mfma_f32_16x16x32_bf16 v[84:87], v[182:185], v[214:217], v[84:87]
	v_mfma_f32_16x16x32_bf16 v[76:79], v[190:193], v[214:217], v[76:79]
	v_mfma_f32_16x16x32_bf16 v[68:71], v[182:185], v[222:225], v[68:71]
	v_mfma_f32_16x16x32_bf16 v[64:67], v[190:193], v[222:225], v[64:67]
	s_setprio 0
	s_barrier
; #define PG8_STAGE(bufoff, gbase, voff, p64) do { _Pragma("unroll") for (int _i = 0; _i < 2; ++_i) { \
;         const char* _gb = (const char*)(gbase) + (size_t)_i * (p64); const unsigned _la = ldsbase + (unsigned)(bufoff) + (unsigned)_i * 8192u; \
;         asm volatile("s_mov_b32 m0, %0\n\ts_nop 0\n\tglobal_load_lds_dwordx4 %1, %2" :: "s"(_la), "v"(voff), "s"(_gb) : "memory"); } } while (0)
; #define PG8_LDA(dst, b, h) do { _Pragma("unroll") for (int m = 0; m < 4; ++m) _Pragma("unroll") for (int k = 0; k < 2; ++k) dst[m][k] = *(const LAS bf16x8*)(lds + PG8_SA(b, h) + aoff + m * 2048 + k * 1024); } while (0)
; #define PG8_MMA(ai, bj, At, Bt) do { __builtin_amdgcn_s_setprio(1); _Pragma("unroll") for (int m = 0; m < 4; ++m) _Pragma("unroll") for (int n = 0; n < 2; ++n) _Pragma("unroll") for (int k = 0; k < 2; ++k) \
;         acc[ai][bj][m][n] = __builtin_amdgcn_mfma_f32_16x16x32_bf16(Bt[n][k], At[m][k], acc[ai][bj][m][n], 0, 0, 0); __builtin_amdgcn_s_setprio(0); } while (0)
; #define PG8_WAIT_V(n) asm volatile("s_waitcnt vmcnt(" #n ")" ::: "memory")
; #define PG8_WAIT_L(n) asm volatile("s_waitcnt lgkmcnt(" #n ")" ::: "memory")
; #define PG8_BAR __builtin_amdgcn_s_barrier()
; #define PG8_SCHED __builtin_amdgcn_sched_barrier(0)
; template <class Epi, class Sched>
; __device__ __forceinline__ void gemm_phase(LAS unsigned char* lds, const Sched& S, const Epi& E) {
;     ...
;             PG8_LDA(At, 1, 1); PG8_STAGE(PG8_SB(1, 0), b3, vB2, hB2 / 2); PG8_STAGE(PG8_SB(1, 1), b3 + hB2, vB2, hB2 / 2); PG8_STAGE(PG8_SA(1, 0), a3, vA2, hA2 / 2);
;             PG8_WAIT_V(8); PG8_WAIT_L(0); PG8_BAR; PG8_MMA(1, 0, At, B0); PG8_MMA(1, 1, At, B1); PG8_BAR; PG8_SCHED;
;         }
;         if (wr == 0) PG8_BAR;
	s_add_u32 s82, s76, 0x80
	s_addc_u32 s83, s77, 0
	ds_read_b128 v[194:197], v155 offset:49152
	ds_read_b128 v[198:201], v155 offset:50176
	ds_read_b128 v[202:205], v155 offset:51200
	ds_read_b128 v[206:209], v155 offset:52224
	ds_read_b128 v[210:213], v155 offset:53248
	ds_read_b128 v[214:217], v155 offset:54272
	ds_read_b128 v[218:221], v155 offset:55296
	ds_read_b128 v[222:225], v155 offset:56320
	s_mov_b32 m0, s50
	s_nop 0
	global_load_lds_dwordx4 v151, s[82:83]
	s_add_u32 s82, s76, 0x20080
	s_mov_b32 m0, s51
	s_addc_u32 s83, s77, 0
	global_load_lds_dwordx4 v151, s[82:83]
	s_add_u32 s82, s76, 0x40080
	s_mov_b32 m0, s65
	s_addc_u32 s83, s77, 0
	global_load_lds_dwordx4 v151, s[82:83]
	s_add_u32 s76, s76, 0x60080
	s_mov_b32 m0, s66
	s_addc_u32 s77, s77, 0
	global_load_lds_dwordx4 v151, s[76:77]
	s_mov_b32 m0, s61
	s_nop 0
	global_load_lds_dwordx4 v150, s[22:23]
	s_add_u32 s16, s16, 0x20080
	s_mov_b32 m0, s64
	s_addc_u32 s17, s17, 0
	global_load_lds_dwordx4 v150, s[16:17]
	s_waitcnt vmcnt(8) lgkmcnt(0)
	s_barrier
	s_setprio 1
	v_mfma_f32_16x16x32_bf16 v[60:63], v[138:141], v[194:197], v[60:63]
	v_mfma_f32_16x16x32_bf16 v[56:59], v[146:149], v[194:197], v[56:59]
	v_mfma_f32_16x16x32_bf16 v[48:51], v[138:141], v[202:205], v[48:51]
	v_mfma_f32_16x16x32_bf16 v[40:43], v[146:149], v[202:205], v[40:43]
	v_mfma_f32_16x16x32_bf16 v[32:35], v[138:141], v[210:213], v[32:35]
	v_mfma_f32_16x16x32_bf16 v[24:27], v[146:149], v[210:213], v[24:27]
	v_mfma_f32_16x16x32_bf16 v[16:19], v[138:141], v[218:221], v[16:19]
	v_mfma_f32_16x16x32_bf16 v[8:11], v[146:149], v[218:221], v[8:11]
	v_mfma_f32_16x16x32_bf16 v[60:63], v[142:145], v[198:201], v[60:63]
	v_mfma_f32_16x16x32_bf16 v[56:59], v[172:175], v[198:201], v[56:59]
	v_mfma_f32_16x16x32_bf16 v[48:51], v[142:145], v[206:209], v[48:51]
	v_mfma_f32_16x16x32_bf16 v[40:43], v[172:175], v[206:209], v[40:43]
	v_mfma_f32_16x16x32_bf16 v[32:35], v[142:145], v[214:217], v[32:35]
	v_mfma_f32_16x16x32_bf16 v[24:27], v[172:175], v[214:217], v[24:27]
	v_mfma_f32_16x16x32_bf16 v[16:19], v[142:145], v[222:225], v[16:19]
	v_mfma_f32_16x16x32_bf16 v[8:11], v[172:175], v[222:225], v[8:11]
	v_mfma_f32_16x16x32_bf16 v[52:55], v[178:181], v[194:197], v[52:55]
	v_mfma_f32_16x16x32_bf16 v[44:47], v[186:189], v[194:197], v[44:47]
	v_mfma_f32_16x16x32_bf16 v[36:39], v[178:181], v[202:205], v[36:39]
	v_mfma_f32_16x16x32_bf16 v[28:31], v[186:189], v[202:205], v[28:31]
	v_mfma_f32_16x16x32_bf16 v[20:23], v[178:181], v[210:213], v[20:23]
	v_mfma_f32_16x16x32_bf16 v[12:15], v[186:189], v[210:213], v[12:15]
	v_mfma_f32_16x16x32_bf16 v[4:7], v[178:181], v[218:221], v[4:7]
	v_mfma_f32_16x16x32_bf16 v[0:3], v[186:189], v[218:221], v[0:3]
	v_mfma_f32_16x16x32_bf16 v[52:55], v[182:185], v[198:201], v[52:55]
	v_mfma_f32_16x16x32_bf16 v[44:47], v[190:193], v[198:201], v[44:47]
	v_mfma_f32_16x16x32_bf16 v[36:39], v[182:185], v[206:209], v[36:39]
	v_mfma_f32_16x16x32_bf16 v[28:31], v[190:193], v[206:209], v[28:31]
	v_mfma_f32_16x16x32_bf16 v[20:23], v[182:185], v[214:217], v[20:23]
	v_mfma_f32_16x16x32_bf16 v[12:15], v[190:193], v[214:217], v[12:15]
	v_mfma_f32_16x16x32_bf16 v[4:7], v[182:185], v[222:225], v[4:7]
	v_mfma_f32_16x16x32_bf16 v[0:3], v[190:193], v[222:225], v[0:3]
	s_setprio 0
	s_barrier
	s_cmp_gt_u32 s81, 13
	s_cbranch_scc0 .LBB0_553
	s_and_b64 vcc, exec, s[6:7]
	s_cbranch_vccz .LBB0_556
	s_barrier

; #define PG8_STAGE(bufoff, gbase, voff, p64) do { _Pragma("unroll") for (int _i = 0; _i < 2; ++_i) { \
;         const char* _gb = (const char*)(gbase) + (size_t)_i * (p64); const unsigned _la = ldsbase + (unsigned)(bufoff) + (unsigned)_i * 8192u; \
;         asm volatile("s_mov_b32 m0, %0\n\ts_nop 0\n\tglobal_load_lds_dwordx4 %1, %2" :: "s"(_la), "v"(voff), "s"(_gb) : "memory"); } } while (0)
; #define PG8_LDA(dst, b, h) do { _Pragma("unroll") for (int m = 0; m < 4; ++m) _Pragma("unroll") for (int k = 0; k < 2; ++k) dst[m][k] = *(const LAS bf16x8*)(lds + PG8_SA(b, h) + aoff + m * 2048 + k * 1024); } while (0)
; #define PG8_LDB(dst, b, h) do { _Pragma("unroll") for (int n = 0; n < 2; ++n) _Pragma("unroll") for (int k = 0; k < 2; ++k) dst[n][k] = *(const LAS bf16x8*)(lds + PG8_SB(b, h) + boff + n * 2048 + k * 1024); } while (0)
; #define PG8_MMA(ai, bj, At, Bt) do { __builtin_amdgcn_s_setprio(1); _Pragma("unroll") for (int m = 0; m < 4; ++m) _Pragma("unroll") for (int n = 0; n < 2; ++n) _Pragma("unroll") for (int k = 0; k < 2; ++k) \
;         acc[ai][bj][m][n] = __builtin_amdgcn_mfma_f32_16x16x32_bf16(Bt[n][k], At[m][k], acc[ai][bj][m][n], 0, 0, 0); __builtin_amdgcn_s_setprio(0); } while (0)
; #define PG8_WAIT_V(n) asm volatile("s_waitcnt vmcnt(" #n ")" ::: "memory")
; #define PG8_BAR __builtin_amdgcn_s_barrier()
; template <class Epi, class Sched>
; __device__ __forceinline__ void gemm_phase(LAS unsigned char* lds, const Sched& S, const Epi& E) {
;     ...
;             const bool last = (t == nt - 2);
;             const char* a1 = cA + (size_t)(t + 1) * kstep;
;             const char* a2 = last ? nA : cA + (size_t)(t + 2) * kstep; const char* b2 = last ? nB : cB + (size_t)(t + 2) * kstep;
;             const char* a3 = a2 + kstep; const char* b3 = b2 + kstep;
;             const unsigned vA2 = voffA, vB2 = voffB, hA2 = hA, hB2 = hB;
;             PG8_LDB(B0, 0, 0); PG8_LDB(B1, 0, 1); PG8_SCHED; PG8_LDA(At, 0, 0); PG8_STAGE(PG8_SA(1, 1), a1 + hA, voffA, hA / 2);
;             PG8_WAIT_V(8); PG8_WAIT_L(0); PG8_BAR; PG8_MMA(0, 0, At, B0); PG8_MMA(0, 1, At, B1); PG8_BAR; PG8_SCHED;
;             PG8_LDA(At, 0, 1); PG8_STAGE(PG8_SB(0, 0), b2, vB2, hB2 / 2); PG8_STAGE(PG8_SB(0, 1), b2 + hB2, vB2, hB2 / 2); PG8_STAGE(PG8_SA(0, 0), a2, vA2, hA2 / 2);
;             PG8_WAIT_V(8); PG8_WAIT_L(0); PG8_BAR; PG8_MMA(1, 0, At, B0); PG8_MMA(1, 1, At, B1); PG8_BAR; PG8_SCHED;
.LBB0_582:
	v_add_u32_e32 v130, 0x10000, v153
	ds_read_b128 v[138:141], v130
	ds_read_b128 v[142:145], v130 offset:1024
	ds_read_b128 v[146:149], v130 offset:2048
	ds_read_b128 v[172:175], v130 offset:3072
	v_add_u32_e32 v130, 0x14000, v153
	ds_read_b128 v[178:181], v130
	ds_read_b128 v[182:185], v130 offset:1024
	ds_read_b128 v[186:189], v130 offset:2048
	ds_read_b128 v[190:193], v130 offset:3072
	s_add_u32 s16, s62, 0xfffc0080
	s_addc_u32 s17, s63, -1
	s_cmp_eq_u32 s75, 12
	s_cselect_b32 s16, s56, s16
	s_cselect_b32 s17, s57, s17
	s_cselect_b32 s72, s58, s55
	s_cselect_b32 s73, s59, s74
	s_add_u32 s22, s16, 0x80
	s_addc_u32 s23, s17, 0
	ds_read_b128 v[194:197], v154
	ds_read_b128 v[198:201], v154 offset:1024
	ds_read_b128 v[202:205], v154 offset:2048
	ds_read_b128 v[206:209], v154 offset:3072
	ds_read_b128 v[210:213], v154 offset:4096
	ds_read_b128 v[214:217], v154 offset:5120
	ds_read_b128 v[218:221], v154 offset:6144
	ds_read_b128 v[222:225], v154 offset:7168
	s_mov_b32 m0, s78
	s_nop 0
	global_load_lds_dwordx4 v128, s[62:63]
	s_add_u32 s82, s62, 0x20000
	s_mov_b32 m0, s80
	s_addc_u32 s83, s63, 0
	global_load_lds_dwordx4 v128, s[82:83]
	s_waitcnt vmcnt(8) lgkmcnt(0)
	s_barrier
	s_setprio 1
	v_mfma_f32_16x16x32_bf16 v[124:127], v[138:141], v[194:197], v[124:127]
	v_mfma_f32_16x16x32_bf16 v[120:123], v[146:149], v[194:197], v[120:123]
	v_mfma_f32_16x16x32_bf16 v[116:119], v[138:141], v[202:205], v[116:119]
	v_mfma_f32_16x16x32_bf16 v[108:111], v[146:149], v[202:205], v[108:111]
	v_mfma_f32_16x16x32_bf16 v[100:103], v[138:141], v[210:213], v[100:103]
	v_mfma_f32_16x16x32_bf16 v[92:95], v[146:149], v[210:213], v[92:95]
	v_mfma_f32_16x16x32_bf16 v[84:87], v[138:141], v[218:221], v[84:87]
	v_mfma_f32_16x16x32_bf16 v[76:79], v[146:149], v[218:221], v[76:79]
	v_mfma_f32_16x16x32_bf16 v[124:127], v[142:145], v[198:201], v[124:127]
	v_mfma_f32_16x16x32_bf16 v[120:123], v[172:175], v[198:201], v[120:123]
	v_mfma_f32_16x16x32_bf16 v[116:119], v[142:145], v[206:209], v[116:119]
	v_mfma_f32_16x16x32_bf16 v[108:111], v[172:175], v[206:209], v[108:111]
	v_mfma_f32_16x16x32_bf16 v[100:103], v[142:145], v[214:217], v[100:103]
	v_mfma_f32_16x16x32_bf16 v[92:95], v[172:175], v[214:217], v[92:95]
	v_mfma_f32_16x16x32_bf16 v[84:87], v[142:145], v[222:225], v[84:87]
	v_mfma_f32_16x16x32_bf16 v[76:79], v[172:175], v[222:225], v[76:79]
	s_add_i32 s75, s75, 2
	s_add_u32 s62, s62, 0x100
	s_addc_u32 s63, s63, 0
	s_add_u32 s55, s55, 0x100
	s_addc_u32 s74, s74, 0
	v_mfma_f32_16x16x32_bf16 v[112:115], v[178:181], v[194:197], v[112:115]
	v_mfma_f32_16x16x32_bf16 v[104:107], v[186:189], v[194:197], v[104:107]
	v_mfma_f32_16x16x32_bf16 v[96:99], v[178:181], v[202:205], v[96:99]
	v_mfma_f32_16x16x32_bf16 v[88:91], v[186:189], v[202:205], v[88:91]
	v_mfma_f32_16x16x32_bf16 v[80:83], v[178:181], v[210:213], v[80:83]
	v_mfma_f32_16x16x32_bf16 v[72:75], v[186:189], v[210:213], v[72:75]
	v_mfma_f32_16x16x32_bf16 v[68:71], v[178:181], v[218:221], v[68:71]
	v_mfma_f32_16x16x32_bf16 v[64:67], v[186:189], v[218:221], v[64:67]
	v_mfma_f32_16x16x32_bf16 v[112:115], v[182:185], v[198:201], v[112:115]
	v_mfma_f32_16x16x32_bf16 v[104:107], v[190:193], v[198:201], v[104:107]
	v_mfma_f32_16x16x32_bf16 v[96:99], v[182:185], v[206:209], v[96:99]
	v_mfma_f32_16x16x32_bf16 v[88:91], v[190:193], v[206:209], v[88:91]
	v_mfma_f32_16x16x32_bf16 v[80:83], v[182:185], v[214:217], v[80:83]
	v_mfma_f32_16x16x32_bf16 v[72:75], v[190:193], v[214:217], v[72:75]
	v_mfma_f32_16x16x32_bf16 v[68:71], v[182:185], v[222:225], v[68:71]
	v_mfma_f32_16x16x32_bf16 v[64:67], v[190:193], v[222:225], v[64:67]
	s_setprio 0
	s_barrier
	s_add_u32 s82, s72, 0x20000
	ds_read_b128 v[194:197], v154 offset:16384
	ds_read_b128 v[198:201], v154 offset:17408
	ds_read_b128 v[202:205], v154 offset:18432
	ds_read_b128 v[206:209], v154 offset:19456
	ds_read_b128 v[210:213], v154 offset:20480
	ds_read_b128 v[214:217], v154 offset:21504
	ds_read_b128 v[218:221], v154 offset:22528
	ds_read_b128 v[222:225], v154 offset:23552
	s_mov_b32 m0, s20
	s_nop 0
	global_load_lds_dwordx4 v150, s[72:73]
	s_mov_b32 m0, s24
	s_addc_u32 s83, s73, 0
	global_load_lds_dwordx4 v150, s[82:83]
	s_add_u32 s82, s72, 0x40000
	s_mov_b32 m0, s33
	s_addc_u32 s83, s73, 0
	global_load_lds_dwordx4 v150, s[82:83]
	s_add_u32 s82, s72, 0x60000
	s_mov_b32 m0, s34
	s_addc_u32 s83, s73, 0
	global_load_lds_dwordx4 v150, s[82:83]
	s_mov_b32 m0, s15
	s_nop 0
	global_load_lds_dwordx4 v128, s[16:17]
	s_add_u32 s82, s16, 0x20000
	s_mov_b32 m0, s35
	s_addc_u32 s83, s17, 0
	global_load_lds_dwordx4 v128, s[82:83]
	s_waitcnt vmcnt(8) lgkmcnt(0)
	s_barrier
; #define PG8_STAGE(bufoff, gbase, voff, p64) do { _Pragma("unroll") for (int _i = 0; _i < 2; ++_i) { \
;         const char* _gb = (const char*)(gbase) + (size_t)_i * (p64); const unsigned _la = ldsbase + (unsigned)(bufoff) + (unsigned)_i * 8192u; \
;         asm volatile("s_mov_b32 m0, %0\n\ts_nop 0\n\tglobal_load_lds_dwordx4 %1, %2" :: "s"(_la), "v"(voff), "s"(_gb) : "memory"); } } while (0)
; #define PG8_LDA(dst, b, h) do { _Pragma("unroll") for (int m = 0; m < 4; ++m) _Pragma("unroll") for (int k = 0; k < 2; ++k) dst[m][k] = *(const LAS bf16x8*)(lds + PG8_SA(b, h) + aoff + m * 2048 + k * 1024); } while (0)
; #define PG8_LDB(dst, b, h) do { _Pragma("unroll") for (int n = 0; n < 2; ++n) _Pragma("unroll") for (int k = 0; k < 2; ++k) dst[n][k] = *(const LAS bf16x8*)(lds + PG8_SB(b, h) + boff + n * 2048 + k * 1024); } while (0)
; #define PG8_MMA(ai, bj, At, Bt) do { __builtin_amdgcn_s_setprio(1); _Pragma("unroll") for (int m = 0; m < 4; ++m) _Pragma("unroll") for (int n = 0; n < 2; ++n) _Pragma("unroll") for (int k = 0; k < 2; ++k) \
;         acc[ai][bj][m][n] = __builtin_amdgcn_mfma_f32_16x16x32_bf16(Bt[n][k], At[m][k], acc[ai][bj][m][n], 0, 0, 0); __builtin_amdgcn_s_setprio(0); } while (0)
; #define PG8_WAIT_V(n) asm volatile("s_waitcnt vmcnt(" #n ")" ::: "memory")
; #define PG8_WAIT_L(n) asm volatile("s_waitcnt lgkmcnt(" #n ")" ::: "memory")
; #define PG8_BAR __builtin_amdgcn_s_barrier()
; #define PG8_SCHED __builtin_amdgcn_sched_barrier(0)
; template <class Epi, class Sched>
; __device__ __forceinline__ void gemm_phase(LAS unsigned char* lds, const Sched& S, const Epi& E) {
;     ...
;             PG8_WAIT_V(8); PG8_WAIT_L(0); PG8_BAR; PG8_MMA(1, 0, At, B0); PG8_MMA(1, 1, At, B1); PG8_BAR; PG8_SCHED;
;             PG8_LDB(B0, 1, 0); PG8_LDB(B1, 1, 1); PG8_SCHED; PG8_LDA(At, 1, 0); PG8_STAGE(PG8_SA(0, 1), a2 + hA2, vA2, hA2 / 2);
;             PG8_WAIT_V(8); PG8_WAIT_L(0); PG8_BAR; PG8_MMA(0, 0, At, B0); PG8_MMA(0, 1, At, B1); PG8_BAR; PG8_SCHED;
	s_setprio 1
	v_mfma_f32_16x16x32_bf16 v[60:63], v[138:141], v[194:197], v[60:63]
	v_mfma_f32_16x16x32_bf16 v[56:59], v[146:149], v[194:197], v[56:59]
	v_mfma_f32_16x16x32_bf16 v[52:55], v[138:141], v[202:205], v[52:55]
	v_mfma_f32_16x16x32_bf16 v[44:47], v[146:149], v[202:205], v[44:47]
	v_mfma_f32_16x16x32_bf16 v[36:39], v[138:141], v[210:213], v[36:39]
	v_mfma_f32_16x16x32_bf16 v[28:31], v[146:149], v[210:213], v[28:31]
	v_mfma_f32_16x16x32_bf16 v[20:23], v[138:141], v[218:221], v[20:23]
	v_mfma_f32_16x16x32_bf16 v[12:15], v[146:149], v[218:221], v[12:15]
	v_mfma_f32_16x16x32_bf16 v[60:63], v[142:145], v[198:201], v[60:63]
	v_mfma_f32_16x16x32_bf16 v[56:59], v[172:175], v[198:201], v[56:59]
	v_mfma_f32_16x16x32_bf16 v[52:55], v[142:145], v[206:209], v[52:55]
	v_mfma_f32_16x16x32_bf16 v[44:47], v[172:175], v[206:209], v[44:47]
	v_mfma_f32_16x16x32_bf16 v[36:39], v[142:145], v[214:217], v[36:39]
	v_mfma_f32_16x16x32_bf16 v[28:31], v[172:175], v[214:217], v[28:31]
	v_mfma_f32_16x16x32_bf16 v[20:23], v[142:145], v[222:225], v[20:23]
	v_mfma_f32_16x16x32_bf16 v[12:15], v[172:175], v[222:225], v[12:15]
	v_mfma_f32_16x16x32_bf16 v[48:51], v[178:181], v[194:197], v[48:51]
	v_mfma_f32_16x16x32_bf16 v[40:43], v[186:189], v[194:197], v[40:43]
	v_mfma_f32_16x16x32_bf16 v[32:35], v[178:181], v[202:205], v[32:35]
	v_mfma_f32_16x16x32_bf16 v[24:27], v[186:189], v[202:205], v[24:27]
	v_mfma_f32_16x16x32_bf16 v[16:19], v[178:181], v[210:213], v[16:19]
	v_mfma_f32_16x16x32_bf16 v[8:11], v[186:189], v[210:213], v[8:11]
	v_mfma_f32_16x16x32_bf16 v[4:7], v[178:181], v[218:221], v[4:7]
	v_mfma_f32_16x16x32_bf16 v[0:3], v[186:189], v[218:221], v[0:3]
	v_mfma_f32_16x16x32_bf16 v[48:51], v[182:185], v[198:201], v[48:51]
	v_mfma_f32_16x16x32_bf16 v[40:43], v[190:193], v[198:201], v[40:43]
	v_mfma_f32_16x16x32_bf16 v[32:35], v[182:185], v[206:209], v[32:35]
	v_mfma_f32_16x16x32_bf16 v[24:27], v[190:193], v[206:209], v[24:27]
	v_mfma_f32_16x16x32_bf16 v[16:19], v[182:185], v[214:217], v[16:19]
	v_mfma_f32_16x16x32_bf16 v[8:11], v[190:193], v[214:217], v[8:11]
	v_mfma_f32_16x16x32_bf16 v[4:7], v[182:185], v[222:225], v[4:7]
	v_mfma_f32_16x16x32_bf16 v[0:3], v[190:193], v[222:225], v[0:3]
	s_setprio 0
	s_barrier
	v_add_u32_e32 v130, 0x18000, v153
	ds_read_b128 v[138:141], v130
	ds_read_b128 v[142:145], v130 offset:1024
	ds_read_b128 v[146:149], v130 offset:2048
	ds_read_b128 v[172:175], v130 offset:3072
	v_add_u32_e32 v130, 0x1c000, v153
	ds_read_b128 v[178:181], v130
	ds_read_b128 v[182:185], v130 offset:1024
	ds_read_b128 v[186:189], v130 offset:2048
	ds_read_b128 v[190:193], v130 offset:3072
	ds_read_b128 v[194:197], v154 offset:32768
	ds_read_b128 v[198:201], v154 offset:33792
	ds_read_b128 v[202:205], v154 offset:34816
	ds_read_b128 v[206:209], v154 offset:35840
	ds_read_b128 v[210:213], v154 offset:36864
	ds_read_b128 v[214:217], v154 offset:37888
	ds_read_b128 v[218:221], v154 offset:38912
	ds_read_b128 v[222:225], v154 offset:39936
	s_add_u32 s82, s16, 0x40000
	s_mov_b32 m0, s36
	s_addc_u32 s83, s17, 0
	global_load_lds_dwordx4 v128, s[82:83]
	s_add_u32 s82, s16, 0x60000
	s_mov_b32 m0, s37
	s_addc_u32 s83, s17, 0
	global_load_lds_dwordx4 v128, s[82:83]
	s_waitcnt vmcnt(8) lgkmcnt(0)
	s_barrier
	s_setprio 1
	v_mfma_f32_16x16x32_bf16 v[124:127], v[138:141], v[194:197], v[124:127]
	v_mfma_f32_16x16x32_bf16 v[120:123], v[146:149], v[194:197], v[120:123]
	v_mfma_f32_16x16x32_bf16 v[116:119], v[138:141], v[202:205], v[116:119]
	v_mfma_f32_16x16x32_bf16 v[108:111], v[146:149], v[202:205], v[108:111]
	v_mfma_f32_16x16x32_bf16 v[100:103], v[138:141], v[210:213], v[100:103]
	v_mfma_f32_16x16x32_bf16 v[92:95], v[146:149], v[210:213], v[92:95]
	v_mfma_f32_16x16x32_bf16 v[84:87], v[138:141], v[218:221], v[84:87]
	v_mfma_f32_16x16x32_bf16 v[76:79], v[146:149], v[218:221], v[76:79]
	v_mfma_f32_16x16x32_bf16 v[124:127], v[142:145], v[198:201], v[124:127]
	v_mfma_f32_16x16x32_bf16 v[120:123], v[172:175], v[198:201], v[120:123]
	v_mfma_f32_16x16x32_bf16 v[116:119], v[142:145], v[206:209], v[116:119]
	v_mfma_f32_16x16x32_bf16 v[108:111], v[172:175], v[206:209], v[108:111]
	v_mfma_f32_16x16x32_bf16 v[100:103], v[142:145], v[214:217], v[100:103]
	v_mfma_f32_16x16x32_bf16 v[92:95], v[172:175], v[214:217], v[92:95]
	v_mfma_f32_16x16x32_bf16 v[84:87], v[142:145], v[222:225], v[84:87]
	v_mfma_f32_16x16x32_bf16 v[76:79], v[172:175], v[222:225], v[76:79]
	v_mfma_f32_16x16x32_bf16 v[112:115], v[178:181], v[194:197], v[112:115]
	v_mfma_f32_16x16x32_bf16 v[104:107], v[186:189], v[194:197], v[104:107]
	v_mfma_f32_16x16x32_bf16 v[96:99], v[178:181], v[202:205], v[96:99]
	v_mfma_f32_16x16x32_bf16 v[88:91], v[186:189], v[202:205], v[88:91]
	v_mfma_f32_16x16x32_bf16 v[80:83], v[178:181], v[210:213], v[80:83]
	v_mfma_f32_16x16x32_bf16 v[72:75], v[186:189], v[210:213], v[72:75]
	v_mfma_f32_16x16x32_bf16 v[68:71], v[178:181], v[218:221], v[68:71]
	v_mfma_f32_16x16x32_bf16 v[64:67], v[186:189], v[218:221], v[64:67]
	v_mfma_f32_16x16x32_bf16 v[112:115], v[182:185], v[198:201], v[112:115]
	v_mfma_f32_16x16x32_bf16 v[104:107], v[190:193], v[198:201], v[104:107]
	v_mfma_f32_16x16x32_bf16 v[96:99], v[182:185], v[206:209], v[96:99]
	v_mfma_f32_16x16x32_bf16 v[88:91], v[190:193], v[206:209], v[88:91]
	v_mfma_f32_16x16x32_bf16 v[80:83], v[182:185], v[214:217], v[80:83]
	v_mfma_f32_16x16x32_bf16 v[72:75], v[190:193], v[214:217], v[72:75]
	v_mfma_f32_16x16x32_bf16 v[68:71], v[182:185], v[222:225], v[68:71]
	v_mfma_f32_16x16x32_bf16 v[64:67], v[190:193], v[222:225], v[64:67]
	s_setprio 0
	s_barrier
; #define PG8_STAGE(bufoff, gbase, voff, p64) do { _Pragma("unroll") for (int _i = 0; _i < 2; ++_i) { \
;         const char* _gb = (const char*)(gbase) + (size_t)_i * (p64); const unsigned _la = ldsbase + (unsigned)(bufoff) + (unsigned)_i * 8192u; \
;         asm volatile("s_mov_b32 m0, %0\n\ts_nop 0\n\tglobal_load_lds_dwordx4 %1, %2" :: "s"(_la), "v"(voff), "s"(_gb) : "memory"); } } while (0)
; #define PG8_LDA(dst, b, h) do { _Pragma("unroll") for (int m = 0; m < 4; ++m) _Pragma("unroll") for (int k = 0; k < 2; ++k) dst[m][k] = *(const LAS bf16x8*)(lds + PG8_SA(b, h) + aoff + m * 2048 + k * 1024); } while (0)
; #define PG8_MMA(ai, bj, At, Bt) do { __builtin_amdgcn_s_setprio(1); _Pragma("unroll") for (int m = 0; m < 4; ++m) _Pragma("unroll") for (int n = 0; n < 2; ++n) _Pragma("unroll") for (int k = 0; k < 2; ++k) \
;         acc[ai][bj][m][n] = __builtin_amdgcn_mfma_f32_16x16x32_bf16(Bt[n][k], At[m][k], acc[ai][bj][m][n], 0, 0, 0); __builtin_amdgcn_s_setprio(0); } while (0)
; #define PG8_WAIT_V(n) asm volatile("s_waitcnt vmcnt(" #n ")" ::: "memory")
; #define PG8_WAIT_L(n) asm volatile("s_waitcnt lgkmcnt(" #n ")" ::: "memory")
; #define PG8_BAR __builtin_amdgcn_s_barrier()
; #define PG8_SCHED __builtin_amdgcn_sched_barrier(0)
; template <class Epi, class Sched>
; __device__ __forceinline__ void gemm_phase(LAS unsigned char* lds, const Sched& S, const Epi& E) {
;     ...
;             PG8_LDA(At, 1, 1); PG8_STAGE(PG8_SB(1, 0), b3, vB2, hB2 / 2); PG8_STAGE(PG8_SB(1, 1), b3 + hB2, vB2, hB2 / 2); PG8_STAGE(PG8_SA(1, 0), a3, vA2, hA2 / 2);
;             PG8_WAIT_V(8); PG8_WAIT_L(0); PG8_BAR; PG8_MMA(1, 0, At, B0); PG8_MMA(1, 1, At, B1); PG8_BAR; PG8_SCHED;
;         }
;         if (wr == 0) PG8_BAR;
	s_add_u32 s82, s72, 0x80
	s_addc_u32 s83, s73, 0
	ds_read_b128 v[194:197], v154 offset:49152
	ds_read_b128 v[198:201], v154 offset:50176
	ds_read_b128 v[202:205], v154 offset:51200
	ds_read_b128 v[206:209], v154 offset:52224
	ds_read_b128 v[210:213], v154 offset:53248
	ds_read_b128 v[214:217], v154 offset:54272
	ds_read_b128 v[218:221], v154 offset:55296
	ds_read_b128 v[222:225], v154 offset:56320
	s_mov_b32 m0, s66
	s_nop 0
	global_load_lds_dwordx4 v150, s[82:83]
	s_add_u32 s82, s72, 0x20080
	s_mov_b32 m0, s67
	s_addc_u32 s83, s73, 0
	global_load_lds_dwordx4 v150, s[82:83]
	s_add_u32 s82, s72, 0x40080
	s_mov_b32 m0, s76
	s_addc_u32 s83, s73, 0
	global_load_lds_dwordx4 v150, s[82:83]
	s_add_u32 s72, s72, 0x60080
	s_mov_b32 m0, s77
	s_addc_u32 s73, s73, 0
	global_load_lds_dwordx4 v150, s[72:73]
	s_mov_b32 m0, s68
	s_nop 0
	global_load_lds_dwordx4 v128, s[22:23]
	s_add_u32 s16, s16, 0x20080
	s_mov_b32 m0, s69
	s_addc_u32 s17, s17, 0
	global_load_lds_dwordx4 v128, s[16:17]
	s_waitcnt vmcnt(8) lgkmcnt(0)
	s_barrier
	s_setprio 1
	v_mfma_f32_16x16x32_bf16 v[60:63], v[138:141], v[194:197], v[60:63]
	v_mfma_f32_16x16x32_bf16 v[56:59], v[146:149], v[194:197], v[56:59]
	v_mfma_f32_16x16x32_bf16 v[52:55], v[138:141], v[202:205], v[52:55]
	v_mfma_f32_16x16x32_bf16 v[44:47], v[146:149], v[202:205], v[44:47]
	v_mfma_f32_16x16x32_bf16 v[36:39], v[138:141], v[210:213], v[36:39]
	v_mfma_f32_16x16x32_bf16 v[28:31], v[146:149], v[210:213], v[28:31]
	v_mfma_f32_16x16x32_bf16 v[20:23], v[138:141], v[218:221], v[20:23]
	v_mfma_f32_16x16x32_bf16 v[12:15], v[146:149], v[218:221], v[12:15]
	v_mfma_f32_16x16x32_bf16 v[60:63], v[142:145], v[198:201], v[60:63]
	v_mfma_f32_16x16x32_bf16 v[56:59], v[172:175], v[198:201], v[56:59]
	v_mfma_f32_16x16x32_bf16 v[52:55], v[142:145], v[206:209], v[52:55]
	v_mfma_f32_16x16x32_bf16 v[44:47], v[172:175], v[206:209], v[44:47]
	v_mfma_f32_16x16x32_bf16 v[36:39], v[142:145], v[214:217], v[36:39]
	v_mfma_f32_16x16x32_bf16 v[28:31], v[172:175], v[214:217], v[28:31]
	v_mfma_f32_16x16x32_bf16 v[20:23], v[142:145], v[222:225], v[20:23]
	v_mfma_f32_16x16x32_bf16 v[12:15], v[172:175], v[222:225], v[12:15]
	v_mfma_f32_16x16x32_bf16 v[48:51], v[178:181], v[194:197], v[48:51]
	v_mfma_f32_16x16x32_bf16 v[40:43], v[186:189], v[194:197], v[40:43]
	v_mfma_f32_16x16x32_bf16 v[32:35], v[178:181], v[202:205], v[32:35]
	v_mfma_f32_16x16x32_bf16 v[24:27], v[186:189], v[202:205], v[24:27]
	v_mfma_f32_16x16x32_bf16 v[16:19], v[178:181], v[210:213], v[16:19]
	v_mfma_f32_16x16x32_bf16 v[8:11], v[186:189], v[210:213], v[8:11]
	v_mfma_f32_16x16x32_bf16 v[4:7], v[178:181], v[218:221], v[4:7]
	v_mfma_f32_16x16x32_bf16 v[0:3], v[186:189], v[218:221], v[0:3]
	v_mfma_f32_16x16x32_bf16 v[48:51], v[182:185], v[198:201], v[48:51]
	v_mfma_f32_16x16x32_bf16 v[40:43], v[190:193], v[198:201], v[40:43]
	v_mfma_f32_16x16x32_bf16 v[32:35], v[182:185], v[206:209], v[32:35]
	v_mfma_f32_16x16x32_bf16 v[24:27], v[190:193], v[206:209], v[24:27]
	v_mfma_f32_16x16x32_bf16 v[16:19], v[182:185], v[214:217], v[16:19]
	v_mfma_f32_16x16x32_bf16 v[8:11], v[190:193], v[214:217], v[8:11]
	v_mfma_f32_16x16x32_bf16 v[4:7], v[182:185], v[222:225], v[4:7]
	v_mfma_f32_16x16x32_bf16 v[0:3], v[190:193], v[222:225], v[0:3]
	s_setprio 0
	s_barrier
	s_cmp_gt_u32 s75, 13
	s_cbranch_scc0 .LBB0_582
	s_and_b64 vcc, exec, s[26:27]
	s_cbranch_vccz .LBB0_585
	s_barrier

; #define PG8_STAGE(bufoff, gbase, voff, p64) do { _Pragma("unroll") for (int _i = 0; _i < 2; ++_i) { \
;         const char* _gb = (const char*)(gbase) + (size_t)_i * (p64); const unsigned _la = ldsbase + (unsigned)(bufoff) + (unsigned)_i * 8192u; \
;         asm volatile("s_mov_b32 m0, %0\n\ts_nop 0\n\tglobal_load_lds_dwordx4 %1, %2" :: "s"(_la), "v"(voff), "s"(_gb) : "memory"); } } while (0)
; #define PG8_LDA(dst, b, h) do { _Pragma("unroll") for (int m = 0; m < 4; ++m) _Pragma("unroll") for (int k = 0; k < 2; ++k) dst[m][k] = *(const LAS bf16x8*)(lds + PG8_SA(b, h) + aoff + m * 2048 + k * 1024); } while (0)
; #define PG8_LDB(dst, b, h) do { _Pragma("unroll") for (int n = 0; n < 2; ++n) _Pragma("unroll") for (int k = 0; k < 2; ++k) dst[n][k] = *(const LAS bf16x8*)(lds + PG8_SB(b, h) + boff + n * 2048 + k * 1024); } while (0)
; #define PG8_MMA(ai, bj, At, Bt) do { __builtin_amdgcn_s_setprio(1); _Pragma("unroll") for (int m = 0; m < 4; ++m) _Pragma("unroll") for (int n = 0; n < 2; ++n) _Pragma("unroll") for (int k = 0; k < 2; ++k) \
;         acc[ai][bj][m][n] = __builtin_amdgcn_mfma_f32_16x16x32_bf16(Bt[n][k], At[m][k], acc[ai][bj][m][n], 0, 0, 0); __builtin_amdgcn_s_setprio(0); } while (0)
; #define PG8_WAIT_V(n) asm volatile("s_waitcnt vmcnt(" #n ")" ::: "memory")
; #define PG8_BAR __builtin_amdgcn_s_barrier()
; template <class Epi, class Sched>
; __device__ __forceinline__ void gemm_phase(LAS unsigned char* lds, const Sched& S, const Epi& E) {
;     ...
;             const bool last = (t == nt - 2);
;             const char* a1 = cA + (size_t)(t + 1) * kstep;
;             const char* a2 = last ? nA : cA + (size_t)(t + 2) * kstep; const char* b2 = last ? nB : cB + (size_t)(t + 2) * kstep;
;             const char* a3 = a2 + kstep; const char* b3 = b2 + kstep;
;             const unsigned vA2 = voffA, vB2 = voffB, hA2 = hA, hB2 = hB;
;             PG8_LDB(B0, 0, 0); PG8_LDB(B1, 0, 1); PG8_SCHED; PG8_LDA(At, 0, 0); PG8_STAGE(PG8_SA(1, 1), a1 + hA, voffA, hA / 2);
;             PG8_WAIT_V(8); PG8_WAIT_L(0); PG8_BAR; PG8_MMA(0, 0, At, B0); PG8_MMA(0, 1, At, B1); PG8_BAR; PG8_SCHED;
;             PG8_LDA(At, 0, 1); PG8_STAGE(PG8_SB(0, 0), b2, vB2, hB2 / 2); PG8_STAGE(PG8_SB(0, 1), b2 + hB2, vB2, hB2 / 2); PG8_STAGE(PG8_SA(0, 0), a2, vA2, hA2 / 2);
;             PG8_WAIT_V(8); PG8_WAIT_L(0); PG8_BAR; PG8_MMA(1, 0, At, B0); PG8_MMA(1, 1, At, B1); PG8_BAR; PG8_SCHED;
.LBB0_660:
	v_add_u32_e32 v130, 0x10000, v143
	ds_read_b128 v[146:149], v130
	ds_read_b128 v[150:153], v130 offset:1024
	ds_read_b128 v[172:175], v130 offset:2048
	ds_read_b128 v[178:181], v130 offset:3072
	v_add_u32_e32 v130, 0x14000, v143
	ds_read_b128 v[182:185], v130
	ds_read_b128 v[186:189], v130 offset:1024
	ds_read_b128 v[190:193], v130 offset:2048
	ds_read_b128 v[194:197], v130 offset:3072
	s_add_u32 s16, s58, 0x100
	s_addc_u32 s17, s59, 0
	s_cmp_eq_u32 s80, 4
	s_cselect_b32 s22, s40, s16
	s_cselect_b32 s23, s41, s17
	s_cselect_b32 s72, s54, s78
	s_cselect_b32 s73, s55, s79
	s_add_u32 s62, s22, 0x80
	s_addc_u32 s63, s23, 0
	ds_read_b128 v[198:201], v144
	ds_read_b128 v[202:205], v144 offset:1024
	ds_read_b128 v[206:209], v144 offset:2048
	ds_read_b128 v[210:213], v144 offset:3072
	ds_read_b128 v[214:217], v144 offset:4096
	ds_read_b128 v[218:221], v144 offset:5120
	ds_read_b128 v[222:225], v144 offset:6144
	ds_read_b128 v[226:229], v144 offset:7168
	s_add_u32 s82, s58, 0x20080
	s_mov_b32 m0, s66
	s_addc_u32 s83, s59, 0
	global_load_lds_dwordx4 v128, s[82:83]
	s_add_u32 s58, s58, 0x30080
	s_mov_b32 m0, s67
	s_addc_u32 s59, s59, 0
	global_load_lds_dwordx4 v128, s[58:59]
	s_waitcnt vmcnt(8) lgkmcnt(0)
	s_barrier
	s_setprio 1
	v_mfma_f32_16x16x32_bf16 v[124:127], v[146:149], v[198:201], v[124:127]
	v_mfma_f32_16x16x32_bf16 v[120:123], v[172:175], v[198:201], v[120:123]
	v_mfma_f32_16x16x32_bf16 v[116:119], v[146:149], v[206:209], v[116:119]
	v_mfma_f32_16x16x32_bf16 v[108:111], v[172:175], v[206:209], v[108:111]
	v_mfma_f32_16x16x32_bf16 v[100:103], v[146:149], v[214:217], v[100:103]
	v_mfma_f32_16x16x32_bf16 v[92:95], v[172:175], v[214:217], v[92:95]
	v_mfma_f32_16x16x32_bf16 v[84:87], v[146:149], v[222:225], v[84:87]
	v_mfma_f32_16x16x32_bf16 v[76:79], v[172:175], v[222:225], v[76:79]
	v_mfma_f32_16x16x32_bf16 v[124:127], v[150:153], v[202:205], v[124:127]
	v_mfma_f32_16x16x32_bf16 v[120:123], v[178:181], v[202:205], v[120:123]
	v_mfma_f32_16x16x32_bf16 v[116:119], v[150:153], v[210:213], v[116:119]
	v_mfma_f32_16x16x32_bf16 v[108:111], v[178:181], v[210:213], v[108:111]
	v_mfma_f32_16x16x32_bf16 v[100:103], v[150:153], v[218:221], v[100:103]
	v_mfma_f32_16x16x32_bf16 v[92:95], v[178:181], v[218:221], v[92:95]
	v_mfma_f32_16x16x32_bf16 v[84:87], v[150:153], v[226:229], v[84:87]
	v_mfma_f32_16x16x32_bf16 v[76:79], v[178:181], v[226:229], v[76:79]
	s_add_i32 s80, s80, 2
	s_add_u32 s78, s78, 0x100
	s_addc_u32 s79, s79, 0
	v_mfma_f32_16x16x32_bf16 v[112:115], v[182:185], v[198:201], v[112:115]
	v_mfma_f32_16x16x32_bf16 v[104:107], v[190:193], v[198:201], v[104:107]
	v_mfma_f32_16x16x32_bf16 v[96:99], v[182:185], v[206:209], v[96:99]
	v_mfma_f32_16x16x32_bf16 v[88:91], v[190:193], v[206:209], v[88:91]
	v_mfma_f32_16x16x32_bf16 v[80:83], v[182:185], v[214:217], v[80:83]
	v_mfma_f32_16x16x32_bf16 v[72:75], v[190:193], v[214:217], v[72:75]
	v_mfma_f32_16x16x32_bf16 v[68:71], v[182:185], v[222:225], v[68:71]
	v_mfma_f32_16x16x32_bf16 v[64:67], v[190:193], v[222:225], v[64:67]
	v_mfma_f32_16x16x32_bf16 v[112:115], v[186:189], v[202:205], v[112:115]
	v_mfma_f32_16x16x32_bf16 v[104:107], v[194:197], v[202:205], v[104:107]
	v_mfma_f32_16x16x32_bf16 v[96:99], v[186:189], v[210:213], v[96:99]
	v_mfma_f32_16x16x32_bf16 v[88:91], v[194:197], v[210:213], v[88:91]
	v_mfma_f32_16x16x32_bf16 v[80:83], v[186:189], v[218:221], v[80:83]
	v_mfma_f32_16x16x32_bf16 v[72:75], v[194:197], v[218:221], v[72:75]
	v_mfma_f32_16x16x32_bf16 v[68:71], v[186:189], v[226:229], v[68:71]
	v_mfma_f32_16x16x32_bf16 v[64:67], v[194:197], v[226:229], v[64:67]
	s_setprio 0
	s_barrier
	s_add_u32 s58, s72, 0x10000
	ds_read_b128 v[198:201], v144 offset:16384
	ds_read_b128 v[202:205], v144 offset:17408
	ds_read_b128 v[206:209], v144 offset:18432
	ds_read_b128 v[210:213], v144 offset:19456
	ds_read_b128 v[214:217], v144 offset:20480
	ds_read_b128 v[218:221], v144 offset:21504
	ds_read_b128 v[222:225], v144 offset:22528
	ds_read_b128 v[226:229], v144 offset:23552
	s_mov_b32 m0, s33
	s_nop 0
	global_load_lds_dwordx4 v140, s[72:73]
	s_mov_b32 m0, s34
	s_addc_u32 s59, s73, 0
	global_load_lds_dwordx4 v140, s[58:59]
	s_add_u32 s58, s72, 0x20000
	s_mov_b32 m0, s35
	s_addc_u32 s59, s73, 0
	global_load_lds_dwordx4 v140, s[58:59]
	s_add_u32 s58, s72, 0x30000
	s_mov_b32 m0, s36
	s_addc_u32 s59, s73, 0
	global_load_lds_dwordx4 v140, s[58:59]
	s_mov_b32 m0, s24
	s_nop 0
	global_load_lds_dwordx4 v128, s[22:23]
	s_add_u32 s58, s22, 0x10000
	s_mov_b32 m0, s37
	s_addc_u32 s59, s23, 0
	global_load_lds_dwordx4 v128, s[58:59]
	s_waitcnt vmcnt(8) lgkmcnt(0)
	s_barrier
; #define PG8_STAGE(bufoff, gbase, voff, p64) do { _Pragma("unroll") for (int _i = 0; _i < 2; ++_i) { \
;         const char* _gb = (const char*)(gbase) + (size_t)_i * (p64); const unsigned _la = ldsbase + (unsigned)(bufoff) + (unsigned)_i * 8192u; \
;         asm volatile("s_mov_b32 m0, %0\n\ts_nop 0\n\tglobal_load_lds_dwordx4 %1, %2" :: "s"(_la), "v"(voff), "s"(_gb) : "memory"); } } while (0)
; #define PG8_LDA(dst, b, h) do { _Pragma("unroll") for (int m = 0; m < 4; ++m) _Pragma("unroll") for (int k = 0; k < 2; ++k) dst[m][k] = *(const LAS bf16x8*)(lds + PG8_SA(b, h) + aoff + m * 2048 + k * 1024); } while (0)
; #define PG8_LDB(dst, b, h) do { _Pragma("unroll") for (int n = 0; n < 2; ++n) _Pragma("unroll") for (int k = 0; k < 2; ++k) dst[n][k] = *(const LAS bf16x8*)(lds + PG8_SB(b, h) + boff + n * 2048 + k * 1024); } while (0)
; #define PG8_MMA(ai, bj, At, Bt) do { __builtin_amdgcn_s_setprio(1); _Pragma("unroll") for (int m = 0; m < 4; ++m) _Pragma("unroll") for (int n = 0; n < 2; ++n) _Pragma("unroll") for (int k = 0; k < 2; ++k) \
;         acc[ai][bj][m][n] = __builtin_amdgcn_mfma_f32_16x16x32_bf16(Bt[n][k], At[m][k], acc[ai][bj][m][n], 0, 0, 0); __builtin_amdgcn_s_setprio(0); } while (0)
; #define PG8_WAIT_V(n) asm volatile("s_waitcnt vmcnt(" #n ")" ::: "memory")
; #define PG8_WAIT_L(n) asm volatile("s_waitcnt lgkmcnt(" #n ")" ::: "memory")
; #define PG8_BAR __builtin_amdgcn_s_barrier()
; #define PG8_SCHED __builtin_amdgcn_sched_barrier(0)
; template <class Epi, class Sched>
; __device__ __forceinline__ void gemm_phase(LAS unsigned char* lds, const Sched& S, const Epi& E) {
;     ...
;             PG8_WAIT_V(8); PG8_WAIT_L(0); PG8_BAR; PG8_MMA(1, 0, At, B0); PG8_MMA(1, 1, At, B1); PG8_BAR; PG8_SCHED;
;             PG8_LDB(B0, 1, 0); PG8_LDB(B1, 1, 1); PG8_SCHED; PG8_LDA(At, 1, 0); PG8_STAGE(PG8_SA(0, 1), a2 + hA2, vA2, hA2 / 2);
;             PG8_WAIT_V(8); PG8_WAIT_L(0); PG8_BAR; PG8_MMA(0, 0, At, B0); PG8_MMA(0, 1, At, B1); PG8_BAR; PG8_SCHED;
	s_setprio 1
	v_mfma_f32_16x16x32_bf16 v[60:63], v[146:149], v[198:201], v[60:63]
	v_mfma_f32_16x16x32_bf16 v[56:59], v[172:175], v[198:201], v[56:59]
	v_mfma_f32_16x16x32_bf16 v[52:55], v[146:149], v[206:209], v[52:55]
	v_mfma_f32_16x16x32_bf16 v[44:47], v[172:175], v[206:209], v[44:47]
	v_mfma_f32_16x16x32_bf16 v[36:39], v[146:149], v[214:217], v[36:39]
	v_mfma_f32_16x16x32_bf16 v[28:31], v[172:175], v[214:217], v[28:31]
	v_mfma_f32_16x16x32_bf16 v[20:23], v[146:149], v[222:225], v[20:23]
	v_mfma_f32_16x16x32_bf16 v[12:15], v[172:175], v[222:225], v[12:15]
	v_mfma_f32_16x16x32_bf16 v[60:63], v[150:153], v[202:205], v[60:63]
	v_mfma_f32_16x16x32_bf16 v[56:59], v[178:181], v[202:205], v[56:59]
	v_mfma_f32_16x16x32_bf16 v[52:55], v[150:153], v[210:213], v[52:55]
	v_mfma_f32_16x16x32_bf16 v[44:47], v[178:181], v[210:213], v[44:47]
	v_mfma_f32_16x16x32_bf16 v[36:39], v[150:153], v[218:221], v[36:39]
	v_mfma_f32_16x16x32_bf16 v[28:31], v[178:181], v[218:221], v[28:31]
	v_mfma_f32_16x16x32_bf16 v[20:23], v[150:153], v[226:229], v[20:23]
	v_mfma_f32_16x16x32_bf16 v[12:15], v[178:181], v[226:229], v[12:15]
	v_mfma_f32_16x16x32_bf16 v[48:51], v[182:185], v[198:201], v[48:51]
	v_mfma_f32_16x16x32_bf16 v[40:43], v[190:193], v[198:201], v[40:43]
	v_mfma_f32_16x16x32_bf16 v[32:35], v[182:185], v[206:209], v[32:35]
	v_mfma_f32_16x16x32_bf16 v[24:27], v[190:193], v[206:209], v[24:27]
	v_mfma_f32_16x16x32_bf16 v[16:19], v[182:185], v[214:217], v[16:19]
	v_mfma_f32_16x16x32_bf16 v[8:11], v[190:193], v[214:217], v[8:11]
	v_mfma_f32_16x16x32_bf16 v[4:7], v[182:185], v[222:225], v[4:7]
	v_mfma_f32_16x16x32_bf16 v[0:3], v[190:193], v[222:225], v[0:3]
	v_mfma_f32_16x16x32_bf16 v[48:51], v[186:189], v[202:205], v[48:51]
	v_mfma_f32_16x16x32_bf16 v[40:43], v[194:197], v[202:205], v[40:43]
	v_mfma_f32_16x16x32_bf16 v[32:35], v[186:189], v[210:213], v[32:35]
	v_mfma_f32_16x16x32_bf16 v[24:27], v[194:197], v[210:213], v[24:27]
	v_mfma_f32_16x16x32_bf16 v[16:19], v[186:189], v[218:221], v[16:19]
	v_mfma_f32_16x16x32_bf16 v[8:11], v[194:197], v[218:221], v[8:11]
	v_mfma_f32_16x16x32_bf16 v[4:7], v[186:189], v[226:229], v[4:7]
	v_mfma_f32_16x16x32_bf16 v[0:3], v[194:197], v[226:229], v[0:3]
	s_setprio 0
	s_barrier
	v_add_u32_e32 v130, 0x18000, v143
	ds_read_b128 v[146:149], v130
	ds_read_b128 v[150:153], v130 offset:1024
	ds_read_b128 v[172:175], v130 offset:2048
	ds_read_b128 v[178:181], v130 offset:3072
	v_add_u32_e32 v130, 0x1c000, v143
	ds_read_b128 v[182:185], v130
	ds_read_b128 v[186:189], v130 offset:1024
	ds_read_b128 v[190:193], v130 offset:2048
	ds_read_b128 v[194:197], v130 offset:3072
	ds_read_b128 v[198:201], v144 offset:32768
	ds_read_b128 v[202:205], v144 offset:33792
	ds_read_b128 v[206:209], v144 offset:34816
	ds_read_b128 v[210:213], v144 offset:35840
	ds_read_b128 v[214:217], v144 offset:36864
	ds_read_b128 v[218:221], v144 offset:37888
	ds_read_b128 v[222:225], v144 offset:38912
	ds_read_b128 v[226:229], v144 offset:39936
	s_add_u32 s58, s22, 0x20000
	s_mov_b32 m0, s42
	s_addc_u32 s59, s23, 0
	global_load_lds_dwordx4 v128, s[58:59]
	s_add_u32 s58, s22, 0x30000
	s_mov_b32 m0, s44
	s_addc_u32 s59, s23, 0
	global_load_lds_dwordx4 v128, s[58:59]
	s_waitcnt vmcnt(8) lgkmcnt(0)
	s_barrier
	s_setprio 1
	v_mfma_f32_16x16x32_bf16 v[124:127], v[146:149], v[198:201], v[124:127]
	v_mfma_f32_16x16x32_bf16 v[120:123], v[172:175], v[198:201], v[120:123]
	v_mfma_f32_16x16x32_bf16 v[116:119], v[146:149], v[206:209], v[116:119]
	v_mfma_f32_16x16x32_bf16 v[108:111], v[172:175], v[206:209], v[108:111]
	v_mfma_f32_16x16x32_bf16 v[100:103], v[146:149], v[214:217], v[100:103]
	v_mfma_f32_16x16x32_bf16 v[92:95], v[172:175], v[214:217], v[92:95]
	v_mfma_f32_16x16x32_bf16 v[84:87], v[146:149], v[222:225], v[84:87]
	v_mfma_f32_16x16x32_bf16 v[76:79], v[172:175], v[222:225], v[76:79]
	v_mfma_f32_16x16x32_bf16 v[124:127], v[150:153], v[202:205], v[124:127]
	v_mfma_f32_16x16x32_bf16 v[120:123], v[178:181], v[202:205], v[120:123]
	v_mfma_f32_16x16x32_bf16 v[116:119], v[150:153], v[210:213], v[116:119]
	v_mfma_f32_16x16x32_bf16 v[108:111], v[178:181], v[210:213], v[108:111]
	v_mfma_f32_16x16x32_bf16 v[100:103], v[150:153], v[218:221], v[100:103]
	v_mfma_f32_16x16x32_bf16 v[92:95], v[178:181], v[218:221], v[92:95]
	v_mfma_f32_16x16x32_bf16 v[84:87], v[150:153], v[226:229], v[84:87]
	v_mfma_f32_16x16x32_bf16 v[76:79], v[178:181], v[226:229], v[76:79]
	v_mfma_f32_16x16x32_bf16 v[112:115], v[182:185], v[198:201], v[112:115]
	v_mfma_f32_16x16x32_bf16 v[104:107], v[190:193], v[198:201], v[104:107]
	v_mfma_f32_16x16x32_bf16 v[96:99], v[182:185], v[206:209], v[96:99]
	v_mfma_f32_16x16x32_bf16 v[88:91], v[190:193], v[206:209], v[88:91]
	v_mfma_f32_16x16x32_bf16 v[80:83], v[182:185], v[214:217], v[80:83]
	v_mfma_f32_16x16x32_bf16 v[72:75], v[190:193], v[214:217], v[72:75]
	v_mfma_f32_16x16x32_bf16 v[68:71], v[182:185], v[222:225], v[68:71]
	v_mfma_f32_16x16x32_bf16 v[64:67], v[190:193], v[222:225], v[64:67]
	v_mfma_f32_16x16x32_bf16 v[112:115], v[186:189], v[202:205], v[112:115]
	v_mfma_f32_16x16x32_bf16 v[104:107], v[194:197], v[202:205], v[104:107]
	v_mfma_f32_16x16x32_bf16 v[96:99], v[186:189], v[210:213], v[96:99]
	v_mfma_f32_16x16x32_bf16 v[88:91], v[194:197], v[210:213], v[88:91]
	v_mfma_f32_16x16x32_bf16 v[80:83], v[186:189], v[218:221], v[80:83]
	v_mfma_f32_16x16x32_bf16 v[72:75], v[194:197], v[218:221], v[72:75]
	v_mfma_f32_16x16x32_bf16 v[68:71], v[186:189], v[226:229], v[68:71]
	v_mfma_f32_16x16x32_bf16 v[64:67], v[194:197], v[226:229], v[64:67]
	s_setprio 0
	s_barrier
; #define PG8_STAGE(bufoff, gbase, voff, p64) do { _Pragma("unroll") for (int _i = 0; _i < 2; ++_i) { \
;         const char* _gb = (const char*)(gbase) + (size_t)_i * (p64); const unsigned _la = ldsbase + (unsigned)(bufoff) + (unsigned)_i * 8192u; \
;         asm volatile("s_mov_b32 m0, %0\n\ts_nop 0\n\tglobal_load_lds_dwordx4 %1, %2" :: "s"(_la), "v"(voff), "s"(_gb) : "memory"); } } while (0)
; #define PG8_LDA(dst, b, h) do { _Pragma("unroll") for (int m = 0; m < 4; ++m) _Pragma("unroll") for (int k = 0; k < 2; ++k) dst[m][k] = *(const LAS bf16x8*)(lds + PG8_SA(b, h) + aoff + m * 2048 + k * 1024); } while (0)
; #define PG8_MMA(ai, bj, At, Bt) do { __builtin_amdgcn_s_setprio(1); _Pragma("unroll") for (int m = 0; m < 4; ++m) _Pragma("unroll") for (int n = 0; n < 2; ++n) _Pragma("unroll") for (int k = 0; k < 2; ++k) \
;         acc[ai][bj][m][n] = __builtin_amdgcn_mfma_f32_16x16x32_bf16(Bt[n][k], At[m][k], acc[ai][bj][m][n], 0, 0, 0); __builtin_amdgcn_s_setprio(0); } while (0)
; #define PG8_WAIT_V(n) asm volatile("s_waitcnt vmcnt(" #n ")" ::: "memory")
; #define PG8_WAIT_L(n) asm volatile("s_waitcnt lgkmcnt(" #n ")" ::: "memory")
; #define PG8_BAR __builtin_amdgcn_s_barrier()
; #define PG8_SCHED __builtin_amdgcn_sched_barrier(0)
; template <class Epi, class Sched>
; __device__ __forceinline__ void gemm_phase(LAS unsigned char* lds, const Sched& S, const Epi& E) {
;     ...
;             PG8_LDA(At, 1, 1); PG8_STAGE(PG8_SB(1, 0), b3, vB2, hB2 / 2); PG8_STAGE(PG8_SB(1, 1), b3 + hB2, vB2, hB2 / 2); PG8_STAGE(PG8_SA(1, 0), a3, vA2, hA2 / 2);
;             PG8_WAIT_V(8); PG8_WAIT_L(0); PG8_BAR; PG8_MMA(1, 0, At, B0); PG8_MMA(1, 1, At, B1); PG8_BAR; PG8_SCHED;
;         }
;         if (wr == 0) PG8_BAR;
	s_add_u32 s58, s72, 0x80
	s_addc_u32 s59, s73, 0
	ds_read_b128 v[198:201], v144 offset:49152
	ds_read_b128 v[202:205], v144 offset:50176
	ds_read_b128 v[206:209], v144 offset:51200
	ds_read_b128 v[210:213], v144 offset:52224
	ds_read_b128 v[214:217], v144 offset:53248
	ds_read_b128 v[218:221], v144 offset:54272
	ds_read_b128 v[222:225], v144 offset:55296
	ds_read_b128 v[226:229], v144 offset:56320
	s_mov_b32 m0, s48
	s_nop 0
	global_load_lds_dwordx4 v140, s[58:59]
	s_add_u32 s58, s72, 0x10080
	s_mov_b32 m0, s50
	s_addc_u32 s59, s73, 0
	global_load_lds_dwordx4 v140, s[58:59]
	s_add_u32 s58, s72, 0x20080
	s_mov_b32 m0, s64
	s_addc_u32 s59, s73, 0
	global_load_lds_dwordx4 v140, s[58:59]
	s_add_u32 s58, s72, 0x30080
	s_mov_b32 m0, s65
	s_addc_u32 s59, s73, 0
	global_load_lds_dwordx4 v140, s[58:59]
	s_mov_b32 m0, s51
	s_nop 0
	global_load_lds_dwordx4 v128, s[62:63]
	s_add_u32 s22, s22, 0x10080
	s_mov_b32 m0, s61
	s_addc_u32 s23, s23, 0
	global_load_lds_dwordx4 v128, s[22:23]
	s_waitcnt vmcnt(8) lgkmcnt(0)
	s_barrier
	s_setprio 1
	v_mfma_f32_16x16x32_bf16 v[60:63], v[146:149], v[198:201], v[60:63]
	v_mfma_f32_16x16x32_bf16 v[56:59], v[172:175], v[198:201], v[56:59]
	v_mfma_f32_16x16x32_bf16 v[52:55], v[146:149], v[206:209], v[52:55]
	v_mfma_f32_16x16x32_bf16 v[44:47], v[172:175], v[206:209], v[44:47]
	v_mfma_f32_16x16x32_bf16 v[36:39], v[146:149], v[214:217], v[36:39]
	v_mfma_f32_16x16x32_bf16 v[28:31], v[172:175], v[214:217], v[28:31]
	v_mfma_f32_16x16x32_bf16 v[20:23], v[146:149], v[222:225], v[20:23]
	v_mfma_f32_16x16x32_bf16 v[12:15], v[172:175], v[222:225], v[12:15]
	v_mfma_f32_16x16x32_bf16 v[60:63], v[150:153], v[202:205], v[60:63]
	v_mfma_f32_16x16x32_bf16 v[56:59], v[178:181], v[202:205], v[56:59]
	v_mfma_f32_16x16x32_bf16 v[52:55], v[150:153], v[210:213], v[52:55]
	v_mfma_f32_16x16x32_bf16 v[44:47], v[178:181], v[210:213], v[44:47]
	v_mfma_f32_16x16x32_bf16 v[36:39], v[150:153], v[218:221], v[36:39]
	v_mfma_f32_16x16x32_bf16 v[28:31], v[178:181], v[218:221], v[28:31]
	v_mfma_f32_16x16x32_bf16 v[20:23], v[150:153], v[226:229], v[20:23]
	v_mfma_f32_16x16x32_bf16 v[12:15], v[178:181], v[226:229], v[12:15]
	v_mfma_f32_16x16x32_bf16 v[48:51], v[182:185], v[198:201], v[48:51]
	v_mfma_f32_16x16x32_bf16 v[40:43], v[190:193], v[198:201], v[40:43]
	v_mfma_f32_16x16x32_bf16 v[32:35], v[182:185], v[206:209], v[32:35]
	v_mfma_f32_16x16x32_bf16 v[24:27], v[190:193], v[206:209], v[24:27]
	v_mfma_f32_16x16x32_bf16 v[16:19], v[182:185], v[214:217], v[16:19]
	v_mfma_f32_16x16x32_bf16 v[8:11], v[190:193], v[214:217], v[8:11]
	v_mfma_f32_16x16x32_bf16 v[4:7], v[182:185], v[222:225], v[4:7]
	v_mfma_f32_16x16x32_bf16 v[0:3], v[190:193], v[222:225], v[0:3]
	v_mfma_f32_16x16x32_bf16 v[48:51], v[186:189], v[202:205], v[48:51]
	v_mfma_f32_16x16x32_bf16 v[40:43], v[194:197], v[202:205], v[40:43]
	v_mfma_f32_16x16x32_bf16 v[32:35], v[186:189], v[210:213], v[32:35]
	v_mfma_f32_16x16x32_bf16 v[24:27], v[194:197], v[210:213], v[24:27]
	v_mfma_f32_16x16x32_bf16 v[16:19], v[186:189], v[218:221], v[16:19]
	v_mfma_f32_16x16x32_bf16 v[8:11], v[194:197], v[218:221], v[8:11]
	v_mfma_f32_16x16x32_bf16 v[4:7], v[186:189], v[226:229], v[4:7]
	v_mfma_f32_16x16x32_bf16 v[0:3], v[194:197], v[226:229], v[0:3]
	s_setprio 0
	s_barrier
	s_cmp_gt_u32 s80, 5
	s_mov_b64 s[58:59], s[16:17]
	s_cbranch_scc0 .LBB0_660
	s_and_b64 vcc, exec, s[38:39]
	s_cbranch_vccz .LBB0_663
	s_barrier

; #define PG8_STAGE(bufoff, gbase, voff, p64) do { _Pragma("unroll") for (int _i = 0; _i < 2; ++_i) { \
;         const char* _gb = (const char*)(gbase) + (size_t)_i * (p64); const unsigned _la = ldsbase + (unsigned)(bufoff) + (unsigned)_i * 8192u; \
;         asm volatile("s_mov_b32 m0, %0\n\ts_nop 0\n\tglobal_load_lds_dwordx4 %1, %2" :: "s"(_la), "v"(voff), "s"(_gb) : "memory"); } } while (0)
; #define PG8_LDA(dst, b, h) do { _Pragma("unroll") for (int m = 0; m < 4; ++m) _Pragma("unroll") for (int k = 0; k < 2; ++k) dst[m][k] = *(const LAS bf16x8*)(lds + PG8_SA(b, h) + aoff + m * 2048 + k * 1024); } while (0)
; #define PG8_LDB(dst, b, h) do { _Pragma("unroll") for (int n = 0; n < 2; ++n) _Pragma("unroll") for (int k = 0; k < 2; ++k) dst[n][k] = *(const LAS bf16x8*)(lds + PG8_SB(b, h) + boff + n * 2048 + k * 1024); } while (0)
; #define PG8_MMA(ai, bj, At, Bt) do { __builtin_amdgcn_s_setprio(1); _Pragma("unroll") for (int m = 0; m < 4; ++m) _Pragma("unroll") for (int n = 0; n < 2; ++n) _Pragma("unroll") for (int k = 0; k < 2; ++k) \
;         acc[ai][bj][m][n] = __builtin_amdgcn_mfma_f32_16x16x32_bf16(Bt[n][k], At[m][k], acc[ai][bj][m][n], 0, 0, 0); __builtin_amdgcn_s_setprio(0); } while (0)
; #define PG8_WAIT_V(n) asm volatile("s_waitcnt vmcnt(" #n ")" ::: "memory")
; template <class Epi, class Sched>
; __device__ __forceinline__ void gemm_phase(LAS unsigned char* lds, const Sched& S, const Epi& E) {
;     ...
;         for (int t = 0; t < nt; t += 2) {
;             const bool last = (t == nt - 2);
;             const char* a1 = cA + (size_t)(t + 1) * kstep;
;             const char* a2 = last ? nA : cA + (size_t)(t + 2) * kstep; const char* b2 = last ? nB : cB + (size_t)(t + 2) * kstep;
;             const char* a3 = a2 + kstep; const char* b3 = b2 + kstep;
;             const unsigned vA2 = voffA, vB2 = voffB, hA2 = hA, hB2 = hB;
;             PG8_LDB(B0, 0, 0); PG8_LDB(B1, 0, 1); PG8_SCHED; PG8_LDA(At, 0, 0); PG8_STAGE(PG8_SA(1, 1), a1 + hA, voffA, hA / 2);
;             PG8_WAIT_V(8); PG8_WAIT_L(0); PG8_BAR; PG8_MMA(0, 0, At, B0); PG8_MMA(0, 1, At, B1); PG8_BAR; PG8_SCHED;
;             PG8_LDA(At, 0, 1); PG8_STAGE(PG8_SB(0, 0), b2, vB2, hB2 / 2); PG8_STAGE(PG8_SB(0, 1), b2 + hB2, vB2, hB2 / 2); PG8_STAGE(PG8_SA(0, 0), a2, vA2, hA2 / 2);
;             PG8_WAIT_V(8); PG8_WAIT_L(0); PG8_BAR; PG8_MMA(1, 0, At, B0); PG8_MMA(1, 1, At, B1); PG8_BAR; PG8_SCHED;
.LBB0_679:
	v_add_u32_e32 v130, 0x10000, v141
	v_add_u32_e32 v131, 0x14000, v141
	ds_read_b128 v[0:3], v130
	ds_read_b128 v[4:7], v130 offset:1024
	ds_read_b128 v[8:11], v130 offset:2048
	ds_read_b128 v[12:15], v130 offset:3072
	ds_read_b128 v[16:19], v131
	ds_read_b128 v[20:23], v131 offset:1024
	ds_read_b128 v[24:27], v131 offset:2048
	ds_read_b128 v[28:31], v131 offset:3072
	s_add_u32 s22, s56, 0x100
	s_addc_u32 s23, s57, 0
	s_add_u32 s76, s58, 0x100
	s_addc_u32 s77, s59, 0
	s_add_u32 s16, s56, 0x180
	s_addc_u32 s17, s57, 0
	ds_read_b128 v[32:35], v142
	ds_read_b128 v[36:39], v142 offset:1024
	ds_read_b128 v[40:43], v142 offset:2048
	ds_read_b128 v[44:47], v142 offset:3072
	ds_read_b128 v[48:51], v142 offset:4096
	ds_read_b128 v[52:55], v142 offset:5120
	ds_read_b128 v[56:59], v142 offset:6144
	ds_read_b128 v[60:63], v142 offset:7168
	s_add_u32 s78, s56, 0x10080
	s_mov_b32 m0, s66
	s_addc_u32 s79, s57, 0
	global_load_lds_dwordx4 v128, s[78:79]
	s_add_u32 s78, s56, 0x18080
	s_mov_b32 m0, s67
	s_addc_u32 s79, s57, 0
	global_load_lds_dwordx4 v128, s[78:79]
	s_waitcnt vmcnt(8) lgkmcnt(0)
	s_barrier
	s_setprio 1
	v_mfma_f32_16x16x32_bf16 v[64:67], v[0:3], v[32:35], 0
	v_mfma_f32_16x16x32_bf16 v[68:71], v[8:11], v[32:35], 0
	v_mfma_f32_16x16x32_bf16 v[72:75], v[0:3], v[40:43], 0
	v_mfma_f32_16x16x32_bf16 v[76:79], v[8:11], v[40:43], 0
	v_mfma_f32_16x16x32_bf16 v[80:83], v[0:3], v[48:51], 0
	v_mfma_f32_16x16x32_bf16 v[84:87], v[8:11], v[48:51], 0
	v_mfma_f32_16x16x32_bf16 v[88:91], v[0:3], v[56:59], 0
	v_mfma_f32_16x16x32_bf16 v[92:95], v[8:11], v[56:59], 0
	v_mfma_f32_16x16x32_bf16 v[64:67], v[4:7], v[36:39], v[64:67]
	v_mfma_f32_16x16x32_bf16 v[68:71], v[12:15], v[36:39], v[68:71]
	v_mfma_f32_16x16x32_bf16 v[72:75], v[4:7], v[44:47], v[72:75]
	v_mfma_f32_16x16x32_bf16 v[76:79], v[12:15], v[44:47], v[76:79]
	v_mfma_f32_16x16x32_bf16 v[80:83], v[4:7], v[52:55], v[80:83]
	v_mfma_f32_16x16x32_bf16 v[84:87], v[12:15], v[52:55], v[84:87]
	v_mfma_f32_16x16x32_bf16 v[88:91], v[4:7], v[60:63], v[88:91]
	v_mfma_f32_16x16x32_bf16 v[92:95], v[12:15], v[60:63], v[92:95]
	v_mfma_f32_16x16x32_bf16 v[96:99], v[16:19], v[32:35], 0
	v_mfma_f32_16x16x32_bf16 v[32:35], v[24:27], v[32:35], 0
	v_mfma_f32_16x16x32_bf16 v[96:99], v[20:23], v[36:39], v[96:99]
	v_mfma_f32_16x16x32_bf16 v[32:35], v[28:31], v[36:39], v[32:35]
	v_mfma_f32_16x16x32_bf16 v[36:39], v[16:19], v[40:43], 0
	v_mfma_f32_16x16x32_bf16 v[40:43], v[24:27], v[40:43], 0
	v_mfma_f32_16x16x32_bf16 v[36:39], v[20:23], v[44:47], v[36:39]
	v_mfma_f32_16x16x32_bf16 v[40:43], v[28:31], v[44:47], v[40:43]
	v_mfma_f32_16x16x32_bf16 v[44:47], v[16:19], v[48:51], 0
	v_mfma_f32_16x16x32_bf16 v[48:51], v[24:27], v[48:51], 0
	v_mfma_f32_16x16x32_bf16 v[44:47], v[20:23], v[52:55], v[44:47]
	v_mfma_f32_16x16x32_bf16 v[48:51], v[28:31], v[52:55], v[48:51]
	v_mfma_f32_16x16x32_bf16 v[52:55], v[16:19], v[56:59], 0
	v_mfma_f32_16x16x32_bf16 v[56:59], v[24:27], v[56:59], 0
	v_mfma_f32_16x16x32_bf16 v[52:55], v[20:23], v[60:63], v[52:55]
	v_mfma_f32_16x16x32_bf16 v[56:59], v[28:31], v[60:63], v[56:59]
	s_setprio 0
	s_barrier
	ds_read_b128 v[60:63], v142 offset:16384
	ds_read_b128 v[100:103], v142 offset:17408
	ds_read_b128 v[104:107], v142 offset:18432
	ds_read_b128 v[108:111], v142 offset:19456
	ds_read_b128 v[112:115], v142 offset:20480
	ds_read_b128 v[116:119], v142 offset:21504
	ds_read_b128 v[120:123], v142 offset:22528
	ds_read_b128 v[124:127], v142 offset:23552
	s_mov_b32 m0, s33
	s_nop 0
	global_load_lds_dwordx4 v138, s[76:77]
	s_add_u32 s76, s58, 0x8100
	s_mov_b32 m0, s34
	s_addc_u32 s77, s59, 0
	global_load_lds_dwordx4 v138, s[76:77]
	s_add_u32 s76, s58, 0x10100
	s_mov_b32 m0, s35
	s_addc_u32 s77, s59, 0
	global_load_lds_dwordx4 v138, s[76:77]
	s_add_u32 s76, s58, 0x18100
	s_mov_b32 m0, s36
	s_addc_u32 s77, s59, 0
	global_load_lds_dwordx4 v138, s[76:77]
	s_mov_b32 m0, s24
	s_nop 0
	global_load_lds_dwordx4 v128, s[22:23]
	s_add_u32 s22, s56, 0x8100
	s_mov_b32 m0, s37
	s_addc_u32 s23, s57, 0
	global_load_lds_dwordx4 v128, s[22:23]
	s_waitcnt vmcnt(8) lgkmcnt(0)
	s_barrier
	s_setprio 1
	v_mfma_f32_16x16x32_bf16 v[144:147], v[0:3], v[60:63], 0
	v_mfma_f32_16x16x32_bf16 v[152:155], v[0:3], v[104:107], 0
	v_mfma_f32_16x16x32_bf16 v[178:181], v[0:3], v[112:115], 0
	v_mfma_f32_16x16x32_bf16 v[0:3], v[0:3], v[120:123], 0
	v_mfma_f32_16x16x32_bf16 v[144:147], v[4:7], v[100:103], v[144:147]
	v_mfma_f32_16x16x32_bf16 v[152:155], v[4:7], v[108:111], v[152:155]
	v_mfma_f32_16x16x32_bf16 v[178:181], v[4:7], v[116:119], v[178:181]
	v_mfma_f32_16x16x32_bf16 v[0:3], v[4:7], v[124:127], v[0:3]
	v_mfma_f32_16x16x32_bf16 v[4:7], v[8:11], v[120:123], 0
	v_mfma_f32_16x16x32_bf16 v[148:151], v[8:11], v[60:63], 0
	v_mfma_f32_16x16x32_bf16 v[172:175], v[8:11], v[104:107], 0
	v_mfma_f32_16x16x32_bf16 v[182:185], v[8:11], v[112:115], 0
	v_mfma_f32_16x16x32_bf16 v[4:7], v[12:15], v[124:127], v[4:7]
	v_mfma_f32_16x16x32_bf16 v[148:151], v[12:15], v[100:103], v[148:151]
	v_mfma_f32_16x16x32_bf16 v[172:175], v[12:15], v[108:111], v[172:175]
	v_mfma_f32_16x16x32_bf16 v[182:185], v[12:15], v[116:119], v[182:185]
	v_mfma_f32_16x16x32_bf16 v[8:11], v[16:19], v[60:63], 0
	v_mfma_f32_16x16x32_bf16 v[12:15], v[24:27], v[60:63], 0
	v_mfma_f32_16x16x32_bf16 v[8:11], v[20:23], v[100:103], v[8:11]
	v_mfma_f32_16x16x32_bf16 v[12:15], v[28:31], v[100:103], v[12:15]
	v_mfma_f32_16x16x32_bf16 v[60:63], v[16:19], v[104:107], 0
	v_mfma_f32_16x16x32_bf16 v[100:103], v[24:27], v[104:107], 0
	v_mfma_f32_16x16x32_bf16 v[104:107], v[16:19], v[112:115], 0
	v_mfma_f32_16x16x32_bf16 v[16:19], v[16:19], v[120:123], 0
	v_mfma_f32_16x16x32_bf16 v[60:63], v[20:23], v[108:111], v[60:63]
	v_mfma_f32_16x16x32_bf16 v[100:103], v[28:31], v[108:111], v[100:103]
	v_mfma_f32_16x16x32_bf16 v[104:107], v[20:23], v[116:119], v[104:107]
	v_mfma_f32_16x16x32_bf16 v[108:111], v[24:27], v[112:115], 0
	v_mfma_f32_16x16x32_bf16 v[16:19], v[20:23], v[124:127], v[16:19]
	v_mfma_f32_16x16x32_bf16 v[20:23], v[24:27], v[120:123], 0
	v_mfma_f32_16x16x32_bf16 v[108:111], v[28:31], v[116:119], v[108:111]
	v_mfma_f32_16x16x32_bf16 v[20:23], v[28:31], v[124:127], v[20:23]
	s_setprio 0
	s_barrier
; #define PG8_STAGE(bufoff, gbase, voff, p64) do { _Pragma("unroll") for (int _i = 0; _i < 2; ++_i) { \
;         const char* _gb = (const char*)(gbase) + (size_t)_i * (p64); const unsigned _la = ldsbase + (unsigned)(bufoff) + (unsigned)_i * 8192u; \
;         asm volatile("s_mov_b32 m0, %0\n\ts_nop 0\n\tglobal_load_lds_dwordx4 %1, %2" :: "s"(_la), "v"(voff), "s"(_gb) : "memory"); } } while (0)
; #define PG8_LDA(dst, b, h) do { _Pragma("unroll") for (int m = 0; m < 4; ++m) _Pragma("unroll") for (int k = 0; k < 2; ++k) dst[m][k] = *(const LAS bf16x8*)(lds + PG8_SA(b, h) + aoff + m * 2048 + k * 1024); } while (0)
; #define PG8_LDB(dst, b, h) do { _Pragma("unroll") for (int n = 0; n < 2; ++n) _Pragma("unroll") for (int k = 0; k < 2; ++k) dst[n][k] = *(const LAS bf16x8*)(lds + PG8_SB(b, h) + boff + n * 2048 + k * 1024); } while (0)
; #define PG8_MMA(ai, bj, At, Bt) do { __builtin_amdgcn_s_setprio(1); _Pragma("unroll") for (int m = 0; m < 4; ++m) _Pragma("unroll") for (int n = 0; n < 2; ++n) _Pragma("unroll") for (int k = 0; k < 2; ++k) \
;         acc[ai][bj][m][n] = __builtin_amdgcn_mfma_f32_16x16x32_bf16(Bt[n][k], At[m][k], acc[ai][bj][m][n], 0, 0, 0); __builtin_amdgcn_s_setprio(0); } while (0)
; #define PG8_WAIT_V(n) asm volatile("s_waitcnt vmcnt(" #n ")" ::: "memory")
; #define PG8_WAIT_L(n) asm volatile("s_waitcnt lgkmcnt(" #n ")" ::: "memory")
; #define PG8_BAR __builtin_amdgcn_s_barrier()
; #define PG8_SCHED __builtin_amdgcn_sched_barrier(0)
; template <class Epi, class Sched>
; __device__ __forceinline__ void gemm_phase(LAS unsigned char* lds, const Sched& S, const Epi& E) {
;     ...
;             PG8_LDB(B0, 1, 0); PG8_LDB(B1, 1, 1); PG8_SCHED; PG8_LDA(At, 1, 0); PG8_STAGE(PG8_SA(0, 1), a2 + hA2, vA2, hA2 / 2);
;             PG8_WAIT_V(8); PG8_WAIT_L(0); PG8_BAR; PG8_MMA(0, 0, At, B0); PG8_MMA(0, 1, At, B1); PG8_BAR; PG8_SCHED;
;             PG8_LDA(At, 1, 1); PG8_STAGE(PG8_SB(1, 0), b3, vB2, hB2 / 2); PG8_STAGE(PG8_SB(1, 1), b3 + hB2, vB2, hB2 / 2); PG8_STAGE(PG8_SA(1, 0), a3, vA2, hA2 / 2);
;             PG8_WAIT_V(8); PG8_WAIT_L(0); PG8_BAR; PG8_MMA(1, 0, At, B0); PG8_MMA(1, 1, At, B1); PG8_BAR; PG8_SCHED;
	v_add_u32_e32 v132, 0x18000, v141
	v_add_u32_e32 v133, 0x1c000, v141
	ds_read_b128 v[24:27], v132
	ds_read_b128 v[28:31], v132 offset:1024
	ds_read_b128 v[112:115], v132 offset:2048
	ds_read_b128 v[116:119], v132 offset:3072
	ds_read_b128 v[120:123], v133
	ds_read_b128 v[124:127], v133 offset:1024
	ds_read_b128 v[186:189], v133 offset:2048
	ds_read_b128 v[190:193], v133 offset:3072
	ds_read_b128 v[194:197], v142 offset:32768
	ds_read_b128 v[198:201], v142 offset:33792
	ds_read_b128 v[202:205], v142 offset:34816
	ds_read_b128 v[206:209], v142 offset:35840
	ds_read_b128 v[210:213], v142 offset:36864
	ds_read_b128 v[214:217], v142 offset:37888
	ds_read_b128 v[218:221], v142 offset:38912
	ds_read_b128 v[222:225], v142 offset:39936
	s_add_u32 s22, s56, 0x10100
	s_mov_b32 m0, s42
	s_addc_u32 s23, s57, 0
	global_load_lds_dwordx4 v128, s[22:23]
	s_add_u32 s22, s56, 0x18100
	s_mov_b32 m0, s44
	s_addc_u32 s23, s57, 0
	global_load_lds_dwordx4 v128, s[22:23]
	s_waitcnt vmcnt(8) lgkmcnt(0)
	s_barrier
	s_setprio 1
	v_mfma_f32_16x16x32_bf16 v[64:67], v[24:27], v[194:197], v[64:67]
	v_mfma_f32_16x16x32_bf16 v[68:71], v[112:115], v[194:197], v[68:71]
	v_mfma_f32_16x16x32_bf16 v[72:75], v[24:27], v[202:205], v[72:75]
	v_mfma_f32_16x16x32_bf16 v[76:79], v[112:115], v[202:205], v[76:79]
	v_mfma_f32_16x16x32_bf16 v[80:83], v[24:27], v[210:213], v[80:83]
	v_mfma_f32_16x16x32_bf16 v[84:87], v[112:115], v[210:213], v[84:87]
	v_mfma_f32_16x16x32_bf16 v[88:91], v[24:27], v[218:221], v[88:91]
	v_mfma_f32_16x16x32_bf16 v[92:95], v[112:115], v[218:221], v[92:95]
	v_mfma_f32_16x16x32_bf16 v[64:67], v[28:31], v[198:201], v[64:67]
	v_mfma_f32_16x16x32_bf16 v[68:71], v[116:119], v[198:201], v[68:71]
	v_mfma_f32_16x16x32_bf16 v[72:75], v[28:31], v[206:209], v[72:75]
	v_mfma_f32_16x16x32_bf16 v[76:79], v[116:119], v[206:209], v[76:79]
	v_mfma_f32_16x16x32_bf16 v[80:83], v[28:31], v[214:217], v[80:83]
	v_mfma_f32_16x16x32_bf16 v[84:87], v[116:119], v[214:217], v[84:87]
	v_mfma_f32_16x16x32_bf16 v[88:91], v[28:31], v[222:225], v[88:91]
	v_mfma_f32_16x16x32_bf16 v[92:95], v[116:119], v[222:225], v[92:95]
	v_mfma_f32_16x16x32_bf16 v[96:99], v[120:123], v[194:197], v[96:99]
	v_mfma_f32_16x16x32_bf16 v[32:35], v[186:189], v[194:197], v[32:35]
	v_mfma_f32_16x16x32_bf16 v[36:39], v[120:123], v[202:205], v[36:39]
	v_mfma_f32_16x16x32_bf16 v[40:43], v[186:189], v[202:205], v[40:43]
	v_mfma_f32_16x16x32_bf16 v[44:47], v[120:123], v[210:213], v[44:47]
	v_mfma_f32_16x16x32_bf16 v[48:51], v[186:189], v[210:213], v[48:51]
	v_mfma_f32_16x16x32_bf16 v[52:55], v[120:123], v[218:221], v[52:55]
	v_mfma_f32_16x16x32_bf16 v[56:59], v[186:189], v[218:221], v[56:59]
	v_mfma_f32_16x16x32_bf16 v[96:99], v[124:127], v[198:201], v[96:99]
	v_mfma_f32_16x16x32_bf16 v[32:35], v[190:193], v[198:201], v[32:35]
	v_mfma_f32_16x16x32_bf16 v[36:39], v[124:127], v[206:209], v[36:39]
	v_mfma_f32_16x16x32_bf16 v[40:43], v[190:193], v[206:209], v[40:43]
	v_mfma_f32_16x16x32_bf16 v[44:47], v[124:127], v[214:217], v[44:47]
	v_mfma_f32_16x16x32_bf16 v[48:51], v[190:193], v[214:217], v[48:51]
	v_mfma_f32_16x16x32_bf16 v[52:55], v[124:127], v[222:225], v[52:55]
	v_mfma_f32_16x16x32_bf16 v[56:59], v[190:193], v[222:225], v[56:59]
	s_setprio 0
	s_barrier
	s_add_u32 s22, s58, 0x180
	s_addc_u32 s23, s59, 0
	ds_read_b128 v[194:197], v142 offset:49152
	ds_read_b128 v[198:201], v142 offset:50176
	ds_read_b128 v[202:205], v142 offset:51200
	ds_read_b128 v[206:209], v142 offset:52224
	ds_read_b128 v[210:213], v142 offset:53248
	ds_read_b128 v[214:217], v142 offset:54272
	ds_read_b128 v[218:221], v142 offset:55296
	ds_read_b128 v[222:225], v142 offset:56320
	s_mov_b32 m0, s51
	s_nop 0
	global_load_lds_dwordx4 v138, s[22:23]
	s_add_u32 s22, s58, 0x8180
	s_mov_b32 m0, s61
	s_addc_u32 s23, s59, 0
	global_load_lds_dwordx4 v138, s[22:23]
	s_add_u32 s22, s58, 0x10180
	s_mov_b32 m0, s64
	s_addc_u32 s23, s59, 0
	global_load_lds_dwordx4 v138, s[22:23]
	s_add_u32 s22, s58, 0x18180
	s_mov_b32 m0, s65
	s_addc_u32 s23, s59, 0
	global_load_lds_dwordx4 v138, s[22:23]
	s_mov_b32 m0, s62
	s_nop 0
	global_load_lds_dwordx4 v128, s[16:17]
	s_add_u32 s16, s56, 0x8180
	s_mov_b32 m0, s63
	s_addc_u32 s17, s57, 0
	global_load_lds_dwordx4 v128, s[16:17]
	s_waitcnt vmcnt(8) lgkmcnt(0)
	s_barrier
	s_setprio 1
	v_mfma_f32_16x16x32_bf16 v[0:3], v[24:27], v[218:221], v[0:3]
	v_mfma_f32_16x16x32_bf16 v[4:7], v[112:115], v[218:221], v[4:7]
	v_mfma_f32_16x16x32_bf16 v[144:147], v[24:27], v[194:197], v[144:147]
	v_mfma_f32_16x16x32_bf16 v[148:151], v[112:115], v[194:197], v[148:151]
	v_mfma_f32_16x16x32_bf16 v[152:155], v[24:27], v[202:205], v[152:155]
	v_mfma_f32_16x16x32_bf16 v[172:175], v[112:115], v[202:205], v[172:175]
	v_mfma_f32_16x16x32_bf16 v[178:181], v[24:27], v[210:213], v[178:181]
	v_mfma_f32_16x16x32_bf16 v[182:185], v[112:115], v[210:213], v[182:185]
	v_mfma_f32_16x16x32_bf16 v[0:3], v[28:31], v[222:225], v[0:3]
	v_mfma_f32_16x16x32_bf16 v[4:7], v[116:119], v[222:225], v[4:7]
	v_mfma_f32_16x16x32_bf16 v[144:147], v[28:31], v[198:201], v[144:147]
	v_mfma_f32_16x16x32_bf16 v[148:151], v[116:119], v[198:201], v[148:151]
	v_mfma_f32_16x16x32_bf16 v[152:155], v[28:31], v[206:209], v[152:155]
	v_mfma_f32_16x16x32_bf16 v[172:175], v[116:119], v[206:209], v[172:175]
	v_mfma_f32_16x16x32_bf16 v[178:181], v[28:31], v[214:217], v[178:181]
	v_mfma_f32_16x16x32_bf16 v[182:185], v[116:119], v[214:217], v[182:185]
	v_mfma_f32_16x16x32_bf16 v[8:11], v[120:123], v[194:197], v[8:11]
	v_mfma_f32_16x16x32_bf16 v[12:15], v[186:189], v[194:197], v[12:15]
	v_mfma_f32_16x16x32_bf16 v[24:27], v[120:123], v[202:205], v[60:63]
	v_mfma_f32_16x16x32_bf16 v[28:31], v[186:189], v[202:205], v[100:103]
	v_mfma_f32_16x16x32_bf16 v[60:63], v[120:123], v[210:213], v[104:107]
	v_mfma_f32_16x16x32_bf16 v[100:103], v[186:189], v[210:213], v[108:111]
	v_mfma_f32_16x16x32_bf16 v[16:19], v[120:123], v[218:221], v[16:19]
	v_mfma_f32_16x16x32_bf16 v[20:23], v[186:189], v[218:221], v[20:23]
	v_mfma_f32_16x16x32_bf16 v[8:11], v[124:127], v[198:201], v[8:11]
	v_mfma_f32_16x16x32_bf16 v[12:15], v[190:193], v[198:201], v[12:15]
	v_mfma_f32_16x16x32_bf16 v[24:27], v[124:127], v[206:209], v[24:27]
	v_mfma_f32_16x16x32_bf16 v[28:31], v[190:193], v[206:209], v[28:31]
	v_mfma_f32_16x16x32_bf16 v[60:63], v[124:127], v[214:217], v[60:63]
	v_mfma_f32_16x16x32_bf16 v[100:103], v[190:193], v[214:217], v[100:103]
	v_mfma_f32_16x16x32_bf16 v[16:19], v[124:127], v[222:225], v[16:19]
	v_mfma_f32_16x16x32_bf16 v[20:23], v[190:193], v[222:225], v[20:23]
	s_setprio 0
	s_barrier
; #define PG8_STAGE(bufoff, gbase, voff, p64) do { _Pragma("unroll") for (int _i = 0; _i < 2; ++_i) { \
;         const char* _gb = (const char*)(gbase) + (size_t)_i * (p64); const unsigned _la = ldsbase + (unsigned)(bufoff) + (unsigned)_i * 8192u; \
;         asm volatile("s_mov_b32 m0, %0\n\ts_nop 0\n\tglobal_load_lds_dwordx4 %1, %2" :: "s"(_la), "v"(voff), "s"(_gb) : "memory"); } } while (0)
; #define PG8_LDA(dst, b, h) do { _Pragma("unroll") for (int m = 0; m < 4; ++m) _Pragma("unroll") for (int k = 0; k < 2; ++k) dst[m][k] = *(const LAS bf16x8*)(lds + PG8_SA(b, h) + aoff + m * 2048 + k * 1024); } while (0)
; #define PG8_LDB(dst, b, h) do { _Pragma("unroll") for (int n = 0; n < 2; ++n) _Pragma("unroll") for (int k = 0; k < 2; ++k) dst[n][k] = *(const LAS bf16x8*)(lds + PG8_SB(b, h) + boff + n * 2048 + k * 1024); } while (0)
; #define PG8_MMA(ai, bj, At, Bt) do { __builtin_amdgcn_s_setprio(1); _Pragma("unroll") for (int m = 0; m < 4; ++m) _Pragma("unroll") for (int n = 0; n < 2; ++n) _Pragma("unroll") for (int k = 0; k < 2; ++k) \
;         acc[ai][bj][m][n] = __builtin_amdgcn_mfma_f32_16x16x32_bf16(Bt[n][k], At[m][k], acc[ai][bj][m][n], 0, 0, 0); __builtin_amdgcn_s_setprio(0); } while (0)
; #define PG8_WAIT_V(n) asm volatile("s_waitcnt vmcnt(" #n ")" ::: "memory")
; #define PG8_WAIT_L(n) asm volatile("s_waitcnt lgkmcnt(" #n ")" ::: "memory")
; #define PG8_BAR __builtin_amdgcn_s_barrier()
; #define PG8_SCHED __builtin_amdgcn_sched_barrier(0)
; template <class Epi, class Sched>
; __device__ __forceinline__ void gemm_phase(LAS unsigned char* lds, const Sched& S, const Epi& E) {
;     ...
;             PG8_LDB(B0, 0, 0); PG8_LDB(B1, 0, 1); PG8_SCHED; PG8_LDA(At, 0, 0); PG8_STAGE(PG8_SA(1, 1), a1 + hA, voffA, hA / 2);
;             PG8_WAIT_V(8); PG8_WAIT_L(0); PG8_BAR; PG8_MMA(0, 0, At, B0); PG8_MMA(0, 1, At, B1); PG8_BAR; PG8_SCHED;
;             PG8_LDA(At, 0, 1); PG8_STAGE(PG8_SB(0, 0), b2, vB2, hB2 / 2); PG8_STAGE(PG8_SB(0, 1), b2 + hB2, vB2, hB2 / 2); PG8_STAGE(PG8_SA(0, 0), a2, vA2, hA2 / 2);
;             PG8_WAIT_V(8); PG8_WAIT_L(0); PG8_BAR; PG8_MMA(1, 0, At, B0); PG8_MMA(1, 1, At, B1); PG8_BAR; PG8_SCHED;
	ds_read_b128 v[104:107], v130
	ds_read_b128 v[108:111], v130 offset:1024
	ds_read_b128 v[112:115], v130 offset:2048
	ds_read_b128 v[116:119], v130 offset:3072
	ds_read_b128 v[120:123], v131
	ds_read_b128 v[124:127], v131 offset:1024
	ds_read_b128 v[186:189], v131 offset:2048
	ds_read_b128 v[190:193], v131 offset:3072
	s_add_u32 s16, s38, 0x80
	s_addc_u32 s17, s39, 0
	ds_read_b128 v[194:197], v142
	ds_read_b128 v[198:201], v142 offset:1024
	ds_read_b128 v[202:205], v142 offset:2048
	ds_read_b128 v[206:209], v142 offset:3072
	ds_read_b128 v[210:213], v142 offset:4096
	ds_read_b128 v[214:217], v142 offset:5120
	ds_read_b128 v[218:221], v142 offset:6144
	ds_read_b128 v[222:225], v142 offset:7168
	s_add_u32 s22, s56, 0x10180
	s_mov_b32 m0, s66
	s_addc_u32 s23, s57, 0
	global_load_lds_dwordx4 v128, s[22:23]
	s_add_u32 s22, s56, 0x18180
	s_mov_b32 m0, s67
	s_addc_u32 s23, s57, 0
	global_load_lds_dwordx4 v128, s[22:23]
	s_waitcnt vmcnt(8) lgkmcnt(0)
	s_barrier
	s_setprio 1
	v_mfma_f32_16x16x32_bf16 v[64:67], v[104:107], v[194:197], v[64:67]
	v_mfma_f32_16x16x32_bf16 v[68:71], v[112:115], v[194:197], v[68:71]
	v_mfma_f32_16x16x32_bf16 v[72:75], v[104:107], v[202:205], v[72:75]
	v_mfma_f32_16x16x32_bf16 v[76:79], v[112:115], v[202:205], v[76:79]
	v_mfma_f32_16x16x32_bf16 v[80:83], v[104:107], v[210:213], v[80:83]
	v_mfma_f32_16x16x32_bf16 v[84:87], v[112:115], v[210:213], v[84:87]
	v_mfma_f32_16x16x32_bf16 v[88:91], v[104:107], v[218:221], v[88:91]
	v_mfma_f32_16x16x32_bf16 v[92:95], v[112:115], v[218:221], v[92:95]
	v_mfma_f32_16x16x32_bf16 v[64:67], v[108:111], v[198:201], v[64:67]
	v_mfma_f32_16x16x32_bf16 v[68:71], v[116:119], v[198:201], v[68:71]
	v_mfma_f32_16x16x32_bf16 v[72:75], v[108:111], v[206:209], v[72:75]
	v_mfma_f32_16x16x32_bf16 v[76:79], v[116:119], v[206:209], v[76:79]
	v_mfma_f32_16x16x32_bf16 v[80:83], v[108:111], v[214:217], v[80:83]
	v_mfma_f32_16x16x32_bf16 v[84:87], v[116:119], v[214:217], v[84:87]
	v_mfma_f32_16x16x32_bf16 v[88:91], v[108:111], v[222:225], v[88:91]
	v_mfma_f32_16x16x32_bf16 v[92:95], v[116:119], v[222:225], v[92:95]
	v_mfma_f32_16x16x32_bf16 v[32:35], v[186:189], v[194:197], v[32:35]
	v_mfma_f32_16x16x32_bf16 v[96:99], v[120:123], v[194:197], v[96:99]
	v_mfma_f32_16x16x32_bf16 v[194:197], v[190:193], v[198:201], v[32:35]
	v_mfma_f32_16x16x32_bf16 v[32:35], v[120:123], v[202:205], v[36:39]
	v_mfma_f32_16x16x32_bf16 v[96:99], v[124:127], v[198:201], v[96:99]
	v_mfma_f32_16x16x32_bf16 v[198:201], v[124:127], v[206:209], v[32:35]
	v_mfma_f32_16x16x32_bf16 v[32:35], v[186:189], v[202:205], v[40:43]
	v_mfma_f32_16x16x32_bf16 v[40:43], v[190:193], v[206:209], v[32:35]
	v_mfma_f32_16x16x32_bf16 v[32:35], v[120:123], v[210:213], v[44:47]
	v_mfma_f32_16x16x32_bf16 v[44:47], v[124:127], v[214:217], v[32:35]
	v_mfma_f32_16x16x32_bf16 v[32:35], v[186:189], v[210:213], v[48:51]
	v_mfma_f32_16x16x32_bf16 v[202:205], v[190:193], v[214:217], v[32:35]
	v_mfma_f32_16x16x32_bf16 v[32:35], v[120:123], v[218:221], v[52:55]
	v_mfma_f32_16x16x32_bf16 v[206:209], v[124:127], v[222:225], v[32:35]
	v_mfma_f32_16x16x32_bf16 v[32:35], v[186:189], v[218:221], v[56:59]
	v_mfma_f32_16x16x32_bf16 v[210:213], v[190:193], v[222:225], v[32:35]
	s_setprio 0
	s_barrier
	s_add_u32 s22, s40, 0x8000
	s_nop 3
	ds_read_b128 v[32:35], v142 offset:16384
	ds_read_b128 v[36:39], v142 offset:17408
	ds_read_b128 v[48:51], v142 offset:18432
	ds_read_b128 v[52:55], v142 offset:19456
	ds_read_b128 v[56:59], v142 offset:20480
	ds_read_b128 v[214:217], v142 offset:21504
	ds_read_b128 v[218:221], v142 offset:22528
	ds_read_b128 v[222:225], v142 offset:23552
	s_mov_b32 m0, s33
	s_nop 0
	global_load_lds_dwordx4 v138, s[40:41]
	s_mov_b32 m0, s34
	s_addc_u32 s23, s41, 0
	global_load_lds_dwordx4 v138, s[22:23]
	s_add_u32 s22, s40, 0x10000
	s_mov_b32 m0, s35
	s_addc_u32 s23, s41, 0
	global_load_lds_dwordx4 v138, s[22:23]
	s_add_u32 s22, s40, 0x18000
	s_mov_b32 m0, s36
	s_addc_u32 s23, s41, 0
	global_load_lds_dwordx4 v138, s[22:23]
	s_mov_b32 m0, s24
	s_nop 0
	global_load_lds_dwordx4 v128, s[38:39]
	s_add_u32 s22, s38, 0x8000
	s_mov_b32 m0, s37
	s_addc_u32 s23, s39, 0
	global_load_lds_dwordx4 v128, s[22:23]
	s_waitcnt vmcnt(8) lgkmcnt(0)
	s_barrier
	s_setprio 1
	v_mfma_f32_16x16x32_bf16 v[0:3], v[104:107], v[218:221], v[0:3]
	v_mfma_f32_16x16x32_bf16 v[144:147], v[104:107], v[32:35], v[144:147]
	v_mfma_f32_16x16x32_bf16 v[152:155], v[104:107], v[48:51], v[152:155]
	v_mfma_f32_16x16x32_bf16 v[178:181], v[104:107], v[56:59], v[178:181]
	v_mfma_f32_16x16x32_bf16 v[104:107], v[108:111], v[222:225], v[0:3]
	v_mfma_f32_16x16x32_bf16 v[0:3], v[112:115], v[218:221], v[4:7]
	v_mfma_f32_16x16x32_bf16 v[144:147], v[108:111], v[36:39], v[144:147]
	v_mfma_f32_16x16x32_bf16 v[148:151], v[112:115], v[32:35], v[148:151]
	v_mfma_f32_16x16x32_bf16 v[152:155], v[108:111], v[52:55], v[152:155]
	v_mfma_f32_16x16x32_bf16 v[172:175], v[112:115], v[48:51], v[172:175]
	v_mfma_f32_16x16x32_bf16 v[178:181], v[108:111], v[214:217], v[178:181]
	v_mfma_f32_16x16x32_bf16 v[182:185], v[112:115], v[56:59], v[182:185]
	v_mfma_f32_16x16x32_bf16 v[108:111], v[116:119], v[222:225], v[0:3]
	v_mfma_f32_16x16x32_bf16 v[148:151], v[116:119], v[36:39], v[148:151]
	v_mfma_f32_16x16x32_bf16 v[172:175], v[116:119], v[52:55], v[172:175]
	v_mfma_f32_16x16x32_bf16 v[182:185], v[116:119], v[214:217], v[182:185]
	v_mfma_f32_16x16x32_bf16 v[0:3], v[120:123], v[32:35], v[8:11]
	v_mfma_f32_16x16x32_bf16 v[112:115], v[124:127], v[36:39], v[0:3]
	v_mfma_f32_16x16x32_bf16 v[0:3], v[186:189], v[32:35], v[12:15]
	v_mfma_f32_16x16x32_bf16 v[116:119], v[190:193], v[36:39], v[0:3]
	v_mfma_f32_16x16x32_bf16 v[0:3], v[120:123], v[48:51], v[24:27]
	v_mfma_f32_16x16x32_bf16 v[226:229], v[124:127], v[52:55], v[0:3]
	v_mfma_f32_16x16x32_bf16 v[0:3], v[186:189], v[48:51], v[28:31]
	v_mfma_f32_16x16x32_bf16 v[230:233], v[190:193], v[52:55], v[0:3]
	v_mfma_f32_16x16x32_bf16 v[0:3], v[120:123], v[56:59], v[60:63]
	v_mfma_f32_16x16x32_bf16 v[234:237], v[124:127], v[214:217], v[0:3]
	v_mfma_f32_16x16x32_bf16 v[0:3], v[186:189], v[56:59], v[100:103]
	v_mfma_f32_16x16x32_bf16 v[214:217], v[190:193], v[214:217], v[0:3]
	v_mfma_f32_16x16x32_bf16 v[0:3], v[120:123], v[218:221], v[16:19]
	v_mfma_f32_16x16x32_bf16 v[238:241], v[124:127], v[222:225], v[0:3]
	v_mfma_f32_16x16x32_bf16 v[0:3], v[186:189], v[218:221], v[20:23]
	v_mfma_f32_16x16x32_bf16 v[186:189], v[190:193], v[222:225], v[0:3]
	s_setprio 0
	s_barrier
; #define PG8_STAGE(bufoff, gbase, voff, p64) do { _Pragma("unroll") for (int _i = 0; _i < 2; ++_i) { \
;         const char* _gb = (const char*)(gbase) + (size_t)_i * (p64); const unsigned _la = ldsbase + (unsigned)(bufoff) + (unsigned)_i * 8192u; \
;         asm volatile("s_mov_b32 m0, %0\n\ts_nop 0\n\tglobal_load_lds_dwordx4 %1, %2" :: "s"(_la), "v"(voff), "s"(_gb) : "memory"); } } while (0)
; #define PG8_LDA(dst, b, h) do { _Pragma("unroll") for (int m = 0; m < 4; ++m) _Pragma("unroll") for (int k = 0; k < 2; ++k) dst[m][k] = *(const LAS bf16x8*)(lds + PG8_SA(b, h) + aoff + m * 2048 + k * 1024); } while (0)
; #define PG8_LDB(dst, b, h) do { _Pragma("unroll") for (int n = 0; n < 2; ++n) _Pragma("unroll") for (int k = 0; k < 2; ++k) dst[n][k] = *(const LAS bf16x8*)(lds + PG8_SB(b, h) + boff + n * 2048 + k * 1024); } while (0)
; #define PG8_MMA(ai, bj, At, Bt) do { __builtin_amdgcn_s_setprio(1); _Pragma("unroll") for (int m = 0; m < 4; ++m) _Pragma("unroll") for (int n = 0; n < 2; ++n) _Pragma("unroll") for (int k = 0; k < 2; ++k) \
;         acc[ai][bj][m][n] = __builtin_amdgcn_mfma_f32_16x16x32_bf16(Bt[n][k], At[m][k], acc[ai][bj][m][n], 0, 0, 0); __builtin_amdgcn_s_setprio(0); } while (0)
; #define PG8_WAIT_V(n) asm volatile("s_waitcnt vmcnt(" #n ")" ::: "memory")
; #define PG8_WAIT_L(n) asm volatile("s_waitcnt lgkmcnt(" #n ")" ::: "memory")
; #define PG8_BAR __builtin_amdgcn_s_barrier()
; #define PG8_SCHED __builtin_amdgcn_sched_barrier(0)
; template <class Epi, class Sched>
; __device__ __forceinline__ void gemm_phase(LAS unsigned char* lds, const Sched& S, const Epi& E) {
;     ...
;             PG8_LDB(B0, 1, 0); PG8_LDB(B1, 1, 1); PG8_SCHED; PG8_LDA(At, 1, 0); PG8_STAGE(PG8_SA(0, 1), a2 + hA2, vA2, hA2 / 2);
;             PG8_WAIT_V(8); PG8_WAIT_L(0); PG8_BAR; PG8_MMA(0, 0, At, B0); PG8_MMA(0, 1, At, B1); PG8_BAR; PG8_SCHED;
;             PG8_LDA(At, 1, 1); PG8_STAGE(PG8_SB(1, 0), b3, vB2, hB2 / 2); PG8_STAGE(PG8_SB(1, 1), b3 + hB2, vB2, hB2 / 2); PG8_STAGE(PG8_SA(1, 0), a3, vA2, hA2 / 2);
;             PG8_WAIT_V(8); PG8_WAIT_L(0); PG8_BAR; PG8_MMA(1, 0, At, B0); PG8_MMA(1, 1, At, B1); PG8_BAR; PG8_SCHED;
;         }
;         if (wr == 0) PG8_BAR;
	ds_read_b128 v[120:123], v132
	ds_read_b128 v[124:127], v132 offset:1024
	ds_read_b128 v[190:193], v132 offset:2048
	ds_read_b128 v[218:221], v132 offset:3072
	ds_read_b128 v[222:225], v133
	ds_read_b128 v[242:245], v133 offset:1024
	ds_read_b128 v[246:249], v133 offset:2048
	ds_read_b128 v[250:253], v133 offset:3072
	ds_read_b128 v[24:27], v142 offset:32768
	ds_read_b128 v[28:31], v142 offset:33792
	ds_read_b128 v[52:55], v142 offset:34816
	ds_read_b128 v[100:103], v142 offset:35840
	ds_read_b128 v[130:133], v142 offset:36864
	ds_read_b128 v[162:165], v142 offset:37888
	ds_read_b128 v[134:137], v142 offset:38912
	ds_read_b128 v[158:161], v142 offset:39936
	s_add_u32 s22, s38, 0x10000
	s_mov_b32 m0, s42
	s_addc_u32 s23, s39, 0
	global_load_lds_dwordx4 v128, s[22:23]
	s_add_u32 s22, s38, 0x18000
	s_mov_b32 m0, s44
	s_addc_u32 s23, s39, 0
	global_load_lds_dwordx4 v128, s[22:23]
	s_waitcnt vmcnt(8) lgkmcnt(0)
	s_barrier
	s_setprio 1
	v_mfma_f32_16x16x32_bf16 v[0:3], v[120:123], v[24:27], v[64:67]
	v_mfma_f32_16x16x32_bf16 v[32:35], v[124:127], v[28:31], v[0:3]
	v_mfma_f32_16x16x32_bf16 v[0:3], v[190:193], v[24:27], v[68:71]
	v_mfma_f32_16x16x32_bf16 v[36:39], v[218:221], v[28:31], v[0:3]
	v_mfma_f32_16x16x32_bf16 v[0:3], v[120:123], v[52:55], v[72:75]
	v_mfma_f32_16x16x32_bf16 v[16:19], v[124:127], v[100:103], v[0:3]
	v_mfma_f32_16x16x32_bf16 v[0:3], v[190:193], v[52:55], v[76:79]
	v_mfma_f32_16x16x32_bf16 v[20:23], v[218:221], v[100:103], v[0:3]
	v_mfma_f32_16x16x32_bf16 v[0:3], v[120:123], v[130:133], v[80:83]
	v_mfma_f32_16x16x32_bf16 v[8:11], v[124:127], v[162:165], v[0:3]
	v_mfma_f32_16x16x32_bf16 v[0:3], v[190:193], v[130:133], v[84:87]
	v_mfma_f32_16x16x32_bf16 v[12:15], v[218:221], v[162:165], v[0:3]
	v_mfma_f32_16x16x32_bf16 v[0:3], v[120:123], v[134:137], v[88:91]
	v_mfma_f32_16x16x32_bf16 v[4:7], v[190:193], v[134:137], v[92:95]
	v_mfma_f32_16x16x32_bf16 v[0:3], v[124:127], v[158:161], v[0:3]
	v_mfma_f32_16x16x32_bf16 v[4:7], v[218:221], v[158:161], v[4:7]
	v_mfma_f32_16x16x32_bf16 v[48:51], v[222:225], v[24:27], v[96:99]
	v_mfma_f32_16x16x32_bf16 v[24:27], v[246:249], v[24:27], v[194:197]
	v_mfma_f32_16x16x32_bf16 v[60:63], v[250:253], v[28:31], v[24:27]
	v_mfma_f32_16x16x32_bf16 v[24:27], v[222:225], v[52:55], v[198:201]
	v_mfma_f32_16x16x32_bf16 v[56:59], v[242:245], v[28:31], v[48:51]
	v_mfma_f32_16x16x32_bf16 v[48:51], v[242:245], v[100:103], v[24:27]
	v_mfma_f32_16x16x32_bf16 v[24:27], v[246:249], v[52:55], v[40:43]
	v_mfma_f32_16x16x32_bf16 v[52:55], v[250:253], v[100:103], v[24:27]
	v_mfma_f32_16x16x32_bf16 v[24:27], v[222:225], v[130:133], v[44:47]
	v_mfma_f32_16x16x32_bf16 v[40:43], v[242:245], v[162:165], v[24:27]
	v_mfma_f32_16x16x32_bf16 v[24:27], v[246:249], v[130:133], v[202:205]
	v_mfma_f32_16x16x32_bf16 v[44:47], v[250:253], v[162:165], v[24:27]
	v_mfma_f32_16x16x32_bf16 v[24:27], v[222:225], v[134:137], v[206:209]
	v_mfma_f32_16x16x32_bf16 v[28:31], v[246:249], v[134:137], v[210:213]
	v_mfma_f32_16x16x32_bf16 v[24:27], v[242:245], v[158:161], v[24:27]
	v_mfma_f32_16x16x32_bf16 v[28:31], v[250:253], v[158:161], v[28:31]
	s_setprio 0
	s_barrier
	s_add_u32 s22, s40, 0x80
	s_addc_u32 s23, s41, 0
	ds_read_b128 v[88:91], v142 offset:49152
	ds_read_b128 v[92:95], v142 offset:50176
	ds_read_b128 v[130:133], v142 offset:51200
	ds_read_b128 v[134:137], v142 offset:52224
	ds_read_b128 v[158:161], v142 offset:53248
	ds_read_b128 v[162:165], v142 offset:54272
	ds_read_b128 v[194:197], v142 offset:55296
	ds_read_b128 v[198:201], v142 offset:56320
	s_mov_b32 m0, s51
	s_nop 0
	global_load_lds_dwordx4 v138, s[22:23]
	s_add_u32 s22, s40, 0x8080
	s_mov_b32 m0, s61
	s_addc_u32 s23, s41, 0
	global_load_lds_dwordx4 v138, s[22:23]
	s_add_u32 s22, s40, 0x10080
	s_mov_b32 m0, s64
	s_addc_u32 s23, s41, 0
	global_load_lds_dwordx4 v138, s[22:23]
	s_add_u32 s22, s40, 0x18080
	s_mov_b32 m0, s65
	s_addc_u32 s23, s41, 0
	global_load_lds_dwordx4 v138, s[22:23]
	s_mov_b32 m0, s62
	s_nop 0
	global_load_lds_dwordx4 v128, s[16:17]
	s_add_u32 s16, s38, 0x8080
	s_mov_b32 m0, s63
	s_addc_u32 s17, s39, 0
	global_load_lds_dwordx4 v128, s[16:17]
	s_waitcnt vmcnt(8) lgkmcnt(0)
	s_barrier
	s_setprio 1
	v_mfma_f32_16x16x32_bf16 v[64:67], v[120:123], v[88:91], v[144:147]
	v_mfma_f32_16x16x32_bf16 v[96:99], v[124:127], v[92:95], v[64:67]
	v_mfma_f32_16x16x32_bf16 v[64:67], v[190:193], v[88:91], v[148:151]
	v_mfma_f32_16x16x32_bf16 v[100:103], v[218:221], v[92:95], v[64:67]
	v_mfma_f32_16x16x32_bf16 v[64:67], v[120:123], v[130:133], v[152:155]
	v_mfma_f32_16x16x32_bf16 v[80:83], v[124:127], v[134:137], v[64:67]
	v_mfma_f32_16x16x32_bf16 v[64:67], v[190:193], v[130:133], v[172:175]
	v_mfma_f32_16x16x32_bf16 v[84:87], v[218:221], v[134:137], v[64:67]
	v_mfma_f32_16x16x32_bf16 v[64:67], v[120:123], v[158:161], v[178:181]
	v_mfma_f32_16x16x32_bf16 v[72:75], v[124:127], v[162:165], v[64:67]
	v_mfma_f32_16x16x32_bf16 v[64:67], v[190:193], v[158:161], v[182:185]
	v_mfma_f32_16x16x32_bf16 v[76:79], v[218:221], v[162:165], v[64:67]
	v_mfma_f32_16x16x32_bf16 v[64:67], v[120:123], v[194:197], v[104:107]
	v_mfma_f32_16x16x32_bf16 v[68:71], v[190:193], v[194:197], v[108:111]
	v_mfma_f32_16x16x32_bf16 v[64:67], v[124:127], v[198:201], v[64:67]
	v_mfma_f32_16x16x32_bf16 v[68:71], v[218:221], v[198:201], v[68:71]
	v_mfma_f32_16x16x32_bf16 v[104:107], v[222:225], v[88:91], v[112:115]
	v_mfma_f32_16x16x32_bf16 v[88:91], v[246:249], v[88:91], v[116:119]
	v_mfma_f32_16x16x32_bf16 v[124:127], v[250:253], v[92:95], v[88:91]
	v_mfma_f32_16x16x32_bf16 v[88:91], v[222:225], v[130:133], v[226:229]
	v_mfma_f32_16x16x32_bf16 v[112:115], v[242:245], v[134:137], v[88:91]
	v_mfma_f32_16x16x32_bf16 v[88:91], v[246:249], v[130:133], v[230:233]
	v_mfma_f32_16x16x32_bf16 v[116:119], v[250:253], v[134:137], v[88:91]
	v_mfma_f32_16x16x32_bf16 v[88:91], v[222:225], v[158:161], v[234:237]
	v_mfma_f32_16x16x32_bf16 v[120:123], v[242:245], v[92:95], v[104:107]
	v_mfma_f32_16x16x32_bf16 v[104:107], v[242:245], v[162:165], v[88:91]
	v_mfma_f32_16x16x32_bf16 v[88:91], v[246:249], v[158:161], v[214:217]
	v_mfma_f32_16x16x32_bf16 v[108:111], v[250:253], v[162:165], v[88:91]
	v_mfma_f32_16x16x32_bf16 v[88:91], v[222:225], v[194:197], v[238:241]
	v_mfma_f32_16x16x32_bf16 v[92:95], v[246:249], v[194:197], v[186:189]
	v_mfma_f32_16x16x32_bf16 v[88:91], v[242:245], v[198:201], v[88:91]
	v_mfma_f32_16x16x32_bf16 v[92:95], v[250:253], v[198:201], v[92:95]
	s_setprio 0
	s_barrier
	s_andn2_b64 vcc, exec, s[8:9]
	s_cbranch_vccnz .LBB0_681
	s_barrier

; #define PG8_STAGE(bufoff, gbase, voff, p64) do { _Pragma("unroll") for (int _i = 0; _i < 2; ++_i) { \
;         const char* _gb = (const char*)(gbase) + (size_t)_i * (p64); const unsigned _la = ldsbase + (unsigned)(bufoff) + (unsigned)_i * 8192u; \
;         asm volatile("s_mov_b32 m0, %0\n\ts_nop 0\n\tglobal_load_lds_dwordx4 %1, %2" :: "s"(_la), "v"(voff), "s"(_gb) : "memory"); } } while (0)
; #define PG8_LDA(dst, b, h) do { _Pragma("unroll") for (int m = 0; m < 4; ++m) _Pragma("unroll") for (int k = 0; k < 2; ++k) dst[m][k] = *(const LAS bf16x8*)(lds + PG8_SA(b, h) + aoff + m * 2048 + k * 1024); } while (0)
; #define PG8_LDB(dst, b, h) do { _Pragma("unroll") for (int n = 0; n < 2; ++n) _Pragma("unroll") for (int k = 0; k < 2; ++k) dst[n][k] = *(const LAS bf16x8*)(lds + PG8_SB(b, h) + boff + n * 2048 + k * 1024); } while (0)
; #define PG8_MMA(ai, bj, At, Bt) do { __builtin_amdgcn_s_setprio(1); _Pragma("unroll") for (int m = 0; m < 4; ++m) _Pragma("unroll") for (int n = 0; n < 2; ++n) _Pragma("unroll") for (int k = 0; k < 2; ++k) \
;         acc[ai][bj][m][n] = __builtin_amdgcn_mfma_f32_16x16x32_bf16(Bt[n][k], At[m][k], acc[ai][bj][m][n], 0, 0, 0); __builtin_amdgcn_s_setprio(0); } while (0)
; #define PG8_WAIT_V(n) asm volatile("s_waitcnt vmcnt(" #n ")" ::: "memory")
; #define PG8_BAR __builtin_amdgcn_s_barrier()
; template <class Epi, class Sched>
; __device__ __forceinline__ void gemm_phase(LAS unsigned char* lds, const Sched& S, const Epi& E) {
;     ...
;             const bool last = (t == nt - 2);
;             const char* a1 = cA + (size_t)(t + 1) * kstep;
;             const char* a2 = last ? nA : cA + (size_t)(t + 2) * kstep; const char* b2 = last ? nB : cB + (size_t)(t + 2) * kstep;
;             const char* a3 = a2 + kstep; const char* b3 = b2 + kstep;
;             const unsigned vA2 = voffA, vB2 = voffB, hA2 = hA, hB2 = hB;
;             PG8_LDB(B0, 0, 0); PG8_LDB(B1, 0, 1); PG8_SCHED; PG8_LDA(At, 0, 0); PG8_STAGE(PG8_SA(1, 1), a1 + hA, voffA, hA / 2);
;             PG8_WAIT_V(8); PG8_WAIT_L(0); PG8_BAR; PG8_MMA(0, 0, At, B0); PG8_MMA(0, 1, At, B1); PG8_BAR; PG8_SCHED;
;             PG8_LDA(At, 0, 1); PG8_STAGE(PG8_SB(0, 0), b2, vB2, hB2 / 2); PG8_STAGE(PG8_SB(0, 1), b2 + hB2, vB2, hB2 / 2); PG8_STAGE(PG8_SA(0, 0), a2, vA2, hA2 / 2);
;             PG8_WAIT_V(8); PG8_WAIT_L(0); PG8_BAR; PG8_MMA(1, 0, At, B0); PG8_MMA(1, 1, At, B1); PG8_BAR; PG8_SCHED;
.LBB0_757:
	v_add_u32_e32 v128, 0x10000, v146
	ds_read_b128 v[130:133], v128
	ds_read_b128 v[134:137], v128 offset:1024
	ds_read_b128 v[138:141], v128 offset:2048
	ds_read_b128 v[148:151], v128 offset:3072
	v_add_u32_e32 v128, 0x14000, v146
	ds_read_b128 v[152:155], v128
	ds_read_b128 v[158:161], v128 offset:1024
	ds_read_b128 v[162:165], v128 offset:2048
	ds_read_b128 v[172:175], v128 offset:3072
	s_add_u32 s16, s56, 0xfffc0080
	s_addc_u32 s17, s57, -1
	s_cmp_eq_u32 s73, 12
	s_cselect_b32 s16, s40, s16
	s_cselect_b32 s17, s41, s17
	s_cselect_b32 s58, s54, s69
	s_cselect_b32 s59, s55, s72
	s_add_u32 s22, s16, 0x80
	s_addc_u32 s23, s17, 0
	ds_read_b128 v[178:181], v147
	ds_read_b128 v[182:185], v147 offset:1024
	ds_read_b128 v[186:189], v147 offset:2048
	ds_read_b128 v[190:193], v147 offset:3072
	ds_read_b128 v[194:197], v147 offset:4096
	ds_read_b128 v[198:201], v147 offset:5120
	ds_read_b128 v[202:205], v147 offset:6144
	ds_read_b128 v[206:209], v147 offset:7168
	s_mov_b32 m0, s62
	s_nop 0
	global_load_lds_dwordx4 v142, s[56:57]
	s_add_u32 s74, s56, 0x20000
	s_mov_b32 m0, s63
	s_addc_u32 s75, s57, 0
	global_load_lds_dwordx4 v142, s[74:75]
	s_waitcnt vmcnt(8) lgkmcnt(0)
	s_barrier
	s_setprio 1
	v_mfma_f32_16x16x32_bf16 v[124:127], v[130:133], v[178:181], v[124:127]
	v_mfma_f32_16x16x32_bf16 v[116:119], v[138:141], v[178:181], v[116:119]
	v_mfma_f32_16x16x32_bf16 v[108:111], v[130:133], v[186:189], v[108:111]
	v_mfma_f32_16x16x32_bf16 v[100:103], v[138:141], v[186:189], v[100:103]
	v_mfma_f32_16x16x32_bf16 v[92:95], v[130:133], v[194:197], v[92:95]
	v_mfma_f32_16x16x32_bf16 v[84:87], v[138:141], v[194:197], v[84:87]
	v_mfma_f32_16x16x32_bf16 v[76:79], v[130:133], v[202:205], v[76:79]
	v_mfma_f32_16x16x32_bf16 v[68:71], v[138:141], v[202:205], v[68:71]
	v_mfma_f32_16x16x32_bf16 v[124:127], v[134:137], v[182:185], v[124:127]
	v_mfma_f32_16x16x32_bf16 v[116:119], v[148:151], v[182:185], v[116:119]
	v_mfma_f32_16x16x32_bf16 v[108:111], v[134:137], v[190:193], v[108:111]
	v_mfma_f32_16x16x32_bf16 v[100:103], v[148:151], v[190:193], v[100:103]
	v_mfma_f32_16x16x32_bf16 v[92:95], v[134:137], v[198:201], v[92:95]
	v_mfma_f32_16x16x32_bf16 v[84:87], v[148:151], v[198:201], v[84:87]
	v_mfma_f32_16x16x32_bf16 v[76:79], v[134:137], v[206:209], v[76:79]
	v_mfma_f32_16x16x32_bf16 v[68:71], v[148:151], v[206:209], v[68:71]
	s_add_i32 s73, s73, 2
	s_add_u32 s56, s56, 0x100
	s_addc_u32 s57, s57, 0
	s_add_u32 s69, s69, 0x100
	s_addc_u32 s72, s72, 0
	v_mfma_f32_16x16x32_bf16 v[120:123], v[152:155], v[178:181], v[120:123]
	v_mfma_f32_16x16x32_bf16 v[112:115], v[162:165], v[178:181], v[112:115]
	v_mfma_f32_16x16x32_bf16 v[104:107], v[152:155], v[186:189], v[104:107]
	v_mfma_f32_16x16x32_bf16 v[96:99], v[162:165], v[186:189], v[96:99]
	v_mfma_f32_16x16x32_bf16 v[88:91], v[152:155], v[194:197], v[88:91]
	v_mfma_f32_16x16x32_bf16 v[80:83], v[162:165], v[194:197], v[80:83]
	v_mfma_f32_16x16x32_bf16 v[72:75], v[152:155], v[202:205], v[72:75]
	v_mfma_f32_16x16x32_bf16 v[64:67], v[162:165], v[202:205], v[64:67]
	v_mfma_f32_16x16x32_bf16 v[120:123], v[158:161], v[182:185], v[120:123]
	v_mfma_f32_16x16x32_bf16 v[112:115], v[172:175], v[182:185], v[112:115]
	v_mfma_f32_16x16x32_bf16 v[104:107], v[158:161], v[190:193], v[104:107]
	v_mfma_f32_16x16x32_bf16 v[96:99], v[172:175], v[190:193], v[96:99]
	v_mfma_f32_16x16x32_bf16 v[88:91], v[158:161], v[198:201], v[88:91]
	v_mfma_f32_16x16x32_bf16 v[80:83], v[172:175], v[198:201], v[80:83]
	v_mfma_f32_16x16x32_bf16 v[72:75], v[158:161], v[206:209], v[72:75]
	v_mfma_f32_16x16x32_bf16 v[64:67], v[172:175], v[206:209], v[64:67]
	s_setprio 0
	s_barrier
	s_add_u32 s74, s58, 0x20000
	ds_read_b128 v[178:181], v147 offset:16384
	ds_read_b128 v[182:185], v147 offset:17408
	ds_read_b128 v[186:189], v147 offset:18432
	ds_read_b128 v[190:193], v147 offset:19456
	ds_read_b128 v[194:197], v147 offset:20480
	ds_read_b128 v[198:201], v147 offset:21504
	ds_read_b128 v[202:205], v147 offset:22528
	ds_read_b128 v[206:209], v147 offset:23552
	s_mov_b32 m0, s20
	s_nop 0
	global_load_lds_dwordx4 v143, s[58:59]
	s_mov_b32 m0, s24
	s_addc_u32 s75, s59, 0
	global_load_lds_dwordx4 v143, s[74:75]
	s_add_u32 s74, s58, 0x40000
	s_mov_b32 m0, s33
	s_addc_u32 s75, s59, 0
	global_load_lds_dwordx4 v143, s[74:75]
	s_add_u32 s74, s58, 0x60000
	s_mov_b32 m0, s34
	s_addc_u32 s75, s59, 0
	global_load_lds_dwordx4 v143, s[74:75]
	s_mov_b32 m0, s15
	s_nop 0
	global_load_lds_dwordx4 v142, s[16:17]
	s_add_u32 s74, s16, 0x20000
	s_mov_b32 m0, s35
	s_addc_u32 s75, s17, 0
	global_load_lds_dwordx4 v142, s[74:75]
	s_waitcnt vmcnt(8) lgkmcnt(0)
	s_barrier
; #define PG8_STAGE(bufoff, gbase, voff, p64) do { _Pragma("unroll") for (int _i = 0; _i < 2; ++_i) { \
;         const char* _gb = (const char*)(gbase) + (size_t)_i * (p64); const unsigned _la = ldsbase + (unsigned)(bufoff) + (unsigned)_i * 8192u; \
;         asm volatile("s_mov_b32 m0, %0\n\ts_nop 0\n\tglobal_load_lds_dwordx4 %1, %2" :: "s"(_la), "v"(voff), "s"(_gb) : "memory"); } } while (0)
; #define PG8_LDA(dst, b, h) do { _Pragma("unroll") for (int m = 0; m < 4; ++m) _Pragma("unroll") for (int k = 0; k < 2; ++k) dst[m][k] = *(const LAS bf16x8*)(lds + PG8_SA(b, h) + aoff + m * 2048 + k * 1024); } while (0)
; #define PG8_LDB(dst, b, h) do { _Pragma("unroll") for (int n = 0; n < 2; ++n) _Pragma("unroll") for (int k = 0; k < 2; ++k) dst[n][k] = *(const LAS bf16x8*)(lds + PG8_SB(b, h) + boff + n * 2048 + k * 1024); } while (0)
; #define PG8_MMA(ai, bj, At, Bt) do { __builtin_amdgcn_s_setprio(1); _Pragma("unroll") for (int m = 0; m < 4; ++m) _Pragma("unroll") for (int n = 0; n < 2; ++n) _Pragma("unroll") for (int k = 0; k < 2; ++k) \
;         acc[ai][bj][m][n] = __builtin_amdgcn_mfma_f32_16x16x32_bf16(Bt[n][k], At[m][k], acc[ai][bj][m][n], 0, 0, 0); __builtin_amdgcn_s_setprio(0); } while (0)
; #define PG8_WAIT_V(n) asm volatile("s_waitcnt vmcnt(" #n ")" ::: "memory")
; #define PG8_WAIT_L(n) asm volatile("s_waitcnt lgkmcnt(" #n ")" ::: "memory")
; #define PG8_BAR __builtin_amdgcn_s_barrier()
; #define PG8_SCHED __builtin_amdgcn_sched_barrier(0)
; template <class Epi, class Sched>
; __device__ __forceinline__ void gemm_phase(LAS unsigned char* lds, const Sched& S, const Epi& E) {
;     ...
;             PG8_WAIT_V(8); PG8_WAIT_L(0); PG8_BAR; PG8_MMA(1, 0, At, B0); PG8_MMA(1, 1, At, B1); PG8_BAR; PG8_SCHED;
;             PG8_LDB(B0, 1, 0); PG8_LDB(B1, 1, 1); PG8_SCHED; PG8_LDA(At, 1, 0); PG8_STAGE(PG8_SA(0, 1), a2 + hA2, vA2, hA2 / 2);
;             PG8_WAIT_V(8); PG8_WAIT_L(0); PG8_BAR; PG8_MMA(0, 0, At, B0); PG8_MMA(0, 1, At, B1); PG8_BAR; PG8_SCHED;
	s_setprio 1
	v_mfma_f32_16x16x32_bf16 v[60:63], v[130:133], v[178:181], v[60:63]
	v_mfma_f32_16x16x32_bf16 v[52:55], v[138:141], v[178:181], v[52:55]
	v_mfma_f32_16x16x32_bf16 v[44:47], v[130:133], v[186:189], v[44:47]
	v_mfma_f32_16x16x32_bf16 v[36:39], v[138:141], v[186:189], v[36:39]
	v_mfma_f32_16x16x32_bf16 v[28:31], v[130:133], v[194:197], v[28:31]
	v_mfma_f32_16x16x32_bf16 v[20:23], v[138:141], v[194:197], v[20:23]
	v_mfma_f32_16x16x32_bf16 v[12:15], v[130:133], v[202:205], v[12:15]
	v_mfma_f32_16x16x32_bf16 v[4:7], v[138:141], v[202:205], v[4:7]
	v_mfma_f32_16x16x32_bf16 v[60:63], v[134:137], v[182:185], v[60:63]
	v_mfma_f32_16x16x32_bf16 v[52:55], v[148:151], v[182:185], v[52:55]
	v_mfma_f32_16x16x32_bf16 v[44:47], v[134:137], v[190:193], v[44:47]
	v_mfma_f32_16x16x32_bf16 v[36:39], v[148:151], v[190:193], v[36:39]
	v_mfma_f32_16x16x32_bf16 v[28:31], v[134:137], v[198:201], v[28:31]
	v_mfma_f32_16x16x32_bf16 v[20:23], v[148:151], v[198:201], v[20:23]
	v_mfma_f32_16x16x32_bf16 v[12:15], v[134:137], v[206:209], v[12:15]
	v_mfma_f32_16x16x32_bf16 v[4:7], v[148:151], v[206:209], v[4:7]
	v_mfma_f32_16x16x32_bf16 v[56:59], v[152:155], v[178:181], v[56:59]
	v_mfma_f32_16x16x32_bf16 v[48:51], v[162:165], v[178:181], v[48:51]
	v_mfma_f32_16x16x32_bf16 v[40:43], v[152:155], v[186:189], v[40:43]
	v_mfma_f32_16x16x32_bf16 v[32:35], v[162:165], v[186:189], v[32:35]
	v_mfma_f32_16x16x32_bf16 v[24:27], v[152:155], v[194:197], v[24:27]
	v_mfma_f32_16x16x32_bf16 v[16:19], v[162:165], v[194:197], v[16:19]
	v_mfma_f32_16x16x32_bf16 v[8:11], v[152:155], v[202:205], v[8:11]
	v_mfma_f32_16x16x32_bf16 v[0:3], v[162:165], v[202:205], v[0:3]
	v_mfma_f32_16x16x32_bf16 v[56:59], v[158:161], v[182:185], v[56:59]
	v_mfma_f32_16x16x32_bf16 v[48:51], v[172:175], v[182:185], v[48:51]
	v_mfma_f32_16x16x32_bf16 v[40:43], v[158:161], v[190:193], v[40:43]
	v_mfma_f32_16x16x32_bf16 v[32:35], v[172:175], v[190:193], v[32:35]
	v_mfma_f32_16x16x32_bf16 v[24:27], v[158:161], v[198:201], v[24:27]
	v_mfma_f32_16x16x32_bf16 v[16:19], v[172:175], v[198:201], v[16:19]
	v_mfma_f32_16x16x32_bf16 v[8:11], v[158:161], v[206:209], v[8:11]
	v_mfma_f32_16x16x32_bf16 v[0:3], v[172:175], v[206:209], v[0:3]
	s_setprio 0
	s_barrier
	v_add_u32_e32 v128, 0x18000, v146
	ds_read_b128 v[130:133], v128
	ds_read_b128 v[134:137], v128 offset:1024
	ds_read_b128 v[138:141], v128 offset:2048
	ds_read_b128 v[148:151], v128 offset:3072
	v_add_u32_e32 v128, 0x1c000, v146
	ds_read_b128 v[152:155], v128
	ds_read_b128 v[158:161], v128 offset:1024
	ds_read_b128 v[162:165], v128 offset:2048
	ds_read_b128 v[172:175], v128 offset:3072
	ds_read_b128 v[178:181], v147 offset:32768
	ds_read_b128 v[182:185], v147 offset:33792
	ds_read_b128 v[186:189], v147 offset:34816
	ds_read_b128 v[190:193], v147 offset:35840
	ds_read_b128 v[194:197], v147 offset:36864
	ds_read_b128 v[198:201], v147 offset:37888
	ds_read_b128 v[202:205], v147 offset:38912
	ds_read_b128 v[206:209], v147 offset:39936
	s_add_u32 s74, s16, 0x40000
	s_mov_b32 m0, s36
	s_addc_u32 s75, s17, 0
	global_load_lds_dwordx4 v142, s[74:75]
	s_add_u32 s74, s16, 0x60000
	s_mov_b32 m0, s37
	s_addc_u32 s75, s17, 0
	global_load_lds_dwordx4 v142, s[74:75]
	s_waitcnt vmcnt(8) lgkmcnt(0)
	s_barrier
	s_setprio 1
	v_mfma_f32_16x16x32_bf16 v[124:127], v[130:133], v[178:181], v[124:127]
	v_mfma_f32_16x16x32_bf16 v[116:119], v[138:141], v[178:181], v[116:119]
	v_mfma_f32_16x16x32_bf16 v[108:111], v[130:133], v[186:189], v[108:111]
	v_mfma_f32_16x16x32_bf16 v[100:103], v[138:141], v[186:189], v[100:103]
	v_mfma_f32_16x16x32_bf16 v[92:95], v[130:133], v[194:197], v[92:95]
	v_mfma_f32_16x16x32_bf16 v[84:87], v[138:141], v[194:197], v[84:87]
	v_mfma_f32_16x16x32_bf16 v[76:79], v[130:133], v[202:205], v[76:79]
	v_mfma_f32_16x16x32_bf16 v[68:71], v[138:141], v[202:205], v[68:71]
	v_mfma_f32_16x16x32_bf16 v[124:127], v[134:137], v[182:185], v[124:127]
	v_mfma_f32_16x16x32_bf16 v[116:119], v[148:151], v[182:185], v[116:119]
	v_mfma_f32_16x16x32_bf16 v[108:111], v[134:137], v[190:193], v[108:111]
	v_mfma_f32_16x16x32_bf16 v[100:103], v[148:151], v[190:193], v[100:103]
	v_mfma_f32_16x16x32_bf16 v[92:95], v[134:137], v[198:201], v[92:95]
	v_mfma_f32_16x16x32_bf16 v[84:87], v[148:151], v[198:201], v[84:87]
	v_mfma_f32_16x16x32_bf16 v[76:79], v[134:137], v[206:209], v[76:79]
	v_mfma_f32_16x16x32_bf16 v[68:71], v[148:151], v[206:209], v[68:71]
	v_mfma_f32_16x16x32_bf16 v[120:123], v[152:155], v[178:181], v[120:123]
	v_mfma_f32_16x16x32_bf16 v[112:115], v[162:165], v[178:181], v[112:115]
	v_mfma_f32_16x16x32_bf16 v[104:107], v[152:155], v[186:189], v[104:107]
	v_mfma_f32_16x16x32_bf16 v[96:99], v[162:165], v[186:189], v[96:99]
	v_mfma_f32_16x16x32_bf16 v[88:91], v[152:155], v[194:197], v[88:91]
	v_mfma_f32_16x16x32_bf16 v[80:83], v[162:165], v[194:197], v[80:83]
	v_mfma_f32_16x16x32_bf16 v[72:75], v[152:155], v[202:205], v[72:75]
	v_mfma_f32_16x16x32_bf16 v[64:67], v[162:165], v[202:205], v[64:67]
	v_mfma_f32_16x16x32_bf16 v[120:123], v[158:161], v[182:185], v[120:123]
	v_mfma_f32_16x16x32_bf16 v[112:115], v[172:175], v[182:185], v[112:115]
	v_mfma_f32_16x16x32_bf16 v[104:107], v[158:161], v[190:193], v[104:107]
	v_mfma_f32_16x16x32_bf16 v[96:99], v[172:175], v[190:193], v[96:99]
	v_mfma_f32_16x16x32_bf16 v[88:91], v[158:161], v[198:201], v[88:91]
	v_mfma_f32_16x16x32_bf16 v[80:83], v[172:175], v[198:201], v[80:83]
	v_mfma_f32_16x16x32_bf16 v[72:75], v[158:161], v[206:209], v[72:75]
	v_mfma_f32_16x16x32_bf16 v[64:67], v[172:175], v[206:209], v[64:67]
	s_setprio 0
	s_barrier
; #define PG8_STAGE(bufoff, gbase, voff, p64) do { _Pragma("unroll") for (int _i = 0; _i < 2; ++_i) { \
;         const char* _gb = (const char*)(gbase) + (size_t)_i * (p64); const unsigned _la = ldsbase + (unsigned)(bufoff) + (unsigned)_i * 8192u; \
;         asm volatile("s_mov_b32 m0, %0\n\ts_nop 0\n\tglobal_load_lds_dwordx4 %1, %2" :: "s"(_la), "v"(voff), "s"(_gb) : "memory"); } } while (0)
; #define PG8_LDA(dst, b, h) do { _Pragma("unroll") for (int m = 0; m < 4; ++m) _Pragma("unroll") for (int k = 0; k < 2; ++k) dst[m][k] = *(const LAS bf16x8*)(lds + PG8_SA(b, h) + aoff + m * 2048 + k * 1024); } while (0)
; #define PG8_MMA(ai, bj, At, Bt) do { __builtin_amdgcn_s_setprio(1); _Pragma("unroll") for (int m = 0; m < 4; ++m) _Pragma("unroll") for (int n = 0; n < 2; ++n) _Pragma("unroll") for (int k = 0; k < 2; ++k) \
;         acc[ai][bj][m][n] = __builtin_amdgcn_mfma_f32_16x16x32_bf16(Bt[n][k], At[m][k], acc[ai][bj][m][n], 0, 0, 0); __builtin_amdgcn_s_setprio(0); } while (0)
; #define PG8_WAIT_V(n) asm volatile("s_waitcnt vmcnt(" #n ")" ::: "memory")
; #define PG8_WAIT_L(n) asm volatile("s_waitcnt lgkmcnt(" #n ")" ::: "memory")
; #define PG8_BAR __builtin_amdgcn_s_barrier()
; #define PG8_SCHED __builtin_amdgcn_sched_barrier(0)
; template <class Epi, class Sched>
; __device__ __forceinline__ void gemm_phase(LAS unsigned char* lds, const Sched& S, const Epi& E) {
;     ...
;             PG8_LDA(At, 1, 1); PG8_STAGE(PG8_SB(1, 0), b3, vB2, hB2 / 2); PG8_STAGE(PG8_SB(1, 1), b3 + hB2, vB2, hB2 / 2); PG8_STAGE(PG8_SA(1, 0), a3, vA2, hA2 / 2);
;             PG8_WAIT_V(8); PG8_WAIT_L(0); PG8_BAR; PG8_MMA(1, 0, At, B0); PG8_MMA(1, 1, At, B1); PG8_BAR; PG8_SCHED;
;         }
;         if (wr == 0) PG8_BAR;
	s_add_u32 s74, s58, 0x80
	s_addc_u32 s75, s59, 0
	ds_read_b128 v[178:181], v147 offset:49152
	ds_read_b128 v[182:185], v147 offset:50176
	ds_read_b128 v[186:189], v147 offset:51200
	ds_read_b128 v[190:193], v147 offset:52224
	ds_read_b128 v[194:197], v147 offset:53248
	ds_read_b128 v[198:201], v147 offset:54272
	ds_read_b128 v[202:205], v147 offset:55296
	ds_read_b128 v[206:209], v147 offset:56320
	s_mov_b32 m0, s45
	s_nop 0
	global_load_lds_dwordx4 v143, s[74:75]
	s_add_u32 s74, s58, 0x20080
	s_mov_b32 m0, s47
	s_addc_u32 s75, s59, 0
	global_load_lds_dwordx4 v143, s[74:75]
	s_add_u32 s74, s58, 0x40080
	s_mov_b32 m0, s51
	s_addc_u32 s75, s59, 0
	global_load_lds_dwordx4 v143, s[74:75]
	s_add_u32 s58, s58, 0x60080
	s_mov_b32 m0, s61
	s_addc_u32 s59, s59, 0
	global_load_lds_dwordx4 v143, s[58:59]
	s_mov_b32 m0, s48
	s_nop 0
	global_load_lds_dwordx4 v142, s[22:23]
	s_add_u32 s16, s16, 0x20080
	s_mov_b32 m0, s50
	s_addc_u32 s17, s17, 0
	global_load_lds_dwordx4 v142, s[16:17]
	s_waitcnt vmcnt(8) lgkmcnt(0)
	s_barrier
	s_setprio 1
	v_mfma_f32_16x16x32_bf16 v[60:63], v[130:133], v[178:181], v[60:63]
	v_mfma_f32_16x16x32_bf16 v[52:55], v[138:141], v[178:181], v[52:55]
	v_mfma_f32_16x16x32_bf16 v[44:47], v[130:133], v[186:189], v[44:47]
	v_mfma_f32_16x16x32_bf16 v[36:39], v[138:141], v[186:189], v[36:39]
	v_mfma_f32_16x16x32_bf16 v[28:31], v[130:133], v[194:197], v[28:31]
	v_mfma_f32_16x16x32_bf16 v[20:23], v[138:141], v[194:197], v[20:23]
	v_mfma_f32_16x16x32_bf16 v[12:15], v[130:133], v[202:205], v[12:15]
	v_mfma_f32_16x16x32_bf16 v[4:7], v[138:141], v[202:205], v[4:7]
	v_mfma_f32_16x16x32_bf16 v[60:63], v[134:137], v[182:185], v[60:63]
	v_mfma_f32_16x16x32_bf16 v[52:55], v[148:151], v[182:185], v[52:55]
	v_mfma_f32_16x16x32_bf16 v[44:47], v[134:137], v[190:193], v[44:47]
	v_mfma_f32_16x16x32_bf16 v[36:39], v[148:151], v[190:193], v[36:39]
	v_mfma_f32_16x16x32_bf16 v[28:31], v[134:137], v[198:201], v[28:31]
	v_mfma_f32_16x16x32_bf16 v[20:23], v[148:151], v[198:201], v[20:23]
	v_mfma_f32_16x16x32_bf16 v[12:15], v[134:137], v[206:209], v[12:15]
	v_mfma_f32_16x16x32_bf16 v[4:7], v[148:151], v[206:209], v[4:7]
	v_mfma_f32_16x16x32_bf16 v[56:59], v[152:155], v[178:181], v[56:59]
	v_mfma_f32_16x16x32_bf16 v[48:51], v[162:165], v[178:181], v[48:51]
	v_mfma_f32_16x16x32_bf16 v[40:43], v[152:155], v[186:189], v[40:43]
	v_mfma_f32_16x16x32_bf16 v[32:35], v[162:165], v[186:189], v[32:35]
	v_mfma_f32_16x16x32_bf16 v[24:27], v[152:155], v[194:197], v[24:27]
	v_mfma_f32_16x16x32_bf16 v[16:19], v[162:165], v[194:197], v[16:19]
	v_mfma_f32_16x16x32_bf16 v[8:11], v[152:155], v[202:205], v[8:11]
	v_mfma_f32_16x16x32_bf16 v[0:3], v[162:165], v[202:205], v[0:3]
	v_mfma_f32_16x16x32_bf16 v[56:59], v[158:161], v[182:185], v[56:59]
	v_mfma_f32_16x16x32_bf16 v[48:51], v[172:175], v[182:185], v[48:51]
	v_mfma_f32_16x16x32_bf16 v[40:43], v[158:161], v[190:193], v[40:43]
	v_mfma_f32_16x16x32_bf16 v[32:35], v[172:175], v[190:193], v[32:35]
	v_mfma_f32_16x16x32_bf16 v[24:27], v[158:161], v[198:201], v[24:27]
	v_mfma_f32_16x16x32_bf16 v[16:19], v[172:175], v[198:201], v[16:19]
	v_mfma_f32_16x16x32_bf16 v[8:11], v[158:161], v[206:209], v[8:11]
	v_mfma_f32_16x16x32_bf16 v[0:3], v[172:175], v[206:209], v[0:3]
	s_setprio 0
	s_barrier
	s_cmp_gt_u32 s73, 13
	s_cbranch_scc0 .LBB0_757
	s_and_b64 vcc, exec, s[38:39]
	s_cbranch_vccz .LBB0_760
	s_barrier

; #define PG8_STAGE(bufoff, gbase, voff, p64) do { _Pragma("unroll") for (int _i = 0; _i < 2; ++_i) { \
;         const char* _gb = (const char*)(gbase) + (size_t)_i * (p64); const unsigned _la = ldsbase + (unsigned)(bufoff) + (unsigned)_i * 8192u; \
;         asm volatile("s_mov_b32 m0, %0\n\ts_nop 0\n\tglobal_load_lds_dwordx4 %1, %2" :: "s"(_la), "v"(voff), "s"(_gb) : "memory"); } } while (0)
; #define PG8_LDA(dst, b, h) do { _Pragma("unroll") for (int m = 0; m < 4; ++m) _Pragma("unroll") for (int k = 0; k < 2; ++k) dst[m][k] = *(const LAS bf16x8*)(lds + PG8_SA(b, h) + aoff + m * 2048 + k * 1024); } while (0)
; #define PG8_LDB(dst, b, h) do { _Pragma("unroll") for (int n = 0; n < 2; ++n) _Pragma("unroll") for (int k = 0; k < 2; ++k) dst[n][k] = *(const LAS bf16x8*)(lds + PG8_SB(b, h) + boff + n * 2048 + k * 1024); } while (0)
; #define PG8_MMA(ai, bj, At, Bt) do { __builtin_amdgcn_s_setprio(1); _Pragma("unroll") for (int m = 0; m < 4; ++m) _Pragma("unroll") for (int n = 0; n < 2; ++n) _Pragma("unroll") for (int k = 0; k < 2; ++k) \
;         acc[ai][bj][m][n] = __builtin_amdgcn_mfma_f32_16x16x32_bf16(Bt[n][k], At[m][k], acc[ai][bj][m][n], 0, 0, 0); __builtin_amdgcn_s_setprio(0); } while (0)
; #define PG8_WAIT_V(n) asm volatile("s_waitcnt vmcnt(" #n ")" ::: "memory")
; template <class Epi, class Sched>
; __device__ __forceinline__ void gemm_phase(LAS unsigned char* lds, const Sched& S, const Epi& E) {
;     ...
;         for (int t = 0; t < nt; t += 2) {
;             const bool last = (t == nt - 2);
;             const char* a1 = cA + (size_t)(t + 1) * kstep;
;             const char* a2 = last ? nA : cA + (size_t)(t + 2) * kstep; const char* b2 = last ? nB : cB + (size_t)(t + 2) * kstep;
;             const char* a3 = a2 + kstep; const char* b3 = b2 + kstep;
;             const unsigned vA2 = voffA, vB2 = voffB, hA2 = hA, hB2 = hB;
;             PG8_LDB(B0, 0, 0); PG8_LDB(B1, 0, 1); PG8_SCHED; PG8_LDA(At, 0, 0); PG8_STAGE(PG8_SA(1, 1), a1 + hA, voffA, hA / 2);
;             PG8_WAIT_V(8); PG8_WAIT_L(0); PG8_BAR; PG8_MMA(0, 0, At, B0); PG8_MMA(0, 1, At, B1); PG8_BAR; PG8_SCHED;
;             PG8_LDA(At, 0, 1); PG8_STAGE(PG8_SB(0, 0), b2, vB2, hB2 / 2); PG8_STAGE(PG8_SB(0, 1), b2 + hB2, vB2, hB2 / 2); PG8_STAGE(PG8_SA(0, 0), a2, vA2, hA2 / 2);
;             PG8_WAIT_V(8); PG8_WAIT_L(0); PG8_BAR; PG8_MMA(1, 0, At, B0); PG8_MMA(1, 1, At, B1); PG8_BAR; PG8_SCHED;
.LBB0_831:
	v_add_u32_e32 v142, 0x10000, v147
	v_add_u32_e32 v143, 0x14000, v147
	ds_read_b128 v[0:3], v142
	ds_read_b128 v[4:7], v142 offset:1024
	s_waitcnt vmcnt(3)
	ds_read_b128 v[8:11], v142 offset:2048
	s_waitcnt vmcnt(2)
	ds_read_b128 v[12:15], v142 offset:3072
	s_waitcnt vmcnt(1)
	ds_read_b128 v[16:19], v143
	s_waitcnt vmcnt(0)
	ds_read_b128 v[20:23], v143 offset:1024
	ds_read_b128 v[24:27], v143 offset:2048
	ds_read_b128 v[28:31], v143 offset:3072
	s_and_b64 s[16:17], s[6:7], exec
	s_cselect_b32 s17, s23, s89
	s_cselect_b32 s16, s22, s88
	s_add_u32 s30, s88, 0x100
	s_addc_u32 s31, s89, 0
	ds_read_b128 v[32:35], v148
	ds_read_b128 v[36:39], v148 offset:1024
	ds_read_b128 v[40:43], v148 offset:2048
	ds_read_b128 v[44:47], v148 offset:3072
	ds_read_b128 v[48:51], v148 offset:4096
	ds_read_b128 v[52:55], v148 offset:5120
	ds_read_b128 v[56:59], v148 offset:6144
	ds_read_b128 v[60:63], v148 offset:7168
	s_mov_b32 m0, s69
	s_nop 0
	global_load_lds_dwordx4 v144, s[94:95]
	s_mov_b32 m0, s24
	s_nop 0
	global_load_lds_dwordx4 v144, s[96:97]
	s_waitcnt vmcnt(8) lgkmcnt(0)
	s_barrier
	s_setprio 1
	v_mfma_f32_16x16x32_bf16 v[64:67], v[0:3], v[32:35], 0
	v_mfma_f32_16x16x32_bf16 v[68:71], v[8:11], v[32:35], 0
	v_mfma_f32_16x16x32_bf16 v[72:75], v[0:3], v[40:43], 0
	v_mfma_f32_16x16x32_bf16 v[76:79], v[8:11], v[40:43], 0
	v_mfma_f32_16x16x32_bf16 v[80:83], v[0:3], v[48:51], 0
	v_mfma_f32_16x16x32_bf16 v[84:87], v[8:11], v[48:51], 0
	v_mfma_f32_16x16x32_bf16 v[88:91], v[0:3], v[56:59], 0
	v_mfma_f32_16x16x32_bf16 v[92:95], v[8:11], v[56:59], 0
	v_mfma_f32_16x16x32_bf16 v[64:67], v[4:7], v[36:39], v[64:67]
	v_mfma_f32_16x16x32_bf16 v[68:71], v[12:15], v[36:39], v[68:71]
	v_mfma_f32_16x16x32_bf16 v[72:75], v[4:7], v[44:47], v[72:75]
	v_mfma_f32_16x16x32_bf16 v[76:79], v[12:15], v[44:47], v[76:79]
	v_mfma_f32_16x16x32_bf16 v[80:83], v[4:7], v[52:55], v[80:83]
	v_mfma_f32_16x16x32_bf16 v[84:87], v[12:15], v[52:55], v[84:87]
	v_mfma_f32_16x16x32_bf16 v[88:91], v[4:7], v[60:63], v[88:91]
	v_mfma_f32_16x16x32_bf16 v[92:95], v[12:15], v[60:63], v[92:95]
	v_mfma_f32_16x16x32_bf16 v[96:99], v[16:19], v[32:35], 0
	v_mfma_f32_16x16x32_bf16 v[32:35], v[24:27], v[32:35], 0
	v_mfma_f32_16x16x32_bf16 v[96:99], v[20:23], v[36:39], v[96:99]
	v_mfma_f32_16x16x32_bf16 v[32:35], v[28:31], v[36:39], v[32:35]
	v_mfma_f32_16x16x32_bf16 v[36:39], v[16:19], v[40:43], 0
	v_mfma_f32_16x16x32_bf16 v[40:43], v[24:27], v[40:43], 0
	v_mfma_f32_16x16x32_bf16 v[36:39], v[20:23], v[44:47], v[36:39]
	v_mfma_f32_16x16x32_bf16 v[40:43], v[28:31], v[44:47], v[40:43]
	v_mfma_f32_16x16x32_bf16 v[44:47], v[16:19], v[48:51], 0
	v_mfma_f32_16x16x32_bf16 v[48:51], v[24:27], v[48:51], 0
	v_mfma_f32_16x16x32_bf16 v[44:47], v[20:23], v[52:55], v[44:47]
	v_mfma_f32_16x16x32_bf16 v[48:51], v[28:31], v[52:55], v[48:51]
	v_mfma_f32_16x16x32_bf16 v[52:55], v[16:19], v[56:59], 0
	v_mfma_f32_16x16x32_bf16 v[56:59], v[24:27], v[56:59], 0
	v_mfma_f32_16x16x32_bf16 v[52:55], v[20:23], v[60:63], v[52:55]
	v_mfma_f32_16x16x32_bf16 v[56:59], v[28:31], v[60:63], v[56:59]
	s_setprio 0
	s_barrier
	ds_read_b128 v[60:63], v148 offset:16384
	ds_read_b128 v[100:103], v148 offset:17408
	ds_read_b128 v[104:107], v148 offset:18432
	ds_read_b128 v[108:111], v148 offset:19456
	ds_read_b128 v[112:115], v148 offset:20480
	ds_read_b128 v[116:119], v148 offset:21504
	ds_read_b128 v[120:123], v148 offset:22528
	ds_read_b128 v[124:127], v148 offset:23552
	s_mov_b32 m0, s12
	s_nop 0
	global_load_lds_dwordx4 v128, s[30:31]
	s_add_u32 s30, s88, 0x20100
	s_mov_b32 m0, s44
	s_addc_u32 s31, s89, 0
	global_load_lds_dwordx4 v128, s[30:31]
	s_add_u32 s30, s88, 0x40100
	s_mov_b32 m0, s42
	s_addc_u32 s31, s89, 0
	global_load_lds_dwordx4 v128, s[30:31]
	s_add_u32 s30, s88, 0x60100
	s_mov_b32 m0, s48
	s_addc_u32 s31, s89, 0
	global_load_lds_dwordx4 v128, s[30:31]
	s_mov_b32 m0, s47
	s_nop 0
	global_load_lds_dwordx4 v144, s[90:91]
	s_mov_b32 m0, s61
	s_nop 0
	global_load_lds_dwordx4 v144, s[38:39]
	s_waitcnt vmcnt(8) lgkmcnt(0)
	s_barrier
	s_setprio 1
	v_mfma_f32_16x16x32_bf16 v[130:133], v[0:3], v[60:63], 0
	v_mfma_f32_16x16x32_bf16 v[138:141], v[0:3], v[104:107], 0
	v_mfma_f32_16x16x32_bf16 v[158:161], v[0:3], v[112:115], 0
	v_mfma_f32_16x16x32_bf16 v[0:3], v[0:3], v[120:123], 0
	v_mfma_f32_16x16x32_bf16 v[130:133], v[4:7], v[100:103], v[130:133]
	v_mfma_f32_16x16x32_bf16 v[138:141], v[4:7], v[108:111], v[138:141]
	v_mfma_f32_16x16x32_bf16 v[158:161], v[4:7], v[116:119], v[158:161]
	v_mfma_f32_16x16x32_bf16 v[0:3], v[4:7], v[124:127], v[0:3]
	v_mfma_f32_16x16x32_bf16 v[4:7], v[8:11], v[120:123], 0
	v_mfma_f32_16x16x32_bf16 v[134:137], v[8:11], v[60:63], 0
	v_mfma_f32_16x16x32_bf16 v[150:153], v[8:11], v[104:107], 0
	v_mfma_f32_16x16x32_bf16 v[162:165], v[8:11], v[112:115], 0
	v_mfma_f32_16x16x32_bf16 v[4:7], v[12:15], v[124:127], v[4:7]
	v_mfma_f32_16x16x32_bf16 v[134:137], v[12:15], v[100:103], v[134:137]
	v_mfma_f32_16x16x32_bf16 v[150:153], v[12:15], v[108:111], v[150:153]
	v_mfma_f32_16x16x32_bf16 v[162:165], v[12:15], v[116:119], v[162:165]
	v_mfma_f32_16x16x32_bf16 v[8:11], v[16:19], v[60:63], 0
	v_mfma_f32_16x16x32_bf16 v[12:15], v[24:27], v[60:63], 0
	v_mfma_f32_16x16x32_bf16 v[8:11], v[20:23], v[100:103], v[8:11]
	v_mfma_f32_16x16x32_bf16 v[12:15], v[28:31], v[100:103], v[12:15]
	v_mfma_f32_16x16x32_bf16 v[60:63], v[16:19], v[104:107], 0
	v_mfma_f32_16x16x32_bf16 v[100:103], v[24:27], v[104:107], 0
	v_mfma_f32_16x16x32_bf16 v[104:107], v[16:19], v[112:115], 0
	v_mfma_f32_16x16x32_bf16 v[16:19], v[16:19], v[120:123], 0
	v_mfma_f32_16x16x32_bf16 v[60:63], v[20:23], v[108:111], v[60:63]
	v_mfma_f32_16x16x32_bf16 v[100:103], v[28:31], v[108:111], v[100:103]
	v_mfma_f32_16x16x32_bf16 v[104:107], v[20:23], v[116:119], v[104:107]
	v_mfma_f32_16x16x32_bf16 v[108:111], v[24:27], v[112:115], 0
	v_mfma_f32_16x16x32_bf16 v[16:19], v[20:23], v[124:127], v[16:19]
	v_mfma_f32_16x16x32_bf16 v[20:23], v[24:27], v[120:123], 0
	v_mfma_f32_16x16x32_bf16 v[108:111], v[28:31], v[116:119], v[108:111]
	v_mfma_f32_16x16x32_bf16 v[20:23], v[28:31], v[124:127], v[20:23]
	s_setprio 0
	s_barrier
; #define PG8_STAGE(bufoff, gbase, voff, p64) do { _Pragma("unroll") for (int _i = 0; _i < 2; ++_i) { \
;         const char* _gb = (const char*)(gbase) + (size_t)_i * (p64); const unsigned _la = ldsbase + (unsigned)(bufoff) + (unsigned)_i * 8192u; \
;         asm volatile("s_mov_b32 m0, %0\n\ts_nop 0\n\tglobal_load_lds_dwordx4 %1, %2" :: "s"(_la), "v"(voff), "s"(_gb) : "memory"); } } while (0)
; #define PG8_LDA(dst, b, h) do { _Pragma("unroll") for (int m = 0; m < 4; ++m) _Pragma("unroll") for (int k = 0; k < 2; ++k) dst[m][k] = *(const LAS bf16x8*)(lds + PG8_SA(b, h) + aoff + m * 2048 + k * 1024); } while (0)
; #define PG8_LDB(dst, b, h) do { _Pragma("unroll") for (int n = 0; n < 2; ++n) _Pragma("unroll") for (int k = 0; k < 2; ++k) dst[n][k] = *(const LAS bf16x8*)(lds + PG8_SB(b, h) + boff + n * 2048 + k * 1024); } while (0)
; #define PG8_MMA(ai, bj, At, Bt) do { __builtin_amdgcn_s_setprio(1); _Pragma("unroll") for (int m = 0; m < 4; ++m) _Pragma("unroll") for (int n = 0; n < 2; ++n) _Pragma("unroll") for (int k = 0; k < 2; ++k) \
;         acc[ai][bj][m][n] = __builtin_amdgcn_mfma_f32_16x16x32_bf16(Bt[n][k], At[m][k], acc[ai][bj][m][n], 0, 0, 0); __builtin_amdgcn_s_setprio(0); } while (0)
; #define PG8_WAIT_V(n) asm volatile("s_waitcnt vmcnt(" #n ")" ::: "memory")
; #define PG8_WAIT_L(n) asm volatile("s_waitcnt lgkmcnt(" #n ")" ::: "memory")
; #define PG8_BAR __builtin_amdgcn_s_barrier()
; #define PG8_SCHED __builtin_amdgcn_sched_barrier(0)
; template <class Epi, class Sched>
; __device__ __forceinline__ void gemm_phase(LAS unsigned char* lds, const Sched& S, const Epi& E) {
;     ...
;             PG8_LDB(B0, 1, 0); PG8_LDB(B1, 1, 1); PG8_SCHED; PG8_LDA(At, 1, 0); PG8_STAGE(PG8_SA(0, 1), a2 + hA2, vA2, hA2 / 2);
;             PG8_WAIT_V(8); PG8_WAIT_L(0); PG8_BAR; PG8_MMA(0, 0, At, B0); PG8_MMA(0, 1, At, B1); PG8_BAR; PG8_SCHED;
;             PG8_LDA(At, 1, 1); PG8_STAGE(PG8_SB(1, 0), b3, vB2, hB2 / 2); PG8_STAGE(PG8_SB(1, 1), b3 + hB2, vB2, hB2 / 2); PG8_STAGE(PG8_SA(1, 0), a3, vA2, hA2 / 2);
;             PG8_WAIT_V(8); PG8_WAIT_L(0); PG8_BAR; PG8_MMA(1, 0, At, B0); PG8_MMA(1, 1, At, B1); PG8_BAR; PG8_SCHED;
	v_add_u32_e32 v149, 0x18000, v147
	v_add_u32_e32 v154, 0x1c000, v147
	ds_read_b128 v[24:27], v149
	ds_read_b128 v[28:31], v149 offset:1024
	ds_read_b128 v[112:115], v149 offset:2048
	ds_read_b128 v[116:119], v149 offset:3072
	ds_read_b128 v[120:123], v154
	ds_read_b128 v[124:127], v154 offset:1024
	ds_read_b128 v[172:175], v154 offset:2048
	ds_read_b128 v[178:181], v154 offset:3072
	ds_read_b128 v[182:185], v148 offset:32768
	ds_read_b128 v[186:189], v148 offset:33792
	ds_read_b128 v[190:193], v148 offset:34816
	ds_read_b128 v[194:197], v148 offset:35840
	ds_read_b128 v[198:201], v148 offset:36864
	ds_read_b128 v[202:205], v148 offset:37888
	ds_read_b128 v[206:209], v148 offset:38912
	ds_read_b128 v[210:213], v148 offset:39936
	s_mov_b32 m0, s14
	s_nop 0
	global_load_lds_dwordx4 v144, s[40:41]
	s_mov_b32 m0, s15
	s_nop 0
	global_load_lds_dwordx4 v144, s[56:57]
	s_waitcnt vmcnt(8) lgkmcnt(0)
	s_barrier
	s_setprio 1
	v_mfma_f32_16x16x32_bf16 v[64:67], v[24:27], v[182:185], v[64:67]
	v_mfma_f32_16x16x32_bf16 v[68:71], v[112:115], v[182:185], v[68:71]
	v_mfma_f32_16x16x32_bf16 v[72:75], v[24:27], v[190:193], v[72:75]
	v_mfma_f32_16x16x32_bf16 v[76:79], v[112:115], v[190:193], v[76:79]
	v_mfma_f32_16x16x32_bf16 v[80:83], v[24:27], v[198:201], v[80:83]
	v_mfma_f32_16x16x32_bf16 v[84:87], v[112:115], v[198:201], v[84:87]
	v_mfma_f32_16x16x32_bf16 v[88:91], v[24:27], v[206:209], v[88:91]
	v_mfma_f32_16x16x32_bf16 v[92:95], v[112:115], v[206:209], v[92:95]
	v_mfma_f32_16x16x32_bf16 v[64:67], v[28:31], v[186:189], v[64:67]
	v_mfma_f32_16x16x32_bf16 v[68:71], v[116:119], v[186:189], v[68:71]
	v_mfma_f32_16x16x32_bf16 v[72:75], v[28:31], v[194:197], v[72:75]
	v_mfma_f32_16x16x32_bf16 v[76:79], v[116:119], v[194:197], v[76:79]
	v_mfma_f32_16x16x32_bf16 v[80:83], v[28:31], v[202:205], v[80:83]
	v_mfma_f32_16x16x32_bf16 v[84:87], v[116:119], v[202:205], v[84:87]
	v_mfma_f32_16x16x32_bf16 v[88:91], v[28:31], v[210:213], v[88:91]
	v_mfma_f32_16x16x32_bf16 v[92:95], v[116:119], v[210:213], v[92:95]
	v_mfma_f32_16x16x32_bf16 v[96:99], v[120:123], v[182:185], v[96:99]
	v_mfma_f32_16x16x32_bf16 v[32:35], v[172:175], v[182:185], v[32:35]
	v_mfma_f32_16x16x32_bf16 v[36:39], v[120:123], v[190:193], v[36:39]
	v_mfma_f32_16x16x32_bf16 v[40:43], v[172:175], v[190:193], v[40:43]
	v_mfma_f32_16x16x32_bf16 v[44:47], v[120:123], v[198:201], v[44:47]
	v_mfma_f32_16x16x32_bf16 v[48:51], v[172:175], v[198:201], v[48:51]
	v_mfma_f32_16x16x32_bf16 v[52:55], v[120:123], v[206:209], v[52:55]
	v_mfma_f32_16x16x32_bf16 v[56:59], v[172:175], v[206:209], v[56:59]
	v_mfma_f32_16x16x32_bf16 v[96:99], v[124:127], v[186:189], v[96:99]
	v_mfma_f32_16x16x32_bf16 v[32:35], v[178:181], v[186:189], v[32:35]
	v_mfma_f32_16x16x32_bf16 v[36:39], v[124:127], v[194:197], v[36:39]
	v_mfma_f32_16x16x32_bf16 v[40:43], v[178:181], v[194:197], v[40:43]
	v_mfma_f32_16x16x32_bf16 v[44:47], v[124:127], v[202:205], v[44:47]
	v_mfma_f32_16x16x32_bf16 v[48:51], v[178:181], v[202:205], v[48:51]
	v_mfma_f32_16x16x32_bf16 v[52:55], v[124:127], v[210:213], v[52:55]
	v_mfma_f32_16x16x32_bf16 v[56:59], v[178:181], v[210:213], v[56:59]
	s_setprio 0
	s_barrier
	s_add_u32 s30, s88, 0x180
	s_addc_u32 s31, s89, 0
	ds_read_b128 v[182:185], v148 offset:49152
	ds_read_b128 v[186:189], v148 offset:50176
	ds_read_b128 v[190:193], v148 offset:51200
	ds_read_b128 v[194:197], v148 offset:52224
	ds_read_b128 v[198:201], v148 offset:53248
	ds_read_b128 v[202:205], v148 offset:54272
	ds_read_b128 v[206:209], v148 offset:55296
	ds_read_b128 v[210:213], v148 offset:56320
	s_mov_b32 m0, s65
	s_nop 0
	global_load_lds_dwordx4 v128, s[30:31]
	s_add_u32 s30, s88, 0x20180
	s_mov_b32 m0, s66
	s_addc_u32 s31, s89, 0
	global_load_lds_dwordx4 v128, s[30:31]
	s_add_u32 s30, s88, 0x40180
	s_mov_b32 m0, s36
	s_addc_u32 s31, s89, 0
	global_load_lds_dwordx4 v128, s[30:31]
	s_add_u32 s30, s88, 0x60180
	s_mov_b32 m0, s37
	s_addc_u32 s31, s89, 0
	global_load_lds_dwordx4 v128, s[30:31]
	s_mov_b32 m0, s67
	s_nop 0
	global_load_lds_dwordx4 v144, s[92:93]
	s_mov_b32 m0, s45
	s_nop 0
	global_load_lds_dwordx4 v144, s[62:63]
	s_waitcnt vmcnt(8) lgkmcnt(0)
	s_barrier
	s_setprio 1
	v_mfma_f32_16x16x32_bf16 v[0:3], v[24:27], v[206:209], v[0:3]
	v_mfma_f32_16x16x32_bf16 v[4:7], v[112:115], v[206:209], v[4:7]
	v_mfma_f32_16x16x32_bf16 v[130:133], v[24:27], v[182:185], v[130:133]
	v_mfma_f32_16x16x32_bf16 v[134:137], v[112:115], v[182:185], v[134:137]
	v_mfma_f32_16x16x32_bf16 v[138:141], v[24:27], v[190:193], v[138:141]
	v_mfma_f32_16x16x32_bf16 v[150:153], v[112:115], v[190:193], v[150:153]
	v_mfma_f32_16x16x32_bf16 v[158:161], v[24:27], v[198:201], v[158:161]
	v_mfma_f32_16x16x32_bf16 v[162:165], v[112:115], v[198:201], v[162:165]
	v_mfma_f32_16x16x32_bf16 v[0:3], v[28:31], v[210:213], v[0:3]
	v_mfma_f32_16x16x32_bf16 v[4:7], v[116:119], v[210:213], v[4:7]
	v_mfma_f32_16x16x32_bf16 v[130:133], v[28:31], v[186:189], v[130:133]
	v_mfma_f32_16x16x32_bf16 v[134:137], v[116:119], v[186:189], v[134:137]
	v_mfma_f32_16x16x32_bf16 v[138:141], v[28:31], v[194:197], v[138:141]
	v_mfma_f32_16x16x32_bf16 v[150:153], v[116:119], v[194:197], v[150:153]
	v_mfma_f32_16x16x32_bf16 v[158:161], v[28:31], v[202:205], v[158:161]
	v_mfma_f32_16x16x32_bf16 v[162:165], v[116:119], v[202:205], v[162:165]
	v_mfma_f32_16x16x32_bf16 v[8:11], v[120:123], v[182:185], v[8:11]
	v_mfma_f32_16x16x32_bf16 v[12:15], v[172:175], v[182:185], v[12:15]
	v_mfma_f32_16x16x32_bf16 v[24:27], v[120:123], v[190:193], v[60:63]
	v_mfma_f32_16x16x32_bf16 v[28:31], v[172:175], v[190:193], v[100:103]
	v_mfma_f32_16x16x32_bf16 v[60:63], v[120:123], v[198:201], v[104:107]
	v_mfma_f32_16x16x32_bf16 v[100:103], v[172:175], v[198:201], v[108:111]
	v_mfma_f32_16x16x32_bf16 v[16:19], v[120:123], v[206:209], v[16:19]
	v_mfma_f32_16x16x32_bf16 v[20:23], v[172:175], v[206:209], v[20:23]
	v_mfma_f32_16x16x32_bf16 v[8:11], v[124:127], v[186:189], v[8:11]
	v_mfma_f32_16x16x32_bf16 v[12:15], v[178:181], v[186:189], v[12:15]
	v_mfma_f32_16x16x32_bf16 v[24:27], v[124:127], v[194:197], v[24:27]
	v_mfma_f32_16x16x32_bf16 v[28:31], v[178:181], v[194:197], v[28:31]
	v_mfma_f32_16x16x32_bf16 v[60:63], v[124:127], v[202:205], v[60:63]
	v_mfma_f32_16x16x32_bf16 v[100:103], v[178:181], v[202:205], v[100:103]
	v_mfma_f32_16x16x32_bf16 v[16:19], v[124:127], v[210:213], v[16:19]
	v_mfma_f32_16x16x32_bf16 v[20:23], v[178:181], v[210:213], v[20:23]
	s_setprio 0
	s_barrier
; #define PG8_STAGE(bufoff, gbase, voff, p64) do { _Pragma("unroll") for (int _i = 0; _i < 2; ++_i) { \
;         const char* _gb = (const char*)(gbase) + (size_t)_i * (p64); const unsigned _la = ldsbase + (unsigned)(bufoff) + (unsigned)_i * 8192u; \
;         asm volatile("s_mov_b32 m0, %0\n\ts_nop 0\n\tglobal_load_lds_dwordx4 %1, %2" :: "s"(_la), "v"(voff), "s"(_gb) : "memory"); } } while (0)
; #define PG8_LDA(dst, b, h) do { _Pragma("unroll") for (int m = 0; m < 4; ++m) _Pragma("unroll") for (int k = 0; k < 2; ++k) dst[m][k] = *(const LAS bf16x8*)(lds + PG8_SA(b, h) + aoff + m * 2048 + k * 1024); } while (0)
; #define PG8_LDB(dst, b, h) do { _Pragma("unroll") for (int n = 0; n < 2; ++n) _Pragma("unroll") for (int k = 0; k < 2; ++k) dst[n][k] = *(const LAS bf16x8*)(lds + PG8_SB(b, h) + boff + n * 2048 + k * 1024); } while (0)
; #define PG8_MMA(ai, bj, At, Bt) do { __builtin_amdgcn_s_setprio(1); _Pragma("unroll") for (int m = 0; m < 4; ++m) _Pragma("unroll") for (int n = 0; n < 2; ++n) _Pragma("unroll") for (int k = 0; k < 2; ++k) \
;         acc[ai][bj][m][n] = __builtin_amdgcn_mfma_f32_16x16x32_bf16(Bt[n][k], At[m][k], acc[ai][bj][m][n], 0, 0, 0); __builtin_amdgcn_s_setprio(0); } while (0)
; #define PG8_WAIT_V(n) asm volatile("s_waitcnt vmcnt(" #n ")" ::: "memory")
; #define PG8_BAR __builtin_amdgcn_s_barrier()
; template <class Epi, class Sched>
; __device__ __forceinline__ void gemm_phase(LAS unsigned char* lds, const Sched& S, const Epi& E) {
;     ...
;             const bool last = (t == nt - 2);
;             const char* a1 = cA + (size_t)(t + 1) * kstep;
;             const char* a2 = last ? nA : cA + (size_t)(t + 2) * kstep; const char* b2 = last ? nB : cB + (size_t)(t + 2) * kstep;
;             const char* a3 = a2 + kstep; const char* b3 = b2 + kstep;
;             const unsigned vA2 = voffA, vB2 = voffB, hA2 = hA, hB2 = hB;
;             PG8_LDB(B0, 0, 0); PG8_LDB(B1, 0, 1); PG8_SCHED; PG8_LDA(At, 0, 0); PG8_STAGE(PG8_SA(1, 1), a1 + hA, voffA, hA / 2);
;             PG8_WAIT_V(8); PG8_WAIT_L(0); PG8_BAR; PG8_MMA(0, 0, At, B0); PG8_MMA(0, 1, At, B1); PG8_BAR; PG8_SCHED;
;             PG8_LDA(At, 0, 1); PG8_STAGE(PG8_SB(0, 0), b2, vB2, hB2 / 2); PG8_STAGE(PG8_SB(0, 1), b2 + hB2, vB2, hB2 / 2); PG8_STAGE(PG8_SA(0, 0), a2, vA2, hA2 / 2);
;             PG8_WAIT_V(8); PG8_WAIT_L(0); PG8_BAR; PG8_MMA(1, 0, At, B0); PG8_MMA(1, 1, At, B1); PG8_BAR; PG8_SCHED;
	ds_read_b128 v[104:107], v142
	ds_read_b128 v[108:111], v142 offset:1024
	ds_read_b128 v[112:115], v142 offset:2048
	ds_read_b128 v[116:119], v142 offset:3072
	ds_read_b128 v[120:123], v143
	ds_read_b128 v[124:127], v143 offset:1024
	ds_read_b128 v[172:175], v143 offset:2048
	ds_read_b128 v[178:181], v143 offset:3072
	ds_read_b128 v[182:185], v148
	ds_read_b128 v[186:189], v148 offset:1024
	ds_read_b128 v[190:193], v148 offset:2048
	ds_read_b128 v[194:197], v148 offset:3072
	ds_read_b128 v[198:201], v148 offset:4096
	ds_read_b128 v[202:205], v148 offset:5120
	ds_read_b128 v[206:209], v148 offset:6144
	ds_read_b128 v[210:213], v148 offset:7168
	s_mov_b32 m0, s69
	s_nop 0
	global_load_lds_dwordx4 v144, s[26:27]
	s_mov_b32 m0, s24
	s_nop 0
	global_load_lds_dwordx4 v144, s[54:55]
	s_waitcnt vmcnt(8) lgkmcnt(0)
	s_barrier
	s_setprio 1
	v_mfma_f32_16x16x32_bf16 v[64:67], v[104:107], v[182:185], v[64:67]
	v_mfma_f32_16x16x32_bf16 v[68:71], v[112:115], v[182:185], v[68:71]
	v_mfma_f32_16x16x32_bf16 v[72:75], v[104:107], v[190:193], v[72:75]
	v_mfma_f32_16x16x32_bf16 v[76:79], v[112:115], v[190:193], v[76:79]
	v_mfma_f32_16x16x32_bf16 v[80:83], v[104:107], v[198:201], v[80:83]
	v_mfma_f32_16x16x32_bf16 v[84:87], v[112:115], v[198:201], v[84:87]
	v_mfma_f32_16x16x32_bf16 v[88:91], v[104:107], v[206:209], v[88:91]
	v_mfma_f32_16x16x32_bf16 v[64:67], v[108:111], v[186:189], v[64:67]
	v_mfma_f32_16x16x32_bf16 v[68:71], v[116:119], v[186:189], v[68:71]
	v_mfma_f32_16x16x32_bf16 v[72:75], v[108:111], v[194:197], v[72:75]
	v_mfma_f32_16x16x32_bf16 v[76:79], v[116:119], v[194:197], v[76:79]
	v_mfma_f32_16x16x32_bf16 v[80:83], v[108:111], v[202:205], v[80:83]
	v_mfma_f32_16x16x32_bf16 v[84:87], v[116:119], v[202:205], v[84:87]
	v_mfma_f32_16x16x32_bf16 v[214:217], v[108:111], v[210:213], v[88:91]
	v_mfma_f32_16x16x32_bf16 v[88:91], v[112:115], v[206:209], v[92:95]
	v_mfma_f32_16x16x32_bf16 v[218:221], v[116:119], v[210:213], v[88:91]
	v_mfma_f32_16x16x32_bf16 v[88:91], v[120:123], v[182:185], v[96:99]
	v_mfma_f32_16x16x32_bf16 v[32:35], v[172:175], v[182:185], v[32:35]
	v_mfma_f32_16x16x32_bf16 v[36:39], v[120:123], v[190:193], v[36:39]
	v_mfma_f32_16x16x32_bf16 v[40:43], v[172:175], v[190:193], v[40:43]
	v_mfma_f32_16x16x32_bf16 v[44:47], v[120:123], v[198:201], v[44:47]
	v_mfma_f32_16x16x32_bf16 v[48:51], v[172:175], v[198:201], v[48:51]
	v_mfma_f32_16x16x32_bf16 v[52:55], v[120:123], v[206:209], v[52:55]
	v_mfma_f32_16x16x32_bf16 v[56:59], v[172:175], v[206:209], v[56:59]
	v_mfma_f32_16x16x32_bf16 v[96:99], v[124:127], v[186:189], v[88:91]
	v_mfma_f32_16x16x32_bf16 v[32:35], v[178:181], v[186:189], v[32:35]
	v_mfma_f32_16x16x32_bf16 v[36:39], v[124:127], v[194:197], v[36:39]
	v_mfma_f32_16x16x32_bf16 v[40:43], v[178:181], v[194:197], v[40:43]
	v_mfma_f32_16x16x32_bf16 v[44:47], v[124:127], v[202:205], v[44:47]
	v_mfma_f32_16x16x32_bf16 v[48:51], v[178:181], v[202:205], v[48:51]
	v_mfma_f32_16x16x32_bf16 v[52:55], v[124:127], v[210:213], v[52:55]
	v_mfma_f32_16x16x32_bf16 v[56:59], v[178:181], v[210:213], v[56:59]
	s_setprio 0
	s_barrier
	s_add_u32 s30, s16, 0x20000
	ds_read_b128 v[88:91], v148 offset:16384
	ds_read_b128 v[92:95], v148 offset:17408
	ds_read_b128 v[182:185], v148 offset:18432
	ds_read_b128 v[186:189], v148 offset:19456
	ds_read_b128 v[190:193], v148 offset:20480
	ds_read_b128 v[194:197], v148 offset:21504
	ds_read_b128 v[198:201], v148 offset:22528
	ds_read_b128 v[202:205], v148 offset:23552
	s_mov_b32 m0, s12
	s_nop 0
	global_load_lds_dwordx4 v128, s[16:17]
	s_mov_b32 m0, s44
	s_addc_u32 s31, s17, 0
	global_load_lds_dwordx4 v128, s[30:31]
	s_add_u32 s30, s16, 0x40000
	s_mov_b32 m0, s42
	s_addc_u32 s31, s17, 0
	global_load_lds_dwordx4 v128, s[30:31]
	s_add_u32 s30, s16, 0x60000
	s_mov_b32 m0, s48
	s_addc_u32 s31, s17, 0
	global_load_lds_dwordx4 v128, s[30:31]
	s_mov_b32 m0, s47
	s_nop 0
	global_load_lds_dwordx4 v144, s[8:9]
	s_mov_b32 m0, s61
	s_nop 0
	global_load_lds_dwordx4 v144, s[10:11]
	s_waitcnt vmcnt(8) lgkmcnt(0)
	s_barrier
	s_setprio 1
	v_mfma_f32_16x16x32_bf16 v[0:3], v[104:107], v[198:201], v[0:3]
	v_mfma_f32_16x16x32_bf16 v[4:7], v[112:115], v[198:201], v[4:7]
	v_mfma_f32_16x16x32_bf16 v[130:133], v[104:107], v[88:91], v[130:133]
	v_mfma_f32_16x16x32_bf16 v[134:137], v[112:115], v[88:91], v[134:137]
	v_mfma_f32_16x16x32_bf16 v[138:141], v[104:107], v[182:185], v[138:141]
	v_mfma_f32_16x16x32_bf16 v[150:153], v[112:115], v[182:185], v[150:153]
	v_mfma_f32_16x16x32_bf16 v[158:161], v[104:107], v[190:193], v[158:161]
	v_mfma_f32_16x16x32_bf16 v[162:165], v[112:115], v[190:193], v[162:165]
	v_mfma_f32_16x16x32_bf16 v[0:3], v[108:111], v[202:205], v[0:3]
	v_mfma_f32_16x16x32_bf16 v[4:7], v[116:119], v[202:205], v[4:7]
	v_mfma_f32_16x16x32_bf16 v[130:133], v[108:111], v[92:95], v[130:133]
	v_mfma_f32_16x16x32_bf16 v[134:137], v[116:119], v[92:95], v[134:137]
	v_mfma_f32_16x16x32_bf16 v[138:141], v[108:111], v[186:189], v[138:141]
	v_mfma_f32_16x16x32_bf16 v[150:153], v[116:119], v[186:189], v[150:153]
	v_mfma_f32_16x16x32_bf16 v[158:161], v[108:111], v[194:197], v[158:161]
	v_mfma_f32_16x16x32_bf16 v[162:165], v[116:119], v[194:197], v[162:165]
	v_mfma_f32_16x16x32_bf16 v[8:11], v[120:123], v[88:91], v[8:11]
	v_mfma_f32_16x16x32_bf16 v[206:209], v[124:127], v[92:95], v[8:11]
	v_mfma_f32_16x16x32_bf16 v[8:11], v[172:175], v[88:91], v[12:15]
	v_mfma_f32_16x16x32_bf16 v[210:213], v[178:181], v[92:95], v[8:11]
	v_mfma_f32_16x16x32_bf16 v[8:11], v[120:123], v[182:185], v[24:27]
	v_mfma_f32_16x16x32_bf16 v[222:225], v[124:127], v[186:189], v[8:11]
	v_mfma_f32_16x16x32_bf16 v[8:11], v[172:175], v[182:185], v[28:31]
	v_mfma_f32_16x16x32_bf16 v[182:185], v[178:181], v[186:189], v[8:11]
	v_mfma_f32_16x16x32_bf16 v[8:11], v[120:123], v[190:193], v[60:63]
	v_mfma_f32_16x16x32_bf16 v[186:189], v[124:127], v[194:197], v[8:11]
	v_mfma_f32_16x16x32_bf16 v[8:11], v[172:175], v[190:193], v[100:103]
	v_mfma_f32_16x16x32_bf16 v[190:193], v[178:181], v[194:197], v[8:11]
	v_mfma_f32_16x16x32_bf16 v[8:11], v[120:123], v[198:201], v[16:19]
	v_mfma_f32_16x16x32_bf16 v[194:197], v[124:127], v[202:205], v[8:11]
	v_mfma_f32_16x16x32_bf16 v[8:11], v[172:175], v[198:201], v[20:23]
	v_mfma_f32_16x16x32_bf16 v[172:175], v[178:181], v[202:205], v[8:11]
	s_setprio 0
	s_barrier
; #define PG8_STAGE(bufoff, gbase, voff, p64) do { _Pragma("unroll") for (int _i = 0; _i < 2; ++_i) { \
;         const char* _gb = (const char*)(gbase) + (size_t)_i * (p64); const unsigned _la = ldsbase + (unsigned)(bufoff) + (unsigned)_i * 8192u; \
;         asm volatile("s_mov_b32 m0, %0\n\ts_nop 0\n\tglobal_load_lds_dwordx4 %1, %2" :: "s"(_la), "v"(voff), "s"(_gb) : "memory"); } } while (0)
; #define PG8_LDA(dst, b, h) do { _Pragma("unroll") for (int m = 0; m < 4; ++m) _Pragma("unroll") for (int k = 0; k < 2; ++k) dst[m][k] = *(const LAS bf16x8*)(lds + PG8_SA(b, h) + aoff + m * 2048 + k * 1024); } while (0)
; #define PG8_LDB(dst, b, h) do { _Pragma("unroll") for (int n = 0; n < 2; ++n) _Pragma("unroll") for (int k = 0; k < 2; ++k) dst[n][k] = *(const LAS bf16x8*)(lds + PG8_SB(b, h) + boff + n * 2048 + k * 1024); } while (0)
; #define PG8_MMA(ai, bj, At, Bt) do { __builtin_amdgcn_s_setprio(1); _Pragma("unroll") for (int m = 0; m < 4; ++m) _Pragma("unroll") for (int n = 0; n < 2; ++n) _Pragma("unroll") for (int k = 0; k < 2; ++k) \
;         acc[ai][bj][m][n] = __builtin_amdgcn_mfma_f32_16x16x32_bf16(Bt[n][k], At[m][k], acc[ai][bj][m][n], 0, 0, 0); __builtin_amdgcn_s_setprio(0); } while (0)
; #define PG8_WAIT_V(n) asm volatile("s_waitcnt vmcnt(" #n ")" ::: "memory")
; #define PG8_WAIT_L(n) asm volatile("s_waitcnt lgkmcnt(" #n ")" ::: "memory")
; #define PG8_BAR __builtin_amdgcn_s_barrier()
; #define PG8_SCHED __builtin_amdgcn_sched_barrier(0)
; template <class Epi, class Sched>
; __device__ __forceinline__ void gemm_phase(LAS unsigned char* lds, const Sched& S, const Epi& E) {
;     ...
;             PG8_LDB(B0, 1, 0); PG8_LDB(B1, 1, 1); PG8_SCHED; PG8_LDA(At, 1, 0); PG8_STAGE(PG8_SA(0, 1), a2 + hA2, vA2, hA2 / 2);
;             PG8_WAIT_V(8); PG8_WAIT_L(0); PG8_BAR; PG8_MMA(0, 0, At, B0); PG8_MMA(0, 1, At, B1); PG8_BAR; PG8_SCHED;
;             PG8_LDA(At, 1, 1); PG8_STAGE(PG8_SB(1, 0), b3, vB2, hB2 / 2); PG8_STAGE(PG8_SB(1, 1), b3 + hB2, vB2, hB2 / 2); PG8_STAGE(PG8_SA(1, 0), a3, vA2, hA2 / 2);
;             PG8_WAIT_V(8); PG8_WAIT_L(0); PG8_BAR; PG8_MMA(1, 0, At, B0); PG8_MMA(1, 1, At, B1); PG8_BAR; PG8_SCHED;
;         }
;         if (wr == 0) PG8_BAR;
	s_nop 4
	ds_read_b128 v[8:11], v149
	ds_read_b128 v[12:15], v149 offset:1024
	ds_read_b128 v[16:19], v149 offset:2048
	ds_read_b128 v[20:23], v149 offset:3072
	ds_read_b128 v[178:181], v154
	ds_read_b128 v[198:201], v154 offset:1024
	ds_read_b128 v[202:205], v154 offset:2048
	ds_read_b128 v[226:229], v154 offset:3072
	ds_read_b128 v[24:27], v148 offset:32768
	ds_read_b128 v[28:31], v148 offset:33792
	ds_read_b128 v[60:63], v148 offset:34816
	ds_read_b128 v[230:233], v148 offset:35840
	ds_read_b128 v[234:237], v148 offset:36864
	ds_read_b128 v[238:241], v148 offset:37888
	ds_read_b128 v[242:245], v148 offset:38912
	ds_read_b128 v[246:249], v148 offset:39936
	s_mov_b32 m0, s14
	s_nop 0
	global_load_lds_dwordx4 v144, s[74:75]
	s_mov_b32 m0, s15
	s_nop 0
	global_load_lds_dwordx4 v144, s[76:77]
	s_waitcnt vmcnt(8) lgkmcnt(0)
	s_barrier
	s_setprio 1
	v_mfma_f32_16x16x32_bf16 v[64:67], v[8:11], v[24:27], v[64:67]
	v_mfma_f32_16x16x32_bf16 v[124:127], v[12:15], v[28:31], v[64:67]
	v_mfma_f32_16x16x32_bf16 v[64:67], v[16:19], v[24:27], v[68:71]
	v_mfma_f32_16x16x32_bf16 v[120:123], v[20:23], v[28:31], v[64:67]
	v_mfma_f32_16x16x32_bf16 v[64:67], v[8:11], v[60:63], v[72:75]
	v_mfma_f32_16x16x32_bf16 v[108:111], v[12:15], v[230:233], v[64:67]
	v_mfma_f32_16x16x32_bf16 v[64:67], v[16:19], v[60:63], v[76:79]
	v_mfma_f32_16x16x32_bf16 v[104:107], v[20:23], v[230:233], v[64:67]
	v_mfma_f32_16x16x32_bf16 v[64:67], v[8:11], v[234:237], v[80:83]
	v_mfma_f32_16x16x32_bf16 v[92:95], v[12:15], v[238:241], v[64:67]
	v_mfma_f32_16x16x32_bf16 v[64:67], v[16:19], v[234:237], v[84:87]
	v_mfma_f32_16x16x32_bf16 v[88:91], v[20:23], v[238:241], v[64:67]
	v_mfma_f32_16x16x32_bf16 v[64:67], v[8:11], v[242:245], v[214:217]
	v_mfma_f32_16x16x32_bf16 v[76:79], v[12:15], v[246:249], v[64:67]
	v_mfma_f32_16x16x32_bf16 v[64:67], v[16:19], v[242:245], v[218:221]
	v_mfma_f32_16x16x32_bf16 v[72:75], v[20:23], v[246:249], v[64:67]
	v_mfma_f32_16x16x32_bf16 v[64:67], v[178:181], v[24:27], v[96:99]
	v_mfma_f32_16x16x32_bf16 v[24:27], v[202:205], v[24:27], v[32:35]
	v_mfma_f32_16x16x32_bf16 v[112:115], v[226:229], v[28:31], v[24:27]
	v_mfma_f32_16x16x32_bf16 v[24:27], v[178:181], v[60:63], v[36:39]
	v_mfma_f32_16x16x32_bf16 v[100:103], v[198:201], v[230:233], v[24:27]
	v_mfma_f32_16x16x32_bf16 v[24:27], v[202:205], v[60:63], v[40:43]
	v_mfma_f32_16x16x32_bf16 v[96:99], v[226:229], v[230:233], v[24:27]
	v_mfma_f32_16x16x32_bf16 v[24:27], v[178:181], v[234:237], v[44:47]
	v_mfma_f32_16x16x32_bf16 v[84:87], v[198:201], v[238:241], v[24:27]
	v_mfma_f32_16x16x32_bf16 v[24:27], v[202:205], v[234:237], v[48:51]
	v_mfma_f32_16x16x32_bf16 v[80:83], v[226:229], v[238:241], v[24:27]
	v_mfma_f32_16x16x32_bf16 v[24:27], v[178:181], v[242:245], v[52:55]
	v_mfma_f32_16x16x32_bf16 v[68:71], v[198:201], v[246:249], v[24:27]
	v_mfma_f32_16x16x32_bf16 v[24:27], v[202:205], v[242:245], v[56:59]
	v_mfma_f32_16x16x32_bf16 v[116:119], v[198:201], v[28:31], v[64:67]
	v_mfma_f32_16x16x32_bf16 v[64:67], v[226:229], v[246:249], v[24:27]
	s_setprio 0
	s_barrier
	s_add_u32 s30, s16, 0x80
	s_addc_u32 s31, s17, 0
	ds_read_b128 v[32:35], v148 offset:49152
	ds_read_b128 v[36:39], v148 offset:50176
	ds_read_b128 v[214:217], v148 offset:51200
	ds_read_b128 v[218:221], v148 offset:52224
	ds_read_b128 v[230:233], v148 offset:53248
	ds_read_b128 v[234:237], v148 offset:54272
	ds_read_b128 v[238:241], v148 offset:55296
	ds_read_b128 v[242:245], v148 offset:56320
	s_mov_b32 m0, s65
	s_nop 0
	global_load_lds_dwordx4 v128, s[30:31]
	s_add_u32 s30, s16, 0x20080
	s_mov_b32 m0, s66
	s_addc_u32 s31, s17, 0
	global_load_lds_dwordx4 v128, s[30:31]
	s_add_u32 s30, s16, 0x40080
	s_mov_b32 m0, s36
	s_addc_u32 s31, s17, 0
	global_load_lds_dwordx4 v128, s[30:31]
	s_add_u32 s16, s16, 0x60080
	s_mov_b32 m0, s37
	s_addc_u32 s17, s17, 0
	global_load_lds_dwordx4 v128, s[16:17]
	s_mov_b32 m0, s67
	s_nop 0
	global_load_lds_dwordx4 v144, s[82:83]
	s_mov_b32 m0, s45
	s_nop 0
	global_load_lds_dwordx4 v144, s[84:85]
	s_waitcnt vmcnt(8) lgkmcnt(0)
	s_barrier
	s_setprio 1
	v_mfma_f32_16x16x32_bf16 v[24:27], v[8:11], v[32:35], v[130:133]
	v_mfma_f32_16x16x32_bf16 v[60:63], v[12:15], v[36:39], v[24:27]
	v_mfma_f32_16x16x32_bf16 v[24:27], v[16:19], v[32:35], v[134:137]
	v_mfma_f32_16x16x32_bf16 v[56:59], v[20:23], v[36:39], v[24:27]
	v_mfma_f32_16x16x32_bf16 v[24:27], v[8:11], v[214:217], v[138:141]
	v_mfma_f32_16x16x32_bf16 v[44:47], v[12:15], v[218:221], v[24:27]
	v_mfma_f32_16x16x32_bf16 v[24:27], v[16:19], v[214:217], v[150:153]
	v_mfma_f32_16x16x32_bf16 v[40:43], v[20:23], v[218:221], v[24:27]
	v_mfma_f32_16x16x32_bf16 v[24:27], v[8:11], v[230:233], v[158:161]
	v_mfma_f32_16x16x32_bf16 v[0:3], v[8:11], v[238:241], v[0:3]
	v_mfma_f32_16x16x32_bf16 v[28:31], v[12:15], v[234:237], v[24:27]
	v_mfma_f32_16x16x32_bf16 v[24:27], v[16:19], v[230:233], v[162:165]
	v_mfma_f32_16x16x32_bf16 v[12:15], v[12:15], v[242:245], v[0:3]
	v_mfma_f32_16x16x32_bf16 v[0:3], v[16:19], v[238:241], v[4:7]
	v_mfma_f32_16x16x32_bf16 v[24:27], v[20:23], v[234:237], v[24:27]
	v_mfma_f32_16x16x32_bf16 v[8:11], v[20:23], v[242:245], v[0:3]
	v_mfma_f32_16x16x32_bf16 v[0:3], v[178:181], v[32:35], v[206:209]
	v_mfma_f32_16x16x32_bf16 v[52:55], v[198:201], v[36:39], v[0:3]
	v_mfma_f32_16x16x32_bf16 v[0:3], v[202:205], v[32:35], v[210:213]
	v_mfma_f32_16x16x32_bf16 v[48:51], v[226:229], v[36:39], v[0:3]
	v_mfma_f32_16x16x32_bf16 v[0:3], v[178:181], v[214:217], v[222:225]
	v_mfma_f32_16x16x32_bf16 v[36:39], v[198:201], v[218:221], v[0:3]
	v_mfma_f32_16x16x32_bf16 v[0:3], v[202:205], v[214:217], v[182:185]
	v_mfma_f32_16x16x32_bf16 v[32:35], v[226:229], v[218:221], v[0:3]
	v_mfma_f32_16x16x32_bf16 v[0:3], v[178:181], v[230:233], v[186:189]
	v_mfma_f32_16x16x32_bf16 v[20:23], v[198:201], v[234:237], v[0:3]
	v_mfma_f32_16x16x32_bf16 v[0:3], v[202:205], v[230:233], v[190:193]
	v_mfma_f32_16x16x32_bf16 v[16:19], v[226:229], v[234:237], v[0:3]
	v_mfma_f32_16x16x32_bf16 v[0:3], v[178:181], v[238:241], v[194:197]
	v_mfma_f32_16x16x32_bf16 v[4:7], v[198:201], v[242:245], v[0:3]
	v_mfma_f32_16x16x32_bf16 v[0:3], v[202:205], v[238:241], v[172:175]
	v_mfma_f32_16x16x32_bf16 v[0:3], v[226:229], v[242:245], v[0:3]
	s_setprio 0
	s_barrier
	s_andn2_b64 vcc, exec, s[86:87]
	s_cbranch_vccnz .LBB0_833
	s_barrier

; #define PG8_STAGE(bufoff, gbase, voff, p64) do { _Pragma("unroll") for (int _i = 0; _i < 2; ++_i) { \
;         const char* _gb = (const char*)(gbase) + (size_t)_i * (p64); const unsigned _la = ldsbase + (unsigned)(bufoff) + (unsigned)_i * 8192u; \
;         asm volatile("s_mov_b32 m0, %0\n\ts_nop 0\n\tglobal_load_lds_dwordx4 %1, %2" :: "s"(_la), "v"(voff), "s"(_gb) : "memory"); } } while (0)
; #define PG8_LDA(dst, b, h) do { _Pragma("unroll") for (int m = 0; m < 4; ++m) _Pragma("unroll") for (int k = 0; k < 2; ++k) dst[m][k] = *(const LAS bf16x8*)(lds + PG8_SA(b, h) + aoff + m * 2048 + k * 1024); } while (0)
; #define PG8_LDB(dst, b, h) do { _Pragma("unroll") for (int n = 0; n < 2; ++n) _Pragma("unroll") for (int k = 0; k < 2; ++k) dst[n][k] = *(const LAS bf16x8*)(lds + PG8_SB(b, h) + boff + n * 2048 + k * 1024); } while (0)
; #define PG8_MMA(ai, bj, At, Bt) do { __builtin_amdgcn_s_setprio(1); _Pragma("unroll") for (int m = 0; m < 4; ++m) _Pragma("unroll") for (int n = 0; n < 2; ++n) _Pragma("unroll") for (int k = 0; k < 2; ++k) \
;         acc[ai][bj][m][n] = __builtin_amdgcn_mfma_f32_16x16x32_bf16(Bt[n][k], At[m][k], acc[ai][bj][m][n], 0, 0, 0); __builtin_amdgcn_s_setprio(0); } while (0)
; #define PG8_WAIT_V(n) asm volatile("s_waitcnt vmcnt(" #n ")" ::: "memory")
; #define PG8_BAR __builtin_amdgcn_s_barrier()
; template <class Epi, class Sched>
; __device__ __forceinline__ void gemm_phase(LAS unsigned char* lds, const Sched& S, const Epi& E) {
;     ...
;             const bool last = (t == nt - 2);
;             const char* a1 = cA + (size_t)(t + 1) * kstep;
;             const char* a2 = last ? nA : cA + (size_t)(t + 2) * kstep; const char* b2 = last ? nB : cB + (size_t)(t + 2) * kstep;
;             const char* a3 = a2 + kstep; const char* b3 = b2 + kstep;
;             const unsigned vA2 = voffA, vB2 = voffB, hA2 = hA, hB2 = hB;
;             PG8_LDB(B0, 0, 0); PG8_LDB(B1, 0, 1); PG8_SCHED; PG8_LDA(At, 0, 0); PG8_STAGE(PG8_SA(1, 1), a1 + hA, voffA, hA / 2);
;             PG8_WAIT_V(8); PG8_WAIT_L(0); PG8_BAR; PG8_MMA(0, 0, At, B0); PG8_MMA(0, 1, At, B1); PG8_BAR; PG8_SCHED;
;             PG8_LDA(At, 0, 1); PG8_STAGE(PG8_SB(0, 0), b2, vB2, hB2 / 2); PG8_STAGE(PG8_SB(0, 1), b2 + hB2, vB2, hB2 / 2); PG8_STAGE(PG8_SA(0, 0), a2, vA2, hA2 / 2);
;             PG8_WAIT_V(8); PG8_WAIT_L(0); PG8_BAR; PG8_MMA(1, 0, At, B0); PG8_MMA(1, 1, At, B1); PG8_BAR; PG8_SCHED;
.LBB0_844:
	v_add_u32_e32 v142, 0x10000, v175
	v_add_u32_e32 v154, 0x14000, v175
	ds_read_b128 v[130:133], v142
	ds_read_b128 v[134:137], v142 offset:1024
	ds_read_b128 v[138:141], v142 offset:2048
	ds_read_b128 v[142:145], v142 offset:3072
	ds_read_b128 v[146:149], v154
	ds_read_b128 v[150:153], v154 offset:1024
	ds_read_b128 v[158:161], v154 offset:2048
	ds_read_b128 v[162:165], v154 offset:3072
	s_add_i32 s80, s8, 2
	s_cmp_eq_u32 s73, s8
	s_cselect_b32 s8, s56, s76
	s_cselect_b32 s9, s57, s77
	s_cselect_b32 s22, s58, s78
	s_cselect_b32 s23, s59, s79
	s_add_u32 s16, s8, 0x80
	s_addc_u32 s17, s9, 0
	ds_read_b128 v[180:183], v177
	ds_read_b128 v[184:187], v177 offset:1024
	ds_read_b128 v[188:191], v177 offset:2048
	ds_read_b128 v[192:195], v177 offset:3072
	ds_read_b128 v[196:199], v177 offset:4096
	ds_read_b128 v[200:203], v177 offset:5120
	ds_read_b128 v[204:207], v177 offset:6144
	ds_read_b128 v[208:211], v177 offset:7168
	s_add_u32 s30, s76, 0x3ff80
	s_mov_b32 m0, s66
	s_addc_u32 s31, s77, 0
	global_load_lds_dwordx4 v172, s[30:31]
	s_add_u32 s30, s76, 0x5ff80
	s_mov_b32 m0, s67
	s_addc_u32 s31, s77, 0
	global_load_lds_dwordx4 v172, s[30:31]
	s_waitcnt vmcnt(8) lgkmcnt(0)
	s_barrier
	s_setprio 1
	v_mfma_f32_16x16x32_bf16 v[124:127], v[130:133], v[180:183], v[124:127]
	v_mfma_f32_16x16x32_bf16 v[120:123], v[138:141], v[180:183], v[120:123]
	v_mfma_f32_16x16x32_bf16 v[116:119], v[130:133], v[188:191], v[116:119]
	v_mfma_f32_16x16x32_bf16 v[112:115], v[138:141], v[188:191], v[112:115]
	v_mfma_f32_16x16x32_bf16 v[108:111], v[130:133], v[196:199], v[108:111]
	v_mfma_f32_16x16x32_bf16 v[104:107], v[138:141], v[196:199], v[104:107]
	v_mfma_f32_16x16x32_bf16 v[100:103], v[130:133], v[204:207], v[100:103]
	v_mfma_f32_16x16x32_bf16 v[96:99], v[138:141], v[204:207], v[96:99]
	v_mfma_f32_16x16x32_bf16 v[124:127], v[134:137], v[184:187], v[124:127]
	v_mfma_f32_16x16x32_bf16 v[120:123], v[142:145], v[184:187], v[120:123]
	v_mfma_f32_16x16x32_bf16 v[116:119], v[134:137], v[192:195], v[116:119]
	v_mfma_f32_16x16x32_bf16 v[112:115], v[142:145], v[192:195], v[112:115]
	v_mfma_f32_16x16x32_bf16 v[108:111], v[134:137], v[200:203], v[108:111]
	v_mfma_f32_16x16x32_bf16 v[104:107], v[142:145], v[200:203], v[104:107]
	v_mfma_f32_16x16x32_bf16 v[100:103], v[134:137], v[208:211], v[100:103]
	v_mfma_f32_16x16x32_bf16 v[96:99], v[142:145], v[208:211], v[96:99]
	s_add_u32 s76, s76, 0x100
	s_addc_u32 s77, s77, 0
	s_add_u32 s78, s78, 0x100
	s_addc_u32 s79, s79, 0
	v_mfma_f32_16x16x32_bf16 v[92:95], v[146:149], v[180:183], v[92:95]
	v_mfma_f32_16x16x32_bf16 v[88:91], v[158:161], v[180:183], v[88:91]
	v_mfma_f32_16x16x32_bf16 v[84:87], v[146:149], v[188:191], v[84:87]
	v_mfma_f32_16x16x32_bf16 v[80:83], v[158:161], v[188:191], v[80:83]
	v_mfma_f32_16x16x32_bf16 v[76:79], v[146:149], v[196:199], v[76:79]
	v_mfma_f32_16x16x32_bf16 v[72:75], v[158:161], v[196:199], v[72:75]
	v_mfma_f32_16x16x32_bf16 v[68:71], v[146:149], v[204:207], v[68:71]
	v_mfma_f32_16x16x32_bf16 v[64:67], v[158:161], v[204:207], v[64:67]
	v_mfma_f32_16x16x32_bf16 v[92:95], v[150:153], v[184:187], v[92:95]
	v_mfma_f32_16x16x32_bf16 v[88:91], v[162:165], v[184:187], v[88:91]
	v_mfma_f32_16x16x32_bf16 v[84:87], v[150:153], v[192:195], v[84:87]
	v_mfma_f32_16x16x32_bf16 v[80:83], v[162:165], v[192:195], v[80:83]
	v_mfma_f32_16x16x32_bf16 v[76:79], v[150:153], v[200:203], v[76:79]
	v_mfma_f32_16x16x32_bf16 v[72:75], v[162:165], v[200:203], v[72:75]
	v_mfma_f32_16x16x32_bf16 v[68:71], v[150:153], v[208:211], v[68:71]
	v_mfma_f32_16x16x32_bf16 v[64:67], v[162:165], v[208:211], v[64:67]
	s_setprio 0
	s_barrier
	s_add_u32 s30, s22, 0x10000
	ds_read_b128 v[180:183], v177 offset:16384
	ds_read_b128 v[184:187], v177 offset:17408
	ds_read_b128 v[188:191], v177 offset:18432
	ds_read_b128 v[192:195], v177 offset:19456
	ds_read_b128 v[196:199], v177 offset:20480
	ds_read_b128 v[200:203], v177 offset:21504
	ds_read_b128 v[204:207], v177 offset:22528
	ds_read_b128 v[208:211], v177 offset:23552
	s_mov_b32 m0, s5
	s_nop 0
	global_load_lds_dwordx4 v128, s[22:23]
	s_mov_b32 m0, s12
	s_addc_u32 s31, s23, 0
	global_load_lds_dwordx4 v128, s[30:31]
	s_add_u32 s30, s22, 0x20000
	s_mov_b32 m0, s14
	s_addc_u32 s31, s23, 0
	global_load_lds_dwordx4 v128, s[30:31]
	s_add_u32 s30, s22, 0x30000
	s_mov_b32 m0, s15
	s_addc_u32 s31, s23, 0
	global_load_lds_dwordx4 v128, s[30:31]
	s_mov_b32 m0, s4
	s_nop 0
	global_load_lds_dwordx4 v172, s[8:9]
	s_add_u32 s30, s8, 0x20000
	s_mov_b32 m0, s24
	s_addc_u32 s31, s9, 0
	global_load_lds_dwordx4 v172, s[30:31]
	s_waitcnt vmcnt(8) lgkmcnt(0)
	s_barrier
; #define PG8_STAGE(bufoff, gbase, voff, p64) do { _Pragma("unroll") for (int _i = 0; _i < 2; ++_i) { \
;         const char* _gb = (const char*)(gbase) + (size_t)_i * (p64); const unsigned _la = ldsbase + (unsigned)(bufoff) + (unsigned)_i * 8192u; \
;         asm volatile("s_mov_b32 m0, %0\n\ts_nop 0\n\tglobal_load_lds_dwordx4 %1, %2" :: "s"(_la), "v"(voff), "s"(_gb) : "memory"); } } while (0)
; #define PG8_LDA(dst, b, h) do { _Pragma("unroll") for (int m = 0; m < 4; ++m) _Pragma("unroll") for (int k = 0; k < 2; ++k) dst[m][k] = *(const LAS bf16x8*)(lds + PG8_SA(b, h) + aoff + m * 2048 + k * 1024); } while (0)
; #define PG8_LDB(dst, b, h) do { _Pragma("unroll") for (int n = 0; n < 2; ++n) _Pragma("unroll") for (int k = 0; k < 2; ++k) dst[n][k] = *(const LAS bf16x8*)(lds + PG8_SB(b, h) + boff + n * 2048 + k * 1024); } while (0)
; #define PG8_MMA(ai, bj, At, Bt) do { __builtin_amdgcn_s_setprio(1); _Pragma("unroll") for (int m = 0; m < 4; ++m) _Pragma("unroll") for (int n = 0; n < 2; ++n) _Pragma("unroll") for (int k = 0; k < 2; ++k) \
;         acc[ai][bj][m][n] = __builtin_amdgcn_mfma_f32_16x16x32_bf16(Bt[n][k], At[m][k], acc[ai][bj][m][n], 0, 0, 0); __builtin_amdgcn_s_setprio(0); } while (0)
; #define PG8_WAIT_V(n) asm volatile("s_waitcnt vmcnt(" #n ")" ::: "memory")
; #define PG8_WAIT_L(n) asm volatile("s_waitcnt lgkmcnt(" #n ")" ::: "memory")
; #define PG8_BAR __builtin_amdgcn_s_barrier()
; #define PG8_SCHED __builtin_amdgcn_sched_barrier(0)
; template <class Epi, class Sched>
; __device__ __forceinline__ void gemm_phase(LAS unsigned char* lds, const Sched& S, const Epi& E) {
;     ...
;             PG8_WAIT_V(8); PG8_WAIT_L(0); PG8_BAR; PG8_MMA(1, 0, At, B0); PG8_MMA(1, 1, At, B1); PG8_BAR; PG8_SCHED;
;             PG8_LDB(B0, 1, 0); PG8_LDB(B1, 1, 1); PG8_SCHED; PG8_LDA(At, 1, 0); PG8_STAGE(PG8_SA(0, 1), a2 + hA2, vA2, hA2 / 2);
;             PG8_WAIT_V(8); PG8_WAIT_L(0); PG8_BAR; PG8_MMA(0, 0, At, B0); PG8_MMA(0, 1, At, B1); PG8_BAR; PG8_SCHED;
	s_setprio 1
	v_mfma_f32_16x16x32_bf16 v[60:63], v[130:133], v[180:183], v[60:63]
	v_mfma_f32_16x16x32_bf16 v[56:59], v[138:141], v[180:183], v[56:59]
	v_mfma_f32_16x16x32_bf16 v[52:55], v[130:133], v[188:191], v[52:55]
	v_mfma_f32_16x16x32_bf16 v[48:51], v[138:141], v[188:191], v[48:51]
	v_mfma_f32_16x16x32_bf16 v[44:47], v[130:133], v[196:199], v[44:47]
	v_mfma_f32_16x16x32_bf16 v[40:43], v[138:141], v[196:199], v[40:43]
	v_mfma_f32_16x16x32_bf16 v[36:39], v[130:133], v[204:207], v[36:39]
	v_mfma_f32_16x16x32_bf16 v[32:35], v[138:141], v[204:207], v[32:35]
	v_mfma_f32_16x16x32_bf16 v[60:63], v[134:137], v[184:187], v[60:63]
	v_mfma_f32_16x16x32_bf16 v[56:59], v[142:145], v[184:187], v[56:59]
	v_mfma_f32_16x16x32_bf16 v[52:55], v[134:137], v[192:195], v[52:55]
	v_mfma_f32_16x16x32_bf16 v[48:51], v[142:145], v[192:195], v[48:51]
	v_mfma_f32_16x16x32_bf16 v[44:47], v[134:137], v[200:203], v[44:47]
	v_mfma_f32_16x16x32_bf16 v[40:43], v[142:145], v[200:203], v[40:43]
	v_mfma_f32_16x16x32_bf16 v[36:39], v[134:137], v[208:211], v[36:39]
	v_mfma_f32_16x16x32_bf16 v[32:35], v[142:145], v[208:211], v[32:35]
	v_mfma_f32_16x16x32_bf16 v[28:31], v[146:149], v[180:183], v[28:31]
	v_mfma_f32_16x16x32_bf16 v[24:27], v[158:161], v[180:183], v[24:27]
	v_mfma_f32_16x16x32_bf16 v[20:23], v[146:149], v[188:191], v[20:23]
	v_mfma_f32_16x16x32_bf16 v[16:19], v[158:161], v[188:191], v[16:19]
	v_mfma_f32_16x16x32_bf16 v[12:15], v[146:149], v[196:199], v[12:15]
	v_mfma_f32_16x16x32_bf16 v[8:11], v[158:161], v[196:199], v[8:11]
	v_mfma_f32_16x16x32_bf16 v[4:7], v[146:149], v[204:207], v[4:7]
	v_mfma_f32_16x16x32_bf16 v[0:3], v[158:161], v[204:207], v[0:3]
	v_mfma_f32_16x16x32_bf16 v[28:31], v[150:153], v[184:187], v[28:31]
	v_mfma_f32_16x16x32_bf16 v[24:27], v[162:165], v[184:187], v[24:27]
	v_mfma_f32_16x16x32_bf16 v[20:23], v[150:153], v[192:195], v[20:23]
	v_mfma_f32_16x16x32_bf16 v[16:19], v[162:165], v[192:195], v[16:19]
	v_mfma_f32_16x16x32_bf16 v[12:15], v[150:153], v[200:203], v[12:15]
	v_mfma_f32_16x16x32_bf16 v[8:11], v[162:165], v[200:203], v[8:11]
	v_mfma_f32_16x16x32_bf16 v[4:7], v[150:153], v[208:211], v[4:7]
	v_mfma_f32_16x16x32_bf16 v[0:3], v[162:165], v[208:211], v[0:3]
	s_setprio 0
	s_barrier
	v_add_u32_e32 v142, 0x18000, v175
	v_add_u32_e32 v154, 0x1c000, v175
	ds_read_b128 v[130:133], v142
	ds_read_b128 v[134:137], v142 offset:1024
	ds_read_b128 v[138:141], v142 offset:2048
	ds_read_b128 v[142:145], v142 offset:3072
	ds_read_b128 v[146:149], v154
	ds_read_b128 v[150:153], v154 offset:1024
	ds_read_b128 v[158:161], v154 offset:2048
	ds_read_b128 v[162:165], v154 offset:3072
	ds_read_b128 v[180:183], v177 offset:32768
	ds_read_b128 v[184:187], v177 offset:33792
	ds_read_b128 v[188:191], v177 offset:34816
	ds_read_b128 v[192:195], v177 offset:35840
	ds_read_b128 v[196:199], v177 offset:36864
	ds_read_b128 v[200:203], v177 offset:37888
	ds_read_b128 v[204:207], v177 offset:38912
	ds_read_b128 v[208:211], v177 offset:39936
	s_add_u32 s30, s8, 0x40000
	s_mov_b32 m0, s33
	s_addc_u32 s31, s9, 0
	global_load_lds_dwordx4 v172, s[30:31]
	s_add_u32 s30, s8, 0x60000
	s_mov_b32 m0, s34
	s_addc_u32 s31, s9, 0
	global_load_lds_dwordx4 v172, s[30:31]
	s_waitcnt vmcnt(8) lgkmcnt(0)
	s_barrier
	s_setprio 1
	v_mfma_f32_16x16x32_bf16 v[124:127], v[130:133], v[180:183], v[124:127]
	v_mfma_f32_16x16x32_bf16 v[120:123], v[138:141], v[180:183], v[120:123]
	v_mfma_f32_16x16x32_bf16 v[116:119], v[130:133], v[188:191], v[116:119]
	v_mfma_f32_16x16x32_bf16 v[112:115], v[138:141], v[188:191], v[112:115]
	v_mfma_f32_16x16x32_bf16 v[108:111], v[130:133], v[196:199], v[108:111]
	v_mfma_f32_16x16x32_bf16 v[104:107], v[138:141], v[196:199], v[104:107]
	v_mfma_f32_16x16x32_bf16 v[100:103], v[130:133], v[204:207], v[100:103]
	v_mfma_f32_16x16x32_bf16 v[96:99], v[138:141], v[204:207], v[96:99]
	v_mfma_f32_16x16x32_bf16 v[124:127], v[134:137], v[184:187], v[124:127]
	v_mfma_f32_16x16x32_bf16 v[120:123], v[142:145], v[184:187], v[120:123]
	v_mfma_f32_16x16x32_bf16 v[116:119], v[134:137], v[192:195], v[116:119]
	v_mfma_f32_16x16x32_bf16 v[112:115], v[142:145], v[192:195], v[112:115]
	v_mfma_f32_16x16x32_bf16 v[108:111], v[134:137], v[200:203], v[108:111]
	v_mfma_f32_16x16x32_bf16 v[104:107], v[142:145], v[200:203], v[104:107]
	v_mfma_f32_16x16x32_bf16 v[100:103], v[134:137], v[208:211], v[100:103]
	v_mfma_f32_16x16x32_bf16 v[96:99], v[142:145], v[208:211], v[96:99]
	v_mfma_f32_16x16x32_bf16 v[92:95], v[146:149], v[180:183], v[92:95]
	v_mfma_f32_16x16x32_bf16 v[88:91], v[158:161], v[180:183], v[88:91]
	v_mfma_f32_16x16x32_bf16 v[84:87], v[146:149], v[188:191], v[84:87]
	v_mfma_f32_16x16x32_bf16 v[80:83], v[158:161], v[188:191], v[80:83]
	v_mfma_f32_16x16x32_bf16 v[76:79], v[146:149], v[196:199], v[76:79]
	v_mfma_f32_16x16x32_bf16 v[72:75], v[158:161], v[196:199], v[72:75]
	v_mfma_f32_16x16x32_bf16 v[68:71], v[146:149], v[204:207], v[68:71]
	v_mfma_f32_16x16x32_bf16 v[64:67], v[158:161], v[204:207], v[64:67]
	v_mfma_f32_16x16x32_bf16 v[92:95], v[150:153], v[184:187], v[92:95]
	v_mfma_f32_16x16x32_bf16 v[88:91], v[162:165], v[184:187], v[88:91]
	v_mfma_f32_16x16x32_bf16 v[84:87], v[150:153], v[192:195], v[84:87]
	v_mfma_f32_16x16x32_bf16 v[80:83], v[162:165], v[192:195], v[80:83]
	v_mfma_f32_16x16x32_bf16 v[76:79], v[150:153], v[200:203], v[76:79]
	v_mfma_f32_16x16x32_bf16 v[72:75], v[162:165], v[200:203], v[72:75]
	v_mfma_f32_16x16x32_bf16 v[68:71], v[150:153], v[208:211], v[68:71]
	v_mfma_f32_16x16x32_bf16 v[64:67], v[162:165], v[208:211], v[64:67]
	s_setprio 0
	s_barrier
; #define PG8_STAGE(bufoff, gbase, voff, p64) do { _Pragma("unroll") for (int _i = 0; _i < 2; ++_i) { \
;         const char* _gb = (const char*)(gbase) + (size_t)_i * (p64); const unsigned _la = ldsbase + (unsigned)(bufoff) + (unsigned)_i * 8192u; \
;         asm volatile("s_mov_b32 m0, %0\n\ts_nop 0\n\tglobal_load_lds_dwordx4 %1, %2" :: "s"(_la), "v"(voff), "s"(_gb) : "memory"); } } while (0)
; #define PG8_LDA(dst, b, h) do { _Pragma("unroll") for (int m = 0; m < 4; ++m) _Pragma("unroll") for (int k = 0; k < 2; ++k) dst[m][k] = *(const LAS bf16x8*)(lds + PG8_SA(b, h) + aoff + m * 2048 + k * 1024); } while (0)
; #define PG8_MMA(ai, bj, At, Bt) do { __builtin_amdgcn_s_setprio(1); _Pragma("unroll") for (int m = 0; m < 4; ++m) _Pragma("unroll") for (int n = 0; n < 2; ++n) _Pragma("unroll") for (int k = 0; k < 2; ++k) \
;         acc[ai][bj][m][n] = __builtin_amdgcn_mfma_f32_16x16x32_bf16(Bt[n][k], At[m][k], acc[ai][bj][m][n], 0, 0, 0); __builtin_amdgcn_s_setprio(0); } while (0)
; #define PG8_WAIT_V(n) asm volatile("s_waitcnt vmcnt(" #n ")" ::: "memory")
; #define PG8_WAIT_L(n) asm volatile("s_waitcnt lgkmcnt(" #n ")" ::: "memory")
; #define PG8_BAR __builtin_amdgcn_s_barrier()
; #define PG8_SCHED __builtin_amdgcn_sched_barrier(0)
; template <class Epi, class Sched>
; __device__ __forceinline__ void gemm_phase(LAS unsigned char* lds, const Sched& S, const Epi& E) {
;     ...
;             PG8_LDA(At, 1, 1); PG8_STAGE(PG8_SB(1, 0), b3, vB2, hB2 / 2); PG8_STAGE(PG8_SB(1, 1), b3 + hB2, vB2, hB2 / 2); PG8_STAGE(PG8_SA(1, 0), a3, vA2, hA2 / 2);
;             PG8_WAIT_V(8); PG8_WAIT_L(0); PG8_BAR; PG8_MMA(1, 0, At, B0); PG8_MMA(1, 1, At, B1); PG8_BAR; PG8_SCHED;
;         }
;         if (wr == 0) PG8_BAR;
	s_add_u32 s30, s22, 0x80
	s_addc_u32 s31, s23, 0
	ds_read_b128 v[180:183], v177 offset:49152
	ds_read_b128 v[184:187], v177 offset:50176
	ds_read_b128 v[188:191], v177 offset:51200
	ds_read_b128 v[192:195], v177 offset:52224
	ds_read_b128 v[196:199], v177 offset:53248
	ds_read_b128 v[200:203], v177 offset:54272
	ds_read_b128 v[204:207], v177 offset:55296
	ds_read_b128 v[208:211], v177 offset:56320
	s_mov_b32 m0, s51
	s_nop 0
	global_load_lds_dwordx4 v128, s[30:31]
	s_add_u32 s30, s22, 0x10080
	s_mov_b32 m0, s61
	s_addc_u32 s31, s23, 0
	global_load_lds_dwordx4 v128, s[30:31]
	s_add_u32 s30, s22, 0x20080
	s_mov_b32 m0, s64
	s_addc_u32 s31, s23, 0
	global_load_lds_dwordx4 v128, s[30:31]
	s_add_u32 s22, s22, 0x30080
	s_mov_b32 m0, s65
	s_addc_u32 s23, s23, 0
	global_load_lds_dwordx4 v128, s[22:23]
	s_mov_b32 m0, s62
	s_nop 0
	global_load_lds_dwordx4 v172, s[16:17]
	s_add_u32 s8, s8, 0x20080
	s_mov_b32 m0, s63
	s_addc_u32 s9, s9, 0
	global_load_lds_dwordx4 v172, s[8:9]
	s_waitcnt vmcnt(8) lgkmcnt(0)
	s_barrier
	s_setprio 1
	v_mfma_f32_16x16x32_bf16 v[60:63], v[130:133], v[180:183], v[60:63]
	v_mfma_f32_16x16x32_bf16 v[56:59], v[138:141], v[180:183], v[56:59]
	v_mfma_f32_16x16x32_bf16 v[52:55], v[130:133], v[188:191], v[52:55]
	v_mfma_f32_16x16x32_bf16 v[48:51], v[138:141], v[188:191], v[48:51]
	v_mfma_f32_16x16x32_bf16 v[44:47], v[130:133], v[196:199], v[44:47]
	v_mfma_f32_16x16x32_bf16 v[40:43], v[138:141], v[196:199], v[40:43]
	v_mfma_f32_16x16x32_bf16 v[36:39], v[130:133], v[204:207], v[36:39]
	v_mfma_f32_16x16x32_bf16 v[32:35], v[138:141], v[204:207], v[32:35]
	v_mfma_f32_16x16x32_bf16 v[60:63], v[134:137], v[184:187], v[60:63]
	v_mfma_f32_16x16x32_bf16 v[56:59], v[142:145], v[184:187], v[56:59]
	v_mfma_f32_16x16x32_bf16 v[52:55], v[134:137], v[192:195], v[52:55]
	v_mfma_f32_16x16x32_bf16 v[48:51], v[142:145], v[192:195], v[48:51]
	v_mfma_f32_16x16x32_bf16 v[44:47], v[134:137], v[200:203], v[44:47]
	v_mfma_f32_16x16x32_bf16 v[40:43], v[142:145], v[200:203], v[40:43]
	v_mfma_f32_16x16x32_bf16 v[36:39], v[134:137], v[208:211], v[36:39]
	v_mfma_f32_16x16x32_bf16 v[32:35], v[142:145], v[208:211], v[32:35]
	v_mfma_f32_16x16x32_bf16 v[28:31], v[146:149], v[180:183], v[28:31]
	v_mfma_f32_16x16x32_bf16 v[24:27], v[158:161], v[180:183], v[24:27]
	v_mfma_f32_16x16x32_bf16 v[20:23], v[146:149], v[188:191], v[20:23]
	v_mfma_f32_16x16x32_bf16 v[16:19], v[158:161], v[188:191], v[16:19]
	v_mfma_f32_16x16x32_bf16 v[12:15], v[146:149], v[196:199], v[12:15]
	v_mfma_f32_16x16x32_bf16 v[8:11], v[158:161], v[196:199], v[8:11]
	v_mfma_f32_16x16x32_bf16 v[4:7], v[146:149], v[204:207], v[4:7]
	v_mfma_f32_16x16x32_bf16 v[0:3], v[158:161], v[204:207], v[0:3]
	v_mfma_f32_16x16x32_bf16 v[28:31], v[150:153], v[184:187], v[28:31]
	v_mfma_f32_16x16x32_bf16 v[24:27], v[162:165], v[184:187], v[24:27]
	v_mfma_f32_16x16x32_bf16 v[20:23], v[150:153], v[192:195], v[20:23]
	v_mfma_f32_16x16x32_bf16 v[16:19], v[162:165], v[192:195], v[16:19]
	v_mfma_f32_16x16x32_bf16 v[12:15], v[150:153], v[200:203], v[12:15]
	v_mfma_f32_16x16x32_bf16 v[8:11], v[162:165], v[200:203], v[8:11]
	v_mfma_f32_16x16x32_bf16 v[4:7], v[150:153], v[208:211], v[4:7]
	v_mfma_f32_16x16x32_bf16 v[0:3], v[162:165], v[208:211], v[0:3]
	s_setprio 0
	s_barrier
	s_cmp_ge_u32 s80, s7
	s_mov_b32 s8, s80
	s_cbranch_scc0 .LBB0_844
	s_and_b64 vcc, exec, s[10:11]
	s_cbranch_vccz .LBB0_847
	s_barrier

; #define PG8_STAGE(bufoff, gbase, voff, p64) do { _Pragma("unroll") for (int _i = 0; _i < 2; ++_i) { \
;         const char* _gb = (const char*)(gbase) + (size_t)_i * (p64); const unsigned _la = ldsbase + (unsigned)(bufoff) + (unsigned)_i * 8192u; \
;         asm volatile("s_mov_b32 m0, %0\n\ts_nop 0\n\tglobal_load_lds_dwordx4 %1, %2" :: "s"(_la), "v"(voff), "s"(_gb) : "memory"); } } while (0)
; #define PG8_LDA(dst, b, h) do { _Pragma("unroll") for (int m = 0; m < 4; ++m) _Pragma("unroll") for (int k = 0; k < 2; ++k) dst[m][k] = *(const LAS bf16x8*)(lds + PG8_SA(b, h) + aoff + m * 2048 + k * 1024); } while (0)
; #define PG8_LDB(dst, b, h) do { _Pragma("unroll") for (int n = 0; n < 2; ++n) _Pragma("unroll") for (int k = 0; k < 2; ++k) dst[n][k] = *(const LAS bf16x8*)(lds + PG8_SB(b, h) + boff + n * 2048 + k * 1024); } while (0)
; #define PG8_MMA(ai, bj, At, Bt) do { __builtin_amdgcn_s_setprio(1); _Pragma("unroll") for (int m = 0; m < 4; ++m) _Pragma("unroll") for (int n = 0; n < 2; ++n) _Pragma("unroll") for (int k = 0; k < 2; ++k) \
;         acc[ai][bj][m][n] = __builtin_amdgcn_mfma_f32_16x16x32_bf16(Bt[n][k], At[m][k], acc[ai][bj][m][n], 0, 0, 0); __builtin_amdgcn_s_setprio(0); } while (0)
; #define PG8_WAIT_V(n) asm volatile("s_waitcnt vmcnt(" #n ")" ::: "memory")
; #define PG8_BAR __builtin_amdgcn_s_barrier()
; template <class Epi, class Sched>
; __device__ __forceinline__ void gemm_phase(LAS unsigned char* lds, const Sched& S, const Epi& E) {
;     ...
;             const bool last = (t == nt - 2);
;             const char* a1 = cA + (size_t)(t + 1) * kstep;
;             const char* a2 = last ? nA : cA + (size_t)(t + 2) * kstep; const char* b2 = last ? nB : cB + (size_t)(t + 2) * kstep;
;             const char* a3 = a2 + kstep; const char* b3 = b2 + kstep;
;             const unsigned vA2 = voffA, vB2 = voffB, hA2 = hA, hB2 = hB;
;             PG8_LDB(B0, 0, 0); PG8_LDB(B1, 0, 1); PG8_SCHED; PG8_LDA(At, 0, 0); PG8_STAGE(PG8_SA(1, 1), a1 + hA, voffA, hA / 2);
;             PG8_WAIT_V(8); PG8_WAIT_L(0); PG8_BAR; PG8_MMA(0, 0, At, B0); PG8_MMA(0, 1, At, B1); PG8_BAR; PG8_SCHED;
;             PG8_LDA(At, 0, 1); PG8_STAGE(PG8_SB(0, 0), b2, vB2, hB2 / 2); PG8_STAGE(PG8_SB(0, 1), b2 + hB2, vB2, hB2 / 2); PG8_STAGE(PG8_SA(0, 0), a2, vA2, hA2 / 2);
;             PG8_WAIT_V(8); PG8_WAIT_L(0); PG8_BAR; PG8_MMA(1, 0, At, B0); PG8_MMA(1, 1, At, B1); PG8_BAR; PG8_SCHED;
.LBB0_981:
	ds_read_b128 v[112:115], v162
	ds_read_b128 v[116:119], v162 offset:1024
	ds_read_b128 v[140:143], v162 offset:2048
	ds_read_b128 v[144:147], v162 offset:3072
	ds_read_b128 v[148:151], v163
	ds_read_b128 v[152:155], v163 offset:1024
	ds_read_b128 v[168:171], v163 offset:2048
	ds_read_b128 v[172:175], v163 offset:3072
	s_add_u32 s30, s26, 0xfffc0080
	s_addc_u32 s38, s27, -1
	s_cmp_eq_u32 s65, 12
	s_cselect_b32 s39, s23, s38
	s_cselect_b32 s38, s22, s30
	s_cselect_b32 s42, s24, s62
	s_cselect_b32 s43, s25, s63
	s_add_u32 s40, s38, 0x80
	s_addc_u32 s41, s39, 0
	ds_read_b128 v[178:181], v164
	ds_read_b128 v[182:185], v164 offset:1024
	ds_read_b128 v[186:189], v164 offset:2048
	ds_read_b128 v[190:193], v164 offset:3072
	ds_read_b128 v[194:197], v164 offset:4096
	ds_read_b128 v[198:201], v164 offset:5120
	ds_read_b128 v[202:205], v164 offset:6144
	ds_read_b128 v[206:209], v164 offset:7168
	s_mov_b32 m0, s58
	s_nop 0
	global_load_lds_dwordx4 v158, s[26:27]
	s_add_u32 s66, s26, 0x20000
	s_mov_b32 m0, s59
	s_addc_u32 s67, s27, 0
	global_load_lds_dwordx4 v158, s[66:67]
	s_waitcnt vmcnt(8) lgkmcnt(0)
	s_barrier
	s_setprio 1
	v_mfma_f32_16x16x32_bf16 v[132:135], v[112:115], v[178:181], v[132:135]
	v_mfma_f32_16x16x32_bf16 v[128:131], v[140:143], v[178:181], v[128:131]
	v_mfma_f32_16x16x32_bf16 v[124:127], v[112:115], v[186:189], v[124:127]
	v_mfma_f32_16x16x32_bf16 v[120:123], v[140:143], v[186:189], v[120:123]
	v_mfma_f32_16x16x32_bf16 v[108:111], v[112:115], v[194:197], v[108:111]
	v_mfma_f32_16x16x32_bf16 v[104:107], v[140:143], v[194:197], v[104:107]
	v_mfma_f32_16x16x32_bf16 v[100:103], v[112:115], v[202:205], v[100:103]
	v_mfma_f32_16x16x32_bf16 v[96:99], v[140:143], v[202:205], v[96:99]
	v_mfma_f32_16x16x32_bf16 v[132:135], v[116:119], v[182:185], v[132:135]
	v_mfma_f32_16x16x32_bf16 v[128:131], v[144:147], v[182:185], v[128:131]
	v_mfma_f32_16x16x32_bf16 v[124:127], v[116:119], v[190:193], v[124:127]
	v_mfma_f32_16x16x32_bf16 v[120:123], v[144:147], v[190:193], v[120:123]
	v_mfma_f32_16x16x32_bf16 v[108:111], v[116:119], v[198:201], v[108:111]
	v_mfma_f32_16x16x32_bf16 v[104:107], v[144:147], v[198:201], v[104:107]
	v_mfma_f32_16x16x32_bf16 v[100:103], v[116:119], v[206:209], v[100:103]
	v_mfma_f32_16x16x32_bf16 v[96:99], v[144:147], v[206:209], v[96:99]
	s_add_i32 s65, s65, 2
	s_add_u32 s26, s26, 0x100
	s_addc_u32 s27, s27, 0
	s_add_u32 s62, s62, 0x100
	s_addc_u32 s63, s63, 0
	v_mfma_f32_16x16x32_bf16 v[60:63], v[148:151], v[178:181], v[60:63]
	v_mfma_f32_16x16x32_bf16 v[56:59], v[168:171], v[178:181], v[56:59]
	v_mfma_f32_16x16x32_bf16 v[52:55], v[148:151], v[186:189], v[52:55]
	v_mfma_f32_16x16x32_bf16 v[48:51], v[168:171], v[186:189], v[48:51]
	v_mfma_f32_16x16x32_bf16 v[44:47], v[148:151], v[194:197], v[44:47]
	v_mfma_f32_16x16x32_bf16 v[40:43], v[168:171], v[194:197], v[40:43]
	v_mfma_f32_16x16x32_bf16 v[36:39], v[148:151], v[202:205], v[36:39]
	v_mfma_f32_16x16x32_bf16 v[32:35], v[168:171], v[202:205], v[32:35]
	v_mfma_f32_16x16x32_bf16 v[60:63], v[152:155], v[182:185], v[60:63]
	v_mfma_f32_16x16x32_bf16 v[56:59], v[172:175], v[182:185], v[56:59]
	v_mfma_f32_16x16x32_bf16 v[52:55], v[152:155], v[190:193], v[52:55]
	v_mfma_f32_16x16x32_bf16 v[48:51], v[172:175], v[190:193], v[48:51]
	v_mfma_f32_16x16x32_bf16 v[44:47], v[152:155], v[198:201], v[44:47]
	v_mfma_f32_16x16x32_bf16 v[40:43], v[172:175], v[198:201], v[40:43]
	v_mfma_f32_16x16x32_bf16 v[36:39], v[152:155], v[206:209], v[36:39]
	v_mfma_f32_16x16x32_bf16 v[32:35], v[172:175], v[206:209], v[32:35]
	s_setprio 0
	s_barrier
	s_add_u32 s66, s42, 0x20000
	ds_read_b128 v[178:181], v164 offset:16384
	ds_read_b128 v[182:185], v164 offset:17408
	ds_read_b128 v[186:189], v164 offset:18432
	ds_read_b128 v[190:193], v164 offset:19456
	ds_read_b128 v[194:197], v164 offset:20480
	ds_read_b128 v[198:201], v164 offset:21504
	ds_read_b128 v[202:205], v164 offset:22528
	ds_read_b128 v[206:209], v164 offset:23552
	s_mov_b32 m0, s35
	s_nop 0
	global_load_lds_dwordx4 v159, s[42:43]
	s_mov_b32 m0, s36
	s_addc_u32 s67, s43, 0
	global_load_lds_dwordx4 v159, s[66:67]
	s_add_u32 s66, s42, 0x40000
	s_mov_b32 m0, s37
	s_addc_u32 s67, s43, 0
	global_load_lds_dwordx4 v159, s[66:67]
	s_add_u32 s66, s42, 0x60000
	s_mov_b32 m0, s44
	s_addc_u32 s67, s43, 0
	global_load_lds_dwordx4 v159, s[66:67]
	s_mov_b32 m0, s34
	s_nop 0
	global_load_lds_dwordx4 v158, s[38:39]
	s_add_u32 s66, s38, 0x20000
	s_mov_b32 m0, s45
	s_addc_u32 s67, s39, 0
	global_load_lds_dwordx4 v158, s[66:67]
	s_waitcnt vmcnt(8) lgkmcnt(0)
	s_barrier
; #define PG8_STAGE(bufoff, gbase, voff, p64) do { _Pragma("unroll") for (int _i = 0; _i < 2; ++_i) { \
;         const char* _gb = (const char*)(gbase) + (size_t)_i * (p64); const unsigned _la = ldsbase + (unsigned)(bufoff) + (unsigned)_i * 8192u; \
;         asm volatile("s_mov_b32 m0, %0\n\ts_nop 0\n\tglobal_load_lds_dwordx4 %1, %2" :: "s"(_la), "v"(voff), "s"(_gb) : "memory"); } } while (0)
; #define PG8_LDA(dst, b, h) do { _Pragma("unroll") for (int m = 0; m < 4; ++m) _Pragma("unroll") for (int k = 0; k < 2; ++k) dst[m][k] = *(const LAS bf16x8*)(lds + PG8_SA(b, h) + aoff + m * 2048 + k * 1024); } while (0)
; #define PG8_LDB(dst, b, h) do { _Pragma("unroll") for (int n = 0; n < 2; ++n) _Pragma("unroll") for (int k = 0; k < 2; ++k) dst[n][k] = *(const LAS bf16x8*)(lds + PG8_SB(b, h) + boff + n * 2048 + k * 1024); } while (0)
; #define PG8_MMA(ai, bj, At, Bt) do { __builtin_amdgcn_s_setprio(1); _Pragma("unroll") for (int m = 0; m < 4; ++m) _Pragma("unroll") for (int n = 0; n < 2; ++n) _Pragma("unroll") for (int k = 0; k < 2; ++k) \
;         acc[ai][bj][m][n] = __builtin_amdgcn_mfma_f32_16x16x32_bf16(Bt[n][k], At[m][k], acc[ai][bj][m][n], 0, 0, 0); __builtin_amdgcn_s_setprio(0); } while (0)
; #define PG8_WAIT_V(n) asm volatile("s_waitcnt vmcnt(" #n ")" ::: "memory")
; #define PG8_WAIT_L(n) asm volatile("s_waitcnt lgkmcnt(" #n ")" ::: "memory")
; #define PG8_BAR __builtin_amdgcn_s_barrier()
; #define PG8_SCHED __builtin_amdgcn_sched_barrier(0)
; template <class Epi, class Sched>
; __device__ __forceinline__ void gemm_phase(LAS unsigned char* lds, const Sched& S, const Epi& E) {
;     ...
;             PG8_WAIT_V(8); PG8_WAIT_L(0); PG8_BAR; PG8_MMA(1, 0, At, B0); PG8_MMA(1, 1, At, B1); PG8_BAR; PG8_SCHED;
;             PG8_LDB(B0, 1, 0); PG8_LDB(B1, 1, 1); PG8_SCHED; PG8_LDA(At, 1, 0); PG8_STAGE(PG8_SA(0, 1), a2 + hA2, vA2, hA2 / 2);
;             PG8_WAIT_V(8); PG8_WAIT_L(0); PG8_BAR; PG8_MMA(0, 0, At, B0); PG8_MMA(0, 1, At, B1); PG8_BAR; PG8_SCHED;
	s_setprio 1
	v_mfma_f32_16x16x32_bf16 v[92:95], v[112:115], v[178:181], v[92:95]
	v_mfma_f32_16x16x32_bf16 v[88:91], v[140:143], v[178:181], v[88:91]
	v_mfma_f32_16x16x32_bf16 v[84:87], v[112:115], v[186:189], v[84:87]
	v_mfma_f32_16x16x32_bf16 v[80:83], v[140:143], v[186:189], v[80:83]
	v_mfma_f32_16x16x32_bf16 v[76:79], v[112:115], v[194:197], v[76:79]
	v_mfma_f32_16x16x32_bf16 v[72:75], v[140:143], v[194:197], v[72:75]
	v_mfma_f32_16x16x32_bf16 v[68:71], v[112:115], v[202:205], v[68:71]
	v_mfma_f32_16x16x32_bf16 v[64:67], v[140:143], v[202:205], v[64:67]
	v_mfma_f32_16x16x32_bf16 v[92:95], v[116:119], v[182:185], v[92:95]
	v_mfma_f32_16x16x32_bf16 v[88:91], v[144:147], v[182:185], v[88:91]
	v_mfma_f32_16x16x32_bf16 v[84:87], v[116:119], v[190:193], v[84:87]
	v_mfma_f32_16x16x32_bf16 v[80:83], v[144:147], v[190:193], v[80:83]
	v_mfma_f32_16x16x32_bf16 v[76:79], v[116:119], v[198:201], v[76:79]
	v_mfma_f32_16x16x32_bf16 v[72:75], v[144:147], v[198:201], v[72:75]
	v_mfma_f32_16x16x32_bf16 v[68:71], v[116:119], v[206:209], v[68:71]
	v_mfma_f32_16x16x32_bf16 v[64:67], v[144:147], v[206:209], v[64:67]
	v_mfma_f32_16x16x32_bf16 v[28:31], v[148:151], v[178:181], v[28:31]
	v_mfma_f32_16x16x32_bf16 v[24:27], v[168:171], v[178:181], v[24:27]
	v_mfma_f32_16x16x32_bf16 v[20:23], v[148:151], v[186:189], v[20:23]
	v_mfma_f32_16x16x32_bf16 v[16:19], v[168:171], v[186:189], v[16:19]
	v_mfma_f32_16x16x32_bf16 v[12:15], v[148:151], v[194:197], v[12:15]
	v_mfma_f32_16x16x32_bf16 v[8:11], v[168:171], v[194:197], v[8:11]
	v_mfma_f32_16x16x32_bf16 v[4:7], v[148:151], v[202:205], v[4:7]
	v_mfma_f32_16x16x32_bf16 v[0:3], v[168:171], v[202:205], v[0:3]
	v_mfma_f32_16x16x32_bf16 v[28:31], v[152:155], v[182:185], v[28:31]
	v_mfma_f32_16x16x32_bf16 v[24:27], v[172:175], v[182:185], v[24:27]
	v_mfma_f32_16x16x32_bf16 v[20:23], v[152:155], v[190:193], v[20:23]
	v_mfma_f32_16x16x32_bf16 v[16:19], v[172:175], v[190:193], v[16:19]
	v_mfma_f32_16x16x32_bf16 v[12:15], v[152:155], v[198:201], v[12:15]
	v_mfma_f32_16x16x32_bf16 v[8:11], v[172:175], v[198:201], v[8:11]
	v_mfma_f32_16x16x32_bf16 v[4:7], v[152:155], v[206:209], v[4:7]
	v_mfma_f32_16x16x32_bf16 v[0:3], v[172:175], v[206:209], v[0:3]
	s_setprio 0
	s_barrier
	ds_read_b128 v[112:115], v165
	ds_read_b128 v[116:119], v165 offset:1024
	ds_read_b128 v[140:143], v165 offset:2048
	ds_read_b128 v[144:147], v165 offset:3072
	ds_read_b128 v[148:151], v166
	ds_read_b128 v[152:155], v166 offset:1024
	ds_read_b128 v[168:171], v166 offset:2048
	ds_read_b128 v[172:175], v166 offset:3072
	ds_read_b128 v[178:181], v164 offset:32768
	ds_read_b128 v[182:185], v164 offset:33792
	ds_read_b128 v[186:189], v164 offset:34816
	ds_read_b128 v[190:193], v164 offset:35840
	ds_read_b128 v[194:197], v164 offset:36864
	ds_read_b128 v[198:201], v164 offset:37888
	ds_read_b128 v[202:205], v164 offset:38912
	ds_read_b128 v[206:209], v164 offset:39936
	s_add_u32 s66, s38, 0x40000
	s_mov_b32 m0, s46
	s_addc_u32 s67, s39, 0
	global_load_lds_dwordx4 v158, s[66:67]
	s_add_u32 s66, s38, 0x60000
	s_mov_b32 m0, s47
	s_addc_u32 s67, s39, 0
	global_load_lds_dwordx4 v158, s[66:67]
	s_waitcnt vmcnt(8) lgkmcnt(0)
	s_barrier
	s_setprio 1
	v_mfma_f32_16x16x32_bf16 v[132:135], v[112:115], v[178:181], v[132:135]
	v_mfma_f32_16x16x32_bf16 v[128:131], v[140:143], v[178:181], v[128:131]
	v_mfma_f32_16x16x32_bf16 v[124:127], v[112:115], v[186:189], v[124:127]
	v_mfma_f32_16x16x32_bf16 v[120:123], v[140:143], v[186:189], v[120:123]
	v_mfma_f32_16x16x32_bf16 v[108:111], v[112:115], v[194:197], v[108:111]
	v_mfma_f32_16x16x32_bf16 v[104:107], v[140:143], v[194:197], v[104:107]
	v_mfma_f32_16x16x32_bf16 v[100:103], v[112:115], v[202:205], v[100:103]
	v_mfma_f32_16x16x32_bf16 v[96:99], v[140:143], v[202:205], v[96:99]
	v_mfma_f32_16x16x32_bf16 v[132:135], v[116:119], v[182:185], v[132:135]
	v_mfma_f32_16x16x32_bf16 v[128:131], v[144:147], v[182:185], v[128:131]
	v_mfma_f32_16x16x32_bf16 v[124:127], v[116:119], v[190:193], v[124:127]
	v_mfma_f32_16x16x32_bf16 v[120:123], v[144:147], v[190:193], v[120:123]
	v_mfma_f32_16x16x32_bf16 v[108:111], v[116:119], v[198:201], v[108:111]
	v_mfma_f32_16x16x32_bf16 v[104:107], v[144:147], v[198:201], v[104:107]
	v_mfma_f32_16x16x32_bf16 v[100:103], v[116:119], v[206:209], v[100:103]
	v_mfma_f32_16x16x32_bf16 v[96:99], v[144:147], v[206:209], v[96:99]
	v_mfma_f32_16x16x32_bf16 v[60:63], v[148:151], v[178:181], v[60:63]
	v_mfma_f32_16x16x32_bf16 v[56:59], v[168:171], v[178:181], v[56:59]
	v_mfma_f32_16x16x32_bf16 v[52:55], v[148:151], v[186:189], v[52:55]
	v_mfma_f32_16x16x32_bf16 v[48:51], v[168:171], v[186:189], v[48:51]
	v_mfma_f32_16x16x32_bf16 v[44:47], v[148:151], v[194:197], v[44:47]
	v_mfma_f32_16x16x32_bf16 v[40:43], v[168:171], v[194:197], v[40:43]
	v_mfma_f32_16x16x32_bf16 v[36:39], v[148:151], v[202:205], v[36:39]
	v_mfma_f32_16x16x32_bf16 v[32:35], v[168:171], v[202:205], v[32:35]
	v_mfma_f32_16x16x32_bf16 v[60:63], v[152:155], v[182:185], v[60:63]
	v_mfma_f32_16x16x32_bf16 v[56:59], v[172:175], v[182:185], v[56:59]
	v_mfma_f32_16x16x32_bf16 v[52:55], v[152:155], v[190:193], v[52:55]
	v_mfma_f32_16x16x32_bf16 v[48:51], v[172:175], v[190:193], v[48:51]
	v_mfma_f32_16x16x32_bf16 v[44:47], v[152:155], v[198:201], v[44:47]
	v_mfma_f32_16x16x32_bf16 v[40:43], v[172:175], v[198:201], v[40:43]
	v_mfma_f32_16x16x32_bf16 v[36:39], v[152:155], v[206:209], v[36:39]
	v_mfma_f32_16x16x32_bf16 v[32:35], v[172:175], v[206:209], v[32:35]
	s_setprio 0
	s_barrier
; #define PG8_STAGE(bufoff, gbase, voff, p64) do { _Pragma("unroll") for (int _i = 0; _i < 2; ++_i) { \
;         const char* _gb = (const char*)(gbase) + (size_t)_i * (p64); const unsigned _la = ldsbase + (unsigned)(bufoff) + (unsigned)_i * 8192u; \
;         asm volatile("s_mov_b32 m0, %0\n\ts_nop 0\n\tglobal_load_lds_dwordx4 %1, %2" :: "s"(_la), "v"(voff), "s"(_gb) : "memory"); } } while (0)
; #define PG8_LDA(dst, b, h) do { _Pragma("unroll") for (int m = 0; m < 4; ++m) _Pragma("unroll") for (int k = 0; k < 2; ++k) dst[m][k] = *(const LAS bf16x8*)(lds + PG8_SA(b, h) + aoff + m * 2048 + k * 1024); } while (0)
; #define PG8_MMA(ai, bj, At, Bt) do { __builtin_amdgcn_s_setprio(1); _Pragma("unroll") for (int m = 0; m < 4; ++m) _Pragma("unroll") for (int n = 0; n < 2; ++n) _Pragma("unroll") for (int k = 0; k < 2; ++k) \
;         acc[ai][bj][m][n] = __builtin_amdgcn_mfma_f32_16x16x32_bf16(Bt[n][k], At[m][k], acc[ai][bj][m][n], 0, 0, 0); __builtin_amdgcn_s_setprio(0); } while (0)
; #define PG8_WAIT_V(n) asm volatile("s_waitcnt vmcnt(" #n ")" ::: "memory")
; #define PG8_WAIT_L(n) asm volatile("s_waitcnt lgkmcnt(" #n ")" ::: "memory")
; #define PG8_BAR __builtin_amdgcn_s_barrier()
; #define PG8_SCHED __builtin_amdgcn_sched_barrier(0)
; template <class Epi, class Sched>
; __device__ __forceinline__ void gemm_phase(LAS unsigned char* lds, const Sched& S, const Epi& E) {
;     ...
;             PG8_LDA(At, 1, 1); PG8_STAGE(PG8_SB(1, 0), b3, vB2, hB2 / 2); PG8_STAGE(PG8_SB(1, 1), b3 + hB2, vB2, hB2 / 2); PG8_STAGE(PG8_SA(1, 0), a3, vA2, hA2 / 2);
;             PG8_WAIT_V(8); PG8_WAIT_L(0); PG8_BAR; PG8_MMA(1, 0, At, B0); PG8_MMA(1, 1, At, B1); PG8_BAR; PG8_SCHED;
;         }
;         if (wr == 0) PG8_BAR;
	s_add_u32 s66, s42, 0x80
	s_addc_u32 s67, s43, 0
	ds_read_b128 v[178:181], v164 offset:49152
	ds_read_b128 v[182:185], v164 offset:50176
	ds_read_b128 v[186:189], v164 offset:51200
	ds_read_b128 v[190:193], v164 offset:52224
	ds_read_b128 v[194:197], v164 offset:53248
	ds_read_b128 v[198:201], v164 offset:54272
	ds_read_b128 v[202:205], v164 offset:55296
	ds_read_b128 v[206:209], v164 offset:56320
	s_mov_b32 m0, s52
	s_nop 0
	global_load_lds_dwordx4 v159, s[66:67]
	s_add_u32 s66, s42, 0x20080
	s_mov_b32 m0, s53
	s_addc_u32 s67, s43, 0
	global_load_lds_dwordx4 v159, s[66:67]
	s_add_u32 s66, s42, 0x40080
	s_mov_b32 m0, s56
	s_addc_u32 s67, s43, 0
	global_load_lds_dwordx4 v159, s[66:67]
	s_add_u32 s42, s42, 0x60080
	s_mov_b32 m0, s57
	s_addc_u32 s43, s43, 0
	global_load_lds_dwordx4 v159, s[42:43]
	s_mov_b32 m0, s54
	s_nop 0
	global_load_lds_dwordx4 v158, s[40:41]
	s_add_u32 s38, s38, 0x20080
	s_mov_b32 m0, s55
	s_addc_u32 s39, s39, 0
	global_load_lds_dwordx4 v158, s[38:39]
	s_waitcnt vmcnt(8) lgkmcnt(0)
	s_barrier
	s_setprio 1
	v_mfma_f32_16x16x32_bf16 v[92:95], v[112:115], v[178:181], v[92:95]
	v_mfma_f32_16x16x32_bf16 v[88:91], v[140:143], v[178:181], v[88:91]
	v_mfma_f32_16x16x32_bf16 v[84:87], v[112:115], v[186:189], v[84:87]
	v_mfma_f32_16x16x32_bf16 v[80:83], v[140:143], v[186:189], v[80:83]
	v_mfma_f32_16x16x32_bf16 v[76:79], v[112:115], v[194:197], v[76:79]
	v_mfma_f32_16x16x32_bf16 v[72:75], v[140:143], v[194:197], v[72:75]
	v_mfma_f32_16x16x32_bf16 v[68:71], v[112:115], v[202:205], v[68:71]
	v_mfma_f32_16x16x32_bf16 v[64:67], v[140:143], v[202:205], v[64:67]
	v_mfma_f32_16x16x32_bf16 v[92:95], v[116:119], v[182:185], v[92:95]
	v_mfma_f32_16x16x32_bf16 v[88:91], v[144:147], v[182:185], v[88:91]
	v_mfma_f32_16x16x32_bf16 v[84:87], v[116:119], v[190:193], v[84:87]
	v_mfma_f32_16x16x32_bf16 v[80:83], v[144:147], v[190:193], v[80:83]
	v_mfma_f32_16x16x32_bf16 v[76:79], v[116:119], v[198:201], v[76:79]
	v_mfma_f32_16x16x32_bf16 v[72:75], v[144:147], v[198:201], v[72:75]
	v_mfma_f32_16x16x32_bf16 v[68:71], v[116:119], v[206:209], v[68:71]
	v_mfma_f32_16x16x32_bf16 v[64:67], v[144:147], v[206:209], v[64:67]
	v_mfma_f32_16x16x32_bf16 v[28:31], v[148:151], v[178:181], v[28:31]
	v_mfma_f32_16x16x32_bf16 v[24:27], v[168:171], v[178:181], v[24:27]
	v_mfma_f32_16x16x32_bf16 v[20:23], v[148:151], v[186:189], v[20:23]
	v_mfma_f32_16x16x32_bf16 v[16:19], v[168:171], v[186:189], v[16:19]
	v_mfma_f32_16x16x32_bf16 v[12:15], v[148:151], v[194:197], v[12:15]
	v_mfma_f32_16x16x32_bf16 v[8:11], v[168:171], v[194:197], v[8:11]
	v_mfma_f32_16x16x32_bf16 v[4:7], v[148:151], v[202:205], v[4:7]
	v_mfma_f32_16x16x32_bf16 v[0:3], v[168:171], v[202:205], v[0:3]
	v_mfma_f32_16x16x32_bf16 v[28:31], v[152:155], v[182:185], v[28:31]
	v_mfma_f32_16x16x32_bf16 v[24:27], v[172:175], v[182:185], v[24:27]
	v_mfma_f32_16x16x32_bf16 v[20:23], v[152:155], v[190:193], v[20:23]
	v_mfma_f32_16x16x32_bf16 v[16:19], v[172:175], v[190:193], v[16:19]
	v_mfma_f32_16x16x32_bf16 v[12:15], v[152:155], v[198:201], v[12:15]
	v_mfma_f32_16x16x32_bf16 v[8:11], v[172:175], v[198:201], v[8:11]
	v_mfma_f32_16x16x32_bf16 v[4:7], v[152:155], v[206:209], v[4:7]
	v_mfma_f32_16x16x32_bf16 v[0:3], v[172:175], v[206:209], v[0:3]
	s_setprio 0
	s_barrier
	s_cmp_gt_u32 s65, 13
	s_cbranch_scc0 .LBB0_981
	s_and_b64 vcc, exec, s[14:15]
	s_cbranch_vccz .LBB0_984
	s_barrier

; #define PG8_STAGE(bufoff, gbase, voff, p64) do { _Pragma("unroll") for (int _i = 0; _i < 2; ++_i) { \
;         const char* _gb = (const char*)(gbase) + (size_t)_i * (p64); const unsigned _la = ldsbase + (unsigned)(bufoff) + (unsigned)_i * 8192u; \
;         asm volatile("s_mov_b32 m0, %0\n\ts_nop 0\n\tglobal_load_lds_dwordx4 %1, %2" :: "s"(_la), "v"(voff), "s"(_gb) : "memory"); } } while (0)
; #define PG8_LDA(dst, b, h) do { _Pragma("unroll") for (int m = 0; m < 4; ++m) _Pragma("unroll") for (int k = 0; k < 2; ++k) dst[m][k] = *(const LAS bf16x8*)(lds + PG8_SA(b, h) + aoff + m * 2048 + k * 1024); } while (0)
; #define PG8_LDB(dst, b, h) do { _Pragma("unroll") for (int n = 0; n < 2; ++n) _Pragma("unroll") for (int k = 0; k < 2; ++k) dst[n][k] = *(const LAS bf16x8*)(lds + PG8_SB(b, h) + boff + n * 2048 + k * 1024); } while (0)
; #define PG8_MMA(ai, bj, At, Bt) do { __builtin_amdgcn_s_setprio(1); _Pragma("unroll") for (int m = 0; m < 4; ++m) _Pragma("unroll") for (int n = 0; n < 2; ++n) _Pragma("unroll") for (int k = 0; k < 2; ++k) \
;         acc[ai][bj][m][n] = __builtin_amdgcn_mfma_f32_16x16x32_bf16(Bt[n][k], At[m][k], acc[ai][bj][m][n], 0, 0, 0); __builtin_amdgcn_s_setprio(0); } while (0)
; #define PG8_WAIT_V(n) asm volatile("s_waitcnt vmcnt(" #n ")" ::: "memory")
; #define PG8_BAR __builtin_amdgcn_s_barrier()
; template <class Epi, class Sched>
; __device__ __forceinline__ void gemm_phase(LAS unsigned char* lds, const Sched& S, const Epi& E) {
;     ...
;             const bool last = (t == nt - 2);
;             const char* a1 = cA + (size_t)(t + 1) * kstep;
;             const char* a2 = last ? nA : cA + (size_t)(t + 2) * kstep; const char* b2 = last ? nB : cB + (size_t)(t + 2) * kstep;
;             const char* a3 = a2 + kstep; const char* b3 = b2 + kstep;
;             const unsigned vA2 = voffA, vB2 = voffB, hA2 = hA, hB2 = hB;
;             PG8_LDB(B0, 0, 0); PG8_LDB(B1, 0, 1); PG8_SCHED; PG8_LDA(At, 0, 0); PG8_STAGE(PG8_SA(1, 1), a1 + hA, voffA, hA / 2);
;             PG8_WAIT_V(8); PG8_WAIT_L(0); PG8_BAR; PG8_MMA(0, 0, At, B0); PG8_MMA(0, 1, At, B1); PG8_BAR; PG8_SCHED;
;             PG8_LDA(At, 0, 1); PG8_STAGE(PG8_SB(0, 0), b2, vB2, hB2 / 2); PG8_STAGE(PG8_SB(0, 1), b2 + hB2, vB2, hB2 / 2); PG8_STAGE(PG8_SA(0, 0), a2, vA2, hA2 / 2);
;             PG8_WAIT_V(8); PG8_WAIT_L(0); PG8_BAR; PG8_MMA(1, 0, At, B0); PG8_MMA(1, 1, At, B1); PG8_BAR; PG8_SCHED;
.LBB0_1011:
	ds_read_b128 v[144:147], v138
	ds_read_b128 v[148:151], v138 offset:1024
	ds_read_b128 v[152:155], v138 offset:2048
	ds_read_b128 v[156:159], v138 offset:3072
	ds_read_b128 v[160:163], v139
	ds_read_b128 v[164:167], v139 offset:1024
	ds_read_b128 v[168:171], v139 offset:2048
	ds_read_b128 v[172:175], v139 offset:3072
	s_add_u32 s30, s26, 0xfffc0080
	s_addc_u32 s38, s27, -1
	s_cmp_eq_u32 s63, 12
	s_cselect_b32 s39, s23, s38
	s_cselect_b32 s38, s22, s30
	s_cselect_b32 s42, s24, s61
	s_cselect_b32 s43, s25, s62
	s_add_u32 s40, s38, 0x80
	s_addc_u32 s41, s39, 0
	ds_read_b128 v[178:181], v140
	ds_read_b128 v[182:185], v140 offset:1024
	ds_read_b128 v[186:189], v140 offset:2048
	ds_read_b128 v[190:193], v140 offset:3072
	ds_read_b128 v[194:197], v140 offset:4096
	ds_read_b128 v[198:201], v140 offset:5120
	ds_read_b128 v[202:205], v140 offset:6144
	ds_read_b128 v[206:209], v140 offset:7168
	s_mov_b32 m0, s57
	s_nop 0
	global_load_lds_dwordx4 v134, s[26:27]
	s_add_u32 s66, s26, 0x20000
	s_mov_b32 m0, s58
	s_addc_u32 s67, s27, 0
	global_load_lds_dwordx4 v134, s[66:67]
	s_waitcnt vmcnt(8) lgkmcnt(0)
	s_barrier
	s_setprio 1
	v_mfma_f32_16x16x32_bf16 v[120:123], v[144:147], v[178:181], v[120:123]
	v_mfma_f32_16x16x32_bf16 v[116:119], v[152:155], v[178:181], v[116:119]
	v_mfma_f32_16x16x32_bf16 v[104:107], v[144:147], v[186:189], v[104:107]
	v_mfma_f32_16x16x32_bf16 v[100:103], v[152:155], v[186:189], v[100:103]
	v_mfma_f32_16x16x32_bf16 v[88:91], v[144:147], v[194:197], v[88:91]
	v_mfma_f32_16x16x32_bf16 v[84:87], v[152:155], v[194:197], v[84:87]
	v_mfma_f32_16x16x32_bf16 v[72:75], v[144:147], v[202:205], v[72:75]
	v_mfma_f32_16x16x32_bf16 v[68:71], v[152:155], v[202:205], v[68:71]
	v_mfma_f32_16x16x32_bf16 v[120:123], v[148:151], v[182:185], v[120:123]
	v_mfma_f32_16x16x32_bf16 v[116:119], v[156:159], v[182:185], v[116:119]
	v_mfma_f32_16x16x32_bf16 v[104:107], v[148:151], v[190:193], v[104:107]
	v_mfma_f32_16x16x32_bf16 v[100:103], v[156:159], v[190:193], v[100:103]
	v_mfma_f32_16x16x32_bf16 v[88:91], v[148:151], v[198:201], v[88:91]
	v_mfma_f32_16x16x32_bf16 v[84:87], v[156:159], v[198:201], v[84:87]
	v_mfma_f32_16x16x32_bf16 v[72:75], v[148:151], v[206:209], v[72:75]
	v_mfma_f32_16x16x32_bf16 v[68:71], v[156:159], v[206:209], v[68:71]
	s_add_i32 s63, s63, 2
	s_add_u32 s26, s26, 0x100
	s_addc_u32 s27, s27, 0
	s_add_u32 s61, s61, 0x100
	s_addc_u32 s62, s62, 0
	v_mfma_f32_16x16x32_bf16 v[124:127], v[160:163], v[178:181], v[124:127]
	v_mfma_f32_16x16x32_bf16 v[112:115], v[168:171], v[178:181], v[112:115]
	v_mfma_f32_16x16x32_bf16 v[108:111], v[160:163], v[186:189], v[108:111]
	v_mfma_f32_16x16x32_bf16 v[96:99], v[168:171], v[186:189], v[96:99]
	v_mfma_f32_16x16x32_bf16 v[92:95], v[160:163], v[194:197], v[92:95]
	v_mfma_f32_16x16x32_bf16 v[80:83], v[168:171], v[194:197], v[80:83]
	v_mfma_f32_16x16x32_bf16 v[76:79], v[160:163], v[202:205], v[76:79]
	v_mfma_f32_16x16x32_bf16 v[64:67], v[168:171], v[202:205], v[64:67]
	v_mfma_f32_16x16x32_bf16 v[124:127], v[164:167], v[182:185], v[124:127]
	v_mfma_f32_16x16x32_bf16 v[112:115], v[172:175], v[182:185], v[112:115]
	v_mfma_f32_16x16x32_bf16 v[108:111], v[164:167], v[190:193], v[108:111]
	v_mfma_f32_16x16x32_bf16 v[96:99], v[172:175], v[190:193], v[96:99]
	v_mfma_f32_16x16x32_bf16 v[92:95], v[164:167], v[198:201], v[92:95]
	v_mfma_f32_16x16x32_bf16 v[80:83], v[172:175], v[198:201], v[80:83]
	v_mfma_f32_16x16x32_bf16 v[76:79], v[164:167], v[206:209], v[76:79]
	v_mfma_f32_16x16x32_bf16 v[64:67], v[172:175], v[206:209], v[64:67]
	s_setprio 0
	s_barrier
	s_add_u32 s66, s42, 0x20000
	ds_read_b128 v[178:181], v140 offset:16384
	ds_read_b128 v[182:185], v140 offset:17408
	ds_read_b128 v[186:189], v140 offset:18432
	ds_read_b128 v[190:193], v140 offset:19456
	ds_read_b128 v[194:197], v140 offset:20480
	ds_read_b128 v[198:201], v140 offset:21504
	ds_read_b128 v[202:205], v140 offset:22528
	ds_read_b128 v[206:209], v140 offset:23552
	s_mov_b32 m0, s35
	s_nop 0
	global_load_lds_dwordx4 v135, s[42:43]
	s_mov_b32 m0, s36
	s_addc_u32 s67, s43, 0
	global_load_lds_dwordx4 v135, s[66:67]
	s_add_u32 s66, s42, 0x40000
	s_mov_b32 m0, s37
	s_addc_u32 s67, s43, 0
	global_load_lds_dwordx4 v135, s[66:67]
	s_add_u32 s66, s42, 0x60000
	s_mov_b32 m0, s44
	s_addc_u32 s67, s43, 0
	global_load_lds_dwordx4 v135, s[66:67]
	s_mov_b32 m0, s34
	s_nop 0
	global_load_lds_dwordx4 v134, s[38:39]
	s_add_u32 s66, s38, 0x20000
	s_mov_b32 m0, s45
	s_addc_u32 s67, s39, 0
	global_load_lds_dwordx4 v134, s[66:67]
	s_waitcnt vmcnt(8) lgkmcnt(0)
	s_barrier
; #define PG8_STAGE(bufoff, gbase, voff, p64) do { _Pragma("unroll") for (int _i = 0; _i < 2; ++_i) { \
;         const char* _gb = (const char*)(gbase) + (size_t)_i * (p64); const unsigned _la = ldsbase + (unsigned)(bufoff) + (unsigned)_i * 8192u; \
;         asm volatile("s_mov_b32 m0, %0\n\ts_nop 0\n\tglobal_load_lds_dwordx4 %1, %2" :: "s"(_la), "v"(voff), "s"(_gb) : "memory"); } } while (0)
; #define PG8_LDA(dst, b, h) do { _Pragma("unroll") for (int m = 0; m < 4; ++m) _Pragma("unroll") for (int k = 0; k < 2; ++k) dst[m][k] = *(const LAS bf16x8*)(lds + PG8_SA(b, h) + aoff + m * 2048 + k * 1024); } while (0)
; #define PG8_LDB(dst, b, h) do { _Pragma("unroll") for (int n = 0; n < 2; ++n) _Pragma("unroll") for (int k = 0; k < 2; ++k) dst[n][k] = *(const LAS bf16x8*)(lds + PG8_SB(b, h) + boff + n * 2048 + k * 1024); } while (0)
; #define PG8_MMA(ai, bj, At, Bt) do { __builtin_amdgcn_s_setprio(1); _Pragma("unroll") for (int m = 0; m < 4; ++m) _Pragma("unroll") for (int n = 0; n < 2; ++n) _Pragma("unroll") for (int k = 0; k < 2; ++k) \
;         acc[ai][bj][m][n] = __builtin_amdgcn_mfma_f32_16x16x32_bf16(Bt[n][k], At[m][k], acc[ai][bj][m][n], 0, 0, 0); __builtin_amdgcn_s_setprio(0); } while (0)
; #define PG8_WAIT_V(n) asm volatile("s_waitcnt vmcnt(" #n ")" ::: "memory")
; #define PG8_WAIT_L(n) asm volatile("s_waitcnt lgkmcnt(" #n ")" ::: "memory")
; #define PG8_BAR __builtin_amdgcn_s_barrier()
; #define PG8_SCHED __builtin_amdgcn_sched_barrier(0)
; template <class Epi, class Sched>
; __device__ __forceinline__ void gemm_phase(LAS unsigned char* lds, const Sched& S, const Epi& E) {
;     ...
;             PG8_WAIT_V(8); PG8_WAIT_L(0); PG8_BAR; PG8_MMA(1, 0, At, B0); PG8_MMA(1, 1, At, B1); PG8_BAR; PG8_SCHED;
;             PG8_LDB(B0, 1, 0); PG8_LDB(B1, 1, 1); PG8_SCHED; PG8_LDA(At, 1, 0); PG8_STAGE(PG8_SA(0, 1), a2 + hA2, vA2, hA2 / 2);
;             PG8_WAIT_V(8); PG8_WAIT_L(0); PG8_BAR; PG8_MMA(0, 0, At, B0); PG8_MMA(0, 1, At, B1); PG8_BAR; PG8_SCHED;
	s_setprio 1
	v_mfma_f32_16x16x32_bf16 v[56:59], v[144:147], v[178:181], v[56:59]
	v_mfma_f32_16x16x32_bf16 v[52:55], v[152:155], v[178:181], v[52:55]
	v_mfma_f32_16x16x32_bf16 v[40:43], v[144:147], v[186:189], v[40:43]
	v_mfma_f32_16x16x32_bf16 v[36:39], v[152:155], v[186:189], v[36:39]
	v_mfma_f32_16x16x32_bf16 v[24:27], v[144:147], v[194:197], v[24:27]
	v_mfma_f32_16x16x32_bf16 v[20:23], v[152:155], v[194:197], v[20:23]
	v_mfma_f32_16x16x32_bf16 v[8:11], v[144:147], v[202:205], v[8:11]
	v_mfma_f32_16x16x32_bf16 v[4:7], v[152:155], v[202:205], v[4:7]
	v_mfma_f32_16x16x32_bf16 v[56:59], v[148:151], v[182:185], v[56:59]
	v_mfma_f32_16x16x32_bf16 v[52:55], v[156:159], v[182:185], v[52:55]
	v_mfma_f32_16x16x32_bf16 v[40:43], v[148:151], v[190:193], v[40:43]
	v_mfma_f32_16x16x32_bf16 v[36:39], v[156:159], v[190:193], v[36:39]
	v_mfma_f32_16x16x32_bf16 v[24:27], v[148:151], v[198:201], v[24:27]
	v_mfma_f32_16x16x32_bf16 v[20:23], v[156:159], v[198:201], v[20:23]
	v_mfma_f32_16x16x32_bf16 v[8:11], v[148:151], v[206:209], v[8:11]
	v_mfma_f32_16x16x32_bf16 v[4:7], v[156:159], v[206:209], v[4:7]
	v_mfma_f32_16x16x32_bf16 v[60:63], v[160:163], v[178:181], v[60:63]
	v_mfma_f32_16x16x32_bf16 v[48:51], v[168:171], v[178:181], v[48:51]
	v_mfma_f32_16x16x32_bf16 v[44:47], v[160:163], v[186:189], v[44:47]
	v_mfma_f32_16x16x32_bf16 v[32:35], v[168:171], v[186:189], v[32:35]
	v_mfma_f32_16x16x32_bf16 v[28:31], v[160:163], v[194:197], v[28:31]
	v_mfma_f32_16x16x32_bf16 v[16:19], v[168:171], v[194:197], v[16:19]
	v_mfma_f32_16x16x32_bf16 v[12:15], v[160:163], v[202:205], v[12:15]
	v_mfma_f32_16x16x32_bf16 v[0:3], v[168:171], v[202:205], v[0:3]
	v_mfma_f32_16x16x32_bf16 v[60:63], v[164:167], v[182:185], v[60:63]
	v_mfma_f32_16x16x32_bf16 v[48:51], v[172:175], v[182:185], v[48:51]
	v_mfma_f32_16x16x32_bf16 v[44:47], v[164:167], v[190:193], v[44:47]
	v_mfma_f32_16x16x32_bf16 v[32:35], v[172:175], v[190:193], v[32:35]
	v_mfma_f32_16x16x32_bf16 v[28:31], v[164:167], v[198:201], v[28:31]
	v_mfma_f32_16x16x32_bf16 v[16:19], v[172:175], v[198:201], v[16:19]
	v_mfma_f32_16x16x32_bf16 v[12:15], v[164:167], v[206:209], v[12:15]
	v_mfma_f32_16x16x32_bf16 v[0:3], v[172:175], v[206:209], v[0:3]
	s_setprio 0
	s_barrier
	ds_read_b128 v[144:147], v141
	ds_read_b128 v[148:151], v141 offset:1024
	ds_read_b128 v[152:155], v141 offset:2048
	ds_read_b128 v[156:159], v141 offset:3072
	ds_read_b128 v[160:163], v142
	ds_read_b128 v[164:167], v142 offset:1024
	ds_read_b128 v[168:171], v142 offset:2048
	ds_read_b128 v[172:175], v142 offset:3072
	ds_read_b128 v[178:181], v140 offset:32768
	ds_read_b128 v[182:185], v140 offset:33792
	ds_read_b128 v[186:189], v140 offset:34816
	ds_read_b128 v[190:193], v140 offset:35840
	ds_read_b128 v[194:197], v140 offset:36864
	ds_read_b128 v[198:201], v140 offset:37888
	ds_read_b128 v[202:205], v140 offset:38912
	ds_read_b128 v[206:209], v140 offset:39936
	s_add_u32 s66, s38, 0x40000
	s_mov_b32 m0, s46
	s_addc_u32 s67, s39, 0
	global_load_lds_dwordx4 v134, s[66:67]
	s_add_u32 s66, s38, 0x60000
	s_mov_b32 m0, s47
	s_addc_u32 s67, s39, 0
	global_load_lds_dwordx4 v134, s[66:67]
	s_waitcnt vmcnt(8) lgkmcnt(0)
	s_barrier
	s_setprio 1
	v_mfma_f32_16x16x32_bf16 v[120:123], v[144:147], v[178:181], v[120:123]
	v_mfma_f32_16x16x32_bf16 v[116:119], v[152:155], v[178:181], v[116:119]
	v_mfma_f32_16x16x32_bf16 v[104:107], v[144:147], v[186:189], v[104:107]
	v_mfma_f32_16x16x32_bf16 v[100:103], v[152:155], v[186:189], v[100:103]
	v_mfma_f32_16x16x32_bf16 v[88:91], v[144:147], v[194:197], v[88:91]
	v_mfma_f32_16x16x32_bf16 v[84:87], v[152:155], v[194:197], v[84:87]
	v_mfma_f32_16x16x32_bf16 v[72:75], v[144:147], v[202:205], v[72:75]
	v_mfma_f32_16x16x32_bf16 v[68:71], v[152:155], v[202:205], v[68:71]
	v_mfma_f32_16x16x32_bf16 v[120:123], v[148:151], v[182:185], v[120:123]
	v_mfma_f32_16x16x32_bf16 v[116:119], v[156:159], v[182:185], v[116:119]
	v_mfma_f32_16x16x32_bf16 v[104:107], v[148:151], v[190:193], v[104:107]
	v_mfma_f32_16x16x32_bf16 v[100:103], v[156:159], v[190:193], v[100:103]
	v_mfma_f32_16x16x32_bf16 v[88:91], v[148:151], v[198:201], v[88:91]
	v_mfma_f32_16x16x32_bf16 v[84:87], v[156:159], v[198:201], v[84:87]
	v_mfma_f32_16x16x32_bf16 v[72:75], v[148:151], v[206:209], v[72:75]
	v_mfma_f32_16x16x32_bf16 v[68:71], v[156:159], v[206:209], v[68:71]
	v_mfma_f32_16x16x32_bf16 v[124:127], v[160:163], v[178:181], v[124:127]
	v_mfma_f32_16x16x32_bf16 v[112:115], v[168:171], v[178:181], v[112:115]
	v_mfma_f32_16x16x32_bf16 v[108:111], v[160:163], v[186:189], v[108:111]
	v_mfma_f32_16x16x32_bf16 v[96:99], v[168:171], v[186:189], v[96:99]
	v_mfma_f32_16x16x32_bf16 v[92:95], v[160:163], v[194:197], v[92:95]
	v_mfma_f32_16x16x32_bf16 v[80:83], v[168:171], v[194:197], v[80:83]
	v_mfma_f32_16x16x32_bf16 v[76:79], v[160:163], v[202:205], v[76:79]
	v_mfma_f32_16x16x32_bf16 v[64:67], v[168:171], v[202:205], v[64:67]
	v_mfma_f32_16x16x32_bf16 v[124:127], v[164:167], v[182:185], v[124:127]
	v_mfma_f32_16x16x32_bf16 v[112:115], v[172:175], v[182:185], v[112:115]
	v_mfma_f32_16x16x32_bf16 v[108:111], v[164:167], v[190:193], v[108:111]
	v_mfma_f32_16x16x32_bf16 v[96:99], v[172:175], v[190:193], v[96:99]
	v_mfma_f32_16x16x32_bf16 v[92:95], v[164:167], v[198:201], v[92:95]
	v_mfma_f32_16x16x32_bf16 v[80:83], v[172:175], v[198:201], v[80:83]
	v_mfma_f32_16x16x32_bf16 v[76:79], v[164:167], v[206:209], v[76:79]
	v_mfma_f32_16x16x32_bf16 v[64:67], v[172:175], v[206:209], v[64:67]
	s_setprio 0
	s_barrier
; #define PG8_STAGE(bufoff, gbase, voff, p64) do { _Pragma("unroll") for (int _i = 0; _i < 2; ++_i) { \
;         const char* _gb = (const char*)(gbase) + (size_t)_i * (p64); const unsigned _la = ldsbase + (unsigned)(bufoff) + (unsigned)_i * 8192u; \
;         asm volatile("s_mov_b32 m0, %0\n\ts_nop 0\n\tglobal_load_lds_dwordx4 %1, %2" :: "s"(_la), "v"(voff), "s"(_gb) : "memory"); } } while (0)
; #define PG8_LDA(dst, b, h) do { _Pragma("unroll") for (int m = 0; m < 4; ++m) _Pragma("unroll") for (int k = 0; k < 2; ++k) dst[m][k] = *(const LAS bf16x8*)(lds + PG8_SA(b, h) + aoff + m * 2048 + k * 1024); } while (0)
; #define PG8_MMA(ai, bj, At, Bt) do { __builtin_amdgcn_s_setprio(1); _Pragma("unroll") for (int m = 0; m < 4; ++m) _Pragma("unroll") for (int n = 0; n < 2; ++n) _Pragma("unroll") for (int k = 0; k < 2; ++k) \
;         acc[ai][bj][m][n] = __builtin_amdgcn_mfma_f32_16x16x32_bf16(Bt[n][k], At[m][k], acc[ai][bj][m][n], 0, 0, 0); __builtin_amdgcn_s_setprio(0); } while (0)
; #define PG8_WAIT_V(n) asm volatile("s_waitcnt vmcnt(" #n ")" ::: "memory")
; #define PG8_WAIT_L(n) asm volatile("s_waitcnt lgkmcnt(" #n ")" ::: "memory")
; #define PG8_BAR __builtin_amdgcn_s_barrier()
; #define PG8_SCHED __builtin_amdgcn_sched_barrier(0)
; template <class Epi, class Sched>
; __device__ __forceinline__ void gemm_phase(LAS unsigned char* lds, const Sched& S, const Epi& E) {
;     ...
;             PG8_LDA(At, 1, 1); PG8_STAGE(PG8_SB(1, 0), b3, vB2, hB2 / 2); PG8_STAGE(PG8_SB(1, 1), b3 + hB2, vB2, hB2 / 2); PG8_STAGE(PG8_SA(1, 0), a3, vA2, hA2 / 2);
;             PG8_WAIT_V(8); PG8_WAIT_L(0); PG8_BAR; PG8_MMA(1, 0, At, B0); PG8_MMA(1, 1, At, B1); PG8_BAR; PG8_SCHED;
;         }
;         if (wr == 0) PG8_BAR;
	s_add_u32 s66, s42, 0x80
	s_addc_u32 s67, s43, 0
	ds_read_b128 v[178:181], v140 offset:49152
	ds_read_b128 v[182:185], v140 offset:50176
	ds_read_b128 v[186:189], v140 offset:51200
	ds_read_b128 v[190:193], v140 offset:52224
	ds_read_b128 v[194:197], v140 offset:53248
	ds_read_b128 v[198:201], v140 offset:54272
	ds_read_b128 v[202:205], v140 offset:55296
	ds_read_b128 v[206:209], v140 offset:56320
	s_mov_b32 m0, s51
	s_nop 0
	global_load_lds_dwordx4 v135, s[66:67]
	s_add_u32 s66, s42, 0x20080
	s_mov_b32 m0, s52
	s_addc_u32 s67, s43, 0
	global_load_lds_dwordx4 v135, s[66:67]
	s_add_u32 s66, s42, 0x40080
	s_mov_b32 m0, s55
	s_addc_u32 s67, s43, 0
	global_load_lds_dwordx4 v135, s[66:67]
	s_add_u32 s42, s42, 0x60080
	s_mov_b32 m0, s56
	s_addc_u32 s43, s43, 0
	global_load_lds_dwordx4 v135, s[42:43]
	s_mov_b32 m0, s53
	s_nop 0
	global_load_lds_dwordx4 v134, s[40:41]
	s_add_u32 s38, s38, 0x20080
	s_mov_b32 m0, s54
	s_addc_u32 s39, s39, 0
	global_load_lds_dwordx4 v134, s[38:39]
	s_waitcnt vmcnt(8) lgkmcnt(0)
	s_barrier
	s_setprio 1
	v_mfma_f32_16x16x32_bf16 v[56:59], v[144:147], v[178:181], v[56:59]
	v_mfma_f32_16x16x32_bf16 v[52:55], v[152:155], v[178:181], v[52:55]
	v_mfma_f32_16x16x32_bf16 v[40:43], v[144:147], v[186:189], v[40:43]
	v_mfma_f32_16x16x32_bf16 v[36:39], v[152:155], v[186:189], v[36:39]
	v_mfma_f32_16x16x32_bf16 v[24:27], v[144:147], v[194:197], v[24:27]
	v_mfma_f32_16x16x32_bf16 v[20:23], v[152:155], v[194:197], v[20:23]
	v_mfma_f32_16x16x32_bf16 v[8:11], v[144:147], v[202:205], v[8:11]
	v_mfma_f32_16x16x32_bf16 v[4:7], v[152:155], v[202:205], v[4:7]
	v_mfma_f32_16x16x32_bf16 v[56:59], v[148:151], v[182:185], v[56:59]
	v_mfma_f32_16x16x32_bf16 v[52:55], v[156:159], v[182:185], v[52:55]
	v_mfma_f32_16x16x32_bf16 v[40:43], v[148:151], v[190:193], v[40:43]
	v_mfma_f32_16x16x32_bf16 v[36:39], v[156:159], v[190:193], v[36:39]
	v_mfma_f32_16x16x32_bf16 v[24:27], v[148:151], v[198:201], v[24:27]
	v_mfma_f32_16x16x32_bf16 v[20:23], v[156:159], v[198:201], v[20:23]
	v_mfma_f32_16x16x32_bf16 v[8:11], v[148:151], v[206:209], v[8:11]
	v_mfma_f32_16x16x32_bf16 v[4:7], v[156:159], v[206:209], v[4:7]
	v_mfma_f32_16x16x32_bf16 v[60:63], v[160:163], v[178:181], v[60:63]
	v_mfma_f32_16x16x32_bf16 v[48:51], v[168:171], v[178:181], v[48:51]
	v_mfma_f32_16x16x32_bf16 v[44:47], v[160:163], v[186:189], v[44:47]
	v_mfma_f32_16x16x32_bf16 v[32:35], v[168:171], v[186:189], v[32:35]
	v_mfma_f32_16x16x32_bf16 v[28:31], v[160:163], v[194:197], v[28:31]
	v_mfma_f32_16x16x32_bf16 v[16:19], v[168:171], v[194:197], v[16:19]
	v_mfma_f32_16x16x32_bf16 v[12:15], v[160:163], v[202:205], v[12:15]
	v_mfma_f32_16x16x32_bf16 v[0:3], v[168:171], v[202:205], v[0:3]
	v_mfma_f32_16x16x32_bf16 v[60:63], v[164:167], v[182:185], v[60:63]
	v_mfma_f32_16x16x32_bf16 v[48:51], v[172:175], v[182:185], v[48:51]
	v_mfma_f32_16x16x32_bf16 v[44:47], v[164:167], v[190:193], v[44:47]
	v_mfma_f32_16x16x32_bf16 v[32:35], v[172:175], v[190:193], v[32:35]
	v_mfma_f32_16x16x32_bf16 v[28:31], v[164:167], v[198:201], v[28:31]
	v_mfma_f32_16x16x32_bf16 v[16:19], v[172:175], v[198:201], v[16:19]
	v_mfma_f32_16x16x32_bf16 v[12:15], v[164:167], v[206:209], v[12:15]
	v_mfma_f32_16x16x32_bf16 v[0:3], v[172:175], v[206:209], v[0:3]
	s_setprio 0
	s_barrier
	s_cmp_gt_u32 s63, 13
	s_cbranch_scc0 .LBB0_1011
	s_and_b64 vcc, exec, s[14:15]
	s_cbranch_vccz .LBB0_1014
	s_barrier

; #define PG8_STAGE(bufoff, gbase, voff, p64) do { _Pragma("unroll") for (int _i = 0; _i < 2; ++_i) { \
;         const char* _gb = (const char*)(gbase) + (size_t)_i * (p64); const unsigned _la = ldsbase + (unsigned)(bufoff) + (unsigned)_i * 8192u; \
;         asm volatile("s_mov_b32 m0, %0\n\ts_nop 0\n\tglobal_load_lds_dwordx4 %1, %2" :: "s"(_la), "v"(voff), "s"(_gb) : "memory"); } } while (0)
; #define PG8_LDA(dst, b, h) do { _Pragma("unroll") for (int m = 0; m < 4; ++m) _Pragma("unroll") for (int k = 0; k < 2; ++k) dst[m][k] = *(const LAS bf16x8*)(lds + PG8_SA(b, h) + aoff + m * 2048 + k * 1024); } while (0)
; #define PG8_LDB(dst, b, h) do { _Pragma("unroll") for (int n = 0; n < 2; ++n) _Pragma("unroll") for (int k = 0; k < 2; ++k) dst[n][k] = *(const LAS bf16x8*)(lds + PG8_SB(b, h) + boff + n * 2048 + k * 1024); } while (0)
; #define PG8_MMA(ai, bj, At, Bt) do { __builtin_amdgcn_s_setprio(1); _Pragma("unroll") for (int m = 0; m < 4; ++m) _Pragma("unroll") for (int n = 0; n < 2; ++n) _Pragma("unroll") for (int k = 0; k < 2; ++k) \
;         acc[ai][bj][m][n] = __builtin_amdgcn_mfma_f32_16x16x32_bf16(Bt[n][k], At[m][k], acc[ai][bj][m][n], 0, 0, 0); __builtin_amdgcn_s_setprio(0); } while (0)
; #define PG8_WAIT_V(n) asm volatile("s_waitcnt vmcnt(" #n ")" ::: "memory")
; #define PG8_BAR __builtin_amdgcn_s_barrier()
; template <class Epi, class Sched>
; __device__ __forceinline__ void gemm_phase(LAS unsigned char* lds, const Sched& S, const Epi& E) {
;     ...
;             const bool last = (t == nt - 2);
;             const char* a1 = cA + (size_t)(t + 1) * kstep;
;             const char* a2 = last ? nA : cA + (size_t)(t + 2) * kstep; const char* b2 = last ? nB : cB + (size_t)(t + 2) * kstep;
;             const char* a3 = a2 + kstep; const char* b3 = b2 + kstep;
;             const unsigned vA2 = voffA, vB2 = voffB, hA2 = hA, hB2 = hB;
;             PG8_LDB(B0, 0, 0); PG8_LDB(B1, 0, 1); PG8_SCHED; PG8_LDA(At, 0, 0); PG8_STAGE(PG8_SA(1, 1), a1 + hA, voffA, hA / 2);
;             PG8_WAIT_V(8); PG8_WAIT_L(0); PG8_BAR; PG8_MMA(0, 0, At, B0); PG8_MMA(0, 1, At, B1); PG8_BAR; PG8_SCHED;
;             PG8_LDA(At, 0, 1); PG8_STAGE(PG8_SB(0, 0), b2, vB2, hB2 / 2); PG8_STAGE(PG8_SB(0, 1), b2 + hB2, vB2, hB2 / 2); PG8_STAGE(PG8_SA(0, 0), a2, vA2, hA2 / 2);
;             PG8_WAIT_V(8); PG8_WAIT_L(0); PG8_BAR; PG8_MMA(1, 0, At, B0); PG8_MMA(1, 1, At, B1); PG8_BAR; PG8_SCHED;
.LBB0_1089:
	ds_read_b128 v[144:147], v138
	ds_read_b128 v[148:151], v138 offset:1024
	ds_read_b128 v[152:155], v138 offset:2048
	ds_read_b128 v[156:159], v138 offset:3072
	ds_read_b128 v[160:163], v139
	ds_read_b128 v[164:167], v139 offset:1024
	ds_read_b128 v[168:171], v139 offset:2048
	ds_read_b128 v[172:175], v139 offset:3072
	s_add_u32 s30, s38, 0xfff80080
	s_addc_u32 s40, s39, -1
	s_cmp_eq_u32 s62, 28
	s_cselect_b32 s41, s25, s40
	s_cselect_b32 s40, s24, s30
	s_cselect_b32 s44, s26, s60
	s_cselect_b32 s45, s27, s61
	s_add_u32 s42, s40, 0x80
	s_addc_u32 s43, s41, 0
	ds_read_b128 v[178:181], v140
	ds_read_b128 v[182:185], v140 offset:1024
	ds_read_b128 v[186:189], v140 offset:2048
	ds_read_b128 v[190:193], v140 offset:3072
	ds_read_b128 v[194:197], v140 offset:4096
	ds_read_b128 v[198:201], v140 offset:5120
	ds_read_b128 v[202:205], v140 offset:6144
	ds_read_b128 v[206:209], v140 offset:7168
	s_mov_b32 m0, s56
	s_nop 0
	global_load_lds_dwordx4 v134, s[38:39]
	s_add_u32 s66, s38, 0x40000
	s_mov_b32 m0, s57
	s_addc_u32 s67, s39, 0
	global_load_lds_dwordx4 v134, s[66:67]
	s_waitcnt vmcnt(8) lgkmcnt(0)
	s_barrier
	s_setprio 1
	v_mfma_f32_16x16x32_bf16 v[124:127], v[144:147], v[178:181], v[124:127]
	v_mfma_f32_16x16x32_bf16 v[120:123], v[152:155], v[178:181], v[120:123]
	v_mfma_f32_16x16x32_bf16 v[116:119], v[144:147], v[186:189], v[116:119]
	v_mfma_f32_16x16x32_bf16 v[108:111], v[152:155], v[186:189], v[108:111]
	v_mfma_f32_16x16x32_bf16 v[100:103], v[144:147], v[194:197], v[100:103]
	v_mfma_f32_16x16x32_bf16 v[92:95], v[152:155], v[194:197], v[92:95]
	v_mfma_f32_16x16x32_bf16 v[84:87], v[144:147], v[202:205], v[84:87]
	v_mfma_f32_16x16x32_bf16 v[76:79], v[152:155], v[202:205], v[76:79]
	v_mfma_f32_16x16x32_bf16 v[124:127], v[148:151], v[182:185], v[124:127]
	v_mfma_f32_16x16x32_bf16 v[120:123], v[156:159], v[182:185], v[120:123]
	v_mfma_f32_16x16x32_bf16 v[116:119], v[148:151], v[190:193], v[116:119]
	v_mfma_f32_16x16x32_bf16 v[108:111], v[156:159], v[190:193], v[108:111]
	v_mfma_f32_16x16x32_bf16 v[100:103], v[148:151], v[198:201], v[100:103]
	v_mfma_f32_16x16x32_bf16 v[92:95], v[156:159], v[198:201], v[92:95]
	v_mfma_f32_16x16x32_bf16 v[84:87], v[148:151], v[206:209], v[84:87]
	v_mfma_f32_16x16x32_bf16 v[76:79], v[156:159], v[206:209], v[76:79]
	s_add_i32 s62, s62, 2
	s_add_u32 s38, s38, 0x100
	s_addc_u32 s39, s39, 0
	s_add_u32 s60, s60, 0x100
	s_addc_u32 s61, s61, 0
	v_mfma_f32_16x16x32_bf16 v[112:115], v[160:163], v[178:181], v[112:115]
	v_mfma_f32_16x16x32_bf16 v[104:107], v[168:171], v[178:181], v[104:107]
	v_mfma_f32_16x16x32_bf16 v[96:99], v[160:163], v[186:189], v[96:99]
	v_mfma_f32_16x16x32_bf16 v[88:91], v[168:171], v[186:189], v[88:91]
	v_mfma_f32_16x16x32_bf16 v[80:83], v[160:163], v[194:197], v[80:83]
	v_mfma_f32_16x16x32_bf16 v[72:75], v[168:171], v[194:197], v[72:75]
	v_mfma_f32_16x16x32_bf16 v[68:71], v[160:163], v[202:205], v[68:71]
	v_mfma_f32_16x16x32_bf16 v[64:67], v[168:171], v[202:205], v[64:67]
	v_mfma_f32_16x16x32_bf16 v[112:115], v[164:167], v[182:185], v[112:115]
	v_mfma_f32_16x16x32_bf16 v[104:107], v[172:175], v[182:185], v[104:107]
	v_mfma_f32_16x16x32_bf16 v[96:99], v[164:167], v[190:193], v[96:99]
	v_mfma_f32_16x16x32_bf16 v[88:91], v[172:175], v[190:193], v[88:91]
	v_mfma_f32_16x16x32_bf16 v[80:83], v[164:167], v[198:201], v[80:83]
	v_mfma_f32_16x16x32_bf16 v[72:75], v[172:175], v[198:201], v[72:75]
	v_mfma_f32_16x16x32_bf16 v[68:71], v[164:167], v[206:209], v[68:71]
	v_mfma_f32_16x16x32_bf16 v[64:67], v[172:175], v[206:209], v[64:67]
	s_setprio 0
	s_barrier
	s_add_u32 s66, s44, 0x40000
	ds_read_b128 v[178:181], v140 offset:16384
	ds_read_b128 v[182:185], v140 offset:17408
	ds_read_b128 v[186:189], v140 offset:18432
	ds_read_b128 v[190:193], v140 offset:19456
	ds_read_b128 v[194:197], v140 offset:20480
	ds_read_b128 v[198:201], v140 offset:21504
	ds_read_b128 v[202:205], v140 offset:22528
	ds_read_b128 v[206:209], v140 offset:23552
	s_mov_b32 m0, s33
	s_nop 0
	global_load_lds_dwordx4 v135, s[44:45]
	s_mov_b32 m0, s34
	s_addc_u32 s67, s45, 0
	global_load_lds_dwordx4 v135, s[66:67]
	s_add_u32 s66, s44, 0x80000
	s_mov_b32 m0, s35
	s_addc_u32 s67, s45, 0
	global_load_lds_dwordx4 v135, s[66:67]
	s_add_u32 s66, s44, 0xc0000
	s_mov_b32 m0, s36
	s_addc_u32 s67, s45, 0
	global_load_lds_dwordx4 v135, s[66:67]
	s_mov_b32 m0, s31
	s_nop 0
	global_load_lds_dwordx4 v134, s[40:41]
	s_add_u32 s66, s40, 0x40000
	s_mov_b32 m0, s37
	s_addc_u32 s67, s41, 0
	global_load_lds_dwordx4 v134, s[66:67]
	s_waitcnt vmcnt(8) lgkmcnt(0)
	s_barrier
; #define PG8_STAGE(bufoff, gbase, voff, p64) do { _Pragma("unroll") for (int _i = 0; _i < 2; ++_i) { \
;         const char* _gb = (const char*)(gbase) + (size_t)_i * (p64); const unsigned _la = ldsbase + (unsigned)(bufoff) + (unsigned)_i * 8192u; \
;         asm volatile("s_mov_b32 m0, %0\n\ts_nop 0\n\tglobal_load_lds_dwordx4 %1, %2" :: "s"(_la), "v"(voff), "s"(_gb) : "memory"); } } while (0)
; #define PG8_LDA(dst, b, h) do { _Pragma("unroll") for (int m = 0; m < 4; ++m) _Pragma("unroll") for (int k = 0; k < 2; ++k) dst[m][k] = *(const LAS bf16x8*)(lds + PG8_SA(b, h) + aoff + m * 2048 + k * 1024); } while (0)
; #define PG8_LDB(dst, b, h) do { _Pragma("unroll") for (int n = 0; n < 2; ++n) _Pragma("unroll") for (int k = 0; k < 2; ++k) dst[n][k] = *(const LAS bf16x8*)(lds + PG8_SB(b, h) + boff + n * 2048 + k * 1024); } while (0)
; #define PG8_MMA(ai, bj, At, Bt) do { __builtin_amdgcn_s_setprio(1); _Pragma("unroll") for (int m = 0; m < 4; ++m) _Pragma("unroll") for (int n = 0; n < 2; ++n) _Pragma("unroll") for (int k = 0; k < 2; ++k) \
;         acc[ai][bj][m][n] = __builtin_amdgcn_mfma_f32_16x16x32_bf16(Bt[n][k], At[m][k], acc[ai][bj][m][n], 0, 0, 0); __builtin_amdgcn_s_setprio(0); } while (0)
; #define PG8_WAIT_V(n) asm volatile("s_waitcnt vmcnt(" #n ")" ::: "memory")
; #define PG8_WAIT_L(n) asm volatile("s_waitcnt lgkmcnt(" #n ")" ::: "memory")
; #define PG8_BAR __builtin_amdgcn_s_barrier()
; #define PG8_SCHED __builtin_amdgcn_sched_barrier(0)
; template <class Epi, class Sched>
; __device__ __forceinline__ void gemm_phase(LAS unsigned char* lds, const Sched& S, const Epi& E) {
;     ...
;             PG8_WAIT_V(8); PG8_WAIT_L(0); PG8_BAR; PG8_MMA(1, 0, At, B0); PG8_MMA(1, 1, At, B1); PG8_BAR; PG8_SCHED;
;             PG8_LDB(B0, 1, 0); PG8_LDB(B1, 1, 1); PG8_SCHED; PG8_LDA(At, 1, 0); PG8_STAGE(PG8_SA(0, 1), a2 + hA2, vA2, hA2 / 2);
;             PG8_WAIT_V(8); PG8_WAIT_L(0); PG8_BAR; PG8_MMA(0, 0, At, B0); PG8_MMA(0, 1, At, B1); PG8_BAR; PG8_SCHED;
	s_setprio 1
	v_mfma_f32_16x16x32_bf16 v[60:63], v[144:147], v[178:181], v[60:63]
	v_mfma_f32_16x16x32_bf16 v[56:59], v[152:155], v[178:181], v[56:59]
	v_mfma_f32_16x16x32_bf16 v[52:55], v[144:147], v[186:189], v[52:55]
	v_mfma_f32_16x16x32_bf16 v[44:47], v[152:155], v[186:189], v[44:47]
	v_mfma_f32_16x16x32_bf16 v[36:39], v[144:147], v[194:197], v[36:39]
	v_mfma_f32_16x16x32_bf16 v[28:31], v[152:155], v[194:197], v[28:31]
	v_mfma_f32_16x16x32_bf16 v[20:23], v[144:147], v[202:205], v[20:23]
	v_mfma_f32_16x16x32_bf16 v[12:15], v[152:155], v[202:205], v[12:15]
	v_mfma_f32_16x16x32_bf16 v[60:63], v[148:151], v[182:185], v[60:63]
	v_mfma_f32_16x16x32_bf16 v[56:59], v[156:159], v[182:185], v[56:59]
	v_mfma_f32_16x16x32_bf16 v[52:55], v[148:151], v[190:193], v[52:55]
	v_mfma_f32_16x16x32_bf16 v[44:47], v[156:159], v[190:193], v[44:47]
	v_mfma_f32_16x16x32_bf16 v[36:39], v[148:151], v[198:201], v[36:39]
	v_mfma_f32_16x16x32_bf16 v[28:31], v[156:159], v[198:201], v[28:31]
	v_mfma_f32_16x16x32_bf16 v[20:23], v[148:151], v[206:209], v[20:23]
	v_mfma_f32_16x16x32_bf16 v[12:15], v[156:159], v[206:209], v[12:15]
	v_mfma_f32_16x16x32_bf16 v[48:51], v[160:163], v[178:181], v[48:51]
	v_mfma_f32_16x16x32_bf16 v[40:43], v[168:171], v[178:181], v[40:43]
	v_mfma_f32_16x16x32_bf16 v[32:35], v[160:163], v[186:189], v[32:35]
	v_mfma_f32_16x16x32_bf16 v[24:27], v[168:171], v[186:189], v[24:27]
	v_mfma_f32_16x16x32_bf16 v[16:19], v[160:163], v[194:197], v[16:19]
	v_mfma_f32_16x16x32_bf16 v[8:11], v[168:171], v[194:197], v[8:11]
	v_mfma_f32_16x16x32_bf16 v[4:7], v[160:163], v[202:205], v[4:7]
	v_mfma_f32_16x16x32_bf16 v[0:3], v[168:171], v[202:205], v[0:3]
	v_mfma_f32_16x16x32_bf16 v[48:51], v[164:167], v[182:185], v[48:51]
	v_mfma_f32_16x16x32_bf16 v[40:43], v[172:175], v[182:185], v[40:43]
	v_mfma_f32_16x16x32_bf16 v[32:35], v[164:167], v[190:193], v[32:35]
	v_mfma_f32_16x16x32_bf16 v[24:27], v[172:175], v[190:193], v[24:27]
	v_mfma_f32_16x16x32_bf16 v[16:19], v[164:167], v[198:201], v[16:19]
	v_mfma_f32_16x16x32_bf16 v[8:11], v[172:175], v[198:201], v[8:11]
	v_mfma_f32_16x16x32_bf16 v[4:7], v[164:167], v[206:209], v[4:7]
	v_mfma_f32_16x16x32_bf16 v[0:3], v[172:175], v[206:209], v[0:3]
	s_setprio 0
	s_barrier
	ds_read_b128 v[144:147], v141
	ds_read_b128 v[148:151], v141 offset:1024
	ds_read_b128 v[152:155], v141 offset:2048
	ds_read_b128 v[156:159], v141 offset:3072
	ds_read_b128 v[160:163], v142
	ds_read_b128 v[164:167], v142 offset:1024
	ds_read_b128 v[168:171], v142 offset:2048
	ds_read_b128 v[172:175], v142 offset:3072
	ds_read_b128 v[178:181], v140 offset:32768
	ds_read_b128 v[182:185], v140 offset:33792
	ds_read_b128 v[186:189], v140 offset:34816
	ds_read_b128 v[190:193], v140 offset:35840
	ds_read_b128 v[194:197], v140 offset:36864
	ds_read_b128 v[198:201], v140 offset:37888
	ds_read_b128 v[202:205], v140 offset:38912
	ds_read_b128 v[206:209], v140 offset:39936
	s_add_u32 s66, s40, 0x80000
	s_mov_b32 m0, s46
	s_addc_u32 s67, s41, 0
	global_load_lds_dwordx4 v134, s[66:67]
	s_add_u32 s66, s40, 0xc0000
	s_mov_b32 m0, s47
	s_addc_u32 s67, s41, 0
	global_load_lds_dwordx4 v134, s[66:67]
	s_waitcnt vmcnt(8) lgkmcnt(0)
	s_barrier
	s_setprio 1
	v_mfma_f32_16x16x32_bf16 v[124:127], v[144:147], v[178:181], v[124:127]
	v_mfma_f32_16x16x32_bf16 v[120:123], v[152:155], v[178:181], v[120:123]
	v_mfma_f32_16x16x32_bf16 v[116:119], v[144:147], v[186:189], v[116:119]
	v_mfma_f32_16x16x32_bf16 v[108:111], v[152:155], v[186:189], v[108:111]
	v_mfma_f32_16x16x32_bf16 v[100:103], v[144:147], v[194:197], v[100:103]
	v_mfma_f32_16x16x32_bf16 v[92:95], v[152:155], v[194:197], v[92:95]
	v_mfma_f32_16x16x32_bf16 v[84:87], v[144:147], v[202:205], v[84:87]
	v_mfma_f32_16x16x32_bf16 v[76:79], v[152:155], v[202:205], v[76:79]
	v_mfma_f32_16x16x32_bf16 v[124:127], v[148:151], v[182:185], v[124:127]
	v_mfma_f32_16x16x32_bf16 v[120:123], v[156:159], v[182:185], v[120:123]
	v_mfma_f32_16x16x32_bf16 v[116:119], v[148:151], v[190:193], v[116:119]
	v_mfma_f32_16x16x32_bf16 v[108:111], v[156:159], v[190:193], v[108:111]
	v_mfma_f32_16x16x32_bf16 v[100:103], v[148:151], v[198:201], v[100:103]
	v_mfma_f32_16x16x32_bf16 v[92:95], v[156:159], v[198:201], v[92:95]
	v_mfma_f32_16x16x32_bf16 v[84:87], v[148:151], v[206:209], v[84:87]
	v_mfma_f32_16x16x32_bf16 v[76:79], v[156:159], v[206:209], v[76:79]
	v_mfma_f32_16x16x32_bf16 v[112:115], v[160:163], v[178:181], v[112:115]
	v_mfma_f32_16x16x32_bf16 v[104:107], v[168:171], v[178:181], v[104:107]
	v_mfma_f32_16x16x32_bf16 v[96:99], v[160:163], v[186:189], v[96:99]
	v_mfma_f32_16x16x32_bf16 v[88:91], v[168:171], v[186:189], v[88:91]
	v_mfma_f32_16x16x32_bf16 v[80:83], v[160:163], v[194:197], v[80:83]
	v_mfma_f32_16x16x32_bf16 v[72:75], v[168:171], v[194:197], v[72:75]
	v_mfma_f32_16x16x32_bf16 v[68:71], v[160:163], v[202:205], v[68:71]
	v_mfma_f32_16x16x32_bf16 v[64:67], v[168:171], v[202:205], v[64:67]
	v_mfma_f32_16x16x32_bf16 v[112:115], v[164:167], v[182:185], v[112:115]
	v_mfma_f32_16x16x32_bf16 v[104:107], v[172:175], v[182:185], v[104:107]
	v_mfma_f32_16x16x32_bf16 v[96:99], v[164:167], v[190:193], v[96:99]
	v_mfma_f32_16x16x32_bf16 v[88:91], v[172:175], v[190:193], v[88:91]
	v_mfma_f32_16x16x32_bf16 v[80:83], v[164:167], v[198:201], v[80:83]
	v_mfma_f32_16x16x32_bf16 v[72:75], v[172:175], v[198:201], v[72:75]
	v_mfma_f32_16x16x32_bf16 v[68:71], v[164:167], v[206:209], v[68:71]
	v_mfma_f32_16x16x32_bf16 v[64:67], v[172:175], v[206:209], v[64:67]
	s_setprio 0
	s_barrier
; #define PG8_STAGE(bufoff, gbase, voff, p64) do { _Pragma("unroll") for (int _i = 0; _i < 2; ++_i) { \
;         const char* _gb = (const char*)(gbase) + (size_t)_i * (p64); const unsigned _la = ldsbase + (unsigned)(bufoff) + (unsigned)_i * 8192u; \
;         asm volatile("s_mov_b32 m0, %0\n\ts_nop 0\n\tglobal_load_lds_dwordx4 %1, %2" :: "s"(_la), "v"(voff), "s"(_gb) : "memory"); } } while (0)
; #define PG8_LDA(dst, b, h) do { _Pragma("unroll") for (int m = 0; m < 4; ++m) _Pragma("unroll") for (int k = 0; k < 2; ++k) dst[m][k] = *(const LAS bf16x8*)(lds + PG8_SA(b, h) + aoff + m * 2048 + k * 1024); } while (0)
; #define PG8_MMA(ai, bj, At, Bt) do { __builtin_amdgcn_s_setprio(1); _Pragma("unroll") for (int m = 0; m < 4; ++m) _Pragma("unroll") for (int n = 0; n < 2; ++n) _Pragma("unroll") for (int k = 0; k < 2; ++k) \
;         acc[ai][bj][m][n] = __builtin_amdgcn_mfma_f32_16x16x32_bf16(Bt[n][k], At[m][k], acc[ai][bj][m][n], 0, 0, 0); __builtin_amdgcn_s_setprio(0); } while (0)
; #define PG8_WAIT_V(n) asm volatile("s_waitcnt vmcnt(" #n ")" ::: "memory")
; #define PG8_WAIT_L(n) asm volatile("s_waitcnt lgkmcnt(" #n ")" ::: "memory")
; #define PG8_BAR __builtin_amdgcn_s_barrier()
; #define PG8_SCHED __builtin_amdgcn_sched_barrier(0)
; template <class Epi, class Sched>
; __device__ __forceinline__ void gemm_phase(LAS unsigned char* lds, const Sched& S, const Epi& E) {
;     ...
;             PG8_LDA(At, 1, 1); PG8_STAGE(PG8_SB(1, 0), b3, vB2, hB2 / 2); PG8_STAGE(PG8_SB(1, 1), b3 + hB2, vB2, hB2 / 2); PG8_STAGE(PG8_SA(1, 0), a3, vA2, hA2 / 2);
;             PG8_WAIT_V(8); PG8_WAIT_L(0); PG8_BAR; PG8_MMA(1, 0, At, B0); PG8_MMA(1, 1, At, B1); PG8_BAR; PG8_SCHED;
;         }
;         if (wr == 0) PG8_BAR;
	s_add_u32 s66, s44, 0x80
	s_addc_u32 s67, s45, 0
	ds_read_b128 v[178:181], v140 offset:49152
	ds_read_b128 v[182:185], v140 offset:50176
	ds_read_b128 v[186:189], v140 offset:51200
	ds_read_b128 v[190:193], v140 offset:52224
	ds_read_b128 v[194:197], v140 offset:53248
	ds_read_b128 v[198:201], v140 offset:54272
	ds_read_b128 v[202:205], v140 offset:55296
	ds_read_b128 v[206:209], v140 offset:56320
	s_mov_b32 m0, s50
	s_nop 0
	global_load_lds_dwordx4 v135, s[66:67]
	s_add_u32 s66, s44, 0x40080
	s_mov_b32 m0, s51
	s_addc_u32 s67, s45, 0
	global_load_lds_dwordx4 v135, s[66:67]
	s_add_u32 s66, s44, 0x80080
	s_mov_b32 m0, s54
	s_addc_u32 s67, s45, 0
	global_load_lds_dwordx4 v135, s[66:67]
	s_add_u32 s44, s44, 0xc0080
	s_mov_b32 m0, s55
	s_addc_u32 s45, s45, 0
	global_load_lds_dwordx4 v135, s[44:45]
	s_mov_b32 m0, s52
	s_nop 0
	global_load_lds_dwordx4 v134, s[42:43]
	s_add_u32 s40, s40, 0x40080
	s_mov_b32 m0, s53
	s_addc_u32 s41, s41, 0
	global_load_lds_dwordx4 v134, s[40:41]
	s_waitcnt vmcnt(8) lgkmcnt(0)
	s_barrier
	s_setprio 1
	v_mfma_f32_16x16x32_bf16 v[60:63], v[144:147], v[178:181], v[60:63]
	v_mfma_f32_16x16x32_bf16 v[56:59], v[152:155], v[178:181], v[56:59]
	v_mfma_f32_16x16x32_bf16 v[52:55], v[144:147], v[186:189], v[52:55]
	v_mfma_f32_16x16x32_bf16 v[44:47], v[152:155], v[186:189], v[44:47]
	v_mfma_f32_16x16x32_bf16 v[36:39], v[144:147], v[194:197], v[36:39]
	v_mfma_f32_16x16x32_bf16 v[28:31], v[152:155], v[194:197], v[28:31]
	v_mfma_f32_16x16x32_bf16 v[20:23], v[144:147], v[202:205], v[20:23]
	v_mfma_f32_16x16x32_bf16 v[12:15], v[152:155], v[202:205], v[12:15]
	v_mfma_f32_16x16x32_bf16 v[60:63], v[148:151], v[182:185], v[60:63]
	v_mfma_f32_16x16x32_bf16 v[56:59], v[156:159], v[182:185], v[56:59]
	v_mfma_f32_16x16x32_bf16 v[52:55], v[148:151], v[190:193], v[52:55]
	v_mfma_f32_16x16x32_bf16 v[44:47], v[156:159], v[190:193], v[44:47]
	v_mfma_f32_16x16x32_bf16 v[36:39], v[148:151], v[198:201], v[36:39]
	v_mfma_f32_16x16x32_bf16 v[28:31], v[156:159], v[198:201], v[28:31]
	v_mfma_f32_16x16x32_bf16 v[20:23], v[148:151], v[206:209], v[20:23]
	v_mfma_f32_16x16x32_bf16 v[12:15], v[156:159], v[206:209], v[12:15]
	v_mfma_f32_16x16x32_bf16 v[48:51], v[160:163], v[178:181], v[48:51]
	v_mfma_f32_16x16x32_bf16 v[40:43], v[168:171], v[178:181], v[40:43]
	v_mfma_f32_16x16x32_bf16 v[32:35], v[160:163], v[186:189], v[32:35]
	v_mfma_f32_16x16x32_bf16 v[24:27], v[168:171], v[186:189], v[24:27]
	v_mfma_f32_16x16x32_bf16 v[16:19], v[160:163], v[194:197], v[16:19]
	v_mfma_f32_16x16x32_bf16 v[8:11], v[168:171], v[194:197], v[8:11]
	v_mfma_f32_16x16x32_bf16 v[4:7], v[160:163], v[202:205], v[4:7]
	v_mfma_f32_16x16x32_bf16 v[0:3], v[168:171], v[202:205], v[0:3]
	v_mfma_f32_16x16x32_bf16 v[48:51], v[164:167], v[182:185], v[48:51]
	v_mfma_f32_16x16x32_bf16 v[40:43], v[172:175], v[182:185], v[40:43]
	v_mfma_f32_16x16x32_bf16 v[32:35], v[164:167], v[190:193], v[32:35]
	v_mfma_f32_16x16x32_bf16 v[24:27], v[172:175], v[190:193], v[24:27]
	v_mfma_f32_16x16x32_bf16 v[16:19], v[164:167], v[198:201], v[16:19]
	v_mfma_f32_16x16x32_bf16 v[8:11], v[172:175], v[198:201], v[8:11]
	v_mfma_f32_16x16x32_bf16 v[4:7], v[164:167], v[206:209], v[4:7]
	v_mfma_f32_16x16x32_bf16 v[0:3], v[172:175], v[206:209], v[0:3]
	s_setprio 0
	s_barrier
	s_cmp_gt_u32 s62, 29
	s_cbranch_scc0 .LBB0_1089
	s_and_b64 vcc, exec, s[18:19]
	s_cbranch_vccz .LBB0_1092
	s_barrier

; #define PG8_STAGE(bufoff, gbase, voff, p64) do { _Pragma("unroll") for (int _i = 0; _i < 2; ++_i) { \
;         const char* _gb = (const char*)(gbase) + (size_t)_i * (p64); const unsigned _la = ldsbase + (unsigned)(bufoff) + (unsigned)_i * 8192u; \
;         asm volatile("s_mov_b32 m0, %0\n\ts_nop 0\n\tglobal_load_lds_dwordx4 %1, %2" :: "s"(_la), "v"(voff), "s"(_gb) : "memory"); } } while (0)
; #define PG8_LDA(dst, b, h) do { _Pragma("unroll") for (int m = 0; m < 4; ++m) _Pragma("unroll") for (int k = 0; k < 2; ++k) dst[m][k] = *(const LAS bf16x8*)(lds + PG8_SA(b, h) + aoff + m * 2048 + k * 1024); } while (0)
; #define PG8_LDB(dst, b, h) do { _Pragma("unroll") for (int n = 0; n < 2; ++n) _Pragma("unroll") for (int k = 0; k < 2; ++k) dst[n][k] = *(const LAS bf16x8*)(lds + PG8_SB(b, h) + boff + n * 2048 + k * 1024); } while (0)
; #define PG8_MMA(ai, bj, At, Bt) do { __builtin_amdgcn_s_setprio(1); _Pragma("unroll") for (int m = 0; m < 4; ++m) _Pragma("unroll") for (int n = 0; n < 2; ++n) _Pragma("unroll") for (int k = 0; k < 2; ++k) \
;         acc[ai][bj][m][n] = __builtin_amdgcn_mfma_f32_16x16x32_bf16(Bt[n][k], At[m][k], acc[ai][bj][m][n], 0, 0, 0); __builtin_amdgcn_s_setprio(0); } while (0)
; #define PG8_WAIT_V(n) asm volatile("s_waitcnt vmcnt(" #n ")" ::: "memory")
; #define PG8_BAR __builtin_amdgcn_s_barrier()
; template <class Epi, class Sched>
; __device__ __forceinline__ void gemm_phase(LAS unsigned char* lds, const Sched& S, const Epi& E) {
;     ...
;             const bool last = (t == nt - 2);
;             const char* a1 = cA + (size_t)(t + 1) * kstep;
;             const char* a2 = last ? nA : cA + (size_t)(t + 2) * kstep; const char* b2 = last ? nB : cB + (size_t)(t + 2) * kstep;
;             const char* a3 = a2 + kstep; const char* b3 = b2 + kstep;
;             const unsigned vA2 = voffA, vB2 = voffB, hA2 = hA, hB2 = hB;
;             PG8_LDB(B0, 0, 0); PG8_LDB(B1, 0, 1); PG8_SCHED; PG8_LDA(At, 0, 0); PG8_STAGE(PG8_SA(1, 1), a1 + hA, voffA, hA / 2);
;             PG8_WAIT_V(8); PG8_WAIT_L(0); PG8_BAR; PG8_MMA(0, 0, At, B0); PG8_MMA(0, 1, At, B1); PG8_BAR; PG8_SCHED;
;             PG8_LDA(At, 0, 1); PG8_STAGE(PG8_SB(0, 0), b2, vB2, hB2 / 2); PG8_STAGE(PG8_SB(0, 1), b2 + hB2, vB2, hB2 / 2); PG8_STAGE(PG8_SA(0, 0), a2, vA2, hA2 / 2);
;             PG8_WAIT_V(8); PG8_WAIT_L(0); PG8_BAR; PG8_MMA(1, 0, At, B0); PG8_MMA(1, 1, At, B1); PG8_BAR; PG8_SCHED;
.LBB0_1192:
	ds_read_b128 v[144:147], v138
	ds_read_b128 v[148:151], v138 offset:1024
	ds_read_b128 v[152:155], v138 offset:2048
	ds_read_b128 v[156:159], v138 offset:3072
	ds_read_b128 v[160:163], v139
	ds_read_b128 v[164:167], v139 offset:1024
	ds_read_b128 v[168:171], v139 offset:2048
	ds_read_b128 v[172:175], v139 offset:3072
	s_add_u32 s26, s24, 0xfffc0080
	s_addc_u32 s27, s25, -1
	s_cmp_eq_u32 s60, 12
	s_cselect_b32 s26, s20, s26
	s_cselect_b32 s27, s21, s27
	s_cselect_b32 s40, s22, s58
	s_cselect_b32 s41, s23, s59
	s_add_u32 s38, s26, 0x80
	s_addc_u32 s39, s27, 0
	ds_read_b128 v[178:181], v140
	ds_read_b128 v[182:185], v140 offset:1024
	ds_read_b128 v[186:189], v140 offset:2048
	ds_read_b128 v[190:193], v140 offset:3072
	ds_read_b128 v[194:197], v140 offset:4096
	ds_read_b128 v[198:201], v140 offset:5120
	ds_read_b128 v[202:205], v140 offset:6144
	ds_read_b128 v[206:209], v140 offset:7168
	s_mov_b32 m0, s54
	s_nop 0
	global_load_lds_dwordx4 v134, s[24:25]
	s_add_u32 s62, s24, 0x20000
	s_mov_b32 m0, s55
	s_addc_u32 s63, s25, 0
	global_load_lds_dwordx4 v134, s[62:63]
	s_waitcnt vmcnt(8) lgkmcnt(0)
	s_barrier
	s_setprio 1
	v_mfma_f32_16x16x32_bf16 v[124:127], v[144:147], v[178:181], v[124:127]
	v_mfma_f32_16x16x32_bf16 v[120:123], v[152:155], v[178:181], v[120:123]
	v_mfma_f32_16x16x32_bf16 v[116:119], v[144:147], v[186:189], v[116:119]
	v_mfma_f32_16x16x32_bf16 v[108:111], v[152:155], v[186:189], v[108:111]
	v_mfma_f32_16x16x32_bf16 v[100:103], v[144:147], v[194:197], v[100:103]
	v_mfma_f32_16x16x32_bf16 v[92:95], v[152:155], v[194:197], v[92:95]
	v_mfma_f32_16x16x32_bf16 v[84:87], v[144:147], v[202:205], v[84:87]
	v_mfma_f32_16x16x32_bf16 v[76:79], v[152:155], v[202:205], v[76:79]
	v_mfma_f32_16x16x32_bf16 v[124:127], v[148:151], v[182:185], v[124:127]
	v_mfma_f32_16x16x32_bf16 v[120:123], v[156:159], v[182:185], v[120:123]
	v_mfma_f32_16x16x32_bf16 v[116:119], v[148:151], v[190:193], v[116:119]
	v_mfma_f32_16x16x32_bf16 v[108:111], v[156:159], v[190:193], v[108:111]
	v_mfma_f32_16x16x32_bf16 v[100:103], v[148:151], v[198:201], v[100:103]
	v_mfma_f32_16x16x32_bf16 v[92:95], v[156:159], v[198:201], v[92:95]
	v_mfma_f32_16x16x32_bf16 v[84:87], v[148:151], v[206:209], v[84:87]
	v_mfma_f32_16x16x32_bf16 v[76:79], v[156:159], v[206:209], v[76:79]
	s_add_i32 s60, s60, 2
	s_add_u32 s24, s24, 0x100
	s_addc_u32 s25, s25, 0
	s_add_u32 s58, s58, 0x100
	s_addc_u32 s59, s59, 0
	v_mfma_f32_16x16x32_bf16 v[112:115], v[160:163], v[178:181], v[112:115]
	v_mfma_f32_16x16x32_bf16 v[104:107], v[168:171], v[178:181], v[104:107]
	v_mfma_f32_16x16x32_bf16 v[96:99], v[160:163], v[186:189], v[96:99]
	v_mfma_f32_16x16x32_bf16 v[88:91], v[168:171], v[186:189], v[88:91]
	v_mfma_f32_16x16x32_bf16 v[80:83], v[160:163], v[194:197], v[80:83]
	v_mfma_f32_16x16x32_bf16 v[72:75], v[168:171], v[194:197], v[72:75]
	v_mfma_f32_16x16x32_bf16 v[68:71], v[160:163], v[202:205], v[68:71]
	v_mfma_f32_16x16x32_bf16 v[64:67], v[168:171], v[202:205], v[64:67]
	v_mfma_f32_16x16x32_bf16 v[112:115], v[164:167], v[182:185], v[112:115]
	v_mfma_f32_16x16x32_bf16 v[104:107], v[172:175], v[182:185], v[104:107]
	v_mfma_f32_16x16x32_bf16 v[96:99], v[164:167], v[190:193], v[96:99]
	v_mfma_f32_16x16x32_bf16 v[88:91], v[172:175], v[190:193], v[88:91]
	v_mfma_f32_16x16x32_bf16 v[80:83], v[164:167], v[198:201], v[80:83]
	v_mfma_f32_16x16x32_bf16 v[72:75], v[172:175], v[198:201], v[72:75]
	v_mfma_f32_16x16x32_bf16 v[68:71], v[164:167], v[206:209], v[68:71]
	v_mfma_f32_16x16x32_bf16 v[64:67], v[172:175], v[206:209], v[64:67]
	s_setprio 0
	s_barrier
	s_add_u32 s62, s40, 0x20000
	ds_read_b128 v[178:181], v140 offset:16384
	ds_read_b128 v[182:185], v140 offset:17408
	ds_read_b128 v[186:189], v140 offset:18432
	ds_read_b128 v[190:193], v140 offset:19456
	ds_read_b128 v[194:197], v140 offset:20480
	ds_read_b128 v[198:201], v140 offset:21504
	ds_read_b128 v[202:205], v140 offset:22528
	ds_read_b128 v[206:209], v140 offset:23552
	s_mov_b32 m0, s35
	s_nop 0
	global_load_lds_dwordx4 v135, s[40:41]
	s_mov_b32 m0, s36
	s_addc_u32 s63, s41, 0
	global_load_lds_dwordx4 v135, s[62:63]
	s_add_u32 s62, s40, 0x40000
	s_mov_b32 m0, s37
	s_addc_u32 s63, s41, 0
	global_load_lds_dwordx4 v135, s[62:63]
	s_add_u32 s62, s40, 0x60000
	s_mov_b32 m0, s42
	s_addc_u32 s63, s41, 0
	global_load_lds_dwordx4 v135, s[62:63]
	s_mov_b32 m0, s34
	s_nop 0
	global_load_lds_dwordx4 v134, s[26:27]
	s_add_u32 s62, s26, 0x20000
	s_mov_b32 m0, s43
	s_addc_u32 s63, s27, 0
	global_load_lds_dwordx4 v134, s[62:63]
	s_waitcnt vmcnt(8) lgkmcnt(0)
	s_barrier
; #define PG8_STAGE(bufoff, gbase, voff, p64) do { _Pragma("unroll") for (int _i = 0; _i < 2; ++_i) { \
;         const char* _gb = (const char*)(gbase) + (size_t)_i * (p64); const unsigned _la = ldsbase + (unsigned)(bufoff) + (unsigned)_i * 8192u; \
;         asm volatile("s_mov_b32 m0, %0\n\ts_nop 0\n\tglobal_load_lds_dwordx4 %1, %2" :: "s"(_la), "v"(voff), "s"(_gb) : "memory"); } } while (0)
; #define PG8_LDA(dst, b, h) do { _Pragma("unroll") for (int m = 0; m < 4; ++m) _Pragma("unroll") for (int k = 0; k < 2; ++k) dst[m][k] = *(const LAS bf16x8*)(lds + PG8_SA(b, h) + aoff + m * 2048 + k * 1024); } while (0)
; #define PG8_LDB(dst, b, h) do { _Pragma("unroll") for (int n = 0; n < 2; ++n) _Pragma("unroll") for (int k = 0; k < 2; ++k) dst[n][k] = *(const LAS bf16x8*)(lds + PG8_SB(b, h) + boff + n * 2048 + k * 1024); } while (0)
; #define PG8_MMA(ai, bj, At, Bt) do { __builtin_amdgcn_s_setprio(1); _Pragma("unroll") for (int m = 0; m < 4; ++m) _Pragma("unroll") for (int n = 0; n < 2; ++n) _Pragma("unroll") for (int k = 0; k < 2; ++k) \
;         acc[ai][bj][m][n] = __builtin_amdgcn_mfma_f32_16x16x32_bf16(Bt[n][k], At[m][k], acc[ai][bj][m][n], 0, 0, 0); __builtin_amdgcn_s_setprio(0); } while (0)
; #define PG8_WAIT_V(n) asm volatile("s_waitcnt vmcnt(" #n ")" ::: "memory")
; #define PG8_WAIT_L(n) asm volatile("s_waitcnt lgkmcnt(" #n ")" ::: "memory")
; #define PG8_BAR __builtin_amdgcn_s_barrier()
; #define PG8_SCHED __builtin_amdgcn_sched_barrier(0)
; template <class Epi, class Sched>
; __device__ __forceinline__ void gemm_phase(LAS unsigned char* lds, const Sched& S, const Epi& E) {
;     ...
;             PG8_WAIT_V(8); PG8_WAIT_L(0); PG8_BAR; PG8_MMA(1, 0, At, B0); PG8_MMA(1, 1, At, B1); PG8_BAR; PG8_SCHED;
;             PG8_LDB(B0, 1, 0); PG8_LDB(B1, 1, 1); PG8_SCHED; PG8_LDA(At, 1, 0); PG8_STAGE(PG8_SA(0, 1), a2 + hA2, vA2, hA2 / 2);
;             PG8_WAIT_V(8); PG8_WAIT_L(0); PG8_BAR; PG8_MMA(0, 0, At, B0); PG8_MMA(0, 1, At, B1); PG8_BAR; PG8_SCHED;
	s_setprio 1
	v_mfma_f32_16x16x32_bf16 v[60:63], v[144:147], v[178:181], v[60:63]
	v_mfma_f32_16x16x32_bf16 v[56:59], v[152:155], v[178:181], v[56:59]
	v_mfma_f32_16x16x32_bf16 v[52:55], v[144:147], v[186:189], v[52:55]
	v_mfma_f32_16x16x32_bf16 v[44:47], v[152:155], v[186:189], v[44:47]
	v_mfma_f32_16x16x32_bf16 v[36:39], v[144:147], v[194:197], v[36:39]
	v_mfma_f32_16x16x32_bf16 v[28:31], v[152:155], v[194:197], v[28:31]
	v_mfma_f32_16x16x32_bf16 v[20:23], v[144:147], v[202:205], v[20:23]
	v_mfma_f32_16x16x32_bf16 v[12:15], v[152:155], v[202:205], v[12:15]
	v_mfma_f32_16x16x32_bf16 v[60:63], v[148:151], v[182:185], v[60:63]
	v_mfma_f32_16x16x32_bf16 v[56:59], v[156:159], v[182:185], v[56:59]
	v_mfma_f32_16x16x32_bf16 v[52:55], v[148:151], v[190:193], v[52:55]
	v_mfma_f32_16x16x32_bf16 v[44:47], v[156:159], v[190:193], v[44:47]
	v_mfma_f32_16x16x32_bf16 v[36:39], v[148:151], v[198:201], v[36:39]
	v_mfma_f32_16x16x32_bf16 v[28:31], v[156:159], v[198:201], v[28:31]
	v_mfma_f32_16x16x32_bf16 v[20:23], v[148:151], v[206:209], v[20:23]
	v_mfma_f32_16x16x32_bf16 v[12:15], v[156:159], v[206:209], v[12:15]
	v_mfma_f32_16x16x32_bf16 v[48:51], v[160:163], v[178:181], v[48:51]
	v_mfma_f32_16x16x32_bf16 v[40:43], v[168:171], v[178:181], v[40:43]
	v_mfma_f32_16x16x32_bf16 v[32:35], v[160:163], v[186:189], v[32:35]
	v_mfma_f32_16x16x32_bf16 v[24:27], v[168:171], v[186:189], v[24:27]
	v_mfma_f32_16x16x32_bf16 v[16:19], v[160:163], v[194:197], v[16:19]
	v_mfma_f32_16x16x32_bf16 v[8:11], v[168:171], v[194:197], v[8:11]
	v_mfma_f32_16x16x32_bf16 v[4:7], v[160:163], v[202:205], v[4:7]
	v_mfma_f32_16x16x32_bf16 v[0:3], v[168:171], v[202:205], v[0:3]
	v_mfma_f32_16x16x32_bf16 v[48:51], v[164:167], v[182:185], v[48:51]
	v_mfma_f32_16x16x32_bf16 v[40:43], v[172:175], v[182:185], v[40:43]
	v_mfma_f32_16x16x32_bf16 v[32:35], v[164:167], v[190:193], v[32:35]
	v_mfma_f32_16x16x32_bf16 v[24:27], v[172:175], v[190:193], v[24:27]
	v_mfma_f32_16x16x32_bf16 v[16:19], v[164:167], v[198:201], v[16:19]
	v_mfma_f32_16x16x32_bf16 v[8:11], v[172:175], v[198:201], v[8:11]
	v_mfma_f32_16x16x32_bf16 v[4:7], v[164:167], v[206:209], v[4:7]
	v_mfma_f32_16x16x32_bf16 v[0:3], v[172:175], v[206:209], v[0:3]
	s_setprio 0
	s_barrier
	ds_read_b128 v[144:147], v141
	ds_read_b128 v[148:151], v141 offset:1024
	ds_read_b128 v[152:155], v141 offset:2048
	ds_read_b128 v[156:159], v141 offset:3072
	ds_read_b128 v[160:163], v142
	ds_read_b128 v[164:167], v142 offset:1024
	ds_read_b128 v[168:171], v142 offset:2048
	ds_read_b128 v[172:175], v142 offset:3072
	ds_read_b128 v[178:181], v140 offset:32768
	ds_read_b128 v[182:185], v140 offset:33792
	ds_read_b128 v[186:189], v140 offset:34816
	ds_read_b128 v[190:193], v140 offset:35840
	ds_read_b128 v[194:197], v140 offset:36864
	ds_read_b128 v[198:201], v140 offset:37888
	ds_read_b128 v[202:205], v140 offset:38912
	ds_read_b128 v[206:209], v140 offset:39936
	s_add_u32 s62, s26, 0x40000
	s_mov_b32 m0, s44
	s_addc_u32 s63, s27, 0
	global_load_lds_dwordx4 v134, s[62:63]
	s_add_u32 s62, s26, 0x60000
	s_mov_b32 m0, s45
	s_addc_u32 s63, s27, 0
	global_load_lds_dwordx4 v134, s[62:63]
	s_waitcnt vmcnt(8) lgkmcnt(0)
	s_barrier
	s_setprio 1
	v_mfma_f32_16x16x32_bf16 v[124:127], v[144:147], v[178:181], v[124:127]
	v_mfma_f32_16x16x32_bf16 v[120:123], v[152:155], v[178:181], v[120:123]
	v_mfma_f32_16x16x32_bf16 v[116:119], v[144:147], v[186:189], v[116:119]
	v_mfma_f32_16x16x32_bf16 v[108:111], v[152:155], v[186:189], v[108:111]
	v_mfma_f32_16x16x32_bf16 v[100:103], v[144:147], v[194:197], v[100:103]
	v_mfma_f32_16x16x32_bf16 v[92:95], v[152:155], v[194:197], v[92:95]
	v_mfma_f32_16x16x32_bf16 v[84:87], v[144:147], v[202:205], v[84:87]
	v_mfma_f32_16x16x32_bf16 v[76:79], v[152:155], v[202:205], v[76:79]
	v_mfma_f32_16x16x32_bf16 v[124:127], v[148:151], v[182:185], v[124:127]
	v_mfma_f32_16x16x32_bf16 v[120:123], v[156:159], v[182:185], v[120:123]
	v_mfma_f32_16x16x32_bf16 v[116:119], v[148:151], v[190:193], v[116:119]
	v_mfma_f32_16x16x32_bf16 v[108:111], v[156:159], v[190:193], v[108:111]
	v_mfma_f32_16x16x32_bf16 v[100:103], v[148:151], v[198:201], v[100:103]
	v_mfma_f32_16x16x32_bf16 v[92:95], v[156:159], v[198:201], v[92:95]
	v_mfma_f32_16x16x32_bf16 v[84:87], v[148:151], v[206:209], v[84:87]
	v_mfma_f32_16x16x32_bf16 v[76:79], v[156:159], v[206:209], v[76:79]
	v_mfma_f32_16x16x32_bf16 v[112:115], v[160:163], v[178:181], v[112:115]
	v_mfma_f32_16x16x32_bf16 v[104:107], v[168:171], v[178:181], v[104:107]
	v_mfma_f32_16x16x32_bf16 v[96:99], v[160:163], v[186:189], v[96:99]
	v_mfma_f32_16x16x32_bf16 v[88:91], v[168:171], v[186:189], v[88:91]
	v_mfma_f32_16x16x32_bf16 v[80:83], v[160:163], v[194:197], v[80:83]
	v_mfma_f32_16x16x32_bf16 v[72:75], v[168:171], v[194:197], v[72:75]
	v_mfma_f32_16x16x32_bf16 v[68:71], v[160:163], v[202:205], v[68:71]
	v_mfma_f32_16x16x32_bf16 v[64:67], v[168:171], v[202:205], v[64:67]
	v_mfma_f32_16x16x32_bf16 v[112:115], v[164:167], v[182:185], v[112:115]
	v_mfma_f32_16x16x32_bf16 v[104:107], v[172:175], v[182:185], v[104:107]
	v_mfma_f32_16x16x32_bf16 v[96:99], v[164:167], v[190:193], v[96:99]
	v_mfma_f32_16x16x32_bf16 v[88:91], v[172:175], v[190:193], v[88:91]
	v_mfma_f32_16x16x32_bf16 v[80:83], v[164:167], v[198:201], v[80:83]
	v_mfma_f32_16x16x32_bf16 v[72:75], v[172:175], v[198:201], v[72:75]
	v_mfma_f32_16x16x32_bf16 v[68:71], v[164:167], v[206:209], v[68:71]
	v_mfma_f32_16x16x32_bf16 v[64:67], v[172:175], v[206:209], v[64:67]
	s_setprio 0
	s_barrier
; #define PG8_STAGE(bufoff, gbase, voff, p64) do { _Pragma("unroll") for (int _i = 0; _i < 2; ++_i) { \
;         const char* _gb = (const char*)(gbase) + (size_t)_i * (p64); const unsigned _la = ldsbase + (unsigned)(bufoff) + (unsigned)_i * 8192u; \
;         asm volatile("s_mov_b32 m0, %0\n\ts_nop 0\n\tglobal_load_lds_dwordx4 %1, %2" :: "s"(_la), "v"(voff), "s"(_gb) : "memory"); } } while (0)
; #define PG8_LDA(dst, b, h) do { _Pragma("unroll") for (int m = 0; m < 4; ++m) _Pragma("unroll") for (int k = 0; k < 2; ++k) dst[m][k] = *(const LAS bf16x8*)(lds + PG8_SA(b, h) + aoff + m * 2048 + k * 1024); } while (0)
; #define PG8_MMA(ai, bj, At, Bt) do { __builtin_amdgcn_s_setprio(1); _Pragma("unroll") for (int m = 0; m < 4; ++m) _Pragma("unroll") for (int n = 0; n < 2; ++n) _Pragma("unroll") for (int k = 0; k < 2; ++k) \
;         acc[ai][bj][m][n] = __builtin_amdgcn_mfma_f32_16x16x32_bf16(Bt[n][k], At[m][k], acc[ai][bj][m][n], 0, 0, 0); __builtin_amdgcn_s_setprio(0); } while (0)
; #define PG8_WAIT_V(n) asm volatile("s_waitcnt vmcnt(" #n ")" ::: "memory")
; #define PG8_WAIT_L(n) asm volatile("s_waitcnt lgkmcnt(" #n ")" ::: "memory")
; #define PG8_BAR __builtin_amdgcn_s_barrier()
; #define PG8_SCHED __builtin_amdgcn_sched_barrier(0)
; template <class Epi, class Sched>
; __device__ __forceinline__ void gemm_phase(LAS unsigned char* lds, const Sched& S, const Epi& E) {
;     ...
;             PG8_LDA(At, 1, 1); PG8_STAGE(PG8_SB(1, 0), b3, vB2, hB2 / 2); PG8_STAGE(PG8_SB(1, 1), b3 + hB2, vB2, hB2 / 2); PG8_STAGE(PG8_SA(1, 0), a3, vA2, hA2 / 2);
;             PG8_WAIT_V(8); PG8_WAIT_L(0); PG8_BAR; PG8_MMA(1, 0, At, B0); PG8_MMA(1, 1, At, B1); PG8_BAR; PG8_SCHED;
;         }
;         if (wr == 0) PG8_BAR;
	s_add_u32 s62, s40, 0x80
	s_addc_u32 s63, s41, 0
	ds_read_b128 v[178:181], v140 offset:49152
	ds_read_b128 v[182:185], v140 offset:50176
	ds_read_b128 v[186:189], v140 offset:51200
	ds_read_b128 v[190:193], v140 offset:52224
	ds_read_b128 v[194:197], v140 offset:53248
	ds_read_b128 v[198:201], v140 offset:54272
	ds_read_b128 v[202:205], v140 offset:55296
	ds_read_b128 v[206:209], v140 offset:56320
	s_mov_b32 m0, s48
	s_nop 0
	global_load_lds_dwordx4 v135, s[62:63]
	s_add_u32 s62, s40, 0x20080
	s_mov_b32 m0, s49
	s_addc_u32 s63, s41, 0
	global_load_lds_dwordx4 v135, s[62:63]
	s_add_u32 s62, s40, 0x40080
	s_mov_b32 m0, s52
	s_addc_u32 s63, s41, 0
	global_load_lds_dwordx4 v135, s[62:63]
	s_add_u32 s40, s40, 0x60080
	s_mov_b32 m0, s53
	s_addc_u32 s41, s41, 0
	global_load_lds_dwordx4 v135, s[40:41]
	s_mov_b32 m0, s50
	s_nop 0
	global_load_lds_dwordx4 v134, s[38:39]
	s_add_u32 s26, s26, 0x20080
	s_mov_b32 m0, s51
	s_addc_u32 s27, s27, 0
	global_load_lds_dwordx4 v134, s[26:27]
	s_waitcnt vmcnt(8) lgkmcnt(0)
	s_barrier
	s_setprio 1
	v_mfma_f32_16x16x32_bf16 v[60:63], v[144:147], v[178:181], v[60:63]
	v_mfma_f32_16x16x32_bf16 v[56:59], v[152:155], v[178:181], v[56:59]
	v_mfma_f32_16x16x32_bf16 v[52:55], v[144:147], v[186:189], v[52:55]
	v_mfma_f32_16x16x32_bf16 v[44:47], v[152:155], v[186:189], v[44:47]
	v_mfma_f32_16x16x32_bf16 v[36:39], v[144:147], v[194:197], v[36:39]
	v_mfma_f32_16x16x32_bf16 v[28:31], v[152:155], v[194:197], v[28:31]
	v_mfma_f32_16x16x32_bf16 v[20:23], v[144:147], v[202:205], v[20:23]
	v_mfma_f32_16x16x32_bf16 v[12:15], v[152:155], v[202:205], v[12:15]
	v_mfma_f32_16x16x32_bf16 v[60:63], v[148:151], v[182:185], v[60:63]
	v_mfma_f32_16x16x32_bf16 v[56:59], v[156:159], v[182:185], v[56:59]
	v_mfma_f32_16x16x32_bf16 v[52:55], v[148:151], v[190:193], v[52:55]
	v_mfma_f32_16x16x32_bf16 v[44:47], v[156:159], v[190:193], v[44:47]
	v_mfma_f32_16x16x32_bf16 v[36:39], v[148:151], v[198:201], v[36:39]
	v_mfma_f32_16x16x32_bf16 v[28:31], v[156:159], v[198:201], v[28:31]
	v_mfma_f32_16x16x32_bf16 v[20:23], v[148:151], v[206:209], v[20:23]
	v_mfma_f32_16x16x32_bf16 v[12:15], v[156:159], v[206:209], v[12:15]
	v_mfma_f32_16x16x32_bf16 v[48:51], v[160:163], v[178:181], v[48:51]
	v_mfma_f32_16x16x32_bf16 v[40:43], v[168:171], v[178:181], v[40:43]
	v_mfma_f32_16x16x32_bf16 v[32:35], v[160:163], v[186:189], v[32:35]
	v_mfma_f32_16x16x32_bf16 v[24:27], v[168:171], v[186:189], v[24:27]
	v_mfma_f32_16x16x32_bf16 v[16:19], v[160:163], v[194:197], v[16:19]
	v_mfma_f32_16x16x32_bf16 v[8:11], v[168:171], v[194:197], v[8:11]
	v_mfma_f32_16x16x32_bf16 v[4:7], v[160:163], v[202:205], v[4:7]
	v_mfma_f32_16x16x32_bf16 v[0:3], v[168:171], v[202:205], v[0:3]
	v_mfma_f32_16x16x32_bf16 v[48:51], v[164:167], v[182:185], v[48:51]
	v_mfma_f32_16x16x32_bf16 v[40:43], v[172:175], v[182:185], v[40:43]
	v_mfma_f32_16x16x32_bf16 v[32:35], v[164:167], v[190:193], v[32:35]
	v_mfma_f32_16x16x32_bf16 v[24:27], v[172:175], v[190:193], v[24:27]
	v_mfma_f32_16x16x32_bf16 v[16:19], v[164:167], v[198:201], v[16:19]
	v_mfma_f32_16x16x32_bf16 v[8:11], v[172:175], v[198:201], v[8:11]
	v_mfma_f32_16x16x32_bf16 v[4:7], v[164:167], v[206:209], v[4:7]
	v_mfma_f32_16x16x32_bf16 v[0:3], v[172:175], v[206:209], v[0:3]
	s_setprio 0
	s_barrier
	s_cmp_gt_u32 s60, 13
	s_cbranch_scc0 .LBB0_1192
	s_and_b64 vcc, exec, s[14:15]
	s_cbranch_vccz .LBB0_1195
	s_barrier

; #define PG8_STAGE(bufoff, gbase, voff, p64) do { _Pragma("unroll") for (int _i = 0; _i < 2; ++_i) { \
;         const char* _gb = (const char*)(gbase) + (size_t)_i * (p64); const unsigned _la = ldsbase + (unsigned)(bufoff) + (unsigned)_i * 8192u; \
;         asm volatile("s_mov_b32 m0, %0\n\ts_nop 0\n\tglobal_load_lds_dwordx4 %1, %2" :: "s"(_la), "v"(voff), "s"(_gb) : "memory"); } } while (0)
; #define PG8_LDA(dst, b, h) do { _Pragma("unroll") for (int m = 0; m < 4; ++m) _Pragma("unroll") for (int k = 0; k < 2; ++k) dst[m][k] = *(const LAS bf16x8*)(lds + PG8_SA(b, h) + aoff + m * 2048 + k * 1024); } while (0)
; #define PG8_LDB(dst, b, h) do { _Pragma("unroll") for (int n = 0; n < 2; ++n) _Pragma("unroll") for (int k = 0; k < 2; ++k) dst[n][k] = *(const LAS bf16x8*)(lds + PG8_SB(b, h) + boff + n * 2048 + k * 1024); } while (0)
; #define PG8_MMA(ai, bj, At, Bt) do { __builtin_amdgcn_s_setprio(1); _Pragma("unroll") for (int m = 0; m < 4; ++m) _Pragma("unroll") for (int n = 0; n < 2; ++n) _Pragma("unroll") for (int k = 0; k < 2; ++k) \
;         acc[ai][bj][m][n] = __builtin_amdgcn_mfma_f32_16x16x32_bf16(Bt[n][k], At[m][k], acc[ai][bj][m][n], 0, 0, 0); __builtin_amdgcn_s_setprio(0); } while (0)
; #define PG8_WAIT_V(n) asm volatile("s_waitcnt vmcnt(" #n ")" ::: "memory")
; #define PG8_BAR __builtin_amdgcn_s_barrier()
; template <class Epi, class Sched>
; __device__ __forceinline__ void gemm_phase(LAS unsigned char* lds, const Sched& S, const Epi& E) {
;     ...
;             const bool last = (t == nt - 2);
;             const char* a1 = cA + (size_t)(t + 1) * kstep;
;             const char* a2 = last ? nA : cA + (size_t)(t + 2) * kstep; const char* b2 = last ? nB : cB + (size_t)(t + 2) * kstep;
;             const char* a3 = a2 + kstep; const char* b3 = b2 + kstep;
;             const unsigned vA2 = voffA, vB2 = voffB, hA2 = hA, hB2 = hB;
;             PG8_LDB(B0, 0, 0); PG8_LDB(B1, 0, 1); PG8_SCHED; PG8_LDA(At, 0, 0); PG8_STAGE(PG8_SA(1, 1), a1 + hA, voffA, hA / 2);
;             PG8_WAIT_V(8); PG8_WAIT_L(0); PG8_BAR; PG8_MMA(0, 0, At, B0); PG8_MMA(0, 1, At, B1); PG8_BAR; PG8_SCHED;
;             PG8_LDA(At, 0, 1); PG8_STAGE(PG8_SB(0, 0), b2, vB2, hB2 / 2); PG8_STAGE(PG8_SB(0, 1), b2 + hB2, vB2, hB2 / 2); PG8_STAGE(PG8_SA(0, 0), a2, vA2, hA2 / 2);
;             PG8_WAIT_V(8); PG8_WAIT_L(0); PG8_BAR; PG8_MMA(1, 0, At, B0); PG8_MMA(1, 1, At, B1); PG8_BAR; PG8_SCHED;
.LBB0_1274:
	ds_read_b128 v[128:131], v156
	ds_read_b128 v[132:135], v156 offset:1024
	ds_read_b128 v[140:143], v156 offset:2048
	ds_read_b128 v[144:147], v156 offset:3072
	ds_read_b128 v[148:151], v157
	ds_read_b128 v[162:165], v157 offset:1024
	ds_read_b128 v[166:169], v157 offset:2048
	ds_read_b128 v[170:173], v157 offset:3072
	s_add_u32 s30, s38, 0xfffc0080
	s_addc_u32 s40, s39, -1
	s_cmp_eq_u32 s63, 12
	s_cselect_b32 s41, s25, s40
	s_cselect_b32 s40, s24, s30
	s_cselect_b32 s44, s26, s61
	s_cselect_b32 s45, s27, s62
	s_add_u32 s42, s40, 0x80
	s_addc_u32 s43, s41, 0
	ds_read_b128 v[178:181], v158
	ds_read_b128 v[182:185], v158 offset:1024
	ds_read_b128 v[186:189], v158 offset:2048
	ds_read_b128 v[190:193], v158 offset:3072
	ds_read_b128 v[194:197], v158 offset:4096
	ds_read_b128 v[198:201], v158 offset:5120
	ds_read_b128 v[202:205], v158 offset:6144
	ds_read_b128 v[206:209], v158 offset:7168
	s_mov_b32 m0, s57
	s_nop 0
	global_load_lds_dwordx4 v152, s[38:39]
	s_add_u32 s66, s38, 0x20000
	s_mov_b32 m0, s58
	s_addc_u32 s67, s39, 0
	global_load_lds_dwordx4 v152, s[66:67]
	s_waitcnt vmcnt(8) lgkmcnt(0)
	s_barrier
	s_setprio 1
	v_mfma_f32_16x16x32_bf16 v[124:127], v[128:131], v[178:181], v[124:127]
	v_mfma_f32_16x16x32_bf16 v[116:119], v[140:143], v[178:181], v[116:119]
	v_mfma_f32_16x16x32_bf16 v[108:111], v[128:131], v[186:189], v[108:111]
	v_mfma_f32_16x16x32_bf16 v[100:103], v[140:143], v[186:189], v[100:103]
	v_mfma_f32_16x16x32_bf16 v[92:95], v[128:131], v[194:197], v[92:95]
	v_mfma_f32_16x16x32_bf16 v[84:87], v[140:143], v[194:197], v[84:87]
	v_mfma_f32_16x16x32_bf16 v[76:79], v[128:131], v[202:205], v[76:79]
	v_mfma_f32_16x16x32_bf16 v[68:71], v[140:143], v[202:205], v[68:71]
	v_mfma_f32_16x16x32_bf16 v[124:127], v[132:135], v[182:185], v[124:127]
	v_mfma_f32_16x16x32_bf16 v[116:119], v[144:147], v[182:185], v[116:119]
	v_mfma_f32_16x16x32_bf16 v[108:111], v[132:135], v[190:193], v[108:111]
	v_mfma_f32_16x16x32_bf16 v[100:103], v[144:147], v[190:193], v[100:103]
	v_mfma_f32_16x16x32_bf16 v[92:95], v[132:135], v[198:201], v[92:95]
	v_mfma_f32_16x16x32_bf16 v[84:87], v[144:147], v[198:201], v[84:87]
	v_mfma_f32_16x16x32_bf16 v[76:79], v[132:135], v[206:209], v[76:79]
	v_mfma_f32_16x16x32_bf16 v[68:71], v[144:147], v[206:209], v[68:71]
	s_add_i32 s63, s63, 2
	s_add_u32 s38, s38, 0x100
	s_addc_u32 s39, s39, 0
	s_add_u32 s61, s61, 0x100
	s_addc_u32 s62, s62, 0
	v_mfma_f32_16x16x32_bf16 v[120:123], v[148:151], v[178:181], v[120:123]
	v_mfma_f32_16x16x32_bf16 v[112:115], v[166:169], v[178:181], v[112:115]
	v_mfma_f32_16x16x32_bf16 v[104:107], v[148:151], v[186:189], v[104:107]
	v_mfma_f32_16x16x32_bf16 v[96:99], v[166:169], v[186:189], v[96:99]
	v_mfma_f32_16x16x32_bf16 v[88:91], v[148:151], v[194:197], v[88:91]
	v_mfma_f32_16x16x32_bf16 v[80:83], v[166:169], v[194:197], v[80:83]
	v_mfma_f32_16x16x32_bf16 v[72:75], v[148:151], v[202:205], v[72:75]
	v_mfma_f32_16x16x32_bf16 v[64:67], v[166:169], v[202:205], v[64:67]
	v_mfma_f32_16x16x32_bf16 v[120:123], v[162:165], v[182:185], v[120:123]
	v_mfma_f32_16x16x32_bf16 v[112:115], v[170:173], v[182:185], v[112:115]
	v_mfma_f32_16x16x32_bf16 v[104:107], v[162:165], v[190:193], v[104:107]
	v_mfma_f32_16x16x32_bf16 v[96:99], v[170:173], v[190:193], v[96:99]
	v_mfma_f32_16x16x32_bf16 v[88:91], v[162:165], v[198:201], v[88:91]
	v_mfma_f32_16x16x32_bf16 v[80:83], v[170:173], v[198:201], v[80:83]
	v_mfma_f32_16x16x32_bf16 v[72:75], v[162:165], v[206:209], v[72:75]
	v_mfma_f32_16x16x32_bf16 v[64:67], v[170:173], v[206:209], v[64:67]
	s_setprio 0
	s_barrier
	s_add_u32 s66, s44, 0x20000
	ds_read_b128 v[178:181], v158 offset:16384
	ds_read_b128 v[182:185], v158 offset:17408
	ds_read_b128 v[186:189], v158 offset:18432
	ds_read_b128 v[190:193], v158 offset:19456
	ds_read_b128 v[194:197], v158 offset:20480
	ds_read_b128 v[198:201], v158 offset:21504
	ds_read_b128 v[202:205], v158 offset:22528
	ds_read_b128 v[206:209], v158 offset:23552
	s_mov_b32 m0, s35
	s_nop 0
	global_load_lds_dwordx4 v153, s[44:45]
	s_mov_b32 m0, s36
	s_addc_u32 s67, s45, 0
	global_load_lds_dwordx4 v153, s[66:67]
	s_add_u32 s66, s44, 0x40000
	s_mov_b32 m0, s37
	s_addc_u32 s67, s45, 0
	global_load_lds_dwordx4 v153, s[66:67]
	s_add_u32 s66, s44, 0x60000
	s_mov_b32 m0, s46
	s_addc_u32 s67, s45, 0
	global_load_lds_dwordx4 v153, s[66:67]
	s_mov_b32 m0, s34
	s_nop 0
	global_load_lds_dwordx4 v152, s[40:41]
	s_add_u32 s66, s40, 0x20000
	s_mov_b32 m0, s47
	s_addc_u32 s67, s41, 0
	global_load_lds_dwordx4 v152, s[66:67]
	s_waitcnt vmcnt(8) lgkmcnt(0)
	s_barrier
; #define PG8_STAGE(bufoff, gbase, voff, p64) do { _Pragma("unroll") for (int _i = 0; _i < 2; ++_i) { \
;         const char* _gb = (const char*)(gbase) + (size_t)_i * (p64); const unsigned _la = ldsbase + (unsigned)(bufoff) + (unsigned)_i * 8192u; \
;         asm volatile("s_mov_b32 m0, %0\n\ts_nop 0\n\tglobal_load_lds_dwordx4 %1, %2" :: "s"(_la), "v"(voff), "s"(_gb) : "memory"); } } while (0)
; #define PG8_LDA(dst, b, h) do { _Pragma("unroll") for (int m = 0; m < 4; ++m) _Pragma("unroll") for (int k = 0; k < 2; ++k) dst[m][k] = *(const LAS bf16x8*)(lds + PG8_SA(b, h) + aoff + m * 2048 + k * 1024); } while (0)
; #define PG8_LDB(dst, b, h) do { _Pragma("unroll") for (int n = 0; n < 2; ++n) _Pragma("unroll") for (int k = 0; k < 2; ++k) dst[n][k] = *(const LAS bf16x8*)(lds + PG8_SB(b, h) + boff + n * 2048 + k * 1024); } while (0)
; #define PG8_MMA(ai, bj, At, Bt) do { __builtin_amdgcn_s_setprio(1); _Pragma("unroll") for (int m = 0; m < 4; ++m) _Pragma("unroll") for (int n = 0; n < 2; ++n) _Pragma("unroll") for (int k = 0; k < 2; ++k) \
;         acc[ai][bj][m][n] = __builtin_amdgcn_mfma_f32_16x16x32_bf16(Bt[n][k], At[m][k], acc[ai][bj][m][n], 0, 0, 0); __builtin_amdgcn_s_setprio(0); } while (0)
; #define PG8_WAIT_V(n) asm volatile("s_waitcnt vmcnt(" #n ")" ::: "memory")
; #define PG8_WAIT_L(n) asm volatile("s_waitcnt lgkmcnt(" #n ")" ::: "memory")
; #define PG8_BAR __builtin_amdgcn_s_barrier()
; #define PG8_SCHED __builtin_amdgcn_sched_barrier(0)
; template <class Epi, class Sched>
; __device__ __forceinline__ void gemm_phase(LAS unsigned char* lds, const Sched& S, const Epi& E) {
;     ...
;             PG8_WAIT_V(8); PG8_WAIT_L(0); PG8_BAR; PG8_MMA(1, 0, At, B0); PG8_MMA(1, 1, At, B1); PG8_BAR; PG8_SCHED;
;             PG8_LDB(B0, 1, 0); PG8_LDB(B1, 1, 1); PG8_SCHED; PG8_LDA(At, 1, 0); PG8_STAGE(PG8_SA(0, 1), a2 + hA2, vA2, hA2 / 2);
;             PG8_WAIT_V(8); PG8_WAIT_L(0); PG8_BAR; PG8_MMA(0, 0, At, B0); PG8_MMA(0, 1, At, B1); PG8_BAR; PG8_SCHED;
	s_setprio 1
	v_mfma_f32_16x16x32_bf16 v[60:63], v[128:131], v[178:181], v[60:63]
	v_mfma_f32_16x16x32_bf16 v[52:55], v[140:143], v[178:181], v[52:55]
	v_mfma_f32_16x16x32_bf16 v[44:47], v[128:131], v[186:189], v[44:47]
	v_mfma_f32_16x16x32_bf16 v[36:39], v[140:143], v[186:189], v[36:39]
	v_mfma_f32_16x16x32_bf16 v[28:31], v[128:131], v[194:197], v[28:31]
	v_mfma_f32_16x16x32_bf16 v[20:23], v[140:143], v[194:197], v[20:23]
	v_mfma_f32_16x16x32_bf16 v[12:15], v[128:131], v[202:205], v[12:15]
	v_mfma_f32_16x16x32_bf16 v[4:7], v[140:143], v[202:205], v[4:7]
	v_mfma_f32_16x16x32_bf16 v[60:63], v[132:135], v[182:185], v[60:63]
	v_mfma_f32_16x16x32_bf16 v[52:55], v[144:147], v[182:185], v[52:55]
	v_mfma_f32_16x16x32_bf16 v[44:47], v[132:135], v[190:193], v[44:47]
	v_mfma_f32_16x16x32_bf16 v[36:39], v[144:147], v[190:193], v[36:39]
	v_mfma_f32_16x16x32_bf16 v[28:31], v[132:135], v[198:201], v[28:31]
	v_mfma_f32_16x16x32_bf16 v[20:23], v[144:147], v[198:201], v[20:23]
	v_mfma_f32_16x16x32_bf16 v[12:15], v[132:135], v[206:209], v[12:15]
	v_mfma_f32_16x16x32_bf16 v[4:7], v[144:147], v[206:209], v[4:7]
	v_mfma_f32_16x16x32_bf16 v[56:59], v[148:151], v[178:181], v[56:59]
	v_mfma_f32_16x16x32_bf16 v[48:51], v[166:169], v[178:181], v[48:51]
	v_mfma_f32_16x16x32_bf16 v[40:43], v[148:151], v[186:189], v[40:43]
	v_mfma_f32_16x16x32_bf16 v[32:35], v[166:169], v[186:189], v[32:35]
	v_mfma_f32_16x16x32_bf16 v[24:27], v[148:151], v[194:197], v[24:27]
	v_mfma_f32_16x16x32_bf16 v[16:19], v[166:169], v[194:197], v[16:19]
	v_mfma_f32_16x16x32_bf16 v[8:11], v[148:151], v[202:205], v[8:11]
	v_mfma_f32_16x16x32_bf16 v[0:3], v[166:169], v[202:205], v[0:3]
	v_mfma_f32_16x16x32_bf16 v[56:59], v[162:165], v[182:185], v[56:59]
	v_mfma_f32_16x16x32_bf16 v[48:51], v[170:173], v[182:185], v[48:51]
	v_mfma_f32_16x16x32_bf16 v[40:43], v[162:165], v[190:193], v[40:43]
	v_mfma_f32_16x16x32_bf16 v[32:35], v[170:173], v[190:193], v[32:35]
	v_mfma_f32_16x16x32_bf16 v[24:27], v[162:165], v[198:201], v[24:27]
	v_mfma_f32_16x16x32_bf16 v[16:19], v[170:173], v[198:201], v[16:19]
	v_mfma_f32_16x16x32_bf16 v[8:11], v[162:165], v[206:209], v[8:11]
	v_mfma_f32_16x16x32_bf16 v[0:3], v[170:173], v[206:209], v[0:3]
	s_setprio 0
	s_barrier
	ds_read_b128 v[128:131], v159
	ds_read_b128 v[132:135], v159 offset:1024
	ds_read_b128 v[140:143], v159 offset:2048
	ds_read_b128 v[144:147], v159 offset:3072
	ds_read_b128 v[148:151], v160
	ds_read_b128 v[162:165], v160 offset:1024
	ds_read_b128 v[166:169], v160 offset:2048
	ds_read_b128 v[170:173], v160 offset:3072
	ds_read_b128 v[178:181], v158 offset:32768
	ds_read_b128 v[182:185], v158 offset:33792
	ds_read_b128 v[186:189], v158 offset:34816
	ds_read_b128 v[190:193], v158 offset:35840
	ds_read_b128 v[194:197], v158 offset:36864
	ds_read_b128 v[198:201], v158 offset:37888
	ds_read_b128 v[202:205], v158 offset:38912
	ds_read_b128 v[206:209], v158 offset:39936
	s_add_u32 s66, s40, 0x40000
	s_mov_b32 m0, s48
	s_addc_u32 s67, s41, 0
	global_load_lds_dwordx4 v152, s[66:67]
	s_add_u32 s66, s40, 0x60000
	s_mov_b32 m0, s49
	s_addc_u32 s67, s41, 0
	global_load_lds_dwordx4 v152, s[66:67]
	s_waitcnt vmcnt(8) lgkmcnt(0)
	s_barrier
	s_setprio 1
	v_mfma_f32_16x16x32_bf16 v[124:127], v[128:131], v[178:181], v[124:127]
	v_mfma_f32_16x16x32_bf16 v[116:119], v[140:143], v[178:181], v[116:119]
	v_mfma_f32_16x16x32_bf16 v[108:111], v[128:131], v[186:189], v[108:111]
	v_mfma_f32_16x16x32_bf16 v[100:103], v[140:143], v[186:189], v[100:103]
	v_mfma_f32_16x16x32_bf16 v[92:95], v[128:131], v[194:197], v[92:95]
	v_mfma_f32_16x16x32_bf16 v[84:87], v[140:143], v[194:197], v[84:87]
	v_mfma_f32_16x16x32_bf16 v[76:79], v[128:131], v[202:205], v[76:79]
	v_mfma_f32_16x16x32_bf16 v[68:71], v[140:143], v[202:205], v[68:71]
	v_mfma_f32_16x16x32_bf16 v[124:127], v[132:135], v[182:185], v[124:127]
	v_mfma_f32_16x16x32_bf16 v[116:119], v[144:147], v[182:185], v[116:119]
	v_mfma_f32_16x16x32_bf16 v[108:111], v[132:135], v[190:193], v[108:111]
	v_mfma_f32_16x16x32_bf16 v[100:103], v[144:147], v[190:193], v[100:103]
	v_mfma_f32_16x16x32_bf16 v[92:95], v[132:135], v[198:201], v[92:95]
	v_mfma_f32_16x16x32_bf16 v[84:87], v[144:147], v[198:201], v[84:87]
	v_mfma_f32_16x16x32_bf16 v[76:79], v[132:135], v[206:209], v[76:79]
	v_mfma_f32_16x16x32_bf16 v[68:71], v[144:147], v[206:209], v[68:71]
	v_mfma_f32_16x16x32_bf16 v[120:123], v[148:151], v[178:181], v[120:123]
	v_mfma_f32_16x16x32_bf16 v[112:115], v[166:169], v[178:181], v[112:115]
	v_mfma_f32_16x16x32_bf16 v[104:107], v[148:151], v[186:189], v[104:107]
	v_mfma_f32_16x16x32_bf16 v[96:99], v[166:169], v[186:189], v[96:99]
	v_mfma_f32_16x16x32_bf16 v[88:91], v[148:151], v[194:197], v[88:91]
	v_mfma_f32_16x16x32_bf16 v[80:83], v[166:169], v[194:197], v[80:83]
	v_mfma_f32_16x16x32_bf16 v[72:75], v[148:151], v[202:205], v[72:75]
	v_mfma_f32_16x16x32_bf16 v[64:67], v[166:169], v[202:205], v[64:67]
	v_mfma_f32_16x16x32_bf16 v[120:123], v[162:165], v[182:185], v[120:123]
	v_mfma_f32_16x16x32_bf16 v[112:115], v[170:173], v[182:185], v[112:115]
	v_mfma_f32_16x16x32_bf16 v[104:107], v[162:165], v[190:193], v[104:107]
	v_mfma_f32_16x16x32_bf16 v[96:99], v[170:173], v[190:193], v[96:99]
	v_mfma_f32_16x16x32_bf16 v[88:91], v[162:165], v[198:201], v[88:91]
	v_mfma_f32_16x16x32_bf16 v[80:83], v[170:173], v[198:201], v[80:83]
	v_mfma_f32_16x16x32_bf16 v[72:75], v[162:165], v[206:209], v[72:75]
	v_mfma_f32_16x16x32_bf16 v[64:67], v[170:173], v[206:209], v[64:67]
	s_setprio 0
	s_barrier
; #define PG8_STAGE(bufoff, gbase, voff, p64) do { _Pragma("unroll") for (int _i = 0; _i < 2; ++_i) { \
;         const char* _gb = (const char*)(gbase) + (size_t)_i * (p64); const unsigned _la = ldsbase + (unsigned)(bufoff) + (unsigned)_i * 8192u; \
;         asm volatile("s_mov_b32 m0, %0\n\ts_nop 0\n\tglobal_load_lds_dwordx4 %1, %2" :: "s"(_la), "v"(voff), "s"(_gb) : "memory"); } } while (0)
; #define PG8_LDA(dst, b, h) do { _Pragma("unroll") for (int m = 0; m < 4; ++m) _Pragma("unroll") for (int k = 0; k < 2; ++k) dst[m][k] = *(const LAS bf16x8*)(lds + PG8_SA(b, h) + aoff + m * 2048 + k * 1024); } while (0)
; #define PG8_MMA(ai, bj, At, Bt) do { __builtin_amdgcn_s_setprio(1); _Pragma("unroll") for (int m = 0; m < 4; ++m) _Pragma("unroll") for (int n = 0; n < 2; ++n) _Pragma("unroll") for (int k = 0; k < 2; ++k) \
;         acc[ai][bj][m][n] = __builtin_amdgcn_mfma_f32_16x16x32_bf16(Bt[n][k], At[m][k], acc[ai][bj][m][n], 0, 0, 0); __builtin_amdgcn_s_setprio(0); } while (0)
; #define PG8_WAIT_V(n) asm volatile("s_waitcnt vmcnt(" #n ")" ::: "memory")
; #define PG8_WAIT_L(n) asm volatile("s_waitcnt lgkmcnt(" #n ")" ::: "memory")
; #define PG8_BAR __builtin_amdgcn_s_barrier()
; #define PG8_SCHED __builtin_amdgcn_sched_barrier(0)
; template <class Epi, class Sched>
; __device__ __forceinline__ void gemm_phase(LAS unsigned char* lds, const Sched& S, const Epi& E) {
;     ...
;             PG8_LDA(At, 1, 1); PG8_STAGE(PG8_SB(1, 0), b3, vB2, hB2 / 2); PG8_STAGE(PG8_SB(1, 1), b3 + hB2, vB2, hB2 / 2); PG8_STAGE(PG8_SA(1, 0), a3, vA2, hA2 / 2);
;             PG8_WAIT_V(8); PG8_WAIT_L(0); PG8_BAR; PG8_MMA(1, 0, At, B0); PG8_MMA(1, 1, At, B1); PG8_BAR; PG8_SCHED;
;         }
;         if (wr == 0) PG8_BAR;
	s_add_u32 s66, s44, 0x80
	s_addc_u32 s67, s45, 0
	ds_read_b128 v[178:181], v158 offset:49152
	ds_read_b128 v[182:185], v158 offset:50176
	ds_read_b128 v[186:189], v158 offset:51200
	ds_read_b128 v[190:193], v158 offset:52224
	ds_read_b128 v[194:197], v158 offset:53248
	ds_read_b128 v[198:201], v158 offset:54272
	ds_read_b128 v[202:205], v158 offset:55296
	ds_read_b128 v[206:209], v158 offset:56320
	s_mov_b32 m0, s51
	s_nop 0
	global_load_lds_dwordx4 v153, s[66:67]
	s_add_u32 s66, s44, 0x20080
	s_mov_b32 m0, s52
	s_addc_u32 s67, s45, 0
	global_load_lds_dwordx4 v153, s[66:67]
	s_add_u32 s66, s44, 0x40080
	s_mov_b32 m0, s55
	s_addc_u32 s67, s45, 0
	global_load_lds_dwordx4 v153, s[66:67]
	s_add_u32 s44, s44, 0x60080
	s_mov_b32 m0, s56
	s_addc_u32 s45, s45, 0
	global_load_lds_dwordx4 v153, s[44:45]
	s_mov_b32 m0, s53
	s_nop 0
	global_load_lds_dwordx4 v152, s[42:43]
	s_add_u32 s40, s40, 0x20080
	s_mov_b32 m0, s54
	s_addc_u32 s41, s41, 0
	global_load_lds_dwordx4 v152, s[40:41]
	s_waitcnt vmcnt(8) lgkmcnt(0)
	s_barrier
	s_setprio 1
	v_mfma_f32_16x16x32_bf16 v[60:63], v[128:131], v[178:181], v[60:63]
	v_mfma_f32_16x16x32_bf16 v[52:55], v[140:143], v[178:181], v[52:55]
	v_mfma_f32_16x16x32_bf16 v[44:47], v[128:131], v[186:189], v[44:47]
	v_mfma_f32_16x16x32_bf16 v[36:39], v[140:143], v[186:189], v[36:39]
	v_mfma_f32_16x16x32_bf16 v[28:31], v[128:131], v[194:197], v[28:31]
	v_mfma_f32_16x16x32_bf16 v[20:23], v[140:143], v[194:197], v[20:23]
	v_mfma_f32_16x16x32_bf16 v[12:15], v[128:131], v[202:205], v[12:15]
	v_mfma_f32_16x16x32_bf16 v[4:7], v[140:143], v[202:205], v[4:7]
	v_mfma_f32_16x16x32_bf16 v[60:63], v[132:135], v[182:185], v[60:63]
	v_mfma_f32_16x16x32_bf16 v[52:55], v[144:147], v[182:185], v[52:55]
	v_mfma_f32_16x16x32_bf16 v[44:47], v[132:135], v[190:193], v[44:47]
	v_mfma_f32_16x16x32_bf16 v[36:39], v[144:147], v[190:193], v[36:39]
	v_mfma_f32_16x16x32_bf16 v[28:31], v[132:135], v[198:201], v[28:31]
	v_mfma_f32_16x16x32_bf16 v[20:23], v[144:147], v[198:201], v[20:23]
	v_mfma_f32_16x16x32_bf16 v[12:15], v[132:135], v[206:209], v[12:15]
	v_mfma_f32_16x16x32_bf16 v[4:7], v[144:147], v[206:209], v[4:7]
	v_mfma_f32_16x16x32_bf16 v[56:59], v[148:151], v[178:181], v[56:59]
	v_mfma_f32_16x16x32_bf16 v[48:51], v[166:169], v[178:181], v[48:51]
	v_mfma_f32_16x16x32_bf16 v[40:43], v[148:151], v[186:189], v[40:43]
	v_mfma_f32_16x16x32_bf16 v[32:35], v[166:169], v[186:189], v[32:35]
	v_mfma_f32_16x16x32_bf16 v[24:27], v[148:151], v[194:197], v[24:27]
	v_mfma_f32_16x16x32_bf16 v[16:19], v[166:169], v[194:197], v[16:19]
	v_mfma_f32_16x16x32_bf16 v[8:11], v[148:151], v[202:205], v[8:11]
	v_mfma_f32_16x16x32_bf16 v[0:3], v[166:169], v[202:205], v[0:3]
	v_mfma_f32_16x16x32_bf16 v[56:59], v[162:165], v[182:185], v[56:59]
	v_mfma_f32_16x16x32_bf16 v[48:51], v[170:173], v[182:185], v[48:51]
	v_mfma_f32_16x16x32_bf16 v[40:43], v[162:165], v[190:193], v[40:43]
	v_mfma_f32_16x16x32_bf16 v[32:35], v[170:173], v[190:193], v[32:35]
	v_mfma_f32_16x16x32_bf16 v[24:27], v[162:165], v[198:201], v[24:27]
	v_mfma_f32_16x16x32_bf16 v[16:19], v[170:173], v[198:201], v[16:19]
	v_mfma_f32_16x16x32_bf16 v[8:11], v[162:165], v[206:209], v[8:11]
	v_mfma_f32_16x16x32_bf16 v[0:3], v[170:173], v[206:209], v[0:3]
	s_setprio 0
	s_barrier
	s_cmp_gt_u32 s63, 13
	s_cbranch_scc0 .LBB0_1274
	s_and_b64 vcc, exec, s[18:19]
	s_cbranch_vccz .LBB0_1277
	s_barrier

; #define PG8_STAGE(bufoff, gbase, voff, p64) do { _Pragma("unroll") for (int _i = 0; _i < 2; ++_i) { \
;         const char* _gb = (const char*)(gbase) + (size_t)_i * (p64); const unsigned _la = ldsbase + (unsigned)(bufoff) + (unsigned)_i * 8192u; \
;         asm volatile("s_mov_b32 m0, %0\n\ts_nop 0\n\tglobal_load_lds_dwordx4 %1, %2" :: "s"(_la), "v"(voff), "s"(_gb) : "memory"); } } while (0)
; #define PG8_LDA(dst, b, h) do { _Pragma("unroll") for (int m = 0; m < 4; ++m) _Pragma("unroll") for (int k = 0; k < 2; ++k) dst[m][k] = *(const LAS bf16x8*)(lds + PG8_SA(b, h) + aoff + m * 2048 + k * 1024); } while (0)
; #define PG8_LDB(dst, b, h) do { _Pragma("unroll") for (int n = 0; n < 2; ++n) _Pragma("unroll") for (int k = 0; k < 2; ++k) dst[n][k] = *(const LAS bf16x8*)(lds + PG8_SB(b, h) + boff + n * 2048 + k * 1024); } while (0)
; #define PG8_MMA(ai, bj, At, Bt) do { __builtin_amdgcn_s_setprio(1); _Pragma("unroll") for (int m = 0; m < 4; ++m) _Pragma("unroll") for (int n = 0; n < 2; ++n) _Pragma("unroll") for (int k = 0; k < 2; ++k) \
;         acc[ai][bj][m][n] = __builtin_amdgcn_mfma_f32_16x16x32_bf16(Bt[n][k], At[m][k], acc[ai][bj][m][n], 0, 0, 0); __builtin_amdgcn_s_setprio(0); } while (0)
; #define PG8_WAIT_V(n) asm volatile("s_waitcnt vmcnt(" #n ")" ::: "memory")
; #define PG8_BAR __builtin_amdgcn_s_barrier()
; template <class Epi, class Sched>
; __device__ __forceinline__ void gemm_phase(LAS unsigned char* lds, const Sched& S, const Epi& E) {
;     ...
;             const bool last = (t == nt - 2);
;             const char* a1 = cA + (size_t)(t + 1) * kstep;
;             const char* a2 = last ? nA : cA + (size_t)(t + 2) * kstep; const char* b2 = last ? nB : cB + (size_t)(t + 2) * kstep;
;             const char* a3 = a2 + kstep; const char* b3 = b2 + kstep;
;             const unsigned vA2 = voffA, vB2 = voffB, hA2 = hA, hB2 = hB;
;             PG8_LDB(B0, 0, 0); PG8_LDB(B1, 0, 1); PG8_SCHED; PG8_LDA(At, 0, 0); PG8_STAGE(PG8_SA(1, 1), a1 + hA, voffA, hA / 2);
;             PG8_WAIT_V(8); PG8_WAIT_L(0); PG8_BAR; PG8_MMA(0, 0, At, B0); PG8_MMA(0, 1, At, B1); PG8_BAR; PG8_SCHED;
;             PG8_LDA(At, 0, 1); PG8_STAGE(PG8_SB(0, 0), b2, vB2, hB2 / 2); PG8_STAGE(PG8_SB(0, 1), b2 + hB2, vB2, hB2 / 2); PG8_STAGE(PG8_SA(0, 0), a2, vA2, hA2 / 2);
;             PG8_WAIT_V(8); PG8_WAIT_L(0); PG8_BAR; PG8_MMA(1, 0, At, B0); PG8_MMA(1, 1, At, B1); PG8_BAR; PG8_SCHED;
.LBB0_1352:
	ds_read_b128 v[128:131], v174
	ds_read_b128 v[132:135], v174 offset:1024
	ds_read_b128 v[136:139], v174 offset:2048
	ds_read_b128 v[144:147], v174 offset:3072
	ds_read_b128 v[148:151], v175
	ds_read_b128 v[152:155], v175 offset:1024
	ds_read_b128 v[156:159], v175 offset:2048
	ds_read_b128 v[160:163], v175 offset:3072
	s_add_u32 s24, s22, 0xfffc0080
	s_addc_u32 s25, s23, -1
	s_cmp_eq_u32 s61, 12
	s_cselect_b32 s24, s18, s24
	s_cselect_b32 s25, s19, s25
	s_cselect_b32 s38, s20, s59
	s_cselect_b32 s39, s21, s60
	s_add_u32 s26, s24, 0x80
	s_addc_u32 s27, s25, 0
	ds_read_b128 v[164:167], v177
	ds_read_b128 v[180:183], v177 offset:1024
	ds_read_b128 v[184:187], v177 offset:2048
	ds_read_b128 v[188:191], v177 offset:3072
	ds_read_b128 v[192:195], v177 offset:4096
	ds_read_b128 v[196:199], v177 offset:5120
	ds_read_b128 v[200:203], v177 offset:6144
	ds_read_b128 v[204:207], v177 offset:7168
	s_mov_b32 m0, s54
	s_nop 0
	global_load_lds_dwordx4 v170, s[22:23]
	s_add_u32 s62, s22, 0x20000
	s_mov_b32 m0, s55
	s_addc_u32 s63, s23, 0
	global_load_lds_dwordx4 v170, s[62:63]
	s_waitcnt vmcnt(8) lgkmcnt(0)
	s_barrier
	s_setprio 1
	v_mfma_f32_16x16x32_bf16 v[84:87], v[128:131], v[164:167], v[84:87]
	v_mfma_f32_16x16x32_bf16 v[76:79], v[136:139], v[164:167], v[76:79]
	v_mfma_f32_16x16x32_bf16 v[124:127], v[128:131], v[184:187], v[124:127]
	v_mfma_f32_16x16x32_bf16 v[120:123], v[136:139], v[184:187], v[120:123]
	v_mfma_f32_16x16x32_bf16 v[116:119], v[128:131], v[192:195], v[116:119]
	v_mfma_f32_16x16x32_bf16 v[112:115], v[136:139], v[192:195], v[112:115]
	v_mfma_f32_16x16x32_bf16 v[108:111], v[128:131], v[200:203], v[108:111]
	v_mfma_f32_16x16x32_bf16 v[104:107], v[136:139], v[200:203], v[104:107]
	v_mfma_f32_16x16x32_bf16 v[84:87], v[132:135], v[180:183], v[84:87]
	v_mfma_f32_16x16x32_bf16 v[76:79], v[144:147], v[180:183], v[76:79]
	v_mfma_f32_16x16x32_bf16 v[124:127], v[132:135], v[188:191], v[124:127]
	v_mfma_f32_16x16x32_bf16 v[120:123], v[144:147], v[188:191], v[120:123]
	v_mfma_f32_16x16x32_bf16 v[116:119], v[132:135], v[196:199], v[116:119]
	v_mfma_f32_16x16x32_bf16 v[112:115], v[144:147], v[196:199], v[112:115]
	v_mfma_f32_16x16x32_bf16 v[108:111], v[132:135], v[204:207], v[108:111]
	v_mfma_f32_16x16x32_bf16 v[104:107], v[144:147], v[204:207], v[104:107]
	s_add_i32 s61, s61, 2
	s_add_u32 s22, s22, 0x100
	s_addc_u32 s23, s23, 0
	s_add_u32 s59, s59, 0x100
	s_addc_u32 s60, s60, 0
	v_mfma_f32_16x16x32_bf16 v[60:63], v[148:151], v[164:167], v[60:63]
	v_mfma_f32_16x16x32_bf16 v[56:59], v[156:159], v[164:167], v[56:59]
	v_mfma_f32_16x16x32_bf16 v[52:55], v[148:151], v[184:187], v[52:55]
	v_mfma_f32_16x16x32_bf16 v[48:51], v[156:159], v[184:187], v[48:51]
	v_mfma_f32_16x16x32_bf16 v[44:47], v[148:151], v[192:195], v[44:47]
	v_mfma_f32_16x16x32_bf16 v[40:43], v[156:159], v[192:195], v[40:43]
	v_mfma_f32_16x16x32_bf16 v[36:39], v[148:151], v[200:203], v[36:39]
	v_mfma_f32_16x16x32_bf16 v[32:35], v[156:159], v[200:203], v[32:35]
	v_mfma_f32_16x16x32_bf16 v[60:63], v[152:155], v[180:183], v[60:63]
	v_mfma_f32_16x16x32_bf16 v[56:59], v[160:163], v[180:183], v[56:59]
	v_mfma_f32_16x16x32_bf16 v[52:55], v[152:155], v[188:191], v[52:55]
	v_mfma_f32_16x16x32_bf16 v[48:51], v[160:163], v[188:191], v[48:51]
	v_mfma_f32_16x16x32_bf16 v[44:47], v[152:155], v[196:199], v[44:47]
	v_mfma_f32_16x16x32_bf16 v[40:43], v[160:163], v[196:199], v[40:43]
	v_mfma_f32_16x16x32_bf16 v[36:39], v[152:155], v[204:207], v[36:39]
	v_mfma_f32_16x16x32_bf16 v[32:35], v[160:163], v[204:207], v[32:35]
	s_setprio 0
	s_barrier
	s_add_u32 s62, s38, 0x20000
	ds_read_b128 v[164:167], v177 offset:16384
	ds_read_b128 v[180:183], v177 offset:17408
	ds_read_b128 v[184:187], v177 offset:18432
	ds_read_b128 v[188:191], v177 offset:19456
	ds_read_b128 v[192:195], v177 offset:20480
	ds_read_b128 v[196:199], v177 offset:21504
	ds_read_b128 v[200:203], v177 offset:22528
	ds_read_b128 v[204:207], v177 offset:23552
	s_mov_b32 m0, s35
	s_nop 0
	global_load_lds_dwordx4 v171, s[38:39]
	s_mov_b32 m0, s36
	s_addc_u32 s63, s39, 0
	global_load_lds_dwordx4 v171, s[62:63]
	s_add_u32 s62, s38, 0x40000
	s_mov_b32 m0, s37
	s_addc_u32 s63, s39, 0
	global_load_lds_dwordx4 v171, s[62:63]
	s_add_u32 s62, s38, 0x60000
	s_mov_b32 m0, s40
	s_addc_u32 s63, s39, 0
	global_load_lds_dwordx4 v171, s[62:63]
	s_mov_b32 m0, s34
	s_nop 0
	global_load_lds_dwordx4 v170, s[24:25]
	s_add_u32 s62, s24, 0x20000
	s_mov_b32 m0, s41
	s_addc_u32 s63, s25, 0
	global_load_lds_dwordx4 v170, s[62:63]
	s_waitcnt vmcnt(8) lgkmcnt(0)
	s_barrier
; #define PG8_STAGE(bufoff, gbase, voff, p64) do { _Pragma("unroll") for (int _i = 0; _i < 2; ++_i) { \
;         const char* _gb = (const char*)(gbase) + (size_t)_i * (p64); const unsigned _la = ldsbase + (unsigned)(bufoff) + (unsigned)_i * 8192u; \
;         asm volatile("s_mov_b32 m0, %0\n\ts_nop 0\n\tglobal_load_lds_dwordx4 %1, %2" :: "s"(_la), "v"(voff), "s"(_gb) : "memory"); } } while (0)
; #define PG8_LDA(dst, b, h) do { _Pragma("unroll") for (int m = 0; m < 4; ++m) _Pragma("unroll") for (int k = 0; k < 2; ++k) dst[m][k] = *(const LAS bf16x8*)(lds + PG8_SA(b, h) + aoff + m * 2048 + k * 1024); } while (0)
; #define PG8_LDB(dst, b, h) do { _Pragma("unroll") for (int n = 0; n < 2; ++n) _Pragma("unroll") for (int k = 0; k < 2; ++k) dst[n][k] = *(const LAS bf16x8*)(lds + PG8_SB(b, h) + boff + n * 2048 + k * 1024); } while (0)
; #define PG8_MMA(ai, bj, At, Bt) do { __builtin_amdgcn_s_setprio(1); _Pragma("unroll") for (int m = 0; m < 4; ++m) _Pragma("unroll") for (int n = 0; n < 2; ++n) _Pragma("unroll") for (int k = 0; k < 2; ++k) \
;         acc[ai][bj][m][n] = __builtin_amdgcn_mfma_f32_16x16x32_bf16(Bt[n][k], At[m][k], acc[ai][bj][m][n], 0, 0, 0); __builtin_amdgcn_s_setprio(0); } while (0)
; #define PG8_WAIT_V(n) asm volatile("s_waitcnt vmcnt(" #n ")" ::: "memory")
; #define PG8_WAIT_L(n) asm volatile("s_waitcnt lgkmcnt(" #n ")" ::: "memory")
; #define PG8_BAR __builtin_amdgcn_s_barrier()
; #define PG8_SCHED __builtin_amdgcn_sched_barrier(0)
; template <class Epi, class Sched>
; __device__ __forceinline__ void gemm_phase(LAS unsigned char* lds, const Sched& S, const Epi& E) {
;     ...
;             PG8_WAIT_V(8); PG8_WAIT_L(0); PG8_BAR; PG8_MMA(1, 0, At, B0); PG8_MMA(1, 1, At, B1); PG8_BAR; PG8_SCHED;
;             PG8_LDB(B0, 1, 0); PG8_LDB(B1, 1, 1); PG8_SCHED; PG8_LDA(At, 1, 0); PG8_STAGE(PG8_SA(0, 1), a2 + hA2, vA2, hA2 / 2);
;             PG8_WAIT_V(8); PG8_WAIT_L(0); PG8_BAR; PG8_MMA(0, 0, At, B0); PG8_MMA(0, 1, At, B1); PG8_BAR; PG8_SCHED;
	s_setprio 1
	v_mfma_f32_16x16x32_bf16 v[100:103], v[128:131], v[164:167], v[100:103]
	v_mfma_f32_16x16x32_bf16 v[96:99], v[136:139], v[164:167], v[96:99]
	v_mfma_f32_16x16x32_bf16 v[92:95], v[128:131], v[184:187], v[92:95]
	v_mfma_f32_16x16x32_bf16 v[88:91], v[136:139], v[184:187], v[88:91]
	v_mfma_f32_16x16x32_bf16 v[80:83], v[128:131], v[192:195], v[80:83]
	v_mfma_f32_16x16x32_bf16 v[72:75], v[136:139], v[192:195], v[72:75]
	v_mfma_f32_16x16x32_bf16 v[68:71], v[128:131], v[200:203], v[68:71]
	v_mfma_f32_16x16x32_bf16 v[64:67], v[136:139], v[200:203], v[64:67]
	v_mfma_f32_16x16x32_bf16 v[100:103], v[132:135], v[180:183], v[100:103]
	v_mfma_f32_16x16x32_bf16 v[96:99], v[144:147], v[180:183], v[96:99]
	v_mfma_f32_16x16x32_bf16 v[92:95], v[132:135], v[188:191], v[92:95]
	v_mfma_f32_16x16x32_bf16 v[88:91], v[144:147], v[188:191], v[88:91]
	v_mfma_f32_16x16x32_bf16 v[80:83], v[132:135], v[196:199], v[80:83]
	v_mfma_f32_16x16x32_bf16 v[72:75], v[144:147], v[196:199], v[72:75]
	v_mfma_f32_16x16x32_bf16 v[68:71], v[132:135], v[204:207], v[68:71]
	v_mfma_f32_16x16x32_bf16 v[64:67], v[144:147], v[204:207], v[64:67]
	v_mfma_f32_16x16x32_bf16 v[28:31], v[148:151], v[164:167], v[28:31]
	v_mfma_f32_16x16x32_bf16 v[24:27], v[156:159], v[164:167], v[24:27]
	v_mfma_f32_16x16x32_bf16 v[20:23], v[148:151], v[184:187], v[20:23]
	v_mfma_f32_16x16x32_bf16 v[16:19], v[156:159], v[184:187], v[16:19]
	v_mfma_f32_16x16x32_bf16 v[12:15], v[148:151], v[192:195], v[12:15]
	v_mfma_f32_16x16x32_bf16 v[8:11], v[156:159], v[192:195], v[8:11]
	v_mfma_f32_16x16x32_bf16 v[4:7], v[148:151], v[200:203], v[4:7]
	v_mfma_f32_16x16x32_bf16 v[0:3], v[156:159], v[200:203], v[0:3]
	v_mfma_f32_16x16x32_bf16 v[28:31], v[152:155], v[180:183], v[28:31]
	v_mfma_f32_16x16x32_bf16 v[24:27], v[160:163], v[180:183], v[24:27]
	v_mfma_f32_16x16x32_bf16 v[20:23], v[152:155], v[188:191], v[20:23]
	v_mfma_f32_16x16x32_bf16 v[16:19], v[160:163], v[188:191], v[16:19]
	v_mfma_f32_16x16x32_bf16 v[12:15], v[152:155], v[196:199], v[12:15]
	v_mfma_f32_16x16x32_bf16 v[8:11], v[160:163], v[196:199], v[8:11]
	v_mfma_f32_16x16x32_bf16 v[4:7], v[152:155], v[204:207], v[4:7]
	v_mfma_f32_16x16x32_bf16 v[0:3], v[160:163], v[204:207], v[0:3]
	s_setprio 0
	s_barrier
	ds_read_b128 v[128:131], v178
	ds_read_b128 v[132:135], v178 offset:1024
	ds_read_b128 v[136:139], v178 offset:2048
	ds_read_b128 v[144:147], v178 offset:3072
	ds_read_b128 v[148:151], v179
	ds_read_b128 v[152:155], v179 offset:1024
	ds_read_b128 v[156:159], v179 offset:2048
	ds_read_b128 v[160:163], v179 offset:3072
	ds_read_b128 v[164:167], v177 offset:32768
	ds_read_b128 v[180:183], v177 offset:33792
	ds_read_b128 v[184:187], v177 offset:34816
	ds_read_b128 v[188:191], v177 offset:35840
	ds_read_b128 v[192:195], v177 offset:36864
	ds_read_b128 v[196:199], v177 offset:37888
	ds_read_b128 v[200:203], v177 offset:38912
	ds_read_b128 v[204:207], v177 offset:39936
	s_add_u32 s62, s24, 0x40000
	s_mov_b32 m0, s42
	s_addc_u32 s63, s25, 0
	global_load_lds_dwordx4 v170, s[62:63]
	s_add_u32 s62, s24, 0x60000
	s_mov_b32 m0, s43
	s_addc_u32 s63, s25, 0
	global_load_lds_dwordx4 v170, s[62:63]
	s_waitcnt vmcnt(8) lgkmcnt(0)
	s_barrier
	s_setprio 1
	v_mfma_f32_16x16x32_bf16 v[84:87], v[128:131], v[164:167], v[84:87]
	v_mfma_f32_16x16x32_bf16 v[76:79], v[136:139], v[164:167], v[76:79]
	v_mfma_f32_16x16x32_bf16 v[124:127], v[128:131], v[184:187], v[124:127]
	v_mfma_f32_16x16x32_bf16 v[120:123], v[136:139], v[184:187], v[120:123]
	v_mfma_f32_16x16x32_bf16 v[116:119], v[128:131], v[192:195], v[116:119]
	v_mfma_f32_16x16x32_bf16 v[112:115], v[136:139], v[192:195], v[112:115]
	v_mfma_f32_16x16x32_bf16 v[108:111], v[128:131], v[200:203], v[108:111]
	v_mfma_f32_16x16x32_bf16 v[104:107], v[136:139], v[200:203], v[104:107]
	v_mfma_f32_16x16x32_bf16 v[84:87], v[132:135], v[180:183], v[84:87]
	v_mfma_f32_16x16x32_bf16 v[76:79], v[144:147], v[180:183], v[76:79]
	v_mfma_f32_16x16x32_bf16 v[124:127], v[132:135], v[188:191], v[124:127]
	v_mfma_f32_16x16x32_bf16 v[120:123], v[144:147], v[188:191], v[120:123]
	v_mfma_f32_16x16x32_bf16 v[116:119], v[132:135], v[196:199], v[116:119]
	v_mfma_f32_16x16x32_bf16 v[112:115], v[144:147], v[196:199], v[112:115]
	v_mfma_f32_16x16x32_bf16 v[108:111], v[132:135], v[204:207], v[108:111]
	v_mfma_f32_16x16x32_bf16 v[104:107], v[144:147], v[204:207], v[104:107]
	v_mfma_f32_16x16x32_bf16 v[60:63], v[148:151], v[164:167], v[60:63]
	v_mfma_f32_16x16x32_bf16 v[56:59], v[156:159], v[164:167], v[56:59]
	v_mfma_f32_16x16x32_bf16 v[52:55], v[148:151], v[184:187], v[52:55]
	v_mfma_f32_16x16x32_bf16 v[48:51], v[156:159], v[184:187], v[48:51]
	v_mfma_f32_16x16x32_bf16 v[44:47], v[148:151], v[192:195], v[44:47]
	v_mfma_f32_16x16x32_bf16 v[40:43], v[156:159], v[192:195], v[40:43]
	v_mfma_f32_16x16x32_bf16 v[36:39], v[148:151], v[200:203], v[36:39]
	v_mfma_f32_16x16x32_bf16 v[32:35], v[156:159], v[200:203], v[32:35]
	v_mfma_f32_16x16x32_bf16 v[60:63], v[152:155], v[180:183], v[60:63]
	v_mfma_f32_16x16x32_bf16 v[56:59], v[160:163], v[180:183], v[56:59]
	v_mfma_f32_16x16x32_bf16 v[52:55], v[152:155], v[188:191], v[52:55]
	v_mfma_f32_16x16x32_bf16 v[48:51], v[160:163], v[188:191], v[48:51]
	v_mfma_f32_16x16x32_bf16 v[44:47], v[152:155], v[196:199], v[44:47]
	v_mfma_f32_16x16x32_bf16 v[40:43], v[160:163], v[196:199], v[40:43]
	v_mfma_f32_16x16x32_bf16 v[36:39], v[152:155], v[204:207], v[36:39]
	v_mfma_f32_16x16x32_bf16 v[32:35], v[160:163], v[204:207], v[32:35]
	s_setprio 0
	s_barrier
; #define PG8_STAGE(bufoff, gbase, voff, p64) do { _Pragma("unroll") for (int _i = 0; _i < 2; ++_i) { \
;         const char* _gb = (const char*)(gbase) + (size_t)_i * (p64); const unsigned _la = ldsbase + (unsigned)(bufoff) + (unsigned)_i * 8192u; \
;         asm volatile("s_mov_b32 m0, %0\n\ts_nop 0\n\tglobal_load_lds_dwordx4 %1, %2" :: "s"(_la), "v"(voff), "s"(_gb) : "memory"); } } while (0)
; #define PG8_LDA(dst, b, h) do { _Pragma("unroll") for (int m = 0; m < 4; ++m) _Pragma("unroll") for (int k = 0; k < 2; ++k) dst[m][k] = *(const LAS bf16x8*)(lds + PG8_SA(b, h) + aoff + m * 2048 + k * 1024); } while (0)
; #define PG8_MMA(ai, bj, At, Bt) do { __builtin_amdgcn_s_setprio(1); _Pragma("unroll") for (int m = 0; m < 4; ++m) _Pragma("unroll") for (int n = 0; n < 2; ++n) _Pragma("unroll") for (int k = 0; k < 2; ++k) \
;         acc[ai][bj][m][n] = __builtin_amdgcn_mfma_f32_16x16x32_bf16(Bt[n][k], At[m][k], acc[ai][bj][m][n], 0, 0, 0); __builtin_amdgcn_s_setprio(0); } while (0)
; #define PG8_WAIT_V(n) asm volatile("s_waitcnt vmcnt(" #n ")" ::: "memory")
; #define PG8_WAIT_L(n) asm volatile("s_waitcnt lgkmcnt(" #n ")" ::: "memory")
; #define PG8_BAR __builtin_amdgcn_s_barrier()
; #define PG8_SCHED __builtin_amdgcn_sched_barrier(0)
; template <class Epi, class Sched>
; __device__ __forceinline__ void gemm_phase(LAS unsigned char* lds, const Sched& S, const Epi& E) {
;     ...
;             PG8_LDA(At, 1, 1); PG8_STAGE(PG8_SB(1, 0), b3, vB2, hB2 / 2); PG8_STAGE(PG8_SB(1, 1), b3 + hB2, vB2, hB2 / 2); PG8_STAGE(PG8_SA(1, 0), a3, vA2, hA2 / 2);
;             PG8_WAIT_V(8); PG8_WAIT_L(0); PG8_BAR; PG8_MMA(1, 0, At, B0); PG8_MMA(1, 1, At, B1); PG8_BAR; PG8_SCHED;
;         }
;         if (wr == 0) PG8_BAR;
	s_add_u32 s62, s38, 0x80
	s_addc_u32 s63, s39, 0
	ds_read_b128 v[164:167], v177 offset:49152
	ds_read_b128 v[180:183], v177 offset:50176
	ds_read_b128 v[184:187], v177 offset:51200
	ds_read_b128 v[188:191], v177 offset:52224
	ds_read_b128 v[192:195], v177 offset:53248
	ds_read_b128 v[196:199], v177 offset:54272
	ds_read_b128 v[200:203], v177 offset:55296
	ds_read_b128 v[204:207], v177 offset:56320
	s_mov_b32 m0, s48
	s_nop 0
	global_load_lds_dwordx4 v171, s[62:63]
	s_add_u32 s62, s38, 0x20080
	s_mov_b32 m0, s49
	s_addc_u32 s63, s39, 0
	global_load_lds_dwordx4 v171, s[62:63]
	s_add_u32 s62, s38, 0x40080
	s_mov_b32 m0, s52
	s_addc_u32 s63, s39, 0
	global_load_lds_dwordx4 v171, s[62:63]
	s_add_u32 s38, s38, 0x60080
	s_mov_b32 m0, s53
	s_addc_u32 s39, s39, 0
	global_load_lds_dwordx4 v171, s[38:39]
	s_mov_b32 m0, s50
	s_nop 0
	global_load_lds_dwordx4 v170, s[26:27]
	s_add_u32 s24, s24, 0x20080
	s_mov_b32 m0, s51
	s_addc_u32 s25, s25, 0
	global_load_lds_dwordx4 v170, s[24:25]
	s_waitcnt vmcnt(8) lgkmcnt(0)
	s_barrier
	s_setprio 1
	v_mfma_f32_16x16x32_bf16 v[100:103], v[128:131], v[164:167], v[100:103]
	v_mfma_f32_16x16x32_bf16 v[96:99], v[136:139], v[164:167], v[96:99]
	v_mfma_f32_16x16x32_bf16 v[92:95], v[128:131], v[184:187], v[92:95]
	v_mfma_f32_16x16x32_bf16 v[88:91], v[136:139], v[184:187], v[88:91]
	v_mfma_f32_16x16x32_bf16 v[80:83], v[128:131], v[192:195], v[80:83]
	v_mfma_f32_16x16x32_bf16 v[72:75], v[136:139], v[192:195], v[72:75]
	v_mfma_f32_16x16x32_bf16 v[68:71], v[128:131], v[200:203], v[68:71]
	v_mfma_f32_16x16x32_bf16 v[64:67], v[136:139], v[200:203], v[64:67]
	v_mfma_f32_16x16x32_bf16 v[100:103], v[132:135], v[180:183], v[100:103]
	v_mfma_f32_16x16x32_bf16 v[96:99], v[144:147], v[180:183], v[96:99]
	v_mfma_f32_16x16x32_bf16 v[92:95], v[132:135], v[188:191], v[92:95]
	v_mfma_f32_16x16x32_bf16 v[88:91], v[144:147], v[188:191], v[88:91]
	v_mfma_f32_16x16x32_bf16 v[80:83], v[132:135], v[196:199], v[80:83]
	v_mfma_f32_16x16x32_bf16 v[72:75], v[144:147], v[196:199], v[72:75]
	v_mfma_f32_16x16x32_bf16 v[68:71], v[132:135], v[204:207], v[68:71]
	v_mfma_f32_16x16x32_bf16 v[64:67], v[144:147], v[204:207], v[64:67]
	v_mfma_f32_16x16x32_bf16 v[28:31], v[148:151], v[164:167], v[28:31]
	v_mfma_f32_16x16x32_bf16 v[24:27], v[156:159], v[164:167], v[24:27]
	v_mfma_f32_16x16x32_bf16 v[20:23], v[148:151], v[184:187], v[20:23]
	v_mfma_f32_16x16x32_bf16 v[16:19], v[156:159], v[184:187], v[16:19]
	v_mfma_f32_16x16x32_bf16 v[12:15], v[148:151], v[192:195], v[12:15]
	v_mfma_f32_16x16x32_bf16 v[8:11], v[156:159], v[192:195], v[8:11]
	v_mfma_f32_16x16x32_bf16 v[4:7], v[148:151], v[200:203], v[4:7]
	v_mfma_f32_16x16x32_bf16 v[0:3], v[156:159], v[200:203], v[0:3]
	v_mfma_f32_16x16x32_bf16 v[28:31], v[152:155], v[180:183], v[28:31]
	v_mfma_f32_16x16x32_bf16 v[24:27], v[160:163], v[180:183], v[24:27]
	v_mfma_f32_16x16x32_bf16 v[20:23], v[152:155], v[188:191], v[20:23]
	v_mfma_f32_16x16x32_bf16 v[16:19], v[160:163], v[188:191], v[16:19]
	v_mfma_f32_16x16x32_bf16 v[12:15], v[152:155], v[196:199], v[12:15]
	v_mfma_f32_16x16x32_bf16 v[8:11], v[160:163], v[196:199], v[8:11]
	v_mfma_f32_16x16x32_bf16 v[4:7], v[152:155], v[204:207], v[4:7]
	v_mfma_f32_16x16x32_bf16 v[0:3], v[160:163], v[204:207], v[0:3]
	s_setprio 0
	s_barrier
	s_cmp_gt_u32 s61, 13
	s_cbranch_scc0 .LBB0_1352
	s_and_b64 vcc, exec, s[12:13]
	s_cbranch_vccz .LBB0_1355
	s_barrier

; #define PG8_STAGE(bufoff, gbase, voff, p64) do { _Pragma("unroll") for (int _i = 0; _i < 2; ++_i) { \
;         const char* _gb = (const char*)(gbase) + (size_t)_i * (p64); const unsigned _la = ldsbase + (unsigned)(bufoff) + (unsigned)_i * 8192u; \
;         asm volatile("s_mov_b32 m0, %0\n\ts_nop 0\n\tglobal_load_lds_dwordx4 %1, %2" :: "s"(_la), "v"(voff), "s"(_gb) : "memory"); } } while (0)
; #define PG8_LDA(dst, b, h) do { _Pragma("unroll") for (int m = 0; m < 4; ++m) _Pragma("unroll") for (int k = 0; k < 2; ++k) dst[m][k] = *(const LAS bf16x8*)(lds + PG8_SA(b, h) + aoff + m * 2048 + k * 1024); } while (0)
; #define PG8_LDB(dst, b, h) do { _Pragma("unroll") for (int n = 0; n < 2; ++n) _Pragma("unroll") for (int k = 0; k < 2; ++k) dst[n][k] = *(const LAS bf16x8*)(lds + PG8_SB(b, h) + boff + n * 2048 + k * 1024); } while (0)
; #define PG8_MMA(ai, bj, At, Bt) do { __builtin_amdgcn_s_setprio(1); _Pragma("unroll") for (int m = 0; m < 4; ++m) _Pragma("unroll") for (int n = 0; n < 2; ++n) _Pragma("unroll") for (int k = 0; k < 2; ++k) \
;         acc[ai][bj][m][n] = __builtin_amdgcn_mfma_f32_16x16x32_bf16(Bt[n][k], At[m][k], acc[ai][bj][m][n], 0, 0, 0); __builtin_amdgcn_s_setprio(0); } while (0)
; #define PG8_WAIT_V(n) asm volatile("s_waitcnt vmcnt(" #n ")" ::: "memory")
; #define PG8_BAR __builtin_amdgcn_s_barrier()
; template <class Epi, class Sched>
; __device__ __forceinline__ void gemm_phase(LAS unsigned char* lds, const Sched& S, const Epi& E) {
;     ...
;             const bool last = (t == nt - 2);
;             const char* a1 = cA + (size_t)(t + 1) * kstep;
;             const char* a2 = last ? nA : cA + (size_t)(t + 2) * kstep; const char* b2 = last ? nB : cB + (size_t)(t + 2) * kstep;
;             const char* a3 = a2 + kstep; const char* b3 = b2 + kstep;
;             const unsigned vA2 = voffA, vB2 = voffB, hA2 = hA, hB2 = hB;
;             PG8_LDB(B0, 0, 0); PG8_LDB(B1, 0, 1); PG8_SCHED; PG8_LDA(At, 0, 0); PG8_STAGE(PG8_SA(1, 1), a1 + hA, voffA, hA / 2);
;             PG8_WAIT_V(8); PG8_WAIT_L(0); PG8_BAR; PG8_MMA(0, 0, At, B0); PG8_MMA(0, 1, At, B1); PG8_BAR; PG8_SCHED;
;             PG8_LDA(At, 0, 1); PG8_STAGE(PG8_SB(0, 0), b2, vB2, hB2 / 2); PG8_STAGE(PG8_SB(0, 1), b2 + hB2, vB2, hB2 / 2); PG8_STAGE(PG8_SA(0, 0), a2, vA2, hA2 / 2);
;             PG8_WAIT_V(8); PG8_WAIT_L(0); PG8_BAR; PG8_MMA(1, 0, At, B0); PG8_MMA(1, 1, At, B1); PG8_BAR; PG8_SCHED;
.LBB0_1485:
	ds_read_b128 v[144:147], v138
	ds_read_b128 v[148:151], v138 offset:1024
	ds_read_b128 v[152:155], v138 offset:2048
	ds_read_b128 v[156:159], v138 offset:3072
	ds_read_b128 v[160:163], v139
	ds_read_b128 v[164:167], v139 offset:1024
	ds_read_b128 v[168:171], v139 offset:2048
	ds_read_b128 v[172:175], v139 offset:3072
	s_add_u32 s26, s24, 0xfffc0080
	s_addc_u32 s27, s25, -1
	s_cmp_eq_u32 s61, 12
	s_cselect_b32 s26, s20, s26
	s_cselect_b32 s27, s21, s27
	s_cselect_b32 s40, s22, s59
	s_cselect_b32 s41, s23, s60
	s_add_u32 s38, s26, 0x80
	s_addc_u32 s39, s27, 0
	ds_read_b128 v[178:181], v140
	ds_read_b128 v[182:185], v140 offset:1024
	ds_read_b128 v[186:189], v140 offset:2048
	ds_read_b128 v[190:193], v140 offset:3072
	ds_read_b128 v[194:197], v140 offset:4096
	ds_read_b128 v[198:201], v140 offset:5120
	ds_read_b128 v[202:205], v140 offset:6144
	ds_read_b128 v[206:209], v140 offset:7168
	s_mov_b32 m0, s54
	s_nop 0
	global_load_lds_dwordx4 v134, s[24:25]
	s_add_u32 s62, s24, 0x20000
	s_mov_b32 m0, s55
	s_addc_u32 s63, s25, 0
	global_load_lds_dwordx4 v134, s[62:63]
	s_waitcnt vmcnt(8) lgkmcnt(0)
	s_barrier
	s_setprio 1
	v_mfma_f32_16x16x32_bf16 v[124:127], v[144:147], v[178:181], v[124:127]
	v_mfma_f32_16x16x32_bf16 v[120:123], v[152:155], v[178:181], v[120:123]
	v_mfma_f32_16x16x32_bf16 v[108:111], v[144:147], v[186:189], v[108:111]
	v_mfma_f32_16x16x32_bf16 v[104:107], v[152:155], v[186:189], v[104:107]
	v_mfma_f32_16x16x32_bf16 v[92:95], v[144:147], v[194:197], v[92:95]
	v_mfma_f32_16x16x32_bf16 v[88:91], v[152:155], v[194:197], v[88:91]
	v_mfma_f32_16x16x32_bf16 v[76:79], v[144:147], v[202:205], v[76:79]
	v_mfma_f32_16x16x32_bf16 v[72:75], v[152:155], v[202:205], v[72:75]
	v_mfma_f32_16x16x32_bf16 v[124:127], v[148:151], v[182:185], v[124:127]
	v_mfma_f32_16x16x32_bf16 v[120:123], v[156:159], v[182:185], v[120:123]
	v_mfma_f32_16x16x32_bf16 v[108:111], v[148:151], v[190:193], v[108:111]
	v_mfma_f32_16x16x32_bf16 v[104:107], v[156:159], v[190:193], v[104:107]
	v_mfma_f32_16x16x32_bf16 v[92:95], v[148:151], v[198:201], v[92:95]
	v_mfma_f32_16x16x32_bf16 v[88:91], v[156:159], v[198:201], v[88:91]
	v_mfma_f32_16x16x32_bf16 v[76:79], v[148:151], v[206:209], v[76:79]
	v_mfma_f32_16x16x32_bf16 v[72:75], v[156:159], v[206:209], v[72:75]
	s_add_i32 s61, s61, 2
	s_add_u32 s24, s24, 0x100
	s_addc_u32 s25, s25, 0
	s_add_u32 s59, s59, 0x100
	s_addc_u32 s60, s60, 0
	v_mfma_f32_16x16x32_bf16 v[116:119], v[160:163], v[178:181], v[116:119]
	v_mfma_f32_16x16x32_bf16 v[112:115], v[168:171], v[178:181], v[112:115]
	v_mfma_f32_16x16x32_bf16 v[100:103], v[160:163], v[186:189], v[100:103]
	v_mfma_f32_16x16x32_bf16 v[96:99], v[168:171], v[186:189], v[96:99]
	v_mfma_f32_16x16x32_bf16 v[84:87], v[160:163], v[194:197], v[84:87]
	v_mfma_f32_16x16x32_bf16 v[80:83], v[168:171], v[194:197], v[80:83]
	v_mfma_f32_16x16x32_bf16 v[68:71], v[160:163], v[202:205], v[68:71]
	v_mfma_f32_16x16x32_bf16 v[64:67], v[168:171], v[202:205], v[64:67]
	v_mfma_f32_16x16x32_bf16 v[116:119], v[164:167], v[182:185], v[116:119]
	v_mfma_f32_16x16x32_bf16 v[112:115], v[172:175], v[182:185], v[112:115]
	v_mfma_f32_16x16x32_bf16 v[100:103], v[164:167], v[190:193], v[100:103]
	v_mfma_f32_16x16x32_bf16 v[96:99], v[172:175], v[190:193], v[96:99]
	v_mfma_f32_16x16x32_bf16 v[84:87], v[164:167], v[198:201], v[84:87]
	v_mfma_f32_16x16x32_bf16 v[80:83], v[172:175], v[198:201], v[80:83]
	v_mfma_f32_16x16x32_bf16 v[68:71], v[164:167], v[206:209], v[68:71]
	v_mfma_f32_16x16x32_bf16 v[64:67], v[172:175], v[206:209], v[64:67]
	s_setprio 0
	s_barrier
	s_add_u32 s62, s40, 0x20000
	ds_read_b128 v[178:181], v140 offset:16384
	ds_read_b128 v[182:185], v140 offset:17408
	ds_read_b128 v[186:189], v140 offset:18432
	ds_read_b128 v[190:193], v140 offset:19456
	ds_read_b128 v[194:197], v140 offset:20480
	ds_read_b128 v[198:201], v140 offset:21504
	ds_read_b128 v[202:205], v140 offset:22528
	ds_read_b128 v[206:209], v140 offset:23552
	s_mov_b32 m0, s36
	s_nop 0
	global_load_lds_dwordx4 v135, s[40:41]
	s_mov_b32 m0, s37
	s_addc_u32 s63, s41, 0
	global_load_lds_dwordx4 v135, s[62:63]
	s_add_u32 s62, s40, 0x40000
	s_mov_b32 m0, s42
	s_addc_u32 s63, s41, 0
	global_load_lds_dwordx4 v135, s[62:63]
	s_add_u32 s62, s40, 0x60000
	s_mov_b32 m0, s43
	s_addc_u32 s63, s41, 0
	global_load_lds_dwordx4 v135, s[62:63]
	s_mov_b32 m0, s34
	s_nop 0
	global_load_lds_dwordx4 v134, s[26:27]
	s_add_u32 s62, s26, 0x20000
	s_mov_b32 m0, s44
	s_addc_u32 s63, s27, 0
	global_load_lds_dwordx4 v134, s[62:63]
	s_waitcnt vmcnt(8) lgkmcnt(0)
	s_barrier
; #define PG8_STAGE(bufoff, gbase, voff, p64) do { _Pragma("unroll") for (int _i = 0; _i < 2; ++_i) { \
;         const char* _gb = (const char*)(gbase) + (size_t)_i * (p64); const unsigned _la = ldsbase + (unsigned)(bufoff) + (unsigned)_i * 8192u; \
;         asm volatile("s_mov_b32 m0, %0\n\ts_nop 0\n\tglobal_load_lds_dwordx4 %1, %2" :: "s"(_la), "v"(voff), "s"(_gb) : "memory"); } } while (0)
; #define PG8_LDA(dst, b, h) do { _Pragma("unroll") for (int m = 0; m < 4; ++m) _Pragma("unroll") for (int k = 0; k < 2; ++k) dst[m][k] = *(const LAS bf16x8*)(lds + PG8_SA(b, h) + aoff + m * 2048 + k * 1024); } while (0)
; #define PG8_LDB(dst, b, h) do { _Pragma("unroll") for (int n = 0; n < 2; ++n) _Pragma("unroll") for (int k = 0; k < 2; ++k) dst[n][k] = *(const LAS bf16x8*)(lds + PG8_SB(b, h) + boff + n * 2048 + k * 1024); } while (0)
; #define PG8_MMA(ai, bj, At, Bt) do { __builtin_amdgcn_s_setprio(1); _Pragma("unroll") for (int m = 0; m < 4; ++m) _Pragma("unroll") for (int n = 0; n < 2; ++n) _Pragma("unroll") for (int k = 0; k < 2; ++k) \
;         acc[ai][bj][m][n] = __builtin_amdgcn_mfma_f32_16x16x32_bf16(Bt[n][k], At[m][k], acc[ai][bj][m][n], 0, 0, 0); __builtin_amdgcn_s_setprio(0); } while (0)
; #define PG8_WAIT_V(n) asm volatile("s_waitcnt vmcnt(" #n ")" ::: "memory")
; #define PG8_WAIT_L(n) asm volatile("s_waitcnt lgkmcnt(" #n ")" ::: "memory")
; #define PG8_BAR __builtin_amdgcn_s_barrier()
; #define PG8_SCHED __builtin_amdgcn_sched_barrier(0)
; template <class Epi, class Sched>
; __device__ __forceinline__ void gemm_phase(LAS unsigned char* lds, const Sched& S, const Epi& E) {
;     ...
;             PG8_WAIT_V(8); PG8_WAIT_L(0); PG8_BAR; PG8_MMA(1, 0, At, B0); PG8_MMA(1, 1, At, B1); PG8_BAR; PG8_SCHED;
;             PG8_LDB(B0, 1, 0); PG8_LDB(B1, 1, 1); PG8_SCHED; PG8_LDA(At, 1, 0); PG8_STAGE(PG8_SA(0, 1), a2 + hA2, vA2, hA2 / 2);
;             PG8_WAIT_V(8); PG8_WAIT_L(0); PG8_BAR; PG8_MMA(0, 0, At, B0); PG8_MMA(0, 1, At, B1); PG8_BAR; PG8_SCHED;
	s_setprio 1
	v_mfma_f32_16x16x32_bf16 v[60:63], v[144:147], v[178:181], v[60:63]
	v_mfma_f32_16x16x32_bf16 v[56:59], v[152:155], v[178:181], v[56:59]
	v_mfma_f32_16x16x32_bf16 v[44:47], v[144:147], v[186:189], v[44:47]
	v_mfma_f32_16x16x32_bf16 v[40:43], v[152:155], v[186:189], v[40:43]
	v_mfma_f32_16x16x32_bf16 v[28:31], v[144:147], v[194:197], v[28:31]
	v_mfma_f32_16x16x32_bf16 v[24:27], v[152:155], v[194:197], v[24:27]
	v_mfma_f32_16x16x32_bf16 v[12:15], v[144:147], v[202:205], v[12:15]
	v_mfma_f32_16x16x32_bf16 v[8:11], v[152:155], v[202:205], v[8:11]
	v_mfma_f32_16x16x32_bf16 v[60:63], v[148:151], v[182:185], v[60:63]
	v_mfma_f32_16x16x32_bf16 v[56:59], v[156:159], v[182:185], v[56:59]
	v_mfma_f32_16x16x32_bf16 v[44:47], v[148:151], v[190:193], v[44:47]
	v_mfma_f32_16x16x32_bf16 v[40:43], v[156:159], v[190:193], v[40:43]
	v_mfma_f32_16x16x32_bf16 v[28:31], v[148:151], v[198:201], v[28:31]
	v_mfma_f32_16x16x32_bf16 v[24:27], v[156:159], v[198:201], v[24:27]
	v_mfma_f32_16x16x32_bf16 v[12:15], v[148:151], v[206:209], v[12:15]
	v_mfma_f32_16x16x32_bf16 v[8:11], v[156:159], v[206:209], v[8:11]
	v_mfma_f32_16x16x32_bf16 v[52:55], v[160:163], v[178:181], v[52:55]
	v_mfma_f32_16x16x32_bf16 v[48:51], v[168:171], v[178:181], v[48:51]
	v_mfma_f32_16x16x32_bf16 v[36:39], v[160:163], v[186:189], v[36:39]
	v_mfma_f32_16x16x32_bf16 v[32:35], v[168:171], v[186:189], v[32:35]
	v_mfma_f32_16x16x32_bf16 v[20:23], v[160:163], v[194:197], v[20:23]
	v_mfma_f32_16x16x32_bf16 v[16:19], v[168:171], v[194:197], v[16:19]
	v_mfma_f32_16x16x32_bf16 v[4:7], v[160:163], v[202:205], v[4:7]
	v_mfma_f32_16x16x32_bf16 v[0:3], v[168:171], v[202:205], v[0:3]
	v_mfma_f32_16x16x32_bf16 v[52:55], v[164:167], v[182:185], v[52:55]
	v_mfma_f32_16x16x32_bf16 v[48:51], v[172:175], v[182:185], v[48:51]
	v_mfma_f32_16x16x32_bf16 v[36:39], v[164:167], v[190:193], v[36:39]
	v_mfma_f32_16x16x32_bf16 v[32:35], v[172:175], v[190:193], v[32:35]
	v_mfma_f32_16x16x32_bf16 v[20:23], v[164:167], v[198:201], v[20:23]
	v_mfma_f32_16x16x32_bf16 v[16:19], v[172:175], v[198:201], v[16:19]
	v_mfma_f32_16x16x32_bf16 v[4:7], v[164:167], v[206:209], v[4:7]
	v_mfma_f32_16x16x32_bf16 v[0:3], v[172:175], v[206:209], v[0:3]
	s_setprio 0
	s_barrier
	ds_read_b128 v[144:147], v141
	ds_read_b128 v[148:151], v141 offset:1024
	ds_read_b128 v[152:155], v141 offset:2048
	ds_read_b128 v[156:159], v141 offset:3072
	ds_read_b128 v[160:163], v142
	ds_read_b128 v[164:167], v142 offset:1024
	ds_read_b128 v[168:171], v142 offset:2048
	ds_read_b128 v[172:175], v142 offset:3072
	ds_read_b128 v[178:181], v140 offset:32768
	ds_read_b128 v[182:185], v140 offset:33792
	ds_read_b128 v[186:189], v140 offset:34816
	ds_read_b128 v[190:193], v140 offset:35840
	ds_read_b128 v[194:197], v140 offset:36864
	ds_read_b128 v[198:201], v140 offset:37888
	ds_read_b128 v[202:205], v140 offset:38912
	ds_read_b128 v[206:209], v140 offset:39936
	s_add_u32 s62, s26, 0x40000
	s_mov_b32 m0, s45
	s_addc_u32 s63, s27, 0
	global_load_lds_dwordx4 v134, s[62:63]
	s_add_u32 s62, s26, 0x60000
	s_mov_b32 m0, s46
	s_addc_u32 s63, s27, 0
	global_load_lds_dwordx4 v134, s[62:63]
	s_waitcnt vmcnt(8) lgkmcnt(0)
	s_barrier
	s_setprio 1
	v_mfma_f32_16x16x32_bf16 v[124:127], v[144:147], v[178:181], v[124:127]
	v_mfma_f32_16x16x32_bf16 v[120:123], v[152:155], v[178:181], v[120:123]
	v_mfma_f32_16x16x32_bf16 v[108:111], v[144:147], v[186:189], v[108:111]
	v_mfma_f32_16x16x32_bf16 v[104:107], v[152:155], v[186:189], v[104:107]
	v_mfma_f32_16x16x32_bf16 v[92:95], v[144:147], v[194:197], v[92:95]
	v_mfma_f32_16x16x32_bf16 v[88:91], v[152:155], v[194:197], v[88:91]
	v_mfma_f32_16x16x32_bf16 v[76:79], v[144:147], v[202:205], v[76:79]
	v_mfma_f32_16x16x32_bf16 v[72:75], v[152:155], v[202:205], v[72:75]
	v_mfma_f32_16x16x32_bf16 v[124:127], v[148:151], v[182:185], v[124:127]
	v_mfma_f32_16x16x32_bf16 v[120:123], v[156:159], v[182:185], v[120:123]
	v_mfma_f32_16x16x32_bf16 v[108:111], v[148:151], v[190:193], v[108:111]
	v_mfma_f32_16x16x32_bf16 v[104:107], v[156:159], v[190:193], v[104:107]
	v_mfma_f32_16x16x32_bf16 v[92:95], v[148:151], v[198:201], v[92:95]
	v_mfma_f32_16x16x32_bf16 v[88:91], v[156:159], v[198:201], v[88:91]
	v_mfma_f32_16x16x32_bf16 v[76:79], v[148:151], v[206:209], v[76:79]
	v_mfma_f32_16x16x32_bf16 v[72:75], v[156:159], v[206:209], v[72:75]
	v_mfma_f32_16x16x32_bf16 v[116:119], v[160:163], v[178:181], v[116:119]
	v_mfma_f32_16x16x32_bf16 v[112:115], v[168:171], v[178:181], v[112:115]
	v_mfma_f32_16x16x32_bf16 v[100:103], v[160:163], v[186:189], v[100:103]
	v_mfma_f32_16x16x32_bf16 v[96:99], v[168:171], v[186:189], v[96:99]
	v_mfma_f32_16x16x32_bf16 v[84:87], v[160:163], v[194:197], v[84:87]
	v_mfma_f32_16x16x32_bf16 v[80:83], v[168:171], v[194:197], v[80:83]
	v_mfma_f32_16x16x32_bf16 v[68:71], v[160:163], v[202:205], v[68:71]
	v_mfma_f32_16x16x32_bf16 v[64:67], v[168:171], v[202:205], v[64:67]
	v_mfma_f32_16x16x32_bf16 v[116:119], v[164:167], v[182:185], v[116:119]
	v_mfma_f32_16x16x32_bf16 v[112:115], v[172:175], v[182:185], v[112:115]
	v_mfma_f32_16x16x32_bf16 v[100:103], v[164:167], v[190:193], v[100:103]
	v_mfma_f32_16x16x32_bf16 v[96:99], v[172:175], v[190:193], v[96:99]
	v_mfma_f32_16x16x32_bf16 v[84:87], v[164:167], v[198:201], v[84:87]
	v_mfma_f32_16x16x32_bf16 v[80:83], v[172:175], v[198:201], v[80:83]
	v_mfma_f32_16x16x32_bf16 v[68:71], v[164:167], v[206:209], v[68:71]
	v_mfma_f32_16x16x32_bf16 v[64:67], v[172:175], v[206:209], v[64:67]
	s_setprio 0
	s_barrier
; #define PG8_STAGE(bufoff, gbase, voff, p64) do { _Pragma("unroll") for (int _i = 0; _i < 2; ++_i) { \
;         const char* _gb = (const char*)(gbase) + (size_t)_i * (p64); const unsigned _la = ldsbase + (unsigned)(bufoff) + (unsigned)_i * 8192u; \
;         asm volatile("s_mov_b32 m0, %0\n\ts_nop 0\n\tglobal_load_lds_dwordx4 %1, %2" :: "s"(_la), "v"(voff), "s"(_gb) : "memory"); } } while (0)
; #define PG8_LDA(dst, b, h) do { _Pragma("unroll") for (int m = 0; m < 4; ++m) _Pragma("unroll") for (int k = 0; k < 2; ++k) dst[m][k] = *(const LAS bf16x8*)(lds + PG8_SA(b, h) + aoff + m * 2048 + k * 1024); } while (0)
; #define PG8_MMA(ai, bj, At, Bt) do { __builtin_amdgcn_s_setprio(1); _Pragma("unroll") for (int m = 0; m < 4; ++m) _Pragma("unroll") for (int n = 0; n < 2; ++n) _Pragma("unroll") for (int k = 0; k < 2; ++k) \
;         acc[ai][bj][m][n] = __builtin_amdgcn_mfma_f32_16x16x32_bf16(Bt[n][k], At[m][k], acc[ai][bj][m][n], 0, 0, 0); __builtin_amdgcn_s_setprio(0); } while (0)
; #define PG8_WAIT_V(n) asm volatile("s_waitcnt vmcnt(" #n ")" ::: "memory")
; #define PG8_WAIT_L(n) asm volatile("s_waitcnt lgkmcnt(" #n ")" ::: "memory")
; #define PG8_BAR __builtin_amdgcn_s_barrier()
; #define PG8_SCHED __builtin_amdgcn_sched_barrier(0)
; template <class Epi, class Sched>
; __device__ __forceinline__ void gemm_phase(LAS unsigned char* lds, const Sched& S, const Epi& E) {
;     ...
;             PG8_LDA(At, 1, 1); PG8_STAGE(PG8_SB(1, 0), b3, vB2, hB2 / 2); PG8_STAGE(PG8_SB(1, 1), b3 + hB2, vB2, hB2 / 2); PG8_STAGE(PG8_SA(1, 0), a3, vA2, hA2 / 2);
;             PG8_WAIT_V(8); PG8_WAIT_L(0); PG8_BAR; PG8_MMA(1, 0, At, B0); PG8_MMA(1, 1, At, B1); PG8_BAR; PG8_SCHED;
;         }
;         if (wr == 0) PG8_BAR;
	s_add_u32 s62, s40, 0x80
	s_addc_u32 s63, s41, 0
	ds_read_b128 v[178:181], v140 offset:49152
	ds_read_b128 v[182:185], v140 offset:50176
	ds_read_b128 v[186:189], v140 offset:51200
	ds_read_b128 v[190:193], v140 offset:52224
	ds_read_b128 v[194:197], v140 offset:53248
	ds_read_b128 v[198:201], v140 offset:54272
	ds_read_b128 v[202:205], v140 offset:55296
	ds_read_b128 v[206:209], v140 offset:56320
	s_mov_b32 m0, s48
	s_nop 0
	global_load_lds_dwordx4 v135, s[62:63]
	s_add_u32 s62, s40, 0x20080
	s_mov_b32 m0, s49
	s_addc_u32 s63, s41, 0
	global_load_lds_dwordx4 v135, s[62:63]
	s_add_u32 s62, s40, 0x40080
	s_mov_b32 m0, s52
	s_addc_u32 s63, s41, 0
	global_load_lds_dwordx4 v135, s[62:63]
	s_add_u32 s40, s40, 0x60080
	s_mov_b32 m0, s53
	s_addc_u32 s41, s41, 0
	global_load_lds_dwordx4 v135, s[40:41]
	s_mov_b32 m0, s50
	s_nop 0
	global_load_lds_dwordx4 v134, s[38:39]
	s_add_u32 s26, s26, 0x20080
	s_mov_b32 m0, s51
	s_addc_u32 s27, s27, 0
	global_load_lds_dwordx4 v134, s[26:27]
	s_waitcnt vmcnt(8) lgkmcnt(0)
	s_barrier
	s_setprio 1
	v_mfma_f32_16x16x32_bf16 v[60:63], v[144:147], v[178:181], v[60:63]
	v_mfma_f32_16x16x32_bf16 v[56:59], v[152:155], v[178:181], v[56:59]
	v_mfma_f32_16x16x32_bf16 v[44:47], v[144:147], v[186:189], v[44:47]
	v_mfma_f32_16x16x32_bf16 v[40:43], v[152:155], v[186:189], v[40:43]
	v_mfma_f32_16x16x32_bf16 v[28:31], v[144:147], v[194:197], v[28:31]
	v_mfma_f32_16x16x32_bf16 v[24:27], v[152:155], v[194:197], v[24:27]
	v_mfma_f32_16x16x32_bf16 v[12:15], v[144:147], v[202:205], v[12:15]
	v_mfma_f32_16x16x32_bf16 v[8:11], v[152:155], v[202:205], v[8:11]
	v_mfma_f32_16x16x32_bf16 v[60:63], v[148:151], v[182:185], v[60:63]
	v_mfma_f32_16x16x32_bf16 v[56:59], v[156:159], v[182:185], v[56:59]
	v_mfma_f32_16x16x32_bf16 v[44:47], v[148:151], v[190:193], v[44:47]
	v_mfma_f32_16x16x32_bf16 v[40:43], v[156:159], v[190:193], v[40:43]
	v_mfma_f32_16x16x32_bf16 v[28:31], v[148:151], v[198:201], v[28:31]
	v_mfma_f32_16x16x32_bf16 v[24:27], v[156:159], v[198:201], v[24:27]
	v_mfma_f32_16x16x32_bf16 v[12:15], v[148:151], v[206:209], v[12:15]
	v_mfma_f32_16x16x32_bf16 v[8:11], v[156:159], v[206:209], v[8:11]
	v_mfma_f32_16x16x32_bf16 v[52:55], v[160:163], v[178:181], v[52:55]
	v_mfma_f32_16x16x32_bf16 v[48:51], v[168:171], v[178:181], v[48:51]
	v_mfma_f32_16x16x32_bf16 v[36:39], v[160:163], v[186:189], v[36:39]
	v_mfma_f32_16x16x32_bf16 v[32:35], v[168:171], v[186:189], v[32:35]
	v_mfma_f32_16x16x32_bf16 v[20:23], v[160:163], v[194:197], v[20:23]
	v_mfma_f32_16x16x32_bf16 v[16:19], v[168:171], v[194:197], v[16:19]
	v_mfma_f32_16x16x32_bf16 v[4:7], v[160:163], v[202:205], v[4:7]
	v_mfma_f32_16x16x32_bf16 v[0:3], v[168:171], v[202:205], v[0:3]
	v_mfma_f32_16x16x32_bf16 v[52:55], v[164:167], v[182:185], v[52:55]
	v_mfma_f32_16x16x32_bf16 v[48:51], v[172:175], v[182:185], v[48:51]
	v_mfma_f32_16x16x32_bf16 v[36:39], v[164:167], v[190:193], v[36:39]
	v_mfma_f32_16x16x32_bf16 v[32:35], v[172:175], v[190:193], v[32:35]
	v_mfma_f32_16x16x32_bf16 v[20:23], v[164:167], v[198:201], v[20:23]
	v_mfma_f32_16x16x32_bf16 v[16:19], v[172:175], v[198:201], v[16:19]
	v_mfma_f32_16x16x32_bf16 v[4:7], v[164:167], v[206:209], v[4:7]
	v_mfma_f32_16x16x32_bf16 v[0:3], v[172:175], v[206:209], v[0:3]
	s_setprio 0
	s_barrier
	s_cmp_gt_u32 s61, 13
	s_cbranch_scc0 .LBB0_1485
	s_and_b64 vcc, exec, s[14:15]
	s_cbranch_vccz .LBB0_1488
	s_barrier

; #define PG8_STAGE(bufoff, gbase, voff, p64) do { _Pragma("unroll") for (int _i = 0; _i < 2; ++_i) { \
;         const char* _gb = (const char*)(gbase) + (size_t)_i * (p64); const unsigned _la = ldsbase + (unsigned)(bufoff) + (unsigned)_i * 8192u; \
;         asm volatile("s_mov_b32 m0, %0\n\ts_nop 0\n\tglobal_load_lds_dwordx4 %1, %2" :: "s"(_la), "v"(voff), "s"(_gb) : "memory"); } } while (0)
; #define PG8_LDA(dst, b, h) do { _Pragma("unroll") for (int m = 0; m < 4; ++m) _Pragma("unroll") for (int k = 0; k < 2; ++k) dst[m][k] = *(const LAS bf16x8*)(lds + PG8_SA(b, h) + aoff + m * 2048 + k * 1024); } while (0)
; #define PG8_LDB(dst, b, h) do { _Pragma("unroll") for (int n = 0; n < 2; ++n) _Pragma("unroll") for (int k = 0; k < 2; ++k) dst[n][k] = *(const LAS bf16x8*)(lds + PG8_SB(b, h) + boff + n * 2048 + k * 1024); } while (0)
; #define PG8_MMA(ai, bj, At, Bt) do { __builtin_amdgcn_s_setprio(1); _Pragma("unroll") for (int m = 0; m < 4; ++m) _Pragma("unroll") for (int n = 0; n < 2; ++n) _Pragma("unroll") for (int k = 0; k < 2; ++k) \
;         acc[ai][bj][m][n] = __builtin_amdgcn_mfma_f32_16x16x32_bf16(Bt[n][k], At[m][k], acc[ai][bj][m][n], 0, 0, 0); __builtin_amdgcn_s_setprio(0); } while (0)
; #define PG8_WAIT_V(n) asm volatile("s_waitcnt vmcnt(" #n ")" ::: "memory")
; #define PG8_WAIT_L(n) asm volatile("s_waitcnt lgkmcnt(" #n ")" ::: "memory")
; #define PG8_BAR __builtin_amdgcn_s_barrier()
; #define PG8_SCHED __builtin_amdgcn_sched_barrier(0)
; template <class Epi, class Sched>
; __device__ __forceinline__ void gemm_phase(LAS unsigned char* lds, const Sched& S, const Epi& E) {
;     ...
;             PG8_LDB(B0, 0, 0); PG8_LDB(B1, 0, 1); PG8_SCHED; PG8_LDA(At, 0, 0); PG8_STAGE(PG8_SA(1, 1), a1 + hA, voffA, hA / 2);
;             PG8_WAIT_V(8); PG8_WAIT_L(0); PG8_BAR; PG8_MMA(0, 0, At, B0); PG8_MMA(0, 1, At, B1); PG8_BAR; PG8_SCHED;
;             PG8_LDA(At, 0, 1); PG8_STAGE(PG8_SB(0, 0), b2, vB2, hB2 / 2); PG8_STAGE(PG8_SB(0, 1), b2 + hB2, vB2, hB2 / 2); PG8_STAGE(PG8_SA(0, 0), a2, vA2, hA2 / 2);
.LBB0_1559:
	ds_read_b128 v[128:131], v179
	ds_read_b128 v[132:135], v179 offset:1024
	ds_read_b128 v[136:139], v179 offset:2048
	ds_read_b128 v[140:143], v179 offset:3072
	ds_read_b128 v[150:153], v180
	ds_read_b128 v[154:157], v180 offset:1024
	ds_read_b128 v[158:161], v180 offset:2048
	ds_read_b128 v[162:165], v180 offset:3072
	s_add_u32 s24, s22, 0xfff50080
	s_addc_u32 s25, s23, -1
	s_cmp_eq_u32 s61, 40
	s_cselect_b32 s24, s18, s24
	s_cselect_b32 s25, s19, s25
	s_cselect_b32 s38, s20, s59
	s_cselect_b32 s39, s21, s60
	s_add_u32 s26, s24, 0x80
	s_addc_u32 s27, s25, 0
	ds_read_b128 v[166:169], v181
	ds_read_b128 v[170:173], v181 offset:1024
	ds_read_b128 v[184:187], v181 offset:2048
	ds_read_b128 v[188:191], v181 offset:3072
	ds_read_b128 v[192:195], v181 offset:4096
	ds_read_b128 v[196:199], v181 offset:5120
	ds_read_b128 v[200:203], v181 offset:6144
	ds_read_b128 v[204:207], v181 offset:7168
	s_mov_b32 m0, s54
	s_nop 0
	global_load_lds_dwordx4 v144, s[22:23]
	s_add_u32 s62, s22, 0x58000
	s_mov_b32 m0, s55
	s_addc_u32 s63, s23, 0
	global_load_lds_dwordx4 v144, s[62:63]
	s_waitcnt vmcnt(8) lgkmcnt(0)
	s_barrier
	s_setprio 1
	v_mfma_f32_16x16x32_bf16 v[124:127], v[128:131], v[166:169], v[124:127]
	v_mfma_f32_16x16x32_bf16 v[120:123], v[136:139], v[166:169], v[120:123]
	v_mfma_f32_16x16x32_bf16 v[116:119], v[128:131], v[184:187], v[116:119]
	v_mfma_f32_16x16x32_bf16 v[112:115], v[136:139], v[184:187], v[112:115]
	v_mfma_f32_16x16x32_bf16 v[108:111], v[128:131], v[192:195], v[108:111]
	v_mfma_f32_16x16x32_bf16 v[104:107], v[136:139], v[192:195], v[104:107]
	v_mfma_f32_16x16x32_bf16 v[100:103], v[128:131], v[200:203], v[100:103]
	v_mfma_f32_16x16x32_bf16 v[96:99], v[136:139], v[200:203], v[96:99]
	v_mfma_f32_16x16x32_bf16 v[124:127], v[132:135], v[170:173], v[124:127]
	v_mfma_f32_16x16x32_bf16 v[120:123], v[140:143], v[170:173], v[120:123]
	v_mfma_f32_16x16x32_bf16 v[116:119], v[132:135], v[188:191], v[116:119]
	v_mfma_f32_16x16x32_bf16 v[112:115], v[140:143], v[188:191], v[112:115]
	v_mfma_f32_16x16x32_bf16 v[108:111], v[132:135], v[196:199], v[108:111]
	v_mfma_f32_16x16x32_bf16 v[104:107], v[140:143], v[196:199], v[104:107]
	v_mfma_f32_16x16x32_bf16 v[100:103], v[132:135], v[204:207], v[100:103]
	v_mfma_f32_16x16x32_bf16 v[96:99], v[140:143], v[204:207], v[96:99]
	s_add_i32 s61, s61, 2
	s_add_u32 s22, s22, 0x100
	s_addc_u32 s23, s23, 0
	s_add_u32 s59, s59, 0x100
	s_addc_u32 s60, s60, 0
	v_mfma_f32_16x16x32_bf16 v[60:63], v[150:153], v[166:169], v[60:63]
	v_mfma_f32_16x16x32_bf16 v[56:59], v[158:161], v[166:169], v[56:59]
	v_mfma_f32_16x16x32_bf16 v[52:55], v[150:153], v[184:187], v[52:55]
	v_mfma_f32_16x16x32_bf16 v[48:51], v[158:161], v[184:187], v[48:51]
	v_mfma_f32_16x16x32_bf16 v[44:47], v[150:153], v[192:195], v[44:47]
	v_mfma_f32_16x16x32_bf16 v[40:43], v[158:161], v[192:195], v[40:43]
	v_mfma_f32_16x16x32_bf16 v[36:39], v[150:153], v[200:203], v[36:39]
	v_mfma_f32_16x16x32_bf16 v[32:35], v[158:161], v[200:203], v[32:35]
	v_mfma_f32_16x16x32_bf16 v[60:63], v[154:157], v[170:173], v[60:63]
	v_mfma_f32_16x16x32_bf16 v[56:59], v[162:165], v[170:173], v[56:59]
	v_mfma_f32_16x16x32_bf16 v[52:55], v[154:157], v[188:191], v[52:55]
	v_mfma_f32_16x16x32_bf16 v[48:51], v[162:165], v[188:191], v[48:51]
	v_mfma_f32_16x16x32_bf16 v[44:47], v[154:157], v[196:199], v[44:47]
	v_mfma_f32_16x16x32_bf16 v[40:43], v[162:165], v[196:199], v[40:43]
	v_mfma_f32_16x16x32_bf16 v[36:39], v[154:157], v[204:207], v[36:39]
	v_mfma_f32_16x16x32_bf16 v[32:35], v[162:165], v[204:207], v[32:35]
	s_setprio 0
	s_barrier
	s_add_u32 s62, s38, 0x58000
	ds_read_b128 v[166:169], v181 offset:16384
	ds_read_b128 v[170:173], v181 offset:17408
	ds_read_b128 v[184:187], v181 offset:18432
	ds_read_b128 v[188:191], v181 offset:19456
	ds_read_b128 v[192:195], v181 offset:20480
	ds_read_b128 v[196:199], v181 offset:21504
	ds_read_b128 v[200:203], v181 offset:22528
	ds_read_b128 v[204:207], v181 offset:23552
	s_mov_b32 m0, s35
	s_nop 0
	global_load_lds_dwordx4 v145, s[38:39]
	s_mov_b32 m0, s36
	s_addc_u32 s63, s39, 0
	global_load_lds_dwordx4 v145, s[62:63]
	s_add_u32 s62, s38, 0xb0000
	s_mov_b32 m0, s37
	s_addc_u32 s63, s39, 0
	global_load_lds_dwordx4 v145, s[62:63]
	s_add_u32 s62, s38, 0x108000
	s_mov_b32 m0, s40
	s_addc_u32 s63, s39, 0
	global_load_lds_dwordx4 v145, s[62:63]
	s_mov_b32 m0, s34
	s_nop 0
	global_load_lds_dwordx4 v144, s[24:25]
	s_add_u32 s62, s24, 0x58000
	s_mov_b32 m0, s41
	s_addc_u32 s63, s25, 0
	global_load_lds_dwordx4 v144, s[62:63]
	s_waitcnt vmcnt(8) lgkmcnt(0)
	s_barrier
; #define PG8_STAGE(bufoff, gbase, voff, p64) do { _Pragma("unroll") for (int _i = 0; _i < 2; ++_i) { \
;         const char* _gb = (const char*)(gbase) + (size_t)_i * (p64); const unsigned _la = ldsbase + (unsigned)(bufoff) + (unsigned)_i * 8192u; \
;         asm volatile("s_mov_b32 m0, %0\n\ts_nop 0\n\tglobal_load_lds_dwordx4 %1, %2" :: "s"(_la), "v"(voff), "s"(_gb) : "memory"); } } while (0)
; #define PG8_LDA(dst, b, h) do { _Pragma("unroll") for (int m = 0; m < 4; ++m) _Pragma("unroll") for (int k = 0; k < 2; ++k) dst[m][k] = *(const LAS bf16x8*)(lds + PG8_SA(b, h) + aoff + m * 2048 + k * 1024); } while (0)
; #define PG8_LDB(dst, b, h) do { _Pragma("unroll") for (int n = 0; n < 2; ++n) _Pragma("unroll") for (int k = 0; k < 2; ++k) dst[n][k] = *(const LAS bf16x8*)(lds + PG8_SB(b, h) + boff + n * 2048 + k * 1024); } while (0)
; #define PG8_MMA(ai, bj, At, Bt) do { __builtin_amdgcn_s_setprio(1); _Pragma("unroll") for (int m = 0; m < 4; ++m) _Pragma("unroll") for (int n = 0; n < 2; ++n) _Pragma("unroll") for (int k = 0; k < 2; ++k) \
;         acc[ai][bj][m][n] = __builtin_amdgcn_mfma_f32_16x16x32_bf16(Bt[n][k], At[m][k], acc[ai][bj][m][n], 0, 0, 0); __builtin_amdgcn_s_setprio(0); } while (0)
; #define PG8_WAIT_V(n) asm volatile("s_waitcnt vmcnt(" #n ")" ::: "memory")
; #define PG8_WAIT_L(n) asm volatile("s_waitcnt lgkmcnt(" #n ")" ::: "memory")
; #define PG8_BAR __builtin_amdgcn_s_barrier()
; #define PG8_SCHED __builtin_amdgcn_sched_barrier(0)
; template <class Epi, class Sched>
; __device__ __forceinline__ void gemm_phase(LAS unsigned char* lds, const Sched& S, const Epi& E) {
;     ...
;             PG8_WAIT_V(8); PG8_WAIT_L(0); PG8_BAR; PG8_MMA(1, 0, At, B0); PG8_MMA(1, 1, At, B1); PG8_BAR; PG8_SCHED;
;             PG8_LDB(B0, 1, 0); PG8_LDB(B1, 1, 1); PG8_SCHED; PG8_LDA(At, 1, 0); PG8_STAGE(PG8_SA(0, 1), a2 + hA2, vA2, hA2 / 2);
;             PG8_WAIT_V(8); PG8_WAIT_L(0); PG8_BAR; PG8_MMA(0, 0, At, B0); PG8_MMA(0, 1, At, B1); PG8_BAR; PG8_SCHED;
	s_setprio 1
	v_mfma_f32_16x16x32_bf16 v[92:95], v[128:131], v[166:169], v[92:95]
	v_mfma_f32_16x16x32_bf16 v[88:91], v[136:139], v[166:169], v[88:91]
	v_mfma_f32_16x16x32_bf16 v[84:87], v[128:131], v[184:187], v[84:87]
	v_mfma_f32_16x16x32_bf16 v[80:83], v[136:139], v[184:187], v[80:83]
	v_mfma_f32_16x16x32_bf16 v[76:79], v[128:131], v[192:195], v[76:79]
	v_mfma_f32_16x16x32_bf16 v[72:75], v[136:139], v[192:195], v[72:75]
	v_mfma_f32_16x16x32_bf16 v[68:71], v[128:131], v[200:203], v[68:71]
	v_mfma_f32_16x16x32_bf16 v[64:67], v[136:139], v[200:203], v[64:67]
	v_mfma_f32_16x16x32_bf16 v[92:95], v[132:135], v[170:173], v[92:95]
	v_mfma_f32_16x16x32_bf16 v[88:91], v[140:143], v[170:173], v[88:91]
	v_mfma_f32_16x16x32_bf16 v[84:87], v[132:135], v[188:191], v[84:87]
	v_mfma_f32_16x16x32_bf16 v[80:83], v[140:143], v[188:191], v[80:83]
	v_mfma_f32_16x16x32_bf16 v[76:79], v[132:135], v[196:199], v[76:79]
	v_mfma_f32_16x16x32_bf16 v[72:75], v[140:143], v[196:199], v[72:75]
	v_mfma_f32_16x16x32_bf16 v[68:71], v[132:135], v[204:207], v[68:71]
	v_mfma_f32_16x16x32_bf16 v[64:67], v[140:143], v[204:207], v[64:67]
	v_mfma_f32_16x16x32_bf16 v[28:31], v[150:153], v[166:169], v[28:31]
	v_mfma_f32_16x16x32_bf16 v[24:27], v[158:161], v[166:169], v[24:27]
	v_mfma_f32_16x16x32_bf16 v[20:23], v[150:153], v[184:187], v[20:23]
	v_mfma_f32_16x16x32_bf16 v[16:19], v[158:161], v[184:187], v[16:19]
	v_mfma_f32_16x16x32_bf16 v[12:15], v[150:153], v[192:195], v[12:15]
	v_mfma_f32_16x16x32_bf16 v[8:11], v[158:161], v[192:195], v[8:11]
	v_mfma_f32_16x16x32_bf16 v[4:7], v[150:153], v[200:203], v[4:7]
	v_mfma_f32_16x16x32_bf16 v[0:3], v[158:161], v[200:203], v[0:3]
	v_mfma_f32_16x16x32_bf16 v[28:31], v[154:157], v[170:173], v[28:31]
	v_mfma_f32_16x16x32_bf16 v[24:27], v[162:165], v[170:173], v[24:27]
	v_mfma_f32_16x16x32_bf16 v[20:23], v[154:157], v[188:191], v[20:23]
	v_mfma_f32_16x16x32_bf16 v[16:19], v[162:165], v[188:191], v[16:19]
	v_mfma_f32_16x16x32_bf16 v[12:15], v[154:157], v[196:199], v[12:15]
	v_mfma_f32_16x16x32_bf16 v[8:11], v[162:165], v[196:199], v[8:11]
	v_mfma_f32_16x16x32_bf16 v[4:7], v[154:157], v[204:207], v[4:7]
	v_mfma_f32_16x16x32_bf16 v[0:3], v[162:165], v[204:207], v[0:3]
	s_setprio 0
	s_barrier
	ds_read_b128 v[128:131], v182
	ds_read_b128 v[132:135], v182 offset:1024
	ds_read_b128 v[136:139], v182 offset:2048
	ds_read_b128 v[140:143], v182 offset:3072
	ds_read_b128 v[150:153], v183
	ds_read_b128 v[154:157], v183 offset:1024
	ds_read_b128 v[158:161], v183 offset:2048
	ds_read_b128 v[162:165], v183 offset:3072
	ds_read_b128 v[166:169], v181 offset:32768
	ds_read_b128 v[170:173], v181 offset:33792
	ds_read_b128 v[184:187], v181 offset:34816
	ds_read_b128 v[188:191], v181 offset:35840
	ds_read_b128 v[192:195], v181 offset:36864
	ds_read_b128 v[196:199], v181 offset:37888
	ds_read_b128 v[200:203], v181 offset:38912
	ds_read_b128 v[204:207], v181 offset:39936
	s_add_u32 s62, s24, 0xb0000
	s_mov_b32 m0, s42
	s_addc_u32 s63, s25, 0
	global_load_lds_dwordx4 v144, s[62:63]
	s_add_u32 s62, s24, 0x108000
	s_mov_b32 m0, s43
	s_addc_u32 s63, s25, 0
	global_load_lds_dwordx4 v144, s[62:63]
	s_waitcnt vmcnt(8) lgkmcnt(0)
	s_barrier
	s_setprio 1
	v_mfma_f32_16x16x32_bf16 v[124:127], v[128:131], v[166:169], v[124:127]
	v_mfma_f32_16x16x32_bf16 v[120:123], v[136:139], v[166:169], v[120:123]
	v_mfma_f32_16x16x32_bf16 v[116:119], v[128:131], v[184:187], v[116:119]
	v_mfma_f32_16x16x32_bf16 v[112:115], v[136:139], v[184:187], v[112:115]
	v_mfma_f32_16x16x32_bf16 v[108:111], v[128:131], v[192:195], v[108:111]
	v_mfma_f32_16x16x32_bf16 v[104:107], v[136:139], v[192:195], v[104:107]
	v_mfma_f32_16x16x32_bf16 v[100:103], v[128:131], v[200:203], v[100:103]
	v_mfma_f32_16x16x32_bf16 v[96:99], v[136:139], v[200:203], v[96:99]
	v_mfma_f32_16x16x32_bf16 v[124:127], v[132:135], v[170:173], v[124:127]
	v_mfma_f32_16x16x32_bf16 v[120:123], v[140:143], v[170:173], v[120:123]
	v_mfma_f32_16x16x32_bf16 v[116:119], v[132:135], v[188:191], v[116:119]
	v_mfma_f32_16x16x32_bf16 v[112:115], v[140:143], v[188:191], v[112:115]
	v_mfma_f32_16x16x32_bf16 v[108:111], v[132:135], v[196:199], v[108:111]
	v_mfma_f32_16x16x32_bf16 v[104:107], v[140:143], v[196:199], v[104:107]
	v_mfma_f32_16x16x32_bf16 v[100:103], v[132:135], v[204:207], v[100:103]
	v_mfma_f32_16x16x32_bf16 v[96:99], v[140:143], v[204:207], v[96:99]
	v_mfma_f32_16x16x32_bf16 v[60:63], v[150:153], v[166:169], v[60:63]
	v_mfma_f32_16x16x32_bf16 v[56:59], v[158:161], v[166:169], v[56:59]
	v_mfma_f32_16x16x32_bf16 v[52:55], v[150:153], v[184:187], v[52:55]
	v_mfma_f32_16x16x32_bf16 v[48:51], v[158:161], v[184:187], v[48:51]
	v_mfma_f32_16x16x32_bf16 v[44:47], v[150:153], v[192:195], v[44:47]
	v_mfma_f32_16x16x32_bf16 v[40:43], v[158:161], v[192:195], v[40:43]
	v_mfma_f32_16x16x32_bf16 v[36:39], v[150:153], v[200:203], v[36:39]
	v_mfma_f32_16x16x32_bf16 v[32:35], v[158:161], v[200:203], v[32:35]
	v_mfma_f32_16x16x32_bf16 v[60:63], v[154:157], v[170:173], v[60:63]
	v_mfma_f32_16x16x32_bf16 v[56:59], v[162:165], v[170:173], v[56:59]
	v_mfma_f32_16x16x32_bf16 v[52:55], v[154:157], v[188:191], v[52:55]
	v_mfma_f32_16x16x32_bf16 v[48:51], v[162:165], v[188:191], v[48:51]
	v_mfma_f32_16x16x32_bf16 v[44:47], v[154:157], v[196:199], v[44:47]
	v_mfma_f32_16x16x32_bf16 v[40:43], v[162:165], v[196:199], v[40:43]
	v_mfma_f32_16x16x32_bf16 v[36:39], v[154:157], v[204:207], v[36:39]
	v_mfma_f32_16x16x32_bf16 v[32:35], v[162:165], v[204:207], v[32:35]
	s_setprio 0
	s_barrier
; #define PG8_STAGE(bufoff, gbase, voff, p64) do { _Pragma("unroll") for (int _i = 0; _i < 2; ++_i) { \
;         const char* _gb = (const char*)(gbase) + (size_t)_i * (p64); const unsigned _la = ldsbase + (unsigned)(bufoff) + (unsigned)_i * 8192u; \
;         asm volatile("s_mov_b32 m0, %0\n\ts_nop 0\n\tglobal_load_lds_dwordx4 %1, %2" :: "s"(_la), "v"(voff), "s"(_gb) : "memory"); } } while (0)
; #define PG8_LDA(dst, b, h) do { _Pragma("unroll") for (int m = 0; m < 4; ++m) _Pragma("unroll") for (int k = 0; k < 2; ++k) dst[m][k] = *(const LAS bf16x8*)(lds + PG8_SA(b, h) + aoff + m * 2048 + k * 1024); } while (0)
; #define PG8_MMA(ai, bj, At, Bt) do { __builtin_amdgcn_s_setprio(1); _Pragma("unroll") for (int m = 0; m < 4; ++m) _Pragma("unroll") for (int n = 0; n < 2; ++n) _Pragma("unroll") for (int k = 0; k < 2; ++k) \
;         acc[ai][bj][m][n] = __builtin_amdgcn_mfma_f32_16x16x32_bf16(Bt[n][k], At[m][k], acc[ai][bj][m][n], 0, 0, 0); __builtin_amdgcn_s_setprio(0); } while (0)
; #define PG8_WAIT_V(n) asm volatile("s_waitcnt vmcnt(" #n ")" ::: "memory")
; #define PG8_WAIT_L(n) asm volatile("s_waitcnt lgkmcnt(" #n ")" ::: "memory")
; #define PG8_BAR __builtin_amdgcn_s_barrier()
; #define PG8_SCHED __builtin_amdgcn_sched_barrier(0)
; template <class Epi, class Sched>
; __device__ __forceinline__ void gemm_phase(LAS unsigned char* lds, const Sched& S, const Epi& E) {
;     ...
;             PG8_LDA(At, 1, 1); PG8_STAGE(PG8_SB(1, 0), b3, vB2, hB2 / 2); PG8_STAGE(PG8_SB(1, 1), b3 + hB2, vB2, hB2 / 2); PG8_STAGE(PG8_SA(1, 0), a3, vA2, hA2 / 2);
;             PG8_WAIT_V(8); PG8_WAIT_L(0); PG8_BAR; PG8_MMA(1, 0, At, B0); PG8_MMA(1, 1, At, B1); PG8_BAR; PG8_SCHED;
;         }
;         if (wr == 0) PG8_BAR;
	s_add_u32 s62, s38, 0x80
	s_addc_u32 s63, s39, 0
	ds_read_b128 v[166:169], v181 offset:49152
	ds_read_b128 v[170:173], v181 offset:50176
	ds_read_b128 v[184:187], v181 offset:51200
	ds_read_b128 v[188:191], v181 offset:52224
	ds_read_b128 v[192:195], v181 offset:53248
	ds_read_b128 v[196:199], v181 offset:54272
	ds_read_b128 v[200:203], v181 offset:55296
	ds_read_b128 v[204:207], v181 offset:56320
	s_mov_b32 m0, s48
	s_nop 0
	global_load_lds_dwordx4 v145, s[62:63]
	s_add_u32 s62, s38, 0x58080
	s_mov_b32 m0, s49
	s_addc_u32 s63, s39, 0
	global_load_lds_dwordx4 v145, s[62:63]
	s_add_u32 s62, s38, 0xb0080
	s_mov_b32 m0, s52
	s_addc_u32 s63, s39, 0
	global_load_lds_dwordx4 v145, s[62:63]
	s_add_u32 s38, s38, 0x108080
	s_mov_b32 m0, s53
	s_addc_u32 s39, s39, 0
	global_load_lds_dwordx4 v145, s[38:39]
	s_mov_b32 m0, s50
	s_nop 0
	global_load_lds_dwordx4 v144, s[26:27]
	s_add_u32 s24, s24, 0x58080
	s_mov_b32 m0, s51
	s_addc_u32 s25, s25, 0
	global_load_lds_dwordx4 v144, s[24:25]
	s_waitcnt vmcnt(8) lgkmcnt(0)
	s_barrier
	s_setprio 1
	v_mfma_f32_16x16x32_bf16 v[92:95], v[128:131], v[166:169], v[92:95]
	v_mfma_f32_16x16x32_bf16 v[88:91], v[136:139], v[166:169], v[88:91]
	v_mfma_f32_16x16x32_bf16 v[84:87], v[128:131], v[184:187], v[84:87]
	v_mfma_f32_16x16x32_bf16 v[80:83], v[136:139], v[184:187], v[80:83]
	v_mfma_f32_16x16x32_bf16 v[76:79], v[128:131], v[192:195], v[76:79]
	v_mfma_f32_16x16x32_bf16 v[72:75], v[136:139], v[192:195], v[72:75]
	v_mfma_f32_16x16x32_bf16 v[68:71], v[128:131], v[200:203], v[68:71]
	v_mfma_f32_16x16x32_bf16 v[64:67], v[136:139], v[200:203], v[64:67]
	v_mfma_f32_16x16x32_bf16 v[92:95], v[132:135], v[170:173], v[92:95]
	v_mfma_f32_16x16x32_bf16 v[88:91], v[140:143], v[170:173], v[88:91]
	v_mfma_f32_16x16x32_bf16 v[84:87], v[132:135], v[188:191], v[84:87]
	v_mfma_f32_16x16x32_bf16 v[80:83], v[140:143], v[188:191], v[80:83]
	v_mfma_f32_16x16x32_bf16 v[76:79], v[132:135], v[196:199], v[76:79]
	v_mfma_f32_16x16x32_bf16 v[72:75], v[140:143], v[196:199], v[72:75]
	v_mfma_f32_16x16x32_bf16 v[68:71], v[132:135], v[204:207], v[68:71]
	v_mfma_f32_16x16x32_bf16 v[64:67], v[140:143], v[204:207], v[64:67]
	v_mfma_f32_16x16x32_bf16 v[28:31], v[150:153], v[166:169], v[28:31]
	v_mfma_f32_16x16x32_bf16 v[24:27], v[158:161], v[166:169], v[24:27]
	v_mfma_f32_16x16x32_bf16 v[20:23], v[150:153], v[184:187], v[20:23]
	v_mfma_f32_16x16x32_bf16 v[16:19], v[158:161], v[184:187], v[16:19]
	v_mfma_f32_16x16x32_bf16 v[12:15], v[150:153], v[192:195], v[12:15]
	v_mfma_f32_16x16x32_bf16 v[8:11], v[158:161], v[192:195], v[8:11]
	v_mfma_f32_16x16x32_bf16 v[4:7], v[150:153], v[200:203], v[4:7]
	v_mfma_f32_16x16x32_bf16 v[0:3], v[158:161], v[200:203], v[0:3]
	v_mfma_f32_16x16x32_bf16 v[28:31], v[154:157], v[170:173], v[28:31]
	v_mfma_f32_16x16x32_bf16 v[24:27], v[162:165], v[170:173], v[24:27]
	v_mfma_f32_16x16x32_bf16 v[20:23], v[154:157], v[188:191], v[20:23]
	v_mfma_f32_16x16x32_bf16 v[16:19], v[162:165], v[188:191], v[16:19]
	v_mfma_f32_16x16x32_bf16 v[12:15], v[154:157], v[196:199], v[12:15]
	v_mfma_f32_16x16x32_bf16 v[8:11], v[162:165], v[196:199], v[8:11]
	v_mfma_f32_16x16x32_bf16 v[4:7], v[154:157], v[204:207], v[4:7]
	v_mfma_f32_16x16x32_bf16 v[0:3], v[162:165], v[204:207], v[0:3]
	s_setprio 0
	s_barrier
	s_cmp_gt_u32 s61, 41
	s_cbranch_scc0 .LBB0_1559
	s_and_b64 vcc, exec, s[12:13]
	s_cbranch_vccz .LBB0_1562
	s_barrier
